# hand-written streaming P1 and P6 (pre-norm/modulate and residual+norm phases): 9 contiguous rows per wave, adaLN params hoisted into registers (reloaded only when the batch index changes), 2-deep row
# speedup vs baseline: 1.0108x; 1.0108x over previous
; __device__ __forceinline__ unsigned cvt_pk_bf16(float lo, float hi) { unsigned r; asm volatile("v_cvt_pk_bf16_f32 %0, %1, %2" : "=v"(r) : "v"(lo), "v"(hi)); return r; }
; #define FRESH() int gtid; do { int t_ = threadIdx.x; asm volatile("" : "+v"(t_)); F.tid = t_; F.lane = t_ & 63; gtid = blockIdx.x * (NWAVES * 64) + t_; (void)gtid; } while (0)
; __device__ __forceinline__ void modulate_store(const f32x4 (&v)[8], float rstd, const float* pn, const float* modr, bf16_t* orow, int lane) {
; #pragma unroll
;     for (int j = 0; j < 8; ++j) { const int col = 4 * lane + 256 * j;
;         const f32x4 g = *(const f32x4*)(pn + col), sh = *(const f32x4*)(modr + col), sc = *(const f32x4*)(modr + DM + col);
;         const f32x4 hh = v[j] * rstd * g * (sc + 1.f) + sh;
;         u32x2 w; w.x = cvt_pk_bf16(hh[0], hh[1]); w.y = cvt_pk_bf16(hh[2], hh[3]);
;         *(u32x2*)(orow + col) = w; }
; __global__ void __launch_bounds__(NWAVES * 64, 2) mk_fwd(Args args) {
;     ...
;     if (IN(1)) { FRESH();
;         for (int row0 = F.gw * 3; row0 < MT; row0 += F.NGW * 3) {
;             f32x4 v[3][8];
; #pragma unroll
;             for (int q = 0; q < 3; ++q) { const int row = row0 + q; const float* src = row < ML ? x + (size_t)row * DM : ctx + (size_t)(row - ML) * DM; load_row_f32(src, F.lane, v[q]); }
; #pragma unroll
;             for (int q = 0; q < 3; ++q) { const int row = row0 + q; const int r = row < ML ? row / SEQ : 8;
;                 const float rstd = __builtin_amdgcn_rsqf(sumsq8(v[q]) * (1.f / DM) + EPS);
;                 modulate_store(v[q], rstd, pre_norm, mod + (size_t)r * 6144, H + (size_t)row * DM, F.lane); }
.LBB0_184:
	s_cmp_lt_i32 s86, 2
	s_cselect_b64 s[0:1], -1, 0
	s_add_u32 s12, s84, 0x4000000
	s_addc_u32 s13, s85, 0
	s_and_b64 s[4:5], s[0:1], s[4:5]
	s_andn2_b64 vcc, exec, s[4:5]
	s_cbranch_vccnz .LBB0_194
	s_cmpk_lg_i32 s63, 0x100
	s_cbranch_scc1 .Lp1_generic
	v_and_b32_e32 v130, 63, v198
	v_lshlrev_b32_e32 v128, 4, v130
	v_add_u32_e32 v129, 0x1000, v128
	v_lshlrev_b32_e32 v130, 3, v130
	v_mov_b32_e32 v131, 0x358637bd
	s_mul_i32 s6, s33, 9
	s_mov_b32 s7, -1
	s_add_i32 s4, s6, 0
	s_cmp_lt_u32 s4, 0x4000
	s_cselect_b32 s10, s68, s72
	s_cselect_b32 s11, s69, s73
	s_cselect_b32 s5, 0, 0x4000
	s_sub_i32 s5, s4, s5
	s_lshl_b32 s5, s5, 13
	s_add_u32 s10, s10, s5
	s_addc_u32 s11, s11, 0
	global_load_dwordx4 v[0:3], v128, s[10:11] offset:0
	global_load_dwordx4 v[4:7], v128, s[10:11] offset:1024
	global_load_dwordx4 v[8:11], v128, s[10:11] offset:2048
	global_load_dwordx4 v[12:15], v128, s[10:11] offset:3072
	global_load_dwordx4 v[16:19], v129, s[10:11] offset:0
	global_load_dwordx4 v[20:23], v129, s[10:11] offset:1024
	global_load_dwordx4 v[24:27], v129, s[10:11] offset:2048
	global_load_dwordx4 v[28:31], v129, s[10:11] offset:3072
	s_add_i32 s4, s6, 0
	s_add_i32 s4, s6, 0
	s_lshr_b32 s8, s4, 11
	s_cmp_lt_u32 s4, 0x4000
	s_cselect_b32 s8, s8, 8
	s_cmp_eq_u32 s8, s7
	s_cbranch_scc1 .Lp1_np0
	s_mov_b32 s7, s8
	s_add_i32 s5, s8, 0
	s_mul_i32 s5, s5, 0x6000
	s_add_u32 s24, s84, s5
	s_addc_u32 s25, s85, 0
	s_add_u32 s24, s24, 0x2000
	s_addc_u32 s25, s25, 0
	s_add_i32 s5, s8, 0
	s_mul_i32 s5, s5, 0x6000
	s_add_u32 s16, s84, s5
	s_addc_u32 s17, s85, 0
	s_add_u32 s18, s80, 0x0
	s_addc_u32 s19, s81, 0
	global_load_dwordx4 v[64:67], v128, s[18:19] offset:0
	global_load_dwordx4 v[96:99], v128, s[16:17] offset:0
	global_load_dwordx4 v[68:71], v128, s[18:19] offset:1024
	global_load_dwordx4 v[100:103], v128, s[16:17] offset:1024
	global_load_dwordx4 v[72:75], v128, s[18:19] offset:2048
	global_load_dwordx4 v[104:107], v128, s[16:17] offset:2048
	global_load_dwordx4 v[76:79], v128, s[18:19] offset:3072
	global_load_dwordx4 v[108:111], v128, s[16:17] offset:3072
	global_load_dwordx4 v[80:83], v129, s[18:19] offset:0
	global_load_dwordx4 v[112:115], v129, s[16:17] offset:0
	global_load_dwordx4 v[84:87], v129, s[18:19] offset:1024
	global_load_dwordx4 v[116:119], v129, s[16:17] offset:1024
	global_load_dwordx4 v[88:91], v129, s[18:19] offset:2048
	global_load_dwordx4 v[120:123], v129, s[16:17] offset:2048
	global_load_dwordx4 v[92:95], v129, s[18:19] offset:3072
	global_load_dwordx4 v[124:127], v129, s[16:17] offset:3072
	global_load_dwordx4 v[32:35], v128, s[24:25] offset:0
	global_load_dwordx4 v[36:39], v128, s[24:25] offset:1024
	global_load_dwordx4 v[40:43], v128, s[24:25] offset:2048
	global_load_dwordx4 v[44:47], v128, s[24:25] offset:3072
	global_load_dwordx4 v[48:51], v129, s[24:25] offset:0
	global_load_dwordx4 v[52:55], v129, s[24:25] offset:1024
	global_load_dwordx4 v[56:59], v129, s[24:25] offset:2048
	global_load_dwordx4 v[60:63], v129, s[24:25] offset:3072
	s_waitcnt vmcnt(0)
	v_add_f32_e32 v32, 1.0, v32
	v_add_f32_e32 v33, 1.0, v33
	v_add_f32_e32 v34, 1.0, v34
	v_add_f32_e32 v35, 1.0, v35
	v_add_f32_e32 v36, 1.0, v36
	v_add_f32_e32 v37, 1.0, v37
	v_add_f32_e32 v38, 1.0, v38
	v_add_f32_e32 v39, 1.0, v39
	v_add_f32_e32 v40, 1.0, v40
	v_add_f32_e32 v41, 1.0, v41
	v_add_f32_e32 v42, 1.0, v42
	v_add_f32_e32 v43, 1.0, v43
	v_add_f32_e32 v44, 1.0, v44
	v_add_f32_e32 v45, 1.0, v45
	v_add_f32_e32 v46, 1.0, v46
	v_add_f32_e32 v47, 1.0, v47
	v_add_f32_e32 v48, 1.0, v48
	v_add_f32_e32 v49, 1.0, v49
	v_add_f32_e32 v50, 1.0, v50
	v_add_f32_e32 v51, 1.0, v51
	v_add_f32_e32 v52, 1.0, v52
	v_add_f32_e32 v53, 1.0, v53
	v_add_f32_e32 v54, 1.0, v54
	v_add_f32_e32 v55, 1.0, v55
	v_add_f32_e32 v56, 1.0, v56
	v_add_f32_e32 v57, 1.0, v57
	v_add_f32_e32 v58, 1.0, v58
	v_add_f32_e32 v59, 1.0, v59
	v_add_f32_e32 v60, 1.0, v60
	v_add_f32_e32 v61, 1.0, v61
	v_add_f32_e32 v62, 1.0, v62
	v_add_f32_e32 v63, 1.0, v63
	v_mul_f32_e32 v64, v64, v32
	v_mul_f32_e32 v65, v65, v33
	v_mul_f32_e32 v66, v66, v34
	v_mul_f32_e32 v67, v67, v35
	v_mul_f32_e32 v68, v68, v36
	v_mul_f32_e32 v69, v69, v37
	v_mul_f32_e32 v70, v70, v38
	v_mul_f32_e32 v71, v71, v39
	v_mul_f32_e32 v72, v72, v40
	v_mul_f32_e32 v73, v73, v41
	v_mul_f32_e32 v74, v74, v42
	v_mul_f32_e32 v75, v75, v43
	v_mul_f32_e32 v76, v76, v44
	v_mul_f32_e32 v77, v77, v45
	v_mul_f32_e32 v78, v78, v46
	v_mul_f32_e32 v79, v79, v47
	v_mul_f32_e32 v80, v80, v48
	v_mul_f32_e32 v81, v81, v49
	v_mul_f32_e32 v82, v82, v50
	v_mul_f32_e32 v83, v83, v51
	v_mul_f32_e32 v84, v84, v52
	v_mul_f32_e32 v85, v85, v53
	v_mul_f32_e32 v86, v86, v54
	v_mul_f32_e32 v87, v87, v55
	v_mul_f32_e32 v88, v88, v56
	v_mul_f32_e32 v89, v89, v57
	v_mul_f32_e32 v90, v90, v58
	v_mul_f32_e32 v91, v91, v59
	v_mul_f32_e32 v92, v92, v60
	v_mul_f32_e32 v93, v93, v61
	v_mul_f32_e32 v94, v94, v62
	v_mul_f32_e32 v95, v95, v63
; __device__ __forceinline__ unsigned cvt_pk_bf16(float lo, float hi) { unsigned r; asm volatile("v_cvt_pk_bf16_f32 %0, %1, %2" : "=v"(r) : "v"(lo), "v"(hi)); return r; }
; __device__ __forceinline__ void load_row_f32(const float* p, int lane, f32x4 (&v)[8]) {
; #pragma unroll
;     for (int j = 0; j < 8; ++j) v[j] = *(const f32x4*)(p + 4 * lane + 256 * j);
; }
; __device__ __forceinline__ float sumsq8(const f32x4 (&v)[8]) {
;     float s = 0.f;
; #pragma unroll
;     for (int j = 0; j < 8; ++j) s += (v[j][0] * v[j][0] + v[j][1] * v[j][1]) + (v[j][2] * v[j][2] + v[j][3] * v[j][3]);
;     return wave_sum(s);
; }
; __device__ __forceinline__ void modulate_store(const f32x4 (&v)[8], float rstd, const float* pn, const float* modr, bf16_t* orow, int lane) {
; #pragma unroll
;     for (int j = 0; j < 8; ++j) { const int col = 4 * lane + 256 * j;
;         const f32x4 g = *(const f32x4*)(pn + col), sh = *(const f32x4*)(modr + col), sc = *(const f32x4*)(modr + DM + col);
;         const f32x4 hh = v[j] * rstd * g * (sc + 1.f) + sh;
;         u32x2 w; w.x = cvt_pk_bf16(hh[0], hh[1]); w.y = cvt_pk_bf16(hh[2], hh[3]);
;         *(u32x2*)(orow + col) = w; }
; __global__ void __launch_bounds__(NWAVES * 64, 2) mk_fwd(Args args) {
;     ...
;                 const float rstd = __builtin_amdgcn_rsqf(sumsq8(v[q]) * (1.f / DM) + EPS);
;                 modulate_store(v[q], rstd, pre_norm, mod + (size_t)r * 6144, H + (size_t)row * DM, F.lane); }
.Lp1_np0:
	s_add_i32 s4, s6, 1
	s_cmp_lt_u32 s4, 0x4000
	s_cselect_b32 s10, s68, s72
	s_cselect_b32 s11, s69, s73
	s_cselect_b32 s5, 0, 0x4000
	s_sub_i32 s5, s4, s5
	s_lshl_b32 s5, s5, 13
	s_add_u32 s10, s10, s5
	s_addc_u32 s11, s11, 0
	global_load_dwordx4 v[32:35], v128, s[10:11] offset:0
	global_load_dwordx4 v[36:39], v128, s[10:11] offset:1024
	global_load_dwordx4 v[40:43], v128, s[10:11] offset:2048
	global_load_dwordx4 v[44:47], v128, s[10:11] offset:3072
	global_load_dwordx4 v[48:51], v129, s[10:11] offset:0
	global_load_dwordx4 v[52:55], v129, s[10:11] offset:1024
	global_load_dwordx4 v[56:59], v129, s[10:11] offset:2048
	global_load_dwordx4 v[60:63], v129, s[10:11] offset:3072
	s_waitcnt vmcnt(8)
	v_mul_f32_e32 v140, v0, v0
	v_mul_f32_e32 v141, v1, v1
	v_fmac_f32_e32 v140, v2, v2
	v_fmac_f32_e32 v141, v3, v3
	v_fmac_f32_e32 v140, v4, v4
	v_fmac_f32_e32 v141, v5, v5
	v_fmac_f32_e32 v140, v6, v6
	v_fmac_f32_e32 v141, v7, v7
	v_fmac_f32_e32 v140, v8, v8
	v_fmac_f32_e32 v141, v9, v9
	v_fmac_f32_e32 v140, v10, v10
	v_fmac_f32_e32 v141, v11, v11
	v_fmac_f32_e32 v140, v12, v12
	v_fmac_f32_e32 v141, v13, v13
	v_fmac_f32_e32 v140, v14, v14
	v_fmac_f32_e32 v141, v15, v15
	v_fmac_f32_e32 v140, v16, v16
	v_fmac_f32_e32 v141, v17, v17
	v_fmac_f32_e32 v140, v18, v18
	v_fmac_f32_e32 v141, v19, v19
	v_fmac_f32_e32 v140, v20, v20
	v_fmac_f32_e32 v141, v21, v21
	v_fmac_f32_e32 v140, v22, v22
	v_fmac_f32_e32 v141, v23, v23
	v_fmac_f32_e32 v140, v24, v24
	v_fmac_f32_e32 v141, v25, v25
	v_fmac_f32_e32 v140, v26, v26
	v_fmac_f32_e32 v141, v27, v27
	v_fmac_f32_e32 v140, v28, v28
	v_fmac_f32_e32 v141, v29, v29
	v_fmac_f32_e32 v140, v30, v30
	v_fmac_f32_e32 v141, v31, v31
	v_add_f32_e32 v140, v140, v141
	s_nop 1
	v_add_f32_dpp v142, v140, v140 quad_perm:[1,0,3,2] row_mask:0xf bank_mask:0xf
	s_nop 1
	v_add_f32_dpp v142, v142, v142 quad_perm:[2,3,0,1] row_mask:0xf bank_mask:0xf
	s_nop 1
	v_add_f32_dpp v142, v142, v142 row_half_mirror row_mask:0xf bank_mask:0xf
	s_nop 1
	v_add_f32_dpp v142, v142, v142 row_mirror row_mask:0xf bank_mask:0xf
	s_nop 1
	v_readlane_b32 s20, v142, 0
	v_readlane_b32 s21, v142, 16
	v_readlane_b32 s22, v142, 32
	v_readlane_b32 s23, v142, 48
	s_nop 1
	v_mov_b32_e32 v143, s20
	v_add_f32_e32 v143, s21, v143
	v_add_f32_e32 v143, s22, v143
	v_add_f32_e32 v143, s23, v143
	v_fmamk_f32 v143, v143, 0x3a000000, v131
	v_rsq_f32_e32 v143, v143
	s_nop 0
	s_add_i32 s4, s6, 0
	s_lshl_b32 s5, s4, 12
	s_add_u32 s14, s84, s5
	s_addc_u32 s15, s85, 0
	s_add_u32 s14, s14, 0x4000000
	s_addc_u32 s15, s15, 0
	v_mul_f32_e32 v136, v143, v0
	v_mul_f32_e32 v137, v143, v1
	v_mul_f32_e32 v138, v143, v2
	v_mul_f32_e32 v139, v143, v3
	v_fma_f32 v136, v136, v64, v96
	v_fma_f32 v137, v137, v65, v97
	v_fma_f32 v138, v138, v66, v98
	v_fma_f32 v139, v139, v67, v99
	v_cvt_pk_bf16_f32 v132, v136, v137
	v_cvt_pk_bf16_f32 v133, v138, v139
	global_store_dwordx2 v130, v[132:133], s[14:15] offset:0
	v_mul_f32_e32 v136, v143, v4
	v_mul_f32_e32 v137, v143, v5
	v_mul_f32_e32 v138, v143, v6
	v_mul_f32_e32 v139, v143, v7
	v_fma_f32 v136, v136, v68, v100
	v_fma_f32 v137, v137, v69, v101
	v_fma_f32 v138, v138, v70, v102
	v_fma_f32 v139, v139, v71, v103
	v_cvt_pk_bf16_f32 v134, v136, v137
	v_cvt_pk_bf16_f32 v135, v138, v139
	global_store_dwordx2 v130, v[134:135], s[14:15] offset:512
	v_mul_f32_e32 v136, v143, v8
	v_mul_f32_e32 v137, v143, v9
	v_mul_f32_e32 v138, v143, v10
	v_mul_f32_e32 v139, v143, v11
	v_fma_f32 v136, v136, v72, v104
	v_fma_f32 v137, v137, v73, v105
	v_fma_f32 v138, v138, v74, v106
	v_fma_f32 v139, v139, v75, v107
	v_cvt_pk_bf16_f32 v132, v136, v137
	v_cvt_pk_bf16_f32 v133, v138, v139
	global_store_dwordx2 v130, v[132:133], s[14:15] offset:1024
	v_mul_f32_e32 v136, v143, v12
	v_mul_f32_e32 v137, v143, v13
	v_mul_f32_e32 v138, v143, v14
	v_mul_f32_e32 v139, v143, v15
	v_fma_f32 v136, v136, v76, v108
	v_fma_f32 v137, v137, v77, v109
	v_fma_f32 v138, v138, v78, v110
	v_fma_f32 v139, v139, v79, v111
	v_cvt_pk_bf16_f32 v134, v136, v137
	v_cvt_pk_bf16_f32 v135, v138, v139
	global_store_dwordx2 v130, v[134:135], s[14:15] offset:1536
	v_mul_f32_e32 v136, v143, v16
	v_mul_f32_e32 v137, v143, v17
	v_mul_f32_e32 v138, v143, v18
	v_mul_f32_e32 v139, v143, v19
	v_fma_f32 v136, v136, v80, v112
	v_fma_f32 v137, v137, v81, v113
	v_fma_f32 v138, v138, v82, v114
	v_fma_f32 v139, v139, v83, v115
	v_cvt_pk_bf16_f32 v132, v136, v137
	v_cvt_pk_bf16_f32 v133, v138, v139
	global_store_dwordx2 v130, v[132:133], s[14:15] offset:2048
	v_mul_f32_e32 v136, v143, v20
	v_mul_f32_e32 v137, v143, v21
	v_mul_f32_e32 v138, v143, v22
	v_mul_f32_e32 v139, v143, v23
	v_fma_f32 v136, v136, v84, v116
	v_fma_f32 v137, v137, v85, v117
	v_fma_f32 v138, v138, v86, v118
	v_fma_f32 v139, v139, v87, v119
	v_cvt_pk_bf16_f32 v134, v136, v137
	v_cvt_pk_bf16_f32 v135, v138, v139
	global_store_dwordx2 v130, v[134:135], s[14:15] offset:2560
	v_mul_f32_e32 v136, v143, v24
	v_mul_f32_e32 v137, v143, v25
	v_mul_f32_e32 v138, v143, v26
	v_mul_f32_e32 v139, v143, v27
	v_fma_f32 v136, v136, v88, v120
	v_fma_f32 v137, v137, v89, v121
	v_fma_f32 v138, v138, v90, v122
	v_fma_f32 v139, v139, v91, v123
	v_cvt_pk_bf16_f32 v132, v136, v137
	v_cvt_pk_bf16_f32 v133, v138, v139
	global_store_dwordx2 v130, v[132:133], s[14:15] offset:3072
	v_mul_f32_e32 v136, v143, v28
	v_mul_f32_e32 v137, v143, v29
	v_mul_f32_e32 v138, v143, v30
	v_mul_f32_e32 v139, v143, v31
	v_fma_f32 v136, v136, v92, v124
	v_fma_f32 v137, v137, v93, v125
	v_fma_f32 v138, v138, v94, v126
	v_fma_f32 v139, v139, v95, v127
	v_cvt_pk_bf16_f32 v134, v136, v137
	v_cvt_pk_bf16_f32 v135, v138, v139
	global_store_dwordx2 v130, v[134:135], s[14:15] offset:3584
	s_add_i32 s4, s6, 2
	s_cmp_lt_u32 s4, 0x4000
	s_cselect_b32 s10, s68, s72
	s_cselect_b32 s11, s69, s73
	s_cselect_b32 s5, 0, 0x4000
	s_sub_i32 s5, s4, s5
	s_lshl_b32 s5, s5, 13
	s_add_u32 s10, s10, s5
	s_addc_u32 s11, s11, 0
	global_load_dwordx4 v[0:3], v128, s[10:11] offset:0
	global_load_dwordx4 v[4:7], v128, s[10:11] offset:1024
	global_load_dwordx4 v[8:11], v128, s[10:11] offset:2048
	global_load_dwordx4 v[12:15], v128, s[10:11] offset:3072
	global_load_dwordx4 v[16:19], v129, s[10:11] offset:0
	global_load_dwordx4 v[20:23], v129, s[10:11] offset:1024
	global_load_dwordx4 v[24:27], v129, s[10:11] offset:2048
	global_load_dwordx4 v[28:31], v129, s[10:11] offset:3072
	s_add_i32 s4, s6, 1
	s_add_i32 s4, s6, 1
	s_lshr_b32 s8, s4, 11
	s_cmp_lt_u32 s4, 0x4000
	s_cselect_b32 s8, s8, 8
	s_cmp_eq_u32 s8, s7
	s_cbranch_scc1 .Lp1_np1
; __device__ __forceinline__ unsigned cvt_pk_bf16(float lo, float hi) { unsigned r; asm volatile("v_cvt_pk_bf16_f32 %0, %1, %2" : "=v"(r) : "v"(lo), "v"(hi)); return r; }
; __device__ __forceinline__ float sumsq8(const f32x4 (&v)[8]) {
;     float s = 0.f;
; #pragma unroll
;     for (int j = 0; j < 8; ++j) s += (v[j][0] * v[j][0] + v[j][1] * v[j][1]) + (v[j][2] * v[j][2] + v[j][3] * v[j][3]);
;     return wave_sum(s);
; }
; __device__ __forceinline__ void modulate_store(const f32x4 (&v)[8], float rstd, const float* pn, const float* modr, bf16_t* orow, int lane) {
; #pragma unroll
;     for (int j = 0; j < 8; ++j) { const int col = 4 * lane + 256 * j;
;         const f32x4 g = *(const f32x4*)(pn + col), sh = *(const f32x4*)(modr + col), sc = *(const f32x4*)(modr + DM + col);
;         const f32x4 hh = v[j] * rstd * g * (sc + 1.f) + sh;
;         u32x2 w; w.x = cvt_pk_bf16(hh[0], hh[1]); w.y = cvt_pk_bf16(hh[2], hh[3]);
;         *(u32x2*)(orow + col) = w; }
	s_mov_b32 s7, s8
	s_add_i32 s5, s8, 0
	s_mul_i32 s5, s5, 0x6000
	s_add_u32 s24, s84, s5
	s_addc_u32 s25, s85, 0
	s_add_u32 s24, s24, 0x2000
	s_addc_u32 s25, s25, 0
	s_add_i32 s5, s8, 0
	s_mul_i32 s5, s5, 0x6000
	s_add_u32 s16, s84, s5
	s_addc_u32 s17, s85, 0
	s_add_u32 s18, s80, 0x0
	s_addc_u32 s19, s81, 0
	global_load_dwordx4 v[64:67], v128, s[18:19] offset:0
	global_load_dwordx4 v[96:99], v128, s[16:17] offset:0
	global_load_dwordx4 v[68:71], v128, s[18:19] offset:1024
	global_load_dwordx4 v[100:103], v128, s[16:17] offset:1024
	global_load_dwordx4 v[72:75], v128, s[18:19] offset:2048
	global_load_dwordx4 v[104:107], v128, s[16:17] offset:2048
	global_load_dwordx4 v[76:79], v128, s[18:19] offset:3072
	global_load_dwordx4 v[108:111], v128, s[16:17] offset:3072
	global_load_dwordx4 v[80:83], v129, s[18:19] offset:0
	global_load_dwordx4 v[112:115], v129, s[16:17] offset:0
	global_load_dwordx4 v[84:87], v129, s[18:19] offset:1024
	global_load_dwordx4 v[116:119], v129, s[16:17] offset:1024
	global_load_dwordx4 v[88:91], v129, s[18:19] offset:2048
	global_load_dwordx4 v[120:123], v129, s[16:17] offset:2048
	global_load_dwordx4 v[92:95], v129, s[18:19] offset:3072
	global_load_dwordx4 v[124:127], v129, s[16:17] offset:3072
	global_load_dwordx4 v[136:139], v128, s[24:25] offset:0
	s_waitcnt vmcnt(0)
	v_add_f32_e32 v136, 1.0, v136
	v_add_f32_e32 v137, 1.0, v137
	v_add_f32_e32 v138, 1.0, v138
	v_add_f32_e32 v139, 1.0, v139
	v_mul_f32_e32 v64, v64, v136
	v_mul_f32_e32 v65, v65, v137
	v_mul_f32_e32 v66, v66, v138
	v_mul_f32_e32 v67, v67, v139
	global_load_dwordx4 v[136:139], v128, s[24:25] offset:1024
	s_waitcnt vmcnt(0)
	v_add_f32_e32 v136, 1.0, v136
	v_add_f32_e32 v137, 1.0, v137
	v_add_f32_e32 v138, 1.0, v138
	v_add_f32_e32 v139, 1.0, v139
	v_mul_f32_e32 v68, v68, v136
	v_mul_f32_e32 v69, v69, v137
	v_mul_f32_e32 v70, v70, v138
	v_mul_f32_e32 v71, v71, v139
	global_load_dwordx4 v[136:139], v128, s[24:25] offset:2048
	s_waitcnt vmcnt(0)
	v_add_f32_e32 v136, 1.0, v136
	v_add_f32_e32 v137, 1.0, v137
	v_add_f32_e32 v138, 1.0, v138
	v_add_f32_e32 v139, 1.0, v139
	v_mul_f32_e32 v72, v72, v136
	v_mul_f32_e32 v73, v73, v137
	v_mul_f32_e32 v74, v74, v138
	v_mul_f32_e32 v75, v75, v139
	global_load_dwordx4 v[136:139], v128, s[24:25] offset:3072
	s_waitcnt vmcnt(0)
	v_add_f32_e32 v136, 1.0, v136
	v_add_f32_e32 v137, 1.0, v137
	v_add_f32_e32 v138, 1.0, v138
	v_add_f32_e32 v139, 1.0, v139
	v_mul_f32_e32 v76, v76, v136
	v_mul_f32_e32 v77, v77, v137
	v_mul_f32_e32 v78, v78, v138
	v_mul_f32_e32 v79, v79, v139
	global_load_dwordx4 v[136:139], v129, s[24:25] offset:0
	s_waitcnt vmcnt(0)
	v_add_f32_e32 v136, 1.0, v136
	v_add_f32_e32 v137, 1.0, v137
	v_add_f32_e32 v138, 1.0, v138
	v_add_f32_e32 v139, 1.0, v139
	v_mul_f32_e32 v80, v80, v136
	v_mul_f32_e32 v81, v81, v137
	v_mul_f32_e32 v82, v82, v138
	v_mul_f32_e32 v83, v83, v139
	global_load_dwordx4 v[136:139], v129, s[24:25] offset:1024
	s_waitcnt vmcnt(0)
	v_add_f32_e32 v136, 1.0, v136
	v_add_f32_e32 v137, 1.0, v137
	v_add_f32_e32 v138, 1.0, v138
	v_add_f32_e32 v139, 1.0, v139
	v_mul_f32_e32 v84, v84, v136
	v_mul_f32_e32 v85, v85, v137
	v_mul_f32_e32 v86, v86, v138
	v_mul_f32_e32 v87, v87, v139
	global_load_dwordx4 v[136:139], v129, s[24:25] offset:2048
	s_waitcnt vmcnt(0)
	v_add_f32_e32 v136, 1.0, v136
	v_add_f32_e32 v137, 1.0, v137
	v_add_f32_e32 v138, 1.0, v138
	v_add_f32_e32 v139, 1.0, v139
	v_mul_f32_e32 v88, v88, v136
	v_mul_f32_e32 v89, v89, v137
	v_mul_f32_e32 v90, v90, v138
	v_mul_f32_e32 v91, v91, v139
	global_load_dwordx4 v[136:139], v129, s[24:25] offset:3072
	s_waitcnt vmcnt(0)
	v_add_f32_e32 v136, 1.0, v136
	v_add_f32_e32 v137, 1.0, v137
	v_add_f32_e32 v138, 1.0, v138
	v_add_f32_e32 v139, 1.0, v139
	v_mul_f32_e32 v92, v92, v136
	v_mul_f32_e32 v93, v93, v137
	v_mul_f32_e32 v94, v94, v138
	v_mul_f32_e32 v95, v95, v139
.Lp1_np1:
	s_waitcnt vmcnt(16)
	v_mul_f32_e32 v140, v32, v32
	v_mul_f32_e32 v141, v33, v33
	v_fmac_f32_e32 v140, v34, v34
	v_fmac_f32_e32 v141, v35, v35
	v_fmac_f32_e32 v140, v36, v36
	v_fmac_f32_e32 v141, v37, v37
	v_fmac_f32_e32 v140, v38, v38
	v_fmac_f32_e32 v141, v39, v39
	v_fmac_f32_e32 v140, v40, v40
	v_fmac_f32_e32 v141, v41, v41
	v_fmac_f32_e32 v140, v42, v42
	v_fmac_f32_e32 v141, v43, v43
	v_fmac_f32_e32 v140, v44, v44
	v_fmac_f32_e32 v141, v45, v45
	v_fmac_f32_e32 v140, v46, v46
	v_fmac_f32_e32 v141, v47, v47
	v_fmac_f32_e32 v140, v48, v48
	v_fmac_f32_e32 v141, v49, v49
	v_fmac_f32_e32 v140, v50, v50
	v_fmac_f32_e32 v141, v51, v51
	v_fmac_f32_e32 v140, v52, v52
	v_fmac_f32_e32 v141, v53, v53
	v_fmac_f32_e32 v140, v54, v54
	v_fmac_f32_e32 v141, v55, v55
	v_fmac_f32_e32 v140, v56, v56
	v_fmac_f32_e32 v141, v57, v57
	v_fmac_f32_e32 v140, v58, v58
	v_fmac_f32_e32 v141, v59, v59
	v_fmac_f32_e32 v140, v60, v60
	v_fmac_f32_e32 v141, v61, v61
	v_fmac_f32_e32 v140, v62, v62
	v_fmac_f32_e32 v141, v63, v63
	v_add_f32_e32 v140, v140, v141
	s_nop 1
	v_add_f32_dpp v142, v140, v140 quad_perm:[1,0,3,2] row_mask:0xf bank_mask:0xf
	s_nop 1
	v_add_f32_dpp v142, v142, v142 quad_perm:[2,3,0,1] row_mask:0xf bank_mask:0xf
	s_nop 1
	v_add_f32_dpp v142, v142, v142 row_half_mirror row_mask:0xf bank_mask:0xf
	s_nop 1
	v_add_f32_dpp v142, v142, v142 row_mirror row_mask:0xf bank_mask:0xf
	s_nop 1
	v_readlane_b32 s20, v142, 0
	v_readlane_b32 s21, v142, 16
	v_readlane_b32 s22, v142, 32
	v_readlane_b32 s23, v142, 48
	s_nop 1
	v_mov_b32_e32 v143, s20
	v_add_f32_e32 v143, s21, v143
	v_add_f32_e32 v143, s22, v143
	v_add_f32_e32 v143, s23, v143
	v_fmamk_f32 v143, v143, 0x3a000000, v131
	v_rsq_f32_e32 v143, v143
	s_nop 0
	s_add_i32 s4, s6, 1
	s_lshl_b32 s5, s4, 12
	s_add_u32 s14, s84, s5
	s_addc_u32 s15, s85, 0
; __device__ __forceinline__ unsigned cvt_pk_bf16(float lo, float hi) { unsigned r; asm volatile("v_cvt_pk_bf16_f32 %0, %1, %2" : "=v"(r) : "v"(lo), "v"(hi)); return r; }
; __device__ __forceinline__ float sumsq8(const f32x4 (&v)[8]) {
;     float s = 0.f;
; #pragma unroll
;     for (int j = 0; j < 8; ++j) s += (v[j][0] * v[j][0] + v[j][1] * v[j][1]) + (v[j][2] * v[j][2] + v[j][3] * v[j][3]);
;     return wave_sum(s);
; }
; __device__ __forceinline__ void modulate_store(const f32x4 (&v)[8], float rstd, const float* pn, const float* modr, bf16_t* orow, int lane) {
; #pragma unroll
;     for (int j = 0; j < 8; ++j) { const int col = 4 * lane + 256 * j;
;         const f32x4 g = *(const f32x4*)(pn + col), sh = *(const f32x4*)(modr + col), sc = *(const f32x4*)(modr + DM + col);
;         const f32x4 hh = v[j] * rstd * g * (sc + 1.f) + sh;
;         u32x2 w; w.x = cvt_pk_bf16(hh[0], hh[1]); w.y = cvt_pk_bf16(hh[2], hh[3]);
;         *(u32x2*)(orow + col) = w; }
	s_add_u32 s14, s14, 0x4000000
	s_addc_u32 s15, s15, 0
	v_mul_f32_e32 v136, v143, v32
	v_mul_f32_e32 v137, v143, v33
	v_mul_f32_e32 v138, v143, v34
	v_mul_f32_e32 v139, v143, v35
	v_fma_f32 v136, v136, v64, v96
	v_fma_f32 v137, v137, v65, v97
	v_fma_f32 v138, v138, v66, v98
	v_fma_f32 v139, v139, v67, v99
	v_cvt_pk_bf16_f32 v132, v136, v137
	v_cvt_pk_bf16_f32 v133, v138, v139
	global_store_dwordx2 v130, v[132:133], s[14:15] offset:0
	v_mul_f32_e32 v136, v143, v36
	v_mul_f32_e32 v137, v143, v37
	v_mul_f32_e32 v138, v143, v38
	v_mul_f32_e32 v139, v143, v39
	v_fma_f32 v136, v136, v68, v100
	v_fma_f32 v137, v137, v69, v101
	v_fma_f32 v138, v138, v70, v102
	v_fma_f32 v139, v139, v71, v103
	v_cvt_pk_bf16_f32 v134, v136, v137
	v_cvt_pk_bf16_f32 v135, v138, v139
	global_store_dwordx2 v130, v[134:135], s[14:15] offset:512
	v_mul_f32_e32 v136, v143, v40
	v_mul_f32_e32 v137, v143, v41
	v_mul_f32_e32 v138, v143, v42
	v_mul_f32_e32 v139, v143, v43
	v_fma_f32 v136, v136, v72, v104
	v_fma_f32 v137, v137, v73, v105
	v_fma_f32 v138, v138, v74, v106
	v_fma_f32 v139, v139, v75, v107
	v_cvt_pk_bf16_f32 v132, v136, v137
	v_cvt_pk_bf16_f32 v133, v138, v139
	global_store_dwordx2 v130, v[132:133], s[14:15] offset:1024
	v_mul_f32_e32 v136, v143, v44
	v_mul_f32_e32 v137, v143, v45
	v_mul_f32_e32 v138, v143, v46
	v_mul_f32_e32 v139, v143, v47
	v_fma_f32 v136, v136, v76, v108
	v_fma_f32 v137, v137, v77, v109
	v_fma_f32 v138, v138, v78, v110
	v_fma_f32 v139, v139, v79, v111
	v_cvt_pk_bf16_f32 v134, v136, v137
	v_cvt_pk_bf16_f32 v135, v138, v139
	global_store_dwordx2 v130, v[134:135], s[14:15] offset:1536
	v_mul_f32_e32 v136, v143, v48
	v_mul_f32_e32 v137, v143, v49
	v_mul_f32_e32 v138, v143, v50
	v_mul_f32_e32 v139, v143, v51
	v_fma_f32 v136, v136, v80, v112
	v_fma_f32 v137, v137, v81, v113
	v_fma_f32 v138, v138, v82, v114
	v_fma_f32 v139, v139, v83, v115
	v_cvt_pk_bf16_f32 v132, v136, v137
	v_cvt_pk_bf16_f32 v133, v138, v139
	global_store_dwordx2 v130, v[132:133], s[14:15] offset:2048
	v_mul_f32_e32 v136, v143, v52
	v_mul_f32_e32 v137, v143, v53
	v_mul_f32_e32 v138, v143, v54
	v_mul_f32_e32 v139, v143, v55
	v_fma_f32 v136, v136, v84, v116
	v_fma_f32 v137, v137, v85, v117
	v_fma_f32 v138, v138, v86, v118
	v_fma_f32 v139, v139, v87, v119
	v_cvt_pk_bf16_f32 v134, v136, v137
	v_cvt_pk_bf16_f32 v135, v138, v139
	global_store_dwordx2 v130, v[134:135], s[14:15] offset:2560
	v_mul_f32_e32 v136, v143, v56
	v_mul_f32_e32 v137, v143, v57
	v_mul_f32_e32 v138, v143, v58
	v_mul_f32_e32 v139, v143, v59
	v_fma_f32 v136, v136, v88, v120
	v_fma_f32 v137, v137, v89, v121
	v_fma_f32 v138, v138, v90, v122
	v_fma_f32 v139, v139, v91, v123
	v_cvt_pk_bf16_f32 v132, v136, v137
	v_cvt_pk_bf16_f32 v133, v138, v139
	global_store_dwordx2 v130, v[132:133], s[14:15] offset:3072
	v_mul_f32_e32 v136, v143, v60
	v_mul_f32_e32 v137, v143, v61
	v_mul_f32_e32 v138, v143, v62
	v_mul_f32_e32 v139, v143, v63
	v_fma_f32 v136, v136, v92, v124
	v_fma_f32 v137, v137, v93, v125
	v_fma_f32 v138, v138, v94, v126
	v_fma_f32 v139, v139, v95, v127
	v_cvt_pk_bf16_f32 v134, v136, v137
	v_cvt_pk_bf16_f32 v135, v138, v139
	global_store_dwordx2 v130, v[134:135], s[14:15] offset:3584
	s_add_i32 s4, s6, 3
	s_cmp_lt_u32 s4, 0x4000
	s_cselect_b32 s10, s68, s72
	s_cselect_b32 s11, s69, s73
	s_cselect_b32 s5, 0, 0x4000
	s_sub_i32 s5, s4, s5
	s_lshl_b32 s5, s5, 13
	s_add_u32 s10, s10, s5
	s_addc_u32 s11, s11, 0
	global_load_dwordx4 v[32:35], v128, s[10:11] offset:0
	global_load_dwordx4 v[36:39], v128, s[10:11] offset:1024
	global_load_dwordx4 v[40:43], v128, s[10:11] offset:2048
	global_load_dwordx4 v[44:47], v128, s[10:11] offset:3072
	global_load_dwordx4 v[48:51], v129, s[10:11] offset:0
	global_load_dwordx4 v[52:55], v129, s[10:11] offset:1024
	global_load_dwordx4 v[56:59], v129, s[10:11] offset:2048
	global_load_dwordx4 v[60:63], v129, s[10:11] offset:3072
	s_add_i32 s4, s6, 2
	s_add_i32 s4, s6, 2
	s_lshr_b32 s8, s4, 11
	s_cmp_lt_u32 s4, 0x4000
	s_cselect_b32 s8, s8, 8
	s_cmp_eq_u32 s8, s7
	s_cbranch_scc1 .Lp1_np2
	s_mov_b32 s7, s8
	s_add_i32 s5, s8, 0
	s_mul_i32 s5, s5, 0x6000
	s_add_u32 s24, s84, s5
	s_addc_u32 s25, s85, 0
	s_add_u32 s24, s24, 0x2000
	s_addc_u32 s25, s25, 0
	s_add_i32 s5, s8, 0
	s_mul_i32 s5, s5, 0x6000
	s_add_u32 s16, s84, s5
	s_addc_u32 s17, s85, 0
	s_add_u32 s18, s80, 0x0
	s_addc_u32 s19, s81, 0
	global_load_dwordx4 v[64:67], v128, s[18:19] offset:0
	global_load_dwordx4 v[96:99], v128, s[16:17] offset:0
	global_load_dwordx4 v[68:71], v128, s[18:19] offset:1024
	global_load_dwordx4 v[100:103], v128, s[16:17] offset:1024
	global_load_dwordx4 v[72:75], v128, s[18:19] offset:2048
	global_load_dwordx4 v[104:107], v128, s[16:17] offset:2048
	global_load_dwordx4 v[76:79], v128, s[18:19] offset:3072
	global_load_dwordx4 v[108:111], v128, s[16:17] offset:3072
	global_load_dwordx4 v[80:83], v129, s[18:19] offset:0
	global_load_dwordx4 v[112:115], v129, s[16:17] offset:0
	global_load_dwordx4 v[84:87], v129, s[18:19] offset:1024
	global_load_dwordx4 v[116:119], v129, s[16:17] offset:1024
	global_load_dwordx4 v[88:91], v129, s[18:19] offset:2048
	global_load_dwordx4 v[120:123], v129, s[16:17] offset:2048
	global_load_dwordx4 v[92:95], v129, s[18:19] offset:3072
	global_load_dwordx4 v[124:127], v129, s[16:17] offset:3072
	global_load_dwordx4 v[136:139], v128, s[24:25] offset:0
	s_waitcnt vmcnt(0)
	v_add_f32_e32 v136, 1.0, v136
	v_add_f32_e32 v137, 1.0, v137
	v_add_f32_e32 v138, 1.0, v138
	v_add_f32_e32 v139, 1.0, v139
	v_mul_f32_e32 v64, v64, v136
	v_mul_f32_e32 v65, v65, v137
	v_mul_f32_e32 v66, v66, v138
	v_mul_f32_e32 v67, v67, v139
	global_load_dwordx4 v[136:139], v128, s[24:25] offset:1024
	s_waitcnt vmcnt(0)
; __device__ __forceinline__ unsigned cvt_pk_bf16(float lo, float hi) { unsigned r; asm volatile("v_cvt_pk_bf16_f32 %0, %1, %2" : "=v"(r) : "v"(lo), "v"(hi)); return r; }
; __device__ __forceinline__ float sumsq8(const f32x4 (&v)[8]) {
;     float s = 0.f;
; #pragma unroll
;     for (int j = 0; j < 8; ++j) s += (v[j][0] * v[j][0] + v[j][1] * v[j][1]) + (v[j][2] * v[j][2] + v[j][3] * v[j][3]);
;     return wave_sum(s);
; }
; __device__ __forceinline__ void modulate_store(const f32x4 (&v)[8], float rstd, const float* pn, const float* modr, bf16_t* orow, int lane) {
; #pragma unroll
;     for (int j = 0; j < 8; ++j) { const int col = 4 * lane + 256 * j;
;         const f32x4 g = *(const f32x4*)(pn + col), sh = *(const f32x4*)(modr + col), sc = *(const f32x4*)(modr + DM + col);
;         const f32x4 hh = v[j] * rstd * g * (sc + 1.f) + sh;
;         u32x2 w; w.x = cvt_pk_bf16(hh[0], hh[1]); w.y = cvt_pk_bf16(hh[2], hh[3]);
;         *(u32x2*)(orow + col) = w; }
	v_add_f32_e32 v136, 1.0, v136
	v_add_f32_e32 v137, 1.0, v137
	v_add_f32_e32 v138, 1.0, v138
	v_add_f32_e32 v139, 1.0, v139
	v_mul_f32_e32 v68, v68, v136
	v_mul_f32_e32 v69, v69, v137
	v_mul_f32_e32 v70, v70, v138
	v_mul_f32_e32 v71, v71, v139
	global_load_dwordx4 v[136:139], v128, s[24:25] offset:2048
	s_waitcnt vmcnt(0)
	v_add_f32_e32 v136, 1.0, v136
	v_add_f32_e32 v137, 1.0, v137
	v_add_f32_e32 v138, 1.0, v138
	v_add_f32_e32 v139, 1.0, v139
	v_mul_f32_e32 v72, v72, v136
	v_mul_f32_e32 v73, v73, v137
	v_mul_f32_e32 v74, v74, v138
	v_mul_f32_e32 v75, v75, v139
	global_load_dwordx4 v[136:139], v128, s[24:25] offset:3072
	s_waitcnt vmcnt(0)
	v_add_f32_e32 v136, 1.0, v136
	v_add_f32_e32 v137, 1.0, v137
	v_add_f32_e32 v138, 1.0, v138
	v_add_f32_e32 v139, 1.0, v139
	v_mul_f32_e32 v76, v76, v136
	v_mul_f32_e32 v77, v77, v137
	v_mul_f32_e32 v78, v78, v138
	v_mul_f32_e32 v79, v79, v139
	global_load_dwordx4 v[136:139], v129, s[24:25] offset:0
	s_waitcnt vmcnt(0)
	v_add_f32_e32 v136, 1.0, v136
	v_add_f32_e32 v137, 1.0, v137
	v_add_f32_e32 v138, 1.0, v138
	v_add_f32_e32 v139, 1.0, v139
	v_mul_f32_e32 v80, v80, v136
	v_mul_f32_e32 v81, v81, v137
	v_mul_f32_e32 v82, v82, v138
	v_mul_f32_e32 v83, v83, v139
	global_load_dwordx4 v[136:139], v129, s[24:25] offset:1024
	s_waitcnt vmcnt(0)
	v_add_f32_e32 v136, 1.0, v136
	v_add_f32_e32 v137, 1.0, v137
	v_add_f32_e32 v138, 1.0, v138
	v_add_f32_e32 v139, 1.0, v139
	v_mul_f32_e32 v84, v84, v136
	v_mul_f32_e32 v85, v85, v137
	v_mul_f32_e32 v86, v86, v138
	v_mul_f32_e32 v87, v87, v139
	global_load_dwordx4 v[136:139], v129, s[24:25] offset:2048
	s_waitcnt vmcnt(0)
	v_add_f32_e32 v136, 1.0, v136
	v_add_f32_e32 v137, 1.0, v137
	v_add_f32_e32 v138, 1.0, v138
	v_add_f32_e32 v139, 1.0, v139
	v_mul_f32_e32 v88, v88, v136
	v_mul_f32_e32 v89, v89, v137
	v_mul_f32_e32 v90, v90, v138
	v_mul_f32_e32 v91, v91, v139
	global_load_dwordx4 v[136:139], v129, s[24:25] offset:3072
	s_waitcnt vmcnt(0)
	v_add_f32_e32 v136, 1.0, v136
	v_add_f32_e32 v137, 1.0, v137
	v_add_f32_e32 v138, 1.0, v138
	v_add_f32_e32 v139, 1.0, v139
	v_mul_f32_e32 v92, v92, v136
	v_mul_f32_e32 v93, v93, v137
	v_mul_f32_e32 v94, v94, v138
	v_mul_f32_e32 v95, v95, v139
.Lp1_np2:
	s_waitcnt vmcnt(16)
	v_mul_f32_e32 v140, v0, v0
	v_mul_f32_e32 v141, v1, v1
	v_fmac_f32_e32 v140, v2, v2
	v_fmac_f32_e32 v141, v3, v3
	v_fmac_f32_e32 v140, v4, v4
	v_fmac_f32_e32 v141, v5, v5
	v_fmac_f32_e32 v140, v6, v6
	v_fmac_f32_e32 v141, v7, v7
	v_fmac_f32_e32 v140, v8, v8
	v_fmac_f32_e32 v141, v9, v9
	v_fmac_f32_e32 v140, v10, v10
	v_fmac_f32_e32 v141, v11, v11
	v_fmac_f32_e32 v140, v12, v12
	v_fmac_f32_e32 v141, v13, v13
	v_fmac_f32_e32 v140, v14, v14
	v_fmac_f32_e32 v141, v15, v15
	v_fmac_f32_e32 v140, v16, v16
	v_fmac_f32_e32 v141, v17, v17
	v_fmac_f32_e32 v140, v18, v18
	v_fmac_f32_e32 v141, v19, v19
	v_fmac_f32_e32 v140, v20, v20
	v_fmac_f32_e32 v141, v21, v21
	v_fmac_f32_e32 v140, v22, v22
	v_fmac_f32_e32 v141, v23, v23
	v_fmac_f32_e32 v140, v24, v24
	v_fmac_f32_e32 v141, v25, v25
	v_fmac_f32_e32 v140, v26, v26
	v_fmac_f32_e32 v141, v27, v27
	v_fmac_f32_e32 v140, v28, v28
	v_fmac_f32_e32 v141, v29, v29
	v_fmac_f32_e32 v140, v30, v30
	v_fmac_f32_e32 v141, v31, v31
	v_add_f32_e32 v140, v140, v141
	s_nop 1
	v_add_f32_dpp v142, v140, v140 quad_perm:[1,0,3,2] row_mask:0xf bank_mask:0xf
	s_nop 1
	v_add_f32_dpp v142, v142, v142 quad_perm:[2,3,0,1] row_mask:0xf bank_mask:0xf
	s_nop 1
	v_add_f32_dpp v142, v142, v142 row_half_mirror row_mask:0xf bank_mask:0xf
	s_nop 1
	v_add_f32_dpp v142, v142, v142 row_mirror row_mask:0xf bank_mask:0xf
	s_nop 1
	v_readlane_b32 s20, v142, 0
	v_readlane_b32 s21, v142, 16
	v_readlane_b32 s22, v142, 32
	v_readlane_b32 s23, v142, 48
	s_nop 1
	v_mov_b32_e32 v143, s20
	v_add_f32_e32 v143, s21, v143
	v_add_f32_e32 v143, s22, v143
	v_add_f32_e32 v143, s23, v143
	v_fmamk_f32 v143, v143, 0x3a000000, v131
	v_rsq_f32_e32 v143, v143
	s_nop 0
	s_add_i32 s4, s6, 2
	s_lshl_b32 s5, s4, 12
	s_add_u32 s14, s84, s5
	s_addc_u32 s15, s85, 0
	s_add_u32 s14, s14, 0x4000000
	s_addc_u32 s15, s15, 0
	v_mul_f32_e32 v136, v143, v0
	v_mul_f32_e32 v137, v143, v1
	v_mul_f32_e32 v138, v143, v2
	v_mul_f32_e32 v139, v143, v3
	v_fma_f32 v136, v136, v64, v96
	v_fma_f32 v137, v137, v65, v97
	v_fma_f32 v138, v138, v66, v98
	v_fma_f32 v139, v139, v67, v99
	v_cvt_pk_bf16_f32 v132, v136, v137
	v_cvt_pk_bf16_f32 v133, v138, v139
	global_store_dwordx2 v130, v[132:133], s[14:15] offset:0
	v_mul_f32_e32 v136, v143, v4
	v_mul_f32_e32 v137, v143, v5
	v_mul_f32_e32 v138, v143, v6
	v_mul_f32_e32 v139, v143, v7
	v_fma_f32 v136, v136, v68, v100
	v_fma_f32 v137, v137, v69, v101
	v_fma_f32 v138, v138, v70, v102
	v_fma_f32 v139, v139, v71, v103
	v_cvt_pk_bf16_f32 v134, v136, v137
	v_cvt_pk_bf16_f32 v135, v138, v139
	global_store_dwordx2 v130, v[134:135], s[14:15] offset:512
	v_mul_f32_e32 v136, v143, v8
	v_mul_f32_e32 v137, v143, v9
	v_mul_f32_e32 v138, v143, v10
	v_mul_f32_e32 v139, v143, v11
	v_fma_f32 v136, v136, v72, v104
	v_fma_f32 v137, v137, v73, v105
	v_fma_f32 v138, v138, v74, v106
	v_fma_f32 v139, v139, v75, v107
	v_cvt_pk_bf16_f32 v132, v136, v137
	v_cvt_pk_bf16_f32 v133, v138, v139
	global_store_dwordx2 v130, v[132:133], s[14:15] offset:1024
	v_mul_f32_e32 v136, v143, v12
	v_mul_f32_e32 v137, v143, v13
	v_mul_f32_e32 v138, v143, v14
	v_mul_f32_e32 v139, v143, v15
	v_fma_f32 v136, v136, v76, v108
	v_fma_f32 v137, v137, v77, v109
	v_fma_f32 v138, v138, v78, v110
	v_fma_f32 v139, v139, v79, v111
	v_cvt_pk_bf16_f32 v134, v136, v137
	v_cvt_pk_bf16_f32 v135, v138, v139
	global_store_dwordx2 v130, v[134:135], s[14:15] offset:1536
	v_mul_f32_e32 v136, v143, v16
	v_mul_f32_e32 v137, v143, v17
; __device__ __forceinline__ unsigned cvt_pk_bf16(float lo, float hi) { unsigned r; asm volatile("v_cvt_pk_bf16_f32 %0, %1, %2" : "=v"(r) : "v"(lo), "v"(hi)); return r; }
; __device__ __forceinline__ float sumsq8(const f32x4 (&v)[8]) {
;     float s = 0.f;
; #pragma unroll
;     for (int j = 0; j < 8; ++j) s += (v[j][0] * v[j][0] + v[j][1] * v[j][1]) + (v[j][2] * v[j][2] + v[j][3] * v[j][3]);
;     return wave_sum(s);
; }
; __device__ __forceinline__ void modulate_store(const f32x4 (&v)[8], float rstd, const float* pn, const float* modr, bf16_t* orow, int lane) {
; #pragma unroll
;     for (int j = 0; j < 8; ++j) { const int col = 4 * lane + 256 * j;
;         const f32x4 g = *(const f32x4*)(pn + col), sh = *(const f32x4*)(modr + col), sc = *(const f32x4*)(modr + DM + col);
;         const f32x4 hh = v[j] * rstd * g * (sc + 1.f) + sh;
;         u32x2 w; w.x = cvt_pk_bf16(hh[0], hh[1]); w.y = cvt_pk_bf16(hh[2], hh[3]);
;         *(u32x2*)(orow + col) = w; }
	v_mul_f32_e32 v138, v143, v18
	v_mul_f32_e32 v139, v143, v19
	v_fma_f32 v136, v136, v80, v112
	v_fma_f32 v137, v137, v81, v113
	v_fma_f32 v138, v138, v82, v114
	v_fma_f32 v139, v139, v83, v115
	v_cvt_pk_bf16_f32 v132, v136, v137
	v_cvt_pk_bf16_f32 v133, v138, v139
	global_store_dwordx2 v130, v[132:133], s[14:15] offset:2048
	v_mul_f32_e32 v136, v143, v20
	v_mul_f32_e32 v137, v143, v21
	v_mul_f32_e32 v138, v143, v22
	v_mul_f32_e32 v139, v143, v23
	v_fma_f32 v136, v136, v84, v116
	v_fma_f32 v137, v137, v85, v117
	v_fma_f32 v138, v138, v86, v118
	v_fma_f32 v139, v139, v87, v119
	v_cvt_pk_bf16_f32 v134, v136, v137
	v_cvt_pk_bf16_f32 v135, v138, v139
	global_store_dwordx2 v130, v[134:135], s[14:15] offset:2560
	v_mul_f32_e32 v136, v143, v24
	v_mul_f32_e32 v137, v143, v25
	v_mul_f32_e32 v138, v143, v26
	v_mul_f32_e32 v139, v143, v27
	v_fma_f32 v136, v136, v88, v120
	v_fma_f32 v137, v137, v89, v121
	v_fma_f32 v138, v138, v90, v122
	v_fma_f32 v139, v139, v91, v123
	v_cvt_pk_bf16_f32 v132, v136, v137
	v_cvt_pk_bf16_f32 v133, v138, v139
	global_store_dwordx2 v130, v[132:133], s[14:15] offset:3072
	v_mul_f32_e32 v136, v143, v28
	v_mul_f32_e32 v137, v143, v29
	v_mul_f32_e32 v138, v143, v30
	v_mul_f32_e32 v139, v143, v31
	v_fma_f32 v136, v136, v92, v124
	v_fma_f32 v137, v137, v93, v125
	v_fma_f32 v138, v138, v94, v126
	v_fma_f32 v139, v139, v95, v127
	v_cvt_pk_bf16_f32 v134, v136, v137
	v_cvt_pk_bf16_f32 v135, v138, v139
	global_store_dwordx2 v130, v[134:135], s[14:15] offset:3584
	s_add_i32 s4, s6, 4
	s_cmp_lt_u32 s4, 0x4000
	s_cselect_b32 s10, s68, s72
	s_cselect_b32 s11, s69, s73
	s_cselect_b32 s5, 0, 0x4000
	s_sub_i32 s5, s4, s5
	s_lshl_b32 s5, s5, 13
	s_add_u32 s10, s10, s5
	s_addc_u32 s11, s11, 0
	global_load_dwordx4 v[0:3], v128, s[10:11] offset:0
	global_load_dwordx4 v[4:7], v128, s[10:11] offset:1024
	global_load_dwordx4 v[8:11], v128, s[10:11] offset:2048
	global_load_dwordx4 v[12:15], v128, s[10:11] offset:3072
	global_load_dwordx4 v[16:19], v129, s[10:11] offset:0
	global_load_dwordx4 v[20:23], v129, s[10:11] offset:1024
	global_load_dwordx4 v[24:27], v129, s[10:11] offset:2048
	global_load_dwordx4 v[28:31], v129, s[10:11] offset:3072
	s_add_i32 s4, s6, 3
	s_add_i32 s4, s6, 3
	s_lshr_b32 s8, s4, 11
	s_cmp_lt_u32 s4, 0x4000
	s_cselect_b32 s8, s8, 8
	s_cmp_eq_u32 s8, s7
	s_cbranch_scc1 .Lp1_np3
	s_mov_b32 s7, s8
	s_add_i32 s5, s8, 0
	s_mul_i32 s5, s5, 0x6000
	s_add_u32 s24, s84, s5
	s_addc_u32 s25, s85, 0
	s_add_u32 s24, s24, 0x2000
	s_addc_u32 s25, s25, 0
	s_add_i32 s5, s8, 0
	s_mul_i32 s5, s5, 0x6000
	s_add_u32 s16, s84, s5
	s_addc_u32 s17, s85, 0
	s_add_u32 s18, s80, 0x0
	s_addc_u32 s19, s81, 0
	global_load_dwordx4 v[64:67], v128, s[18:19] offset:0
	global_load_dwordx4 v[96:99], v128, s[16:17] offset:0
	global_load_dwordx4 v[68:71], v128, s[18:19] offset:1024
	global_load_dwordx4 v[100:103], v128, s[16:17] offset:1024
	global_load_dwordx4 v[72:75], v128, s[18:19] offset:2048
	global_load_dwordx4 v[104:107], v128, s[16:17] offset:2048
	global_load_dwordx4 v[76:79], v128, s[18:19] offset:3072
	global_load_dwordx4 v[108:111], v128, s[16:17] offset:3072
	global_load_dwordx4 v[80:83], v129, s[18:19] offset:0
	global_load_dwordx4 v[112:115], v129, s[16:17] offset:0
	global_load_dwordx4 v[84:87], v129, s[18:19] offset:1024
	global_load_dwordx4 v[116:119], v129, s[16:17] offset:1024
	global_load_dwordx4 v[88:91], v129, s[18:19] offset:2048
	global_load_dwordx4 v[120:123], v129, s[16:17] offset:2048
	global_load_dwordx4 v[92:95], v129, s[18:19] offset:3072
	global_load_dwordx4 v[124:127], v129, s[16:17] offset:3072
	global_load_dwordx4 v[136:139], v128, s[24:25] offset:0
	s_waitcnt vmcnt(0)
	v_add_f32_e32 v136, 1.0, v136
	v_add_f32_e32 v137, 1.0, v137
	v_add_f32_e32 v138, 1.0, v138
	v_add_f32_e32 v139, 1.0, v139
	v_mul_f32_e32 v64, v64, v136
	v_mul_f32_e32 v65, v65, v137
	v_mul_f32_e32 v66, v66, v138
	v_mul_f32_e32 v67, v67, v139
	global_load_dwordx4 v[136:139], v128, s[24:25] offset:1024
	s_waitcnt vmcnt(0)
	v_add_f32_e32 v136, 1.0, v136
	v_add_f32_e32 v137, 1.0, v137
	v_add_f32_e32 v138, 1.0, v138
	v_add_f32_e32 v139, 1.0, v139
	v_mul_f32_e32 v68, v68, v136
	v_mul_f32_e32 v69, v69, v137
	v_mul_f32_e32 v70, v70, v138
	v_mul_f32_e32 v71, v71, v139
	global_load_dwordx4 v[136:139], v128, s[24:25] offset:2048
	s_waitcnt vmcnt(0)
	v_add_f32_e32 v136, 1.0, v136
	v_add_f32_e32 v137, 1.0, v137
	v_add_f32_e32 v138, 1.0, v138
	v_add_f32_e32 v139, 1.0, v139
	v_mul_f32_e32 v72, v72, v136
	v_mul_f32_e32 v73, v73, v137
	v_mul_f32_e32 v74, v74, v138
	v_mul_f32_e32 v75, v75, v139
	global_load_dwordx4 v[136:139], v128, s[24:25] offset:3072
	s_waitcnt vmcnt(0)
	v_add_f32_e32 v136, 1.0, v136
	v_add_f32_e32 v137, 1.0, v137
	v_add_f32_e32 v138, 1.0, v138
	v_add_f32_e32 v139, 1.0, v139
	v_mul_f32_e32 v76, v76, v136
	v_mul_f32_e32 v77, v77, v137
	v_mul_f32_e32 v78, v78, v138
	v_mul_f32_e32 v79, v79, v139
	global_load_dwordx4 v[136:139], v129, s[24:25] offset:0
	s_waitcnt vmcnt(0)
	v_add_f32_e32 v136, 1.0, v136
	v_add_f32_e32 v137, 1.0, v137
	v_add_f32_e32 v138, 1.0, v138
	v_add_f32_e32 v139, 1.0, v139
	v_mul_f32_e32 v80, v80, v136
	v_mul_f32_e32 v81, v81, v137
	v_mul_f32_e32 v82, v82, v138
	v_mul_f32_e32 v83, v83, v139
	global_load_dwordx4 v[136:139], v129, s[24:25] offset:1024
	s_waitcnt vmcnt(0)
	v_add_f32_e32 v136, 1.0, v136
	v_add_f32_e32 v137, 1.0, v137
	v_add_f32_e32 v138, 1.0, v138
	v_add_f32_e32 v139, 1.0, v139
	v_mul_f32_e32 v84, v84, v136
	v_mul_f32_e32 v85, v85, v137
	v_mul_f32_e32 v86, v86, v138
	v_mul_f32_e32 v87, v87, v139
	global_load_dwordx4 v[136:139], v129, s[24:25] offset:2048
	s_waitcnt vmcnt(0)
	v_add_f32_e32 v136, 1.0, v136
	v_add_f32_e32 v137, 1.0, v137
	v_add_f32_e32 v138, 1.0, v138
	v_add_f32_e32 v139, 1.0, v139
	v_mul_f32_e32 v88, v88, v136
	v_mul_f32_e32 v89, v89, v137
	v_mul_f32_e32 v90, v90, v138
	v_mul_f32_e32 v91, v91, v139
	global_load_dwordx4 v[136:139], v129, s[24:25] offset:3072
	s_waitcnt vmcnt(0)
	v_add_f32_e32 v136, 1.0, v136
	v_add_f32_e32 v137, 1.0, v137
	v_add_f32_e32 v138, 1.0, v138
	v_add_f32_e32 v139, 1.0, v139
	v_mul_f32_e32 v92, v92, v136
	v_mul_f32_e32 v93, v93, v137
	v_mul_f32_e32 v94, v94, v138
	v_mul_f32_e32 v95, v95, v139
; __device__ __forceinline__ unsigned cvt_pk_bf16(float lo, float hi) { unsigned r; asm volatile("v_cvt_pk_bf16_f32 %0, %1, %2" : "=v"(r) : "v"(lo), "v"(hi)); return r; }
; __device__ __forceinline__ float sumsq8(const f32x4 (&v)[8]) {
;     float s = 0.f;
; #pragma unroll
;     for (int j = 0; j < 8; ++j) s += (v[j][0] * v[j][0] + v[j][1] * v[j][1]) + (v[j][2] * v[j][2] + v[j][3] * v[j][3]);
;     return wave_sum(s);
; }
; __device__ __forceinline__ void modulate_store(const f32x4 (&v)[8], float rstd, const float* pn, const float* modr, bf16_t* orow, int lane) {
; #pragma unroll
;     for (int j = 0; j < 8; ++j) { const int col = 4 * lane + 256 * j;
;         const f32x4 g = *(const f32x4*)(pn + col), sh = *(const f32x4*)(modr + col), sc = *(const f32x4*)(modr + DM + col);
;         const f32x4 hh = v[j] * rstd * g * (sc + 1.f) + sh;
;         u32x2 w; w.x = cvt_pk_bf16(hh[0], hh[1]); w.y = cvt_pk_bf16(hh[2], hh[3]);
;         *(u32x2*)(orow + col) = w; }
.Lp1_np3:
	s_waitcnt vmcnt(16)
	v_mul_f32_e32 v140, v32, v32
	v_mul_f32_e32 v141, v33, v33
	v_fmac_f32_e32 v140, v34, v34
	v_fmac_f32_e32 v141, v35, v35
	v_fmac_f32_e32 v140, v36, v36
	v_fmac_f32_e32 v141, v37, v37
	v_fmac_f32_e32 v140, v38, v38
	v_fmac_f32_e32 v141, v39, v39
	v_fmac_f32_e32 v140, v40, v40
	v_fmac_f32_e32 v141, v41, v41
	v_fmac_f32_e32 v140, v42, v42
	v_fmac_f32_e32 v141, v43, v43
	v_fmac_f32_e32 v140, v44, v44
	v_fmac_f32_e32 v141, v45, v45
	v_fmac_f32_e32 v140, v46, v46
	v_fmac_f32_e32 v141, v47, v47
	v_fmac_f32_e32 v140, v48, v48
	v_fmac_f32_e32 v141, v49, v49
	v_fmac_f32_e32 v140, v50, v50
	v_fmac_f32_e32 v141, v51, v51
	v_fmac_f32_e32 v140, v52, v52
	v_fmac_f32_e32 v141, v53, v53
	v_fmac_f32_e32 v140, v54, v54
	v_fmac_f32_e32 v141, v55, v55
	v_fmac_f32_e32 v140, v56, v56
	v_fmac_f32_e32 v141, v57, v57
	v_fmac_f32_e32 v140, v58, v58
	v_fmac_f32_e32 v141, v59, v59
	v_fmac_f32_e32 v140, v60, v60
	v_fmac_f32_e32 v141, v61, v61
	v_fmac_f32_e32 v140, v62, v62
	v_fmac_f32_e32 v141, v63, v63
	v_add_f32_e32 v140, v140, v141
	s_nop 1
	v_add_f32_dpp v142, v140, v140 quad_perm:[1,0,3,2] row_mask:0xf bank_mask:0xf
	s_nop 1
	v_add_f32_dpp v142, v142, v142 quad_perm:[2,3,0,1] row_mask:0xf bank_mask:0xf
	s_nop 1
	v_add_f32_dpp v142, v142, v142 row_half_mirror row_mask:0xf bank_mask:0xf
	s_nop 1
	v_add_f32_dpp v142, v142, v142 row_mirror row_mask:0xf bank_mask:0xf
	s_nop 1
	v_readlane_b32 s20, v142, 0
	v_readlane_b32 s21, v142, 16
	v_readlane_b32 s22, v142, 32
	v_readlane_b32 s23, v142, 48
	s_nop 1
	v_mov_b32_e32 v143, s20
	v_add_f32_e32 v143, s21, v143
	v_add_f32_e32 v143, s22, v143
	v_add_f32_e32 v143, s23, v143
	v_fmamk_f32 v143, v143, 0x3a000000, v131
	v_rsq_f32_e32 v143, v143
	s_nop 0
	s_add_i32 s4, s6, 3
	s_lshl_b32 s5, s4, 12
	s_add_u32 s14, s84, s5
	s_addc_u32 s15, s85, 0
	s_add_u32 s14, s14, 0x4000000
	s_addc_u32 s15, s15, 0
	v_mul_f32_e32 v136, v143, v32
	v_mul_f32_e32 v137, v143, v33
	v_mul_f32_e32 v138, v143, v34
	v_mul_f32_e32 v139, v143, v35
	v_fma_f32 v136, v136, v64, v96
	v_fma_f32 v137, v137, v65, v97
	v_fma_f32 v138, v138, v66, v98
	v_fma_f32 v139, v139, v67, v99
	v_cvt_pk_bf16_f32 v132, v136, v137
	v_cvt_pk_bf16_f32 v133, v138, v139
	global_store_dwordx2 v130, v[132:133], s[14:15] offset:0
	v_mul_f32_e32 v136, v143, v36
	v_mul_f32_e32 v137, v143, v37
	v_mul_f32_e32 v138, v143, v38
	v_mul_f32_e32 v139, v143, v39
	v_fma_f32 v136, v136, v68, v100
	v_fma_f32 v137, v137, v69, v101
	v_fma_f32 v138, v138, v70, v102
	v_fma_f32 v139, v139, v71, v103
	v_cvt_pk_bf16_f32 v134, v136, v137
	v_cvt_pk_bf16_f32 v135, v138, v139
	global_store_dwordx2 v130, v[134:135], s[14:15] offset:512
	v_mul_f32_e32 v136, v143, v40
	v_mul_f32_e32 v137, v143, v41
	v_mul_f32_e32 v138, v143, v42
	v_mul_f32_e32 v139, v143, v43
	v_fma_f32 v136, v136, v72, v104
	v_fma_f32 v137, v137, v73, v105
	v_fma_f32 v138, v138, v74, v106
	v_fma_f32 v139, v139, v75, v107
	v_cvt_pk_bf16_f32 v132, v136, v137
	v_cvt_pk_bf16_f32 v133, v138, v139
	global_store_dwordx2 v130, v[132:133], s[14:15] offset:1024
	v_mul_f32_e32 v136, v143, v44
	v_mul_f32_e32 v137, v143, v45
	v_mul_f32_e32 v138, v143, v46
	v_mul_f32_e32 v139, v143, v47
	v_fma_f32 v136, v136, v76, v108
	v_fma_f32 v137, v137, v77, v109
	v_fma_f32 v138, v138, v78, v110
	v_fma_f32 v139, v139, v79, v111
	v_cvt_pk_bf16_f32 v134, v136, v137
	v_cvt_pk_bf16_f32 v135, v138, v139
	global_store_dwordx2 v130, v[134:135], s[14:15] offset:1536
	v_mul_f32_e32 v136, v143, v48
	v_mul_f32_e32 v137, v143, v49
	v_mul_f32_e32 v138, v143, v50
	v_mul_f32_e32 v139, v143, v51
	v_fma_f32 v136, v136, v80, v112
	v_fma_f32 v137, v137, v81, v113
	v_fma_f32 v138, v138, v82, v114
	v_fma_f32 v139, v139, v83, v115
	v_cvt_pk_bf16_f32 v132, v136, v137
	v_cvt_pk_bf16_f32 v133, v138, v139
	global_store_dwordx2 v130, v[132:133], s[14:15] offset:2048
	v_mul_f32_e32 v136, v143, v52
	v_mul_f32_e32 v137, v143, v53
	v_mul_f32_e32 v138, v143, v54
	v_mul_f32_e32 v139, v143, v55
	v_fma_f32 v136, v136, v84, v116
	v_fma_f32 v137, v137, v85, v117
	v_fma_f32 v138, v138, v86, v118
	v_fma_f32 v139, v139, v87, v119
	v_cvt_pk_bf16_f32 v134, v136, v137
	v_cvt_pk_bf16_f32 v135, v138, v139
	global_store_dwordx2 v130, v[134:135], s[14:15] offset:2560
	v_mul_f32_e32 v136, v143, v56
	v_mul_f32_e32 v137, v143, v57
	v_mul_f32_e32 v138, v143, v58
	v_mul_f32_e32 v139, v143, v59
	v_fma_f32 v136, v136, v88, v120
	v_fma_f32 v137, v137, v89, v121
	v_fma_f32 v138, v138, v90, v122
	v_fma_f32 v139, v139, v91, v123
	v_cvt_pk_bf16_f32 v132, v136, v137
	v_cvt_pk_bf16_f32 v133, v138, v139
	global_store_dwordx2 v130, v[132:133], s[14:15] offset:3072
	v_mul_f32_e32 v136, v143, v60
	v_mul_f32_e32 v137, v143, v61
	v_mul_f32_e32 v138, v143, v62
	v_mul_f32_e32 v139, v143, v63
	v_fma_f32 v136, v136, v92, v124
	v_fma_f32 v137, v137, v93, v125
	v_fma_f32 v138, v138, v94, v126
	v_fma_f32 v139, v139, v95, v127
	v_cvt_pk_bf16_f32 v134, v136, v137
	v_cvt_pk_bf16_f32 v135, v138, v139
	global_store_dwordx2 v130, v[134:135], s[14:15] offset:3584
	s_add_i32 s4, s6, 5
	s_cmp_lt_u32 s4, 0x4000
	s_cselect_b32 s10, s68, s72
	s_cselect_b32 s11, s69, s73
	s_cselect_b32 s5, 0, 0x4000
	s_sub_i32 s5, s4, s5
	s_lshl_b32 s5, s5, 13
	s_add_u32 s10, s10, s5
	s_addc_u32 s11, s11, 0
	global_load_dwordx4 v[32:35], v128, s[10:11] offset:0
	global_load_dwordx4 v[36:39], v128, s[10:11] offset:1024
	global_load_dwordx4 v[40:43], v128, s[10:11] offset:2048
	global_load_dwordx4 v[44:47], v128, s[10:11] offset:3072
	global_load_dwordx4 v[48:51], v129, s[10:11] offset:0
	global_load_dwordx4 v[52:55], v129, s[10:11] offset:1024
	global_load_dwordx4 v[56:59], v129, s[10:11] offset:2048
	global_load_dwordx4 v[60:63], v129, s[10:11] offset:3072
	s_add_i32 s4, s6, 4
	s_add_i32 s4, s6, 4
	s_lshr_b32 s8, s4, 11
	s_cmp_lt_u32 s4, 0x4000
	s_cselect_b32 s8, s8, 8
	s_cmp_eq_u32 s8, s7
	s_cbranch_scc1 .Lp1_np4
; __device__ __forceinline__ unsigned cvt_pk_bf16(float lo, float hi) { unsigned r; asm volatile("v_cvt_pk_bf16_f32 %0, %1, %2" : "=v"(r) : "v"(lo), "v"(hi)); return r; }
; __device__ __forceinline__ float sumsq8(const f32x4 (&v)[8]) {
;     float s = 0.f;
; #pragma unroll
;     for (int j = 0; j < 8; ++j) s += (v[j][0] * v[j][0] + v[j][1] * v[j][1]) + (v[j][2] * v[j][2] + v[j][3] * v[j][3]);
;     return wave_sum(s);
; }
; __device__ __forceinline__ void modulate_store(const f32x4 (&v)[8], float rstd, const float* pn, const float* modr, bf16_t* orow, int lane) {
; #pragma unroll
;     for (int j = 0; j < 8; ++j) { const int col = 4 * lane + 256 * j;
;         const f32x4 g = *(const f32x4*)(pn + col), sh = *(const f32x4*)(modr + col), sc = *(const f32x4*)(modr + DM + col);
;         const f32x4 hh = v[j] * rstd * g * (sc + 1.f) + sh;
;         u32x2 w; w.x = cvt_pk_bf16(hh[0], hh[1]); w.y = cvt_pk_bf16(hh[2], hh[3]);
;         *(u32x2*)(orow + col) = w; }
	s_mov_b32 s7, s8
	s_add_i32 s5, s8, 0
	s_mul_i32 s5, s5, 0x6000
	s_add_u32 s24, s84, s5
	s_addc_u32 s25, s85, 0
	s_add_u32 s24, s24, 0x2000
	s_addc_u32 s25, s25, 0
	s_add_i32 s5, s8, 0
	s_mul_i32 s5, s5, 0x6000
	s_add_u32 s16, s84, s5
	s_addc_u32 s17, s85, 0
	s_add_u32 s18, s80, 0x0
	s_addc_u32 s19, s81, 0
	global_load_dwordx4 v[64:67], v128, s[18:19] offset:0
	global_load_dwordx4 v[96:99], v128, s[16:17] offset:0
	global_load_dwordx4 v[68:71], v128, s[18:19] offset:1024
	global_load_dwordx4 v[100:103], v128, s[16:17] offset:1024
	global_load_dwordx4 v[72:75], v128, s[18:19] offset:2048
	global_load_dwordx4 v[104:107], v128, s[16:17] offset:2048
	global_load_dwordx4 v[76:79], v128, s[18:19] offset:3072
	global_load_dwordx4 v[108:111], v128, s[16:17] offset:3072
	global_load_dwordx4 v[80:83], v129, s[18:19] offset:0
	global_load_dwordx4 v[112:115], v129, s[16:17] offset:0
	global_load_dwordx4 v[84:87], v129, s[18:19] offset:1024
	global_load_dwordx4 v[116:119], v129, s[16:17] offset:1024
	global_load_dwordx4 v[88:91], v129, s[18:19] offset:2048
	global_load_dwordx4 v[120:123], v129, s[16:17] offset:2048
	global_load_dwordx4 v[92:95], v129, s[18:19] offset:3072
	global_load_dwordx4 v[124:127], v129, s[16:17] offset:3072
	global_load_dwordx4 v[136:139], v128, s[24:25] offset:0
	s_waitcnt vmcnt(0)
	v_add_f32_e32 v136, 1.0, v136
	v_add_f32_e32 v137, 1.0, v137
	v_add_f32_e32 v138, 1.0, v138
	v_add_f32_e32 v139, 1.0, v139
	v_mul_f32_e32 v64, v64, v136
	v_mul_f32_e32 v65, v65, v137
	v_mul_f32_e32 v66, v66, v138
	v_mul_f32_e32 v67, v67, v139
	global_load_dwordx4 v[136:139], v128, s[24:25] offset:1024
	s_waitcnt vmcnt(0)
	v_add_f32_e32 v136, 1.0, v136
	v_add_f32_e32 v137, 1.0, v137
	v_add_f32_e32 v138, 1.0, v138
	v_add_f32_e32 v139, 1.0, v139
	v_mul_f32_e32 v68, v68, v136
	v_mul_f32_e32 v69, v69, v137
	v_mul_f32_e32 v70, v70, v138
	v_mul_f32_e32 v71, v71, v139
	global_load_dwordx4 v[136:139], v128, s[24:25] offset:2048
	s_waitcnt vmcnt(0)
	v_add_f32_e32 v136, 1.0, v136
	v_add_f32_e32 v137, 1.0, v137
	v_add_f32_e32 v138, 1.0, v138
	v_add_f32_e32 v139, 1.0, v139
	v_mul_f32_e32 v72, v72, v136
	v_mul_f32_e32 v73, v73, v137
	v_mul_f32_e32 v74, v74, v138
	v_mul_f32_e32 v75, v75, v139
	global_load_dwordx4 v[136:139], v128, s[24:25] offset:3072
	s_waitcnt vmcnt(0)
	v_add_f32_e32 v136, 1.0, v136
	v_add_f32_e32 v137, 1.0, v137
	v_add_f32_e32 v138, 1.0, v138
	v_add_f32_e32 v139, 1.0, v139
	v_mul_f32_e32 v76, v76, v136
	v_mul_f32_e32 v77, v77, v137
	v_mul_f32_e32 v78, v78, v138
	v_mul_f32_e32 v79, v79, v139
	global_load_dwordx4 v[136:139], v129, s[24:25] offset:0
	s_waitcnt vmcnt(0)
	v_add_f32_e32 v136, 1.0, v136
	v_add_f32_e32 v137, 1.0, v137
	v_add_f32_e32 v138, 1.0, v138
	v_add_f32_e32 v139, 1.0, v139
	v_mul_f32_e32 v80, v80, v136
	v_mul_f32_e32 v81, v81, v137
	v_mul_f32_e32 v82, v82, v138
	v_mul_f32_e32 v83, v83, v139
	global_load_dwordx4 v[136:139], v129, s[24:25] offset:1024
	s_waitcnt vmcnt(0)
	v_add_f32_e32 v136, 1.0, v136
	v_add_f32_e32 v137, 1.0, v137
	v_add_f32_e32 v138, 1.0, v138
	v_add_f32_e32 v139, 1.0, v139
	v_mul_f32_e32 v84, v84, v136
	v_mul_f32_e32 v85, v85, v137
	v_mul_f32_e32 v86, v86, v138
	v_mul_f32_e32 v87, v87, v139
	global_load_dwordx4 v[136:139], v129, s[24:25] offset:2048
	s_waitcnt vmcnt(0)
	v_add_f32_e32 v136, 1.0, v136
	v_add_f32_e32 v137, 1.0, v137
	v_add_f32_e32 v138, 1.0, v138
	v_add_f32_e32 v139, 1.0, v139
	v_mul_f32_e32 v88, v88, v136
	v_mul_f32_e32 v89, v89, v137
	v_mul_f32_e32 v90, v90, v138
	v_mul_f32_e32 v91, v91, v139
	global_load_dwordx4 v[136:139], v129, s[24:25] offset:3072
	s_waitcnt vmcnt(0)
	v_add_f32_e32 v136, 1.0, v136
	v_add_f32_e32 v137, 1.0, v137
	v_add_f32_e32 v138, 1.0, v138
	v_add_f32_e32 v139, 1.0, v139
	v_mul_f32_e32 v92, v92, v136
	v_mul_f32_e32 v93, v93, v137
	v_mul_f32_e32 v94, v94, v138
	v_mul_f32_e32 v95, v95, v139
.Lp1_np4:
	s_waitcnt vmcnt(16)
	v_mul_f32_e32 v140, v0, v0
	v_mul_f32_e32 v141, v1, v1
	v_fmac_f32_e32 v140, v2, v2
	v_fmac_f32_e32 v141, v3, v3
	v_fmac_f32_e32 v140, v4, v4
	v_fmac_f32_e32 v141, v5, v5
	v_fmac_f32_e32 v140, v6, v6
	v_fmac_f32_e32 v141, v7, v7
	v_fmac_f32_e32 v140, v8, v8
	v_fmac_f32_e32 v141, v9, v9
	v_fmac_f32_e32 v140, v10, v10
	v_fmac_f32_e32 v141, v11, v11
	v_fmac_f32_e32 v140, v12, v12
	v_fmac_f32_e32 v141, v13, v13
	v_fmac_f32_e32 v140, v14, v14
	v_fmac_f32_e32 v141, v15, v15
	v_fmac_f32_e32 v140, v16, v16
	v_fmac_f32_e32 v141, v17, v17
	v_fmac_f32_e32 v140, v18, v18
	v_fmac_f32_e32 v141, v19, v19
	v_fmac_f32_e32 v140, v20, v20
	v_fmac_f32_e32 v141, v21, v21
	v_fmac_f32_e32 v140, v22, v22
	v_fmac_f32_e32 v141, v23, v23
	v_fmac_f32_e32 v140, v24, v24
	v_fmac_f32_e32 v141, v25, v25
	v_fmac_f32_e32 v140, v26, v26
	v_fmac_f32_e32 v141, v27, v27
	v_fmac_f32_e32 v140, v28, v28
	v_fmac_f32_e32 v141, v29, v29
	v_fmac_f32_e32 v140, v30, v30
	v_fmac_f32_e32 v141, v31, v31
	v_add_f32_e32 v140, v140, v141
	s_nop 1
	v_add_f32_dpp v142, v140, v140 quad_perm:[1,0,3,2] row_mask:0xf bank_mask:0xf
	s_nop 1
	v_add_f32_dpp v142, v142, v142 quad_perm:[2,3,0,1] row_mask:0xf bank_mask:0xf
	s_nop 1
	v_add_f32_dpp v142, v142, v142 row_half_mirror row_mask:0xf bank_mask:0xf
	s_nop 1
	v_add_f32_dpp v142, v142, v142 row_mirror row_mask:0xf bank_mask:0xf
	s_nop 1
	v_readlane_b32 s20, v142, 0
	v_readlane_b32 s21, v142, 16
	v_readlane_b32 s22, v142, 32
	v_readlane_b32 s23, v142, 48
	s_nop 1
	v_mov_b32_e32 v143, s20
	v_add_f32_e32 v143, s21, v143
	v_add_f32_e32 v143, s22, v143
	v_add_f32_e32 v143, s23, v143
	v_fmamk_f32 v143, v143, 0x3a000000, v131
	v_rsq_f32_e32 v143, v143
	s_nop 0
	s_add_i32 s4, s6, 4
	s_lshl_b32 s5, s4, 12
	s_add_u32 s14, s84, s5
	s_addc_u32 s15, s85, 0
	s_add_u32 s14, s14, 0x4000000
; __device__ __forceinline__ unsigned cvt_pk_bf16(float lo, float hi) { unsigned r; asm volatile("v_cvt_pk_bf16_f32 %0, %1, %2" : "=v"(r) : "v"(lo), "v"(hi)); return r; }
; __device__ __forceinline__ float sumsq8(const f32x4 (&v)[8]) {
;     float s = 0.f;
; #pragma unroll
;     for (int j = 0; j < 8; ++j) s += (v[j][0] * v[j][0] + v[j][1] * v[j][1]) + (v[j][2] * v[j][2] + v[j][3] * v[j][3]);
;     return wave_sum(s);
; }
; __device__ __forceinline__ void modulate_store(const f32x4 (&v)[8], float rstd, const float* pn, const float* modr, bf16_t* orow, int lane) {
; #pragma unroll
;     for (int j = 0; j < 8; ++j) { const int col = 4 * lane + 256 * j;
;         const f32x4 g = *(const f32x4*)(pn + col), sh = *(const f32x4*)(modr + col), sc = *(const f32x4*)(modr + DM + col);
;         const f32x4 hh = v[j] * rstd * g * (sc + 1.f) + sh;
;         u32x2 w; w.x = cvt_pk_bf16(hh[0], hh[1]); w.y = cvt_pk_bf16(hh[2], hh[3]);
;         *(u32x2*)(orow + col) = w; }
	s_addc_u32 s15, s15, 0
	v_mul_f32_e32 v136, v143, v0
	v_mul_f32_e32 v137, v143, v1
	v_mul_f32_e32 v138, v143, v2
	v_mul_f32_e32 v139, v143, v3
	v_fma_f32 v136, v136, v64, v96
	v_fma_f32 v137, v137, v65, v97
	v_fma_f32 v138, v138, v66, v98
	v_fma_f32 v139, v139, v67, v99
	v_cvt_pk_bf16_f32 v132, v136, v137
	v_cvt_pk_bf16_f32 v133, v138, v139
	global_store_dwordx2 v130, v[132:133], s[14:15] offset:0
	v_mul_f32_e32 v136, v143, v4
	v_mul_f32_e32 v137, v143, v5
	v_mul_f32_e32 v138, v143, v6
	v_mul_f32_e32 v139, v143, v7
	v_fma_f32 v136, v136, v68, v100
	v_fma_f32 v137, v137, v69, v101
	v_fma_f32 v138, v138, v70, v102
	v_fma_f32 v139, v139, v71, v103
	v_cvt_pk_bf16_f32 v134, v136, v137
	v_cvt_pk_bf16_f32 v135, v138, v139
	global_store_dwordx2 v130, v[134:135], s[14:15] offset:512
	v_mul_f32_e32 v136, v143, v8
	v_mul_f32_e32 v137, v143, v9
	v_mul_f32_e32 v138, v143, v10
	v_mul_f32_e32 v139, v143, v11
	v_fma_f32 v136, v136, v72, v104
	v_fma_f32 v137, v137, v73, v105
	v_fma_f32 v138, v138, v74, v106
	v_fma_f32 v139, v139, v75, v107
	v_cvt_pk_bf16_f32 v132, v136, v137
	v_cvt_pk_bf16_f32 v133, v138, v139
	global_store_dwordx2 v130, v[132:133], s[14:15] offset:1024
	v_mul_f32_e32 v136, v143, v12
	v_mul_f32_e32 v137, v143, v13
	v_mul_f32_e32 v138, v143, v14
	v_mul_f32_e32 v139, v143, v15
	v_fma_f32 v136, v136, v76, v108
	v_fma_f32 v137, v137, v77, v109
	v_fma_f32 v138, v138, v78, v110
	v_fma_f32 v139, v139, v79, v111
	v_cvt_pk_bf16_f32 v134, v136, v137
	v_cvt_pk_bf16_f32 v135, v138, v139
	global_store_dwordx2 v130, v[134:135], s[14:15] offset:1536
	v_mul_f32_e32 v136, v143, v16
	v_mul_f32_e32 v137, v143, v17
	v_mul_f32_e32 v138, v143, v18
	v_mul_f32_e32 v139, v143, v19
	v_fma_f32 v136, v136, v80, v112
	v_fma_f32 v137, v137, v81, v113
	v_fma_f32 v138, v138, v82, v114
	v_fma_f32 v139, v139, v83, v115
	v_cvt_pk_bf16_f32 v132, v136, v137
	v_cvt_pk_bf16_f32 v133, v138, v139
	global_store_dwordx2 v130, v[132:133], s[14:15] offset:2048
	v_mul_f32_e32 v136, v143, v20
	v_mul_f32_e32 v137, v143, v21
	v_mul_f32_e32 v138, v143, v22
	v_mul_f32_e32 v139, v143, v23
	v_fma_f32 v136, v136, v84, v116
	v_fma_f32 v137, v137, v85, v117
	v_fma_f32 v138, v138, v86, v118
	v_fma_f32 v139, v139, v87, v119
	v_cvt_pk_bf16_f32 v134, v136, v137
	v_cvt_pk_bf16_f32 v135, v138, v139
	global_store_dwordx2 v130, v[134:135], s[14:15] offset:2560
	v_mul_f32_e32 v136, v143, v24
	v_mul_f32_e32 v137, v143, v25
	v_mul_f32_e32 v138, v143, v26
	v_mul_f32_e32 v139, v143, v27
	v_fma_f32 v136, v136, v88, v120
	v_fma_f32 v137, v137, v89, v121
	v_fma_f32 v138, v138, v90, v122
	v_fma_f32 v139, v139, v91, v123
	v_cvt_pk_bf16_f32 v132, v136, v137
	v_cvt_pk_bf16_f32 v133, v138, v139
	global_store_dwordx2 v130, v[132:133], s[14:15] offset:3072
	v_mul_f32_e32 v136, v143, v28
	v_mul_f32_e32 v137, v143, v29
	v_mul_f32_e32 v138, v143, v30
	v_mul_f32_e32 v139, v143, v31
	v_fma_f32 v136, v136, v92, v124
	v_fma_f32 v137, v137, v93, v125
	v_fma_f32 v138, v138, v94, v126
	v_fma_f32 v139, v139, v95, v127
	v_cvt_pk_bf16_f32 v134, v136, v137
	v_cvt_pk_bf16_f32 v135, v138, v139
	global_store_dwordx2 v130, v[134:135], s[14:15] offset:3584
	s_add_i32 s4, s6, 6
	s_cmp_lt_u32 s4, 0x4000
	s_cselect_b32 s10, s68, s72
	s_cselect_b32 s11, s69, s73
	s_cselect_b32 s5, 0, 0x4000
	s_sub_i32 s5, s4, s5
	s_lshl_b32 s5, s5, 13
	s_add_u32 s10, s10, s5
	s_addc_u32 s11, s11, 0
	global_load_dwordx4 v[0:3], v128, s[10:11] offset:0
	global_load_dwordx4 v[4:7], v128, s[10:11] offset:1024
	global_load_dwordx4 v[8:11], v128, s[10:11] offset:2048
	global_load_dwordx4 v[12:15], v128, s[10:11] offset:3072
	global_load_dwordx4 v[16:19], v129, s[10:11] offset:0
	global_load_dwordx4 v[20:23], v129, s[10:11] offset:1024
	global_load_dwordx4 v[24:27], v129, s[10:11] offset:2048
	global_load_dwordx4 v[28:31], v129, s[10:11] offset:3072
	s_add_i32 s4, s6, 5
	s_add_i32 s4, s6, 5
	s_lshr_b32 s8, s4, 11
	s_cmp_lt_u32 s4, 0x4000
	s_cselect_b32 s8, s8, 8
	s_cmp_eq_u32 s8, s7
	s_cbranch_scc1 .Lp1_np5
	s_mov_b32 s7, s8
	s_add_i32 s5, s8, 0
	s_mul_i32 s5, s5, 0x6000
	s_add_u32 s24, s84, s5
	s_addc_u32 s25, s85, 0
	s_add_u32 s24, s24, 0x2000
	s_addc_u32 s25, s25, 0
	s_add_i32 s5, s8, 0
	s_mul_i32 s5, s5, 0x6000
	s_add_u32 s16, s84, s5
	s_addc_u32 s17, s85, 0
	s_add_u32 s18, s80, 0x0
	s_addc_u32 s19, s81, 0
	global_load_dwordx4 v[64:67], v128, s[18:19] offset:0
	global_load_dwordx4 v[96:99], v128, s[16:17] offset:0
	global_load_dwordx4 v[68:71], v128, s[18:19] offset:1024
	global_load_dwordx4 v[100:103], v128, s[16:17] offset:1024
	global_load_dwordx4 v[72:75], v128, s[18:19] offset:2048
	global_load_dwordx4 v[104:107], v128, s[16:17] offset:2048
	global_load_dwordx4 v[76:79], v128, s[18:19] offset:3072
	global_load_dwordx4 v[108:111], v128, s[16:17] offset:3072
	global_load_dwordx4 v[80:83], v129, s[18:19] offset:0
	global_load_dwordx4 v[112:115], v129, s[16:17] offset:0
	global_load_dwordx4 v[84:87], v129, s[18:19] offset:1024
	global_load_dwordx4 v[116:119], v129, s[16:17] offset:1024
	global_load_dwordx4 v[88:91], v129, s[18:19] offset:2048
	global_load_dwordx4 v[120:123], v129, s[16:17] offset:2048
	global_load_dwordx4 v[92:95], v129, s[18:19] offset:3072
	global_load_dwordx4 v[124:127], v129, s[16:17] offset:3072
	global_load_dwordx4 v[136:139], v128, s[24:25] offset:0
	s_waitcnt vmcnt(0)
	v_add_f32_e32 v136, 1.0, v136
	v_add_f32_e32 v137, 1.0, v137
	v_add_f32_e32 v138, 1.0, v138
	v_add_f32_e32 v139, 1.0, v139
	v_mul_f32_e32 v64, v64, v136
	v_mul_f32_e32 v65, v65, v137
	v_mul_f32_e32 v66, v66, v138
	v_mul_f32_e32 v67, v67, v139
	global_load_dwordx4 v[136:139], v128, s[24:25] offset:1024
	s_waitcnt vmcnt(0)
; __device__ __forceinline__ unsigned cvt_pk_bf16(float lo, float hi) { unsigned r; asm volatile("v_cvt_pk_bf16_f32 %0, %1, %2" : "=v"(r) : "v"(lo), "v"(hi)); return r; }
; __device__ __forceinline__ float sumsq8(const f32x4 (&v)[8]) {
;     float s = 0.f;
; #pragma unroll
;     for (int j = 0; j < 8; ++j) s += (v[j][0] * v[j][0] + v[j][1] * v[j][1]) + (v[j][2] * v[j][2] + v[j][3] * v[j][3]);
;     return wave_sum(s);
; }
; __device__ __forceinline__ void modulate_store(const f32x4 (&v)[8], float rstd, const float* pn, const float* modr, bf16_t* orow, int lane) {
; #pragma unroll
;     for (int j = 0; j < 8; ++j) { const int col = 4 * lane + 256 * j;
;         const f32x4 g = *(const f32x4*)(pn + col), sh = *(const f32x4*)(modr + col), sc = *(const f32x4*)(modr + DM + col);
;         const f32x4 hh = v[j] * rstd * g * (sc + 1.f) + sh;
;         u32x2 w; w.x = cvt_pk_bf16(hh[0], hh[1]); w.y = cvt_pk_bf16(hh[2], hh[3]);
;         *(u32x2*)(orow + col) = w; }
	v_add_f32_e32 v136, 1.0, v136
	v_add_f32_e32 v137, 1.0, v137
	v_add_f32_e32 v138, 1.0, v138
	v_add_f32_e32 v139, 1.0, v139
	v_mul_f32_e32 v68, v68, v136
	v_mul_f32_e32 v69, v69, v137
	v_mul_f32_e32 v70, v70, v138
	v_mul_f32_e32 v71, v71, v139
	global_load_dwordx4 v[136:139], v128, s[24:25] offset:2048
	s_waitcnt vmcnt(0)
	v_add_f32_e32 v136, 1.0, v136
	v_add_f32_e32 v137, 1.0, v137
	v_add_f32_e32 v138, 1.0, v138
	v_add_f32_e32 v139, 1.0, v139
	v_mul_f32_e32 v72, v72, v136
	v_mul_f32_e32 v73, v73, v137
	v_mul_f32_e32 v74, v74, v138
	v_mul_f32_e32 v75, v75, v139
	global_load_dwordx4 v[136:139], v128, s[24:25] offset:3072
	s_waitcnt vmcnt(0)
	v_add_f32_e32 v136, 1.0, v136
	v_add_f32_e32 v137, 1.0, v137
	v_add_f32_e32 v138, 1.0, v138
	v_add_f32_e32 v139, 1.0, v139
	v_mul_f32_e32 v76, v76, v136
	v_mul_f32_e32 v77, v77, v137
	v_mul_f32_e32 v78, v78, v138
	v_mul_f32_e32 v79, v79, v139
	global_load_dwordx4 v[136:139], v129, s[24:25] offset:0
	s_waitcnt vmcnt(0)
	v_add_f32_e32 v136, 1.0, v136
	v_add_f32_e32 v137, 1.0, v137
	v_add_f32_e32 v138, 1.0, v138
	v_add_f32_e32 v139, 1.0, v139
	v_mul_f32_e32 v80, v80, v136
	v_mul_f32_e32 v81, v81, v137
	v_mul_f32_e32 v82, v82, v138
	v_mul_f32_e32 v83, v83, v139
	global_load_dwordx4 v[136:139], v129, s[24:25] offset:1024
	s_waitcnt vmcnt(0)
	v_add_f32_e32 v136, 1.0, v136
	v_add_f32_e32 v137, 1.0, v137
	v_add_f32_e32 v138, 1.0, v138
	v_add_f32_e32 v139, 1.0, v139
	v_mul_f32_e32 v84, v84, v136
	v_mul_f32_e32 v85, v85, v137
	v_mul_f32_e32 v86, v86, v138
	v_mul_f32_e32 v87, v87, v139
	global_load_dwordx4 v[136:139], v129, s[24:25] offset:2048
	s_waitcnt vmcnt(0)
	v_add_f32_e32 v136, 1.0, v136
	v_add_f32_e32 v137, 1.0, v137
	v_add_f32_e32 v138, 1.0, v138
	v_add_f32_e32 v139, 1.0, v139
	v_mul_f32_e32 v88, v88, v136
	v_mul_f32_e32 v89, v89, v137
	v_mul_f32_e32 v90, v90, v138
	v_mul_f32_e32 v91, v91, v139
	global_load_dwordx4 v[136:139], v129, s[24:25] offset:3072
	s_waitcnt vmcnt(0)
	v_add_f32_e32 v136, 1.0, v136
	v_add_f32_e32 v137, 1.0, v137
	v_add_f32_e32 v138, 1.0, v138
	v_add_f32_e32 v139, 1.0, v139
	v_mul_f32_e32 v92, v92, v136
	v_mul_f32_e32 v93, v93, v137
	v_mul_f32_e32 v94, v94, v138
	v_mul_f32_e32 v95, v95, v139
.Lp1_np5:
	s_waitcnt vmcnt(16)
	v_mul_f32_e32 v140, v32, v32
	v_mul_f32_e32 v141, v33, v33
	v_fmac_f32_e32 v140, v34, v34
	v_fmac_f32_e32 v141, v35, v35
	v_fmac_f32_e32 v140, v36, v36
	v_fmac_f32_e32 v141, v37, v37
	v_fmac_f32_e32 v140, v38, v38
	v_fmac_f32_e32 v141, v39, v39
	v_fmac_f32_e32 v140, v40, v40
	v_fmac_f32_e32 v141, v41, v41
	v_fmac_f32_e32 v140, v42, v42
	v_fmac_f32_e32 v141, v43, v43
	v_fmac_f32_e32 v140, v44, v44
	v_fmac_f32_e32 v141, v45, v45
	v_fmac_f32_e32 v140, v46, v46
	v_fmac_f32_e32 v141, v47, v47
	v_fmac_f32_e32 v140, v48, v48
	v_fmac_f32_e32 v141, v49, v49
	v_fmac_f32_e32 v140, v50, v50
	v_fmac_f32_e32 v141, v51, v51
	v_fmac_f32_e32 v140, v52, v52
	v_fmac_f32_e32 v141, v53, v53
	v_fmac_f32_e32 v140, v54, v54
	v_fmac_f32_e32 v141, v55, v55
	v_fmac_f32_e32 v140, v56, v56
	v_fmac_f32_e32 v141, v57, v57
	v_fmac_f32_e32 v140, v58, v58
	v_fmac_f32_e32 v141, v59, v59
	v_fmac_f32_e32 v140, v60, v60
	v_fmac_f32_e32 v141, v61, v61
	v_fmac_f32_e32 v140, v62, v62
	v_fmac_f32_e32 v141, v63, v63
	v_add_f32_e32 v140, v140, v141
	s_nop 1
	v_add_f32_dpp v142, v140, v140 quad_perm:[1,0,3,2] row_mask:0xf bank_mask:0xf
	s_nop 1
	v_add_f32_dpp v142, v142, v142 quad_perm:[2,3,0,1] row_mask:0xf bank_mask:0xf
	s_nop 1
	v_add_f32_dpp v142, v142, v142 row_half_mirror row_mask:0xf bank_mask:0xf
	s_nop 1
	v_add_f32_dpp v142, v142, v142 row_mirror row_mask:0xf bank_mask:0xf
	s_nop 1
	v_readlane_b32 s20, v142, 0
	v_readlane_b32 s21, v142, 16
	v_readlane_b32 s22, v142, 32
	v_readlane_b32 s23, v142, 48
	s_nop 1
	v_mov_b32_e32 v143, s20
	v_add_f32_e32 v143, s21, v143
	v_add_f32_e32 v143, s22, v143
	v_add_f32_e32 v143, s23, v143
	v_fmamk_f32 v143, v143, 0x3a000000, v131
	v_rsq_f32_e32 v143, v143
	s_nop 0
	s_add_i32 s4, s6, 5
	s_lshl_b32 s5, s4, 12
	s_add_u32 s14, s84, s5
	s_addc_u32 s15, s85, 0
	s_add_u32 s14, s14, 0x4000000
	s_addc_u32 s15, s15, 0
	v_mul_f32_e32 v136, v143, v32
	v_mul_f32_e32 v137, v143, v33
	v_mul_f32_e32 v138, v143, v34
	v_mul_f32_e32 v139, v143, v35
	v_fma_f32 v136, v136, v64, v96
	v_fma_f32 v137, v137, v65, v97
	v_fma_f32 v138, v138, v66, v98
	v_fma_f32 v139, v139, v67, v99
	v_cvt_pk_bf16_f32 v132, v136, v137
	v_cvt_pk_bf16_f32 v133, v138, v139
	global_store_dwordx2 v130, v[132:133], s[14:15] offset:0
	v_mul_f32_e32 v136, v143, v36
	v_mul_f32_e32 v137, v143, v37
	v_mul_f32_e32 v138, v143, v38
	v_mul_f32_e32 v139, v143, v39
	v_fma_f32 v136, v136, v68, v100
	v_fma_f32 v137, v137, v69, v101
	v_fma_f32 v138, v138, v70, v102
	v_fma_f32 v139, v139, v71, v103
	v_cvt_pk_bf16_f32 v134, v136, v137
	v_cvt_pk_bf16_f32 v135, v138, v139
	global_store_dwordx2 v130, v[134:135], s[14:15] offset:512
	v_mul_f32_e32 v136, v143, v40
	v_mul_f32_e32 v137, v143, v41
	v_mul_f32_e32 v138, v143, v42
	v_mul_f32_e32 v139, v143, v43
	v_fma_f32 v136, v136, v72, v104
	v_fma_f32 v137, v137, v73, v105
	v_fma_f32 v138, v138, v74, v106
	v_fma_f32 v139, v139, v75, v107
	v_cvt_pk_bf16_f32 v132, v136, v137
	v_cvt_pk_bf16_f32 v133, v138, v139
	global_store_dwordx2 v130, v[132:133], s[14:15] offset:1024
	v_mul_f32_e32 v136, v143, v44
	v_mul_f32_e32 v137, v143, v45
	v_mul_f32_e32 v138, v143, v46
	v_mul_f32_e32 v139, v143, v47
	v_fma_f32 v136, v136, v76, v108
	v_fma_f32 v137, v137, v77, v109
	v_fma_f32 v138, v138, v78, v110
	v_fma_f32 v139, v139, v79, v111
	v_cvt_pk_bf16_f32 v134, v136, v137
	v_cvt_pk_bf16_f32 v135, v138, v139
	global_store_dwordx2 v130, v[134:135], s[14:15] offset:1536
	v_mul_f32_e32 v136, v143, v48
; __device__ __forceinline__ unsigned cvt_pk_bf16(float lo, float hi) { unsigned r; asm volatile("v_cvt_pk_bf16_f32 %0, %1, %2" : "=v"(r) : "v"(lo), "v"(hi)); return r; }
; __device__ __forceinline__ float sumsq8(const f32x4 (&v)[8]) {
;     float s = 0.f;
; #pragma unroll
;     for (int j = 0; j < 8; ++j) s += (v[j][0] * v[j][0] + v[j][1] * v[j][1]) + (v[j][2] * v[j][2] + v[j][3] * v[j][3]);
;     return wave_sum(s);
; }
; __device__ __forceinline__ void modulate_store(const f32x4 (&v)[8], float rstd, const float* pn, const float* modr, bf16_t* orow, int lane) {
; #pragma unroll
;     for (int j = 0; j < 8; ++j) { const int col = 4 * lane + 256 * j;
;         const f32x4 g = *(const f32x4*)(pn + col), sh = *(const f32x4*)(modr + col), sc = *(const f32x4*)(modr + DM + col);
;         const f32x4 hh = v[j] * rstd * g * (sc + 1.f) + sh;
;         u32x2 w; w.x = cvt_pk_bf16(hh[0], hh[1]); w.y = cvt_pk_bf16(hh[2], hh[3]);
;         *(u32x2*)(orow + col) = w; }
	v_mul_f32_e32 v137, v143, v49
	v_mul_f32_e32 v138, v143, v50
	v_mul_f32_e32 v139, v143, v51
	v_fma_f32 v136, v136, v80, v112
	v_fma_f32 v137, v137, v81, v113
	v_fma_f32 v138, v138, v82, v114
	v_fma_f32 v139, v139, v83, v115
	v_cvt_pk_bf16_f32 v132, v136, v137
	v_cvt_pk_bf16_f32 v133, v138, v139
	global_store_dwordx2 v130, v[132:133], s[14:15] offset:2048
	v_mul_f32_e32 v136, v143, v52
	v_mul_f32_e32 v137, v143, v53
	v_mul_f32_e32 v138, v143, v54
	v_mul_f32_e32 v139, v143, v55
	v_fma_f32 v136, v136, v84, v116
	v_fma_f32 v137, v137, v85, v117
	v_fma_f32 v138, v138, v86, v118
	v_fma_f32 v139, v139, v87, v119
	v_cvt_pk_bf16_f32 v134, v136, v137
	v_cvt_pk_bf16_f32 v135, v138, v139
	global_store_dwordx2 v130, v[134:135], s[14:15] offset:2560
	v_mul_f32_e32 v136, v143, v56
	v_mul_f32_e32 v137, v143, v57
	v_mul_f32_e32 v138, v143, v58
	v_mul_f32_e32 v139, v143, v59
	v_fma_f32 v136, v136, v88, v120
	v_fma_f32 v137, v137, v89, v121
	v_fma_f32 v138, v138, v90, v122
	v_fma_f32 v139, v139, v91, v123
	v_cvt_pk_bf16_f32 v132, v136, v137
	v_cvt_pk_bf16_f32 v133, v138, v139
	global_store_dwordx2 v130, v[132:133], s[14:15] offset:3072
	v_mul_f32_e32 v136, v143, v60
	v_mul_f32_e32 v137, v143, v61
	v_mul_f32_e32 v138, v143, v62
	v_mul_f32_e32 v139, v143, v63
	v_fma_f32 v136, v136, v92, v124
	v_fma_f32 v137, v137, v93, v125
	v_fma_f32 v138, v138, v94, v126
	v_fma_f32 v139, v139, v95, v127
	v_cvt_pk_bf16_f32 v134, v136, v137
	v_cvt_pk_bf16_f32 v135, v138, v139
	global_store_dwordx2 v130, v[134:135], s[14:15] offset:3584
	s_add_i32 s4, s6, 7
	s_cmp_lt_u32 s4, 0x4000
	s_cselect_b32 s10, s68, s72
	s_cselect_b32 s11, s69, s73
	s_cselect_b32 s5, 0, 0x4000
	s_sub_i32 s5, s4, s5
	s_lshl_b32 s5, s5, 13
	s_add_u32 s10, s10, s5
	s_addc_u32 s11, s11, 0
	global_load_dwordx4 v[32:35], v128, s[10:11] offset:0
	global_load_dwordx4 v[36:39], v128, s[10:11] offset:1024
	global_load_dwordx4 v[40:43], v128, s[10:11] offset:2048
	global_load_dwordx4 v[44:47], v128, s[10:11] offset:3072
	global_load_dwordx4 v[48:51], v129, s[10:11] offset:0
	global_load_dwordx4 v[52:55], v129, s[10:11] offset:1024
	global_load_dwordx4 v[56:59], v129, s[10:11] offset:2048
	global_load_dwordx4 v[60:63], v129, s[10:11] offset:3072
	s_add_i32 s4, s6, 6
	s_add_i32 s4, s6, 6
	s_lshr_b32 s8, s4, 11
	s_cmp_lt_u32 s4, 0x4000
	s_cselect_b32 s8, s8, 8
	s_cmp_eq_u32 s8, s7
	s_cbranch_scc1 .Lp1_np6
	s_mov_b32 s7, s8
	s_add_i32 s5, s8, 0
	s_mul_i32 s5, s5, 0x6000
	s_add_u32 s24, s84, s5
	s_addc_u32 s25, s85, 0
	s_add_u32 s24, s24, 0x2000
	s_addc_u32 s25, s25, 0
	s_add_i32 s5, s8, 0
	s_mul_i32 s5, s5, 0x6000
	s_add_u32 s16, s84, s5
	s_addc_u32 s17, s85, 0
	s_add_u32 s18, s80, 0x0
	s_addc_u32 s19, s81, 0
	global_load_dwordx4 v[64:67], v128, s[18:19] offset:0
	global_load_dwordx4 v[96:99], v128, s[16:17] offset:0
	global_load_dwordx4 v[68:71], v128, s[18:19] offset:1024
	global_load_dwordx4 v[100:103], v128, s[16:17] offset:1024
	global_load_dwordx4 v[72:75], v128, s[18:19] offset:2048
	global_load_dwordx4 v[104:107], v128, s[16:17] offset:2048
	global_load_dwordx4 v[76:79], v128, s[18:19] offset:3072
	global_load_dwordx4 v[108:111], v128, s[16:17] offset:3072
	global_load_dwordx4 v[80:83], v129, s[18:19] offset:0
	global_load_dwordx4 v[112:115], v129, s[16:17] offset:0
	global_load_dwordx4 v[84:87], v129, s[18:19] offset:1024
	global_load_dwordx4 v[116:119], v129, s[16:17] offset:1024
	global_load_dwordx4 v[88:91], v129, s[18:19] offset:2048
	global_load_dwordx4 v[120:123], v129, s[16:17] offset:2048
	global_load_dwordx4 v[92:95], v129, s[18:19] offset:3072
	global_load_dwordx4 v[124:127], v129, s[16:17] offset:3072
	global_load_dwordx4 v[136:139], v128, s[24:25] offset:0
	s_waitcnt vmcnt(0)
	v_add_f32_e32 v136, 1.0, v136
	v_add_f32_e32 v137, 1.0, v137
	v_add_f32_e32 v138, 1.0, v138
	v_add_f32_e32 v139, 1.0, v139
	v_mul_f32_e32 v64, v64, v136
	v_mul_f32_e32 v65, v65, v137
	v_mul_f32_e32 v66, v66, v138
	v_mul_f32_e32 v67, v67, v139
	global_load_dwordx4 v[136:139], v128, s[24:25] offset:1024
	s_waitcnt vmcnt(0)
	v_add_f32_e32 v136, 1.0, v136
	v_add_f32_e32 v137, 1.0, v137
	v_add_f32_e32 v138, 1.0, v138
	v_add_f32_e32 v139, 1.0, v139
	v_mul_f32_e32 v68, v68, v136
	v_mul_f32_e32 v69, v69, v137
	v_mul_f32_e32 v70, v70, v138
	v_mul_f32_e32 v71, v71, v139
	global_load_dwordx4 v[136:139], v128, s[24:25] offset:2048
	s_waitcnt vmcnt(0)
	v_add_f32_e32 v136, 1.0, v136
	v_add_f32_e32 v137, 1.0, v137
	v_add_f32_e32 v138, 1.0, v138
	v_add_f32_e32 v139, 1.0, v139
	v_mul_f32_e32 v72, v72, v136
	v_mul_f32_e32 v73, v73, v137
	v_mul_f32_e32 v74, v74, v138
	v_mul_f32_e32 v75, v75, v139
	global_load_dwordx4 v[136:139], v128, s[24:25] offset:3072
	s_waitcnt vmcnt(0)
	v_add_f32_e32 v136, 1.0, v136
	v_add_f32_e32 v137, 1.0, v137
	v_add_f32_e32 v138, 1.0, v138
	v_add_f32_e32 v139, 1.0, v139
	v_mul_f32_e32 v76, v76, v136
	v_mul_f32_e32 v77, v77, v137
	v_mul_f32_e32 v78, v78, v138
	v_mul_f32_e32 v79, v79, v139
	global_load_dwordx4 v[136:139], v129, s[24:25] offset:0
	s_waitcnt vmcnt(0)
	v_add_f32_e32 v136, 1.0, v136
	v_add_f32_e32 v137, 1.0, v137
	v_add_f32_e32 v138, 1.0, v138
	v_add_f32_e32 v139, 1.0, v139
	v_mul_f32_e32 v80, v80, v136
	v_mul_f32_e32 v81, v81, v137
	v_mul_f32_e32 v82, v82, v138
	v_mul_f32_e32 v83, v83, v139
	global_load_dwordx4 v[136:139], v129, s[24:25] offset:1024
	s_waitcnt vmcnt(0)
	v_add_f32_e32 v136, 1.0, v136
	v_add_f32_e32 v137, 1.0, v137
	v_add_f32_e32 v138, 1.0, v138
	v_add_f32_e32 v139, 1.0, v139
	v_mul_f32_e32 v84, v84, v136
	v_mul_f32_e32 v85, v85, v137
	v_mul_f32_e32 v86, v86, v138
	v_mul_f32_e32 v87, v87, v139
	global_load_dwordx4 v[136:139], v129, s[24:25] offset:2048
	s_waitcnt vmcnt(0)
	v_add_f32_e32 v136, 1.0, v136
	v_add_f32_e32 v137, 1.0, v137
	v_add_f32_e32 v138, 1.0, v138
	v_add_f32_e32 v139, 1.0, v139
	v_mul_f32_e32 v88, v88, v136
	v_mul_f32_e32 v89, v89, v137
	v_mul_f32_e32 v90, v90, v138
	v_mul_f32_e32 v91, v91, v139
	global_load_dwordx4 v[136:139], v129, s[24:25] offset:3072
	s_waitcnt vmcnt(0)
	v_add_f32_e32 v136, 1.0, v136
	v_add_f32_e32 v137, 1.0, v137
	v_add_f32_e32 v138, 1.0, v138
	v_add_f32_e32 v139, 1.0, v139
	v_mul_f32_e32 v92, v92, v136
	v_mul_f32_e32 v93, v93, v137
	v_mul_f32_e32 v94, v94, v138
	v_mul_f32_e32 v95, v95, v139
; __device__ __forceinline__ unsigned cvt_pk_bf16(float lo, float hi) { unsigned r; asm volatile("v_cvt_pk_bf16_f32 %0, %1, %2" : "=v"(r) : "v"(lo), "v"(hi)); return r; }
; __device__ __forceinline__ float sumsq8(const f32x4 (&v)[8]) {
;     float s = 0.f;
; #pragma unroll
;     for (int j = 0; j < 8; ++j) s += (v[j][0] * v[j][0] + v[j][1] * v[j][1]) + (v[j][2] * v[j][2] + v[j][3] * v[j][3]);
;     return wave_sum(s);
; }
; __device__ __forceinline__ void modulate_store(const f32x4 (&v)[8], float rstd, const float* pn, const float* modr, bf16_t* orow, int lane) {
; #pragma unroll
;     for (int j = 0; j < 8; ++j) { const int col = 4 * lane + 256 * j;
;         const f32x4 g = *(const f32x4*)(pn + col), sh = *(const f32x4*)(modr + col), sc = *(const f32x4*)(modr + DM + col);
;         const f32x4 hh = v[j] * rstd * g * (sc + 1.f) + sh;
;         u32x2 w; w.x = cvt_pk_bf16(hh[0], hh[1]); w.y = cvt_pk_bf16(hh[2], hh[3]);
;         *(u32x2*)(orow + col) = w; }
.Lp1_np6:
	s_waitcnt vmcnt(16)
	v_mul_f32_e32 v140, v0, v0
	v_mul_f32_e32 v141, v1, v1
	v_fmac_f32_e32 v140, v2, v2
	v_fmac_f32_e32 v141, v3, v3
	v_fmac_f32_e32 v140, v4, v4
	v_fmac_f32_e32 v141, v5, v5
	v_fmac_f32_e32 v140, v6, v6
	v_fmac_f32_e32 v141, v7, v7
	v_fmac_f32_e32 v140, v8, v8
	v_fmac_f32_e32 v141, v9, v9
	v_fmac_f32_e32 v140, v10, v10
	v_fmac_f32_e32 v141, v11, v11
	v_fmac_f32_e32 v140, v12, v12
	v_fmac_f32_e32 v141, v13, v13
	v_fmac_f32_e32 v140, v14, v14
	v_fmac_f32_e32 v141, v15, v15
	v_fmac_f32_e32 v140, v16, v16
	v_fmac_f32_e32 v141, v17, v17
	v_fmac_f32_e32 v140, v18, v18
	v_fmac_f32_e32 v141, v19, v19
	v_fmac_f32_e32 v140, v20, v20
	v_fmac_f32_e32 v141, v21, v21
	v_fmac_f32_e32 v140, v22, v22
	v_fmac_f32_e32 v141, v23, v23
	v_fmac_f32_e32 v140, v24, v24
	v_fmac_f32_e32 v141, v25, v25
	v_fmac_f32_e32 v140, v26, v26
	v_fmac_f32_e32 v141, v27, v27
	v_fmac_f32_e32 v140, v28, v28
	v_fmac_f32_e32 v141, v29, v29
	v_fmac_f32_e32 v140, v30, v30
	v_fmac_f32_e32 v141, v31, v31
	v_add_f32_e32 v140, v140, v141
	s_nop 1
	v_add_f32_dpp v142, v140, v140 quad_perm:[1,0,3,2] row_mask:0xf bank_mask:0xf
	s_nop 1
	v_add_f32_dpp v142, v142, v142 quad_perm:[2,3,0,1] row_mask:0xf bank_mask:0xf
	s_nop 1
	v_add_f32_dpp v142, v142, v142 row_half_mirror row_mask:0xf bank_mask:0xf
	s_nop 1
	v_add_f32_dpp v142, v142, v142 row_mirror row_mask:0xf bank_mask:0xf
	s_nop 1
	v_readlane_b32 s20, v142, 0
	v_readlane_b32 s21, v142, 16
	v_readlane_b32 s22, v142, 32
	v_readlane_b32 s23, v142, 48
	s_nop 1
	v_mov_b32_e32 v143, s20
	v_add_f32_e32 v143, s21, v143
	v_add_f32_e32 v143, s22, v143
	v_add_f32_e32 v143, s23, v143
	v_fmamk_f32 v143, v143, 0x3a000000, v131
	v_rsq_f32_e32 v143, v143
	s_nop 0
	s_add_i32 s4, s6, 6
	s_lshl_b32 s5, s4, 12
	s_add_u32 s14, s84, s5
	s_addc_u32 s15, s85, 0
	s_add_u32 s14, s14, 0x4000000
	s_addc_u32 s15, s15, 0
	v_mul_f32_e32 v136, v143, v0
	v_mul_f32_e32 v137, v143, v1
	v_mul_f32_e32 v138, v143, v2
	v_mul_f32_e32 v139, v143, v3
	v_fma_f32 v136, v136, v64, v96
	v_fma_f32 v137, v137, v65, v97
	v_fma_f32 v138, v138, v66, v98
	v_fma_f32 v139, v139, v67, v99
	v_cvt_pk_bf16_f32 v132, v136, v137
	v_cvt_pk_bf16_f32 v133, v138, v139
	global_store_dwordx2 v130, v[132:133], s[14:15] offset:0
	v_mul_f32_e32 v136, v143, v4
	v_mul_f32_e32 v137, v143, v5
	v_mul_f32_e32 v138, v143, v6
	v_mul_f32_e32 v139, v143, v7
	v_fma_f32 v136, v136, v68, v100
	v_fma_f32 v137, v137, v69, v101
	v_fma_f32 v138, v138, v70, v102
	v_fma_f32 v139, v139, v71, v103
	v_cvt_pk_bf16_f32 v134, v136, v137
	v_cvt_pk_bf16_f32 v135, v138, v139
	global_store_dwordx2 v130, v[134:135], s[14:15] offset:512
	v_mul_f32_e32 v136, v143, v8
	v_mul_f32_e32 v137, v143, v9
	v_mul_f32_e32 v138, v143, v10
	v_mul_f32_e32 v139, v143, v11
	v_fma_f32 v136, v136, v72, v104
	v_fma_f32 v137, v137, v73, v105
	v_fma_f32 v138, v138, v74, v106
	v_fma_f32 v139, v139, v75, v107
	v_cvt_pk_bf16_f32 v132, v136, v137
	v_cvt_pk_bf16_f32 v133, v138, v139
	global_store_dwordx2 v130, v[132:133], s[14:15] offset:1024
	v_mul_f32_e32 v136, v143, v12
	v_mul_f32_e32 v137, v143, v13
	v_mul_f32_e32 v138, v143, v14
	v_mul_f32_e32 v139, v143, v15
	v_fma_f32 v136, v136, v76, v108
	v_fma_f32 v137, v137, v77, v109
	v_fma_f32 v138, v138, v78, v110
	v_fma_f32 v139, v139, v79, v111
	v_cvt_pk_bf16_f32 v134, v136, v137
	v_cvt_pk_bf16_f32 v135, v138, v139
	global_store_dwordx2 v130, v[134:135], s[14:15] offset:1536
	v_mul_f32_e32 v136, v143, v16
	v_mul_f32_e32 v137, v143, v17
	v_mul_f32_e32 v138, v143, v18
	v_mul_f32_e32 v139, v143, v19
	v_fma_f32 v136, v136, v80, v112
	v_fma_f32 v137, v137, v81, v113
	v_fma_f32 v138, v138, v82, v114
	v_fma_f32 v139, v139, v83, v115
	v_cvt_pk_bf16_f32 v132, v136, v137
	v_cvt_pk_bf16_f32 v133, v138, v139
	global_store_dwordx2 v130, v[132:133], s[14:15] offset:2048
	v_mul_f32_e32 v136, v143, v20
	v_mul_f32_e32 v137, v143, v21
	v_mul_f32_e32 v138, v143, v22
	v_mul_f32_e32 v139, v143, v23
	v_fma_f32 v136, v136, v84, v116
	v_fma_f32 v137, v137, v85, v117
	v_fma_f32 v138, v138, v86, v118
	v_fma_f32 v139, v139, v87, v119
	v_cvt_pk_bf16_f32 v134, v136, v137
	v_cvt_pk_bf16_f32 v135, v138, v139
	global_store_dwordx2 v130, v[134:135], s[14:15] offset:2560
	v_mul_f32_e32 v136, v143, v24
	v_mul_f32_e32 v137, v143, v25
	v_mul_f32_e32 v138, v143, v26
	v_mul_f32_e32 v139, v143, v27
	v_fma_f32 v136, v136, v88, v120
	v_fma_f32 v137, v137, v89, v121
	v_fma_f32 v138, v138, v90, v122
	v_fma_f32 v139, v139, v91, v123
	v_cvt_pk_bf16_f32 v132, v136, v137
	v_cvt_pk_bf16_f32 v133, v138, v139
	global_store_dwordx2 v130, v[132:133], s[14:15] offset:3072
	v_mul_f32_e32 v136, v143, v28
	v_mul_f32_e32 v137, v143, v29
	v_mul_f32_e32 v138, v143, v30
	v_mul_f32_e32 v139, v143, v31
	v_fma_f32 v136, v136, v92, v124
	v_fma_f32 v137, v137, v93, v125
	v_fma_f32 v138, v138, v94, v126
	v_fma_f32 v139, v139, v95, v127
	v_cvt_pk_bf16_f32 v134, v136, v137
	v_cvt_pk_bf16_f32 v135, v138, v139
	global_store_dwordx2 v130, v[134:135], s[14:15] offset:3584
	s_add_i32 s4, s6, 8
	s_cmp_lt_u32 s4, 0x4000
	s_cselect_b32 s10, s68, s72
	s_cselect_b32 s11, s69, s73
	s_cselect_b32 s5, 0, 0x4000
	s_sub_i32 s5, s4, s5
	s_lshl_b32 s5, s5, 13
	s_add_u32 s10, s10, s5
	s_addc_u32 s11, s11, 0
	global_load_dwordx4 v[0:3], v128, s[10:11] offset:0
	global_load_dwordx4 v[4:7], v128, s[10:11] offset:1024
	global_load_dwordx4 v[8:11], v128, s[10:11] offset:2048
	global_load_dwordx4 v[12:15], v128, s[10:11] offset:3072
	global_load_dwordx4 v[16:19], v129, s[10:11] offset:0
	global_load_dwordx4 v[20:23], v129, s[10:11] offset:1024
	global_load_dwordx4 v[24:27], v129, s[10:11] offset:2048
	global_load_dwordx4 v[28:31], v129, s[10:11] offset:3072
	s_add_i32 s4, s6, 7
	s_add_i32 s4, s6, 7
	s_lshr_b32 s8, s4, 11
	s_cmp_lt_u32 s4, 0x4000
	s_cselect_b32 s8, s8, 8
	s_cmp_eq_u32 s8, s7
	s_cbranch_scc1 .Lp1_np7
; __device__ __forceinline__ unsigned cvt_pk_bf16(float lo, float hi) { unsigned r; asm volatile("v_cvt_pk_bf16_f32 %0, %1, %2" : "=v"(r) : "v"(lo), "v"(hi)); return r; }
; __device__ __forceinline__ float sumsq8(const f32x4 (&v)[8]) {
;     float s = 0.f;
; #pragma unroll
;     for (int j = 0; j < 8; ++j) s += (v[j][0] * v[j][0] + v[j][1] * v[j][1]) + (v[j][2] * v[j][2] + v[j][3] * v[j][3]);
;     return wave_sum(s);
; }
; __device__ __forceinline__ void modulate_store(const f32x4 (&v)[8], float rstd, const float* pn, const float* modr, bf16_t* orow, int lane) {
; #pragma unroll
;     for (int j = 0; j < 8; ++j) { const int col = 4 * lane + 256 * j;
;         const f32x4 g = *(const f32x4*)(pn + col), sh = *(const f32x4*)(modr + col), sc = *(const f32x4*)(modr + DM + col);
;         const f32x4 hh = v[j] * rstd * g * (sc + 1.f) + sh;
;         u32x2 w; w.x = cvt_pk_bf16(hh[0], hh[1]); w.y = cvt_pk_bf16(hh[2], hh[3]);
;         *(u32x2*)(orow + col) = w; }
	s_mov_b32 s7, s8
	s_add_i32 s5, s8, 0
	s_mul_i32 s5, s5, 0x6000
	s_add_u32 s24, s84, s5
	s_addc_u32 s25, s85, 0
	s_add_u32 s24, s24, 0x2000
	s_addc_u32 s25, s25, 0
	s_add_i32 s5, s8, 0
	s_mul_i32 s5, s5, 0x6000
	s_add_u32 s16, s84, s5
	s_addc_u32 s17, s85, 0
	s_add_u32 s18, s80, 0x0
	s_addc_u32 s19, s81, 0
	global_load_dwordx4 v[64:67], v128, s[18:19] offset:0
	global_load_dwordx4 v[96:99], v128, s[16:17] offset:0
	global_load_dwordx4 v[68:71], v128, s[18:19] offset:1024
	global_load_dwordx4 v[100:103], v128, s[16:17] offset:1024
	global_load_dwordx4 v[72:75], v128, s[18:19] offset:2048
	global_load_dwordx4 v[104:107], v128, s[16:17] offset:2048
	global_load_dwordx4 v[76:79], v128, s[18:19] offset:3072
	global_load_dwordx4 v[108:111], v128, s[16:17] offset:3072
	global_load_dwordx4 v[80:83], v129, s[18:19] offset:0
	global_load_dwordx4 v[112:115], v129, s[16:17] offset:0
	global_load_dwordx4 v[84:87], v129, s[18:19] offset:1024
	global_load_dwordx4 v[116:119], v129, s[16:17] offset:1024
	global_load_dwordx4 v[88:91], v129, s[18:19] offset:2048
	global_load_dwordx4 v[120:123], v129, s[16:17] offset:2048
	global_load_dwordx4 v[92:95], v129, s[18:19] offset:3072
	global_load_dwordx4 v[124:127], v129, s[16:17] offset:3072
	global_load_dwordx4 v[136:139], v128, s[24:25] offset:0
	s_waitcnt vmcnt(0)
	v_add_f32_e32 v136, 1.0, v136
	v_add_f32_e32 v137, 1.0, v137
	v_add_f32_e32 v138, 1.0, v138
	v_add_f32_e32 v139, 1.0, v139
	v_mul_f32_e32 v64, v64, v136
	v_mul_f32_e32 v65, v65, v137
	v_mul_f32_e32 v66, v66, v138
	v_mul_f32_e32 v67, v67, v139
	global_load_dwordx4 v[136:139], v128, s[24:25] offset:1024
	s_waitcnt vmcnt(0)
	v_add_f32_e32 v136, 1.0, v136
	v_add_f32_e32 v137, 1.0, v137
	v_add_f32_e32 v138, 1.0, v138
	v_add_f32_e32 v139, 1.0, v139
	v_mul_f32_e32 v68, v68, v136
	v_mul_f32_e32 v69, v69, v137
	v_mul_f32_e32 v70, v70, v138
	v_mul_f32_e32 v71, v71, v139
	global_load_dwordx4 v[136:139], v128, s[24:25] offset:2048
	s_waitcnt vmcnt(0)
	v_add_f32_e32 v136, 1.0, v136
	v_add_f32_e32 v137, 1.0, v137
	v_add_f32_e32 v138, 1.0, v138
	v_add_f32_e32 v139, 1.0, v139
	v_mul_f32_e32 v72, v72, v136
	v_mul_f32_e32 v73, v73, v137
	v_mul_f32_e32 v74, v74, v138
	v_mul_f32_e32 v75, v75, v139
	global_load_dwordx4 v[136:139], v128, s[24:25] offset:3072
	s_waitcnt vmcnt(0)
	v_add_f32_e32 v136, 1.0, v136
	v_add_f32_e32 v137, 1.0, v137
	v_add_f32_e32 v138, 1.0, v138
	v_add_f32_e32 v139, 1.0, v139
	v_mul_f32_e32 v76, v76, v136
	v_mul_f32_e32 v77, v77, v137
	v_mul_f32_e32 v78, v78, v138
	v_mul_f32_e32 v79, v79, v139
	global_load_dwordx4 v[136:139], v129, s[24:25] offset:0
	s_waitcnt vmcnt(0)
	v_add_f32_e32 v136, 1.0, v136
	v_add_f32_e32 v137, 1.0, v137
	v_add_f32_e32 v138, 1.0, v138
	v_add_f32_e32 v139, 1.0, v139
	v_mul_f32_e32 v80, v80, v136
	v_mul_f32_e32 v81, v81, v137
	v_mul_f32_e32 v82, v82, v138
	v_mul_f32_e32 v83, v83, v139
	global_load_dwordx4 v[136:139], v129, s[24:25] offset:1024
	s_waitcnt vmcnt(0)
	v_add_f32_e32 v136, 1.0, v136
	v_add_f32_e32 v137, 1.0, v137
	v_add_f32_e32 v138, 1.0, v138
	v_add_f32_e32 v139, 1.0, v139
	v_mul_f32_e32 v84, v84, v136
	v_mul_f32_e32 v85, v85, v137
	v_mul_f32_e32 v86, v86, v138
	v_mul_f32_e32 v87, v87, v139
	global_load_dwordx4 v[136:139], v129, s[24:25] offset:2048
	s_waitcnt vmcnt(0)
	v_add_f32_e32 v136, 1.0, v136
	v_add_f32_e32 v137, 1.0, v137
	v_add_f32_e32 v138, 1.0, v138
	v_add_f32_e32 v139, 1.0, v139
	v_mul_f32_e32 v88, v88, v136
	v_mul_f32_e32 v89, v89, v137
	v_mul_f32_e32 v90, v90, v138
	v_mul_f32_e32 v91, v91, v139
	global_load_dwordx4 v[136:139], v129, s[24:25] offset:3072
	s_waitcnt vmcnt(0)
	v_add_f32_e32 v136, 1.0, v136
	v_add_f32_e32 v137, 1.0, v137
	v_add_f32_e32 v138, 1.0, v138
	v_add_f32_e32 v139, 1.0, v139
	v_mul_f32_e32 v92, v92, v136
	v_mul_f32_e32 v93, v93, v137
	v_mul_f32_e32 v94, v94, v138
	v_mul_f32_e32 v95, v95, v139
.Lp1_np7:
	s_waitcnt vmcnt(16)
	v_mul_f32_e32 v140, v32, v32
	v_mul_f32_e32 v141, v33, v33
	v_fmac_f32_e32 v140, v34, v34
	v_fmac_f32_e32 v141, v35, v35
	v_fmac_f32_e32 v140, v36, v36
	v_fmac_f32_e32 v141, v37, v37
	v_fmac_f32_e32 v140, v38, v38
	v_fmac_f32_e32 v141, v39, v39
	v_fmac_f32_e32 v140, v40, v40
	v_fmac_f32_e32 v141, v41, v41
	v_fmac_f32_e32 v140, v42, v42
	v_fmac_f32_e32 v141, v43, v43
	v_fmac_f32_e32 v140, v44, v44
	v_fmac_f32_e32 v141, v45, v45
	v_fmac_f32_e32 v140, v46, v46
	v_fmac_f32_e32 v141, v47, v47
	v_fmac_f32_e32 v140, v48, v48
	v_fmac_f32_e32 v141, v49, v49
	v_fmac_f32_e32 v140, v50, v50
	v_fmac_f32_e32 v141, v51, v51
	v_fmac_f32_e32 v140, v52, v52
	v_fmac_f32_e32 v141, v53, v53
	v_fmac_f32_e32 v140, v54, v54
	v_fmac_f32_e32 v141, v55, v55
	v_fmac_f32_e32 v140, v56, v56
	v_fmac_f32_e32 v141, v57, v57
	v_fmac_f32_e32 v140, v58, v58
	v_fmac_f32_e32 v141, v59, v59
	v_fmac_f32_e32 v140, v60, v60
	v_fmac_f32_e32 v141, v61, v61
	v_fmac_f32_e32 v140, v62, v62
	v_fmac_f32_e32 v141, v63, v63
	v_add_f32_e32 v140, v140, v141
	s_nop 1
	v_add_f32_dpp v142, v140, v140 quad_perm:[1,0,3,2] row_mask:0xf bank_mask:0xf
	s_nop 1
	v_add_f32_dpp v142, v142, v142 quad_perm:[2,3,0,1] row_mask:0xf bank_mask:0xf
	s_nop 1
	v_add_f32_dpp v142, v142, v142 row_half_mirror row_mask:0xf bank_mask:0xf
	s_nop 1
	v_add_f32_dpp v142, v142, v142 row_mirror row_mask:0xf bank_mask:0xf
	s_nop 1
	v_readlane_b32 s20, v142, 0
	v_readlane_b32 s21, v142, 16
	v_readlane_b32 s22, v142, 32
	v_readlane_b32 s23, v142, 48
	s_nop 1
	v_mov_b32_e32 v143, s20
	v_add_f32_e32 v143, s21, v143
	v_add_f32_e32 v143, s22, v143
	v_add_f32_e32 v143, s23, v143
	v_fmamk_f32 v143, v143, 0x3a000000, v131
	v_rsq_f32_e32 v143, v143
	s_nop 0
	s_add_i32 s4, s6, 7
	s_lshl_b32 s5, s4, 12
	s_add_u32 s14, s84, s5
	s_addc_u32 s15, s85, 0
; __device__ __forceinline__ unsigned cvt_pk_bf16(float lo, float hi) { unsigned r; asm volatile("v_cvt_pk_bf16_f32 %0, %1, %2" : "=v"(r) : "v"(lo), "v"(hi)); return r; }
; __device__ __forceinline__ float sumsq8(const f32x4 (&v)[8]) {
;     float s = 0.f;
; #pragma unroll
;     for (int j = 0; j < 8; ++j) s += (v[j][0] * v[j][0] + v[j][1] * v[j][1]) + (v[j][2] * v[j][2] + v[j][3] * v[j][3]);
;     return wave_sum(s);
; }
; __device__ __forceinline__ void modulate_store(const f32x4 (&v)[8], float rstd, const float* pn, const float* modr, bf16_t* orow, int lane) {
; #pragma unroll
;     for (int j = 0; j < 8; ++j) { const int col = 4 * lane + 256 * j;
;         const f32x4 g = *(const f32x4*)(pn + col), sh = *(const f32x4*)(modr + col), sc = *(const f32x4*)(modr + DM + col);
;         const f32x4 hh = v[j] * rstd * g * (sc + 1.f) + sh;
;         u32x2 w; w.x = cvt_pk_bf16(hh[0], hh[1]); w.y = cvt_pk_bf16(hh[2], hh[3]);
;         *(u32x2*)(orow + col) = w; }
	s_add_u32 s14, s14, 0x4000000
	s_addc_u32 s15, s15, 0
	v_mul_f32_e32 v136, v143, v32
	v_mul_f32_e32 v137, v143, v33
	v_mul_f32_e32 v138, v143, v34
	v_mul_f32_e32 v139, v143, v35
	v_fma_f32 v136, v136, v64, v96
	v_fma_f32 v137, v137, v65, v97
	v_fma_f32 v138, v138, v66, v98
	v_fma_f32 v139, v139, v67, v99
	v_cvt_pk_bf16_f32 v132, v136, v137
	v_cvt_pk_bf16_f32 v133, v138, v139
	global_store_dwordx2 v130, v[132:133], s[14:15] offset:0
	v_mul_f32_e32 v136, v143, v36
	v_mul_f32_e32 v137, v143, v37
	v_mul_f32_e32 v138, v143, v38
	v_mul_f32_e32 v139, v143, v39
	v_fma_f32 v136, v136, v68, v100
	v_fma_f32 v137, v137, v69, v101
	v_fma_f32 v138, v138, v70, v102
	v_fma_f32 v139, v139, v71, v103
	v_cvt_pk_bf16_f32 v134, v136, v137
	v_cvt_pk_bf16_f32 v135, v138, v139
	global_store_dwordx2 v130, v[134:135], s[14:15] offset:512
	v_mul_f32_e32 v136, v143, v40
	v_mul_f32_e32 v137, v143, v41
	v_mul_f32_e32 v138, v143, v42
	v_mul_f32_e32 v139, v143, v43
	v_fma_f32 v136, v136, v72, v104
	v_fma_f32 v137, v137, v73, v105
	v_fma_f32 v138, v138, v74, v106
	v_fma_f32 v139, v139, v75, v107
	v_cvt_pk_bf16_f32 v132, v136, v137
	v_cvt_pk_bf16_f32 v133, v138, v139
	global_store_dwordx2 v130, v[132:133], s[14:15] offset:1024
	v_mul_f32_e32 v136, v143, v44
	v_mul_f32_e32 v137, v143, v45
	v_mul_f32_e32 v138, v143, v46
	v_mul_f32_e32 v139, v143, v47
	v_fma_f32 v136, v136, v76, v108
	v_fma_f32 v137, v137, v77, v109
	v_fma_f32 v138, v138, v78, v110
	v_fma_f32 v139, v139, v79, v111
	v_cvt_pk_bf16_f32 v134, v136, v137
	v_cvt_pk_bf16_f32 v135, v138, v139
	global_store_dwordx2 v130, v[134:135], s[14:15] offset:1536
	v_mul_f32_e32 v136, v143, v48
	v_mul_f32_e32 v137, v143, v49
	v_mul_f32_e32 v138, v143, v50
	v_mul_f32_e32 v139, v143, v51
	v_fma_f32 v136, v136, v80, v112
	v_fma_f32 v137, v137, v81, v113
	v_fma_f32 v138, v138, v82, v114
	v_fma_f32 v139, v139, v83, v115
	v_cvt_pk_bf16_f32 v132, v136, v137
	v_cvt_pk_bf16_f32 v133, v138, v139
	global_store_dwordx2 v130, v[132:133], s[14:15] offset:2048
	v_mul_f32_e32 v136, v143, v52
	v_mul_f32_e32 v137, v143, v53
	v_mul_f32_e32 v138, v143, v54
	v_mul_f32_e32 v139, v143, v55
	v_fma_f32 v136, v136, v84, v116
	v_fma_f32 v137, v137, v85, v117
	v_fma_f32 v138, v138, v86, v118
	v_fma_f32 v139, v139, v87, v119
	v_cvt_pk_bf16_f32 v134, v136, v137
	v_cvt_pk_bf16_f32 v135, v138, v139
	global_store_dwordx2 v130, v[134:135], s[14:15] offset:2560
	v_mul_f32_e32 v136, v143, v56
	v_mul_f32_e32 v137, v143, v57
	v_mul_f32_e32 v138, v143, v58
	v_mul_f32_e32 v139, v143, v59
	v_fma_f32 v136, v136, v88, v120
	v_fma_f32 v137, v137, v89, v121
	v_fma_f32 v138, v138, v90, v122
	v_fma_f32 v139, v139, v91, v123
	v_cvt_pk_bf16_f32 v132, v136, v137
	v_cvt_pk_bf16_f32 v133, v138, v139
	global_store_dwordx2 v130, v[132:133], s[14:15] offset:3072
	v_mul_f32_e32 v136, v143, v60
	v_mul_f32_e32 v137, v143, v61
	v_mul_f32_e32 v138, v143, v62
	v_mul_f32_e32 v139, v143, v63
	v_fma_f32 v136, v136, v92, v124
	v_fma_f32 v137, v137, v93, v125
	v_fma_f32 v138, v138, v94, v126
	v_fma_f32 v139, v139, v95, v127
	v_cvt_pk_bf16_f32 v134, v136, v137
	v_cvt_pk_bf16_f32 v135, v138, v139
	global_store_dwordx2 v130, v[134:135], s[14:15] offset:3584
	s_add_i32 s4, s6, 8
	s_add_i32 s4, s6, 8
	s_lshr_b32 s8, s4, 11
	s_cmp_lt_u32 s4, 0x4000
	s_cselect_b32 s8, s8, 8
	s_cmp_eq_u32 s8, s7
	s_cbranch_scc1 .Lp1_np8
	s_mov_b32 s7, s8
	s_add_i32 s5, s8, 0
	s_mul_i32 s5, s5, 0x6000
	s_add_u32 s24, s84, s5
	s_addc_u32 s25, s85, 0
	s_add_u32 s24, s24, 0x2000
	s_addc_u32 s25, s25, 0
	s_add_i32 s5, s8, 0
	s_mul_i32 s5, s5, 0x6000
	s_add_u32 s16, s84, s5
	s_addc_u32 s17, s85, 0
	s_add_u32 s18, s80, 0x0
	s_addc_u32 s19, s81, 0
	global_load_dwordx4 v[64:67], v128, s[18:19] offset:0
	global_load_dwordx4 v[96:99], v128, s[16:17] offset:0
	global_load_dwordx4 v[68:71], v128, s[18:19] offset:1024
	global_load_dwordx4 v[100:103], v128, s[16:17] offset:1024
	global_load_dwordx4 v[72:75], v128, s[18:19] offset:2048
	global_load_dwordx4 v[104:107], v128, s[16:17] offset:2048
	global_load_dwordx4 v[76:79], v128, s[18:19] offset:3072
	global_load_dwordx4 v[108:111], v128, s[16:17] offset:3072
	global_load_dwordx4 v[80:83], v129, s[18:19] offset:0
	global_load_dwordx4 v[112:115], v129, s[16:17] offset:0
	global_load_dwordx4 v[84:87], v129, s[18:19] offset:1024
	global_load_dwordx4 v[116:119], v129, s[16:17] offset:1024
	global_load_dwordx4 v[88:91], v129, s[18:19] offset:2048
	global_load_dwordx4 v[120:123], v129, s[16:17] offset:2048
	global_load_dwordx4 v[92:95], v129, s[18:19] offset:3072
	global_load_dwordx4 v[124:127], v129, s[16:17] offset:3072
	global_load_dwordx4 v[136:139], v128, s[24:25] offset:0
	s_waitcnt vmcnt(0)
	v_add_f32_e32 v136, 1.0, v136
	v_add_f32_e32 v137, 1.0, v137
	v_add_f32_e32 v138, 1.0, v138
	v_add_f32_e32 v139, 1.0, v139
	v_mul_f32_e32 v64, v64, v136
	v_mul_f32_e32 v65, v65, v137
	v_mul_f32_e32 v66, v66, v138
	v_mul_f32_e32 v67, v67, v139
	global_load_dwordx4 v[136:139], v128, s[24:25] offset:1024
	s_waitcnt vmcnt(0)
	v_add_f32_e32 v136, 1.0, v136
	v_add_f32_e32 v137, 1.0, v137
	v_add_f32_e32 v138, 1.0, v138
	v_add_f32_e32 v139, 1.0, v139
	v_mul_f32_e32 v68, v68, v136
	v_mul_f32_e32 v69, v69, v137
	v_mul_f32_e32 v70, v70, v138
	v_mul_f32_e32 v71, v71, v139
	global_load_dwordx4 v[136:139], v128, s[24:25] offset:2048
	s_waitcnt vmcnt(0)
	v_add_f32_e32 v136, 1.0, v136
	v_add_f32_e32 v137, 1.0, v137
	v_add_f32_e32 v138, 1.0, v138
	v_add_f32_e32 v139, 1.0, v139
	v_mul_f32_e32 v72, v72, v136
	v_mul_f32_e32 v73, v73, v137
	v_mul_f32_e32 v74, v74, v138
	v_mul_f32_e32 v75, v75, v139
	global_load_dwordx4 v[136:139], v128, s[24:25] offset:3072
	s_waitcnt vmcnt(0)
; __device__ __forceinline__ unsigned cvt_pk_bf16(float lo, float hi) { unsigned r; asm volatile("v_cvt_pk_bf16_f32 %0, %1, %2" : "=v"(r) : "v"(lo), "v"(hi)); return r; }
; __device__ __forceinline__ float sumsq8(const f32x4 (&v)[8]) {
;     float s = 0.f;
; #pragma unroll
;     for (int j = 0; j < 8; ++j) s += (v[j][0] * v[j][0] + v[j][1] * v[j][1]) + (v[j][2] * v[j][2] + v[j][3] * v[j][3]);
;     return wave_sum(s);
; }
; __device__ __forceinline__ void modulate_store(const f32x4 (&v)[8], float rstd, const float* pn, const float* modr, bf16_t* orow, int lane) {
; #pragma unroll
;     for (int j = 0; j < 8; ++j) { const int col = 4 * lane + 256 * j;
;         const f32x4 g = *(const f32x4*)(pn + col), sh = *(const f32x4*)(modr + col), sc = *(const f32x4*)(modr + DM + col);
;         const f32x4 hh = v[j] * rstd * g * (sc + 1.f) + sh;
;         u32x2 w; w.x = cvt_pk_bf16(hh[0], hh[1]); w.y = cvt_pk_bf16(hh[2], hh[3]);
;         *(u32x2*)(orow + col) = w; }
	v_add_f32_e32 v136, 1.0, v136
	v_add_f32_e32 v137, 1.0, v137
	v_add_f32_e32 v138, 1.0, v138
	v_add_f32_e32 v139, 1.0, v139
	v_mul_f32_e32 v76, v76, v136
	v_mul_f32_e32 v77, v77, v137
	v_mul_f32_e32 v78, v78, v138
	v_mul_f32_e32 v79, v79, v139
	global_load_dwordx4 v[136:139], v129, s[24:25] offset:0
	s_waitcnt vmcnt(0)
	v_add_f32_e32 v136, 1.0, v136
	v_add_f32_e32 v137, 1.0, v137
	v_add_f32_e32 v138, 1.0, v138
	v_add_f32_e32 v139, 1.0, v139
	v_mul_f32_e32 v80, v80, v136
	v_mul_f32_e32 v81, v81, v137
	v_mul_f32_e32 v82, v82, v138
	v_mul_f32_e32 v83, v83, v139
	global_load_dwordx4 v[136:139], v129, s[24:25] offset:1024
	s_waitcnt vmcnt(0)
	v_add_f32_e32 v136, 1.0, v136
	v_add_f32_e32 v137, 1.0, v137
	v_add_f32_e32 v138, 1.0, v138
	v_add_f32_e32 v139, 1.0, v139
	v_mul_f32_e32 v84, v84, v136
	v_mul_f32_e32 v85, v85, v137
	v_mul_f32_e32 v86, v86, v138
	v_mul_f32_e32 v87, v87, v139
	global_load_dwordx4 v[136:139], v129, s[24:25] offset:2048
	s_waitcnt vmcnt(0)
	v_add_f32_e32 v136, 1.0, v136
	v_add_f32_e32 v137, 1.0, v137
	v_add_f32_e32 v138, 1.0, v138
	v_add_f32_e32 v139, 1.0, v139
	v_mul_f32_e32 v88, v88, v136
	v_mul_f32_e32 v89, v89, v137
	v_mul_f32_e32 v90, v90, v138
	v_mul_f32_e32 v91, v91, v139
	global_load_dwordx4 v[136:139], v129, s[24:25] offset:3072
	s_waitcnt vmcnt(0)
	v_add_f32_e32 v136, 1.0, v136
	v_add_f32_e32 v137, 1.0, v137
	v_add_f32_e32 v138, 1.0, v138
	v_add_f32_e32 v139, 1.0, v139
	v_mul_f32_e32 v92, v92, v136
	v_mul_f32_e32 v93, v93, v137
	v_mul_f32_e32 v94, v94, v138
	v_mul_f32_e32 v95, v95, v139
.Lp1_np8:
	s_waitcnt vmcnt(8)
	v_mul_f32_e32 v140, v0, v0
	v_mul_f32_e32 v141, v1, v1
	v_fmac_f32_e32 v140, v2, v2
	v_fmac_f32_e32 v141, v3, v3
	v_fmac_f32_e32 v140, v4, v4
	v_fmac_f32_e32 v141, v5, v5
	v_fmac_f32_e32 v140, v6, v6
	v_fmac_f32_e32 v141, v7, v7
	v_fmac_f32_e32 v140, v8, v8
	v_fmac_f32_e32 v141, v9, v9
	v_fmac_f32_e32 v140, v10, v10
	v_fmac_f32_e32 v141, v11, v11
	v_fmac_f32_e32 v140, v12, v12
	v_fmac_f32_e32 v141, v13, v13
	v_fmac_f32_e32 v140, v14, v14
	v_fmac_f32_e32 v141, v15, v15
	v_fmac_f32_e32 v140, v16, v16
	v_fmac_f32_e32 v141, v17, v17
	v_fmac_f32_e32 v140, v18, v18
	v_fmac_f32_e32 v141, v19, v19
	v_fmac_f32_e32 v140, v20, v20
	v_fmac_f32_e32 v141, v21, v21
	v_fmac_f32_e32 v140, v22, v22
	v_fmac_f32_e32 v141, v23, v23
	v_fmac_f32_e32 v140, v24, v24
	v_fmac_f32_e32 v141, v25, v25
	v_fmac_f32_e32 v140, v26, v26
	v_fmac_f32_e32 v141, v27, v27
	v_fmac_f32_e32 v140, v28, v28
	v_fmac_f32_e32 v141, v29, v29
	v_fmac_f32_e32 v140, v30, v30
	v_fmac_f32_e32 v141, v31, v31
	v_add_f32_e32 v140, v140, v141
	s_nop 1
	v_add_f32_dpp v142, v140, v140 quad_perm:[1,0,3,2] row_mask:0xf bank_mask:0xf
	s_nop 1
	v_add_f32_dpp v142, v142, v142 quad_perm:[2,3,0,1] row_mask:0xf bank_mask:0xf
	s_nop 1
	v_add_f32_dpp v142, v142, v142 row_half_mirror row_mask:0xf bank_mask:0xf
	s_nop 1
	v_add_f32_dpp v142, v142, v142 row_mirror row_mask:0xf bank_mask:0xf
	s_nop 1
	v_readlane_b32 s20, v142, 0
	v_readlane_b32 s21, v142, 16
	v_readlane_b32 s22, v142, 32
	v_readlane_b32 s23, v142, 48
	s_nop 1
	v_mov_b32_e32 v143, s20
	v_add_f32_e32 v143, s21, v143
	v_add_f32_e32 v143, s22, v143
	v_add_f32_e32 v143, s23, v143
	v_fmamk_f32 v143, v143, 0x3a000000, v131
	v_rsq_f32_e32 v143, v143
	s_nop 0
	s_add_i32 s4, s6, 8
	s_lshl_b32 s5, s4, 12
	s_add_u32 s14, s84, s5
	s_addc_u32 s15, s85, 0
	s_add_u32 s14, s14, 0x4000000
	s_addc_u32 s15, s15, 0
	v_mul_f32_e32 v136, v143, v0
	v_mul_f32_e32 v137, v143, v1
	v_mul_f32_e32 v138, v143, v2
	v_mul_f32_e32 v139, v143, v3
	v_fma_f32 v136, v136, v64, v96
	v_fma_f32 v137, v137, v65, v97
	v_fma_f32 v138, v138, v66, v98
	v_fma_f32 v139, v139, v67, v99
	v_cvt_pk_bf16_f32 v132, v136, v137
	v_cvt_pk_bf16_f32 v133, v138, v139
	global_store_dwordx2 v130, v[132:133], s[14:15] offset:0
	v_mul_f32_e32 v136, v143, v4
	v_mul_f32_e32 v137, v143, v5
	v_mul_f32_e32 v138, v143, v6
	v_mul_f32_e32 v139, v143, v7
	v_fma_f32 v136, v136, v68, v100
	v_fma_f32 v137, v137, v69, v101
	v_fma_f32 v138, v138, v70, v102
	v_fma_f32 v139, v139, v71, v103
	v_cvt_pk_bf16_f32 v134, v136, v137
	v_cvt_pk_bf16_f32 v135, v138, v139
	global_store_dwordx2 v130, v[134:135], s[14:15] offset:512
	v_mul_f32_e32 v136, v143, v8
	v_mul_f32_e32 v137, v143, v9
	v_mul_f32_e32 v138, v143, v10
	v_mul_f32_e32 v139, v143, v11
	v_fma_f32 v136, v136, v72, v104
	v_fma_f32 v137, v137, v73, v105
	v_fma_f32 v138, v138, v74, v106
	v_fma_f32 v139, v139, v75, v107
	v_cvt_pk_bf16_f32 v132, v136, v137
	v_cvt_pk_bf16_f32 v133, v138, v139
	global_store_dwordx2 v130, v[132:133], s[14:15] offset:1024
	v_mul_f32_e32 v136, v143, v12
	v_mul_f32_e32 v137, v143, v13
	v_mul_f32_e32 v138, v143, v14
	v_mul_f32_e32 v139, v143, v15
	v_fma_f32 v136, v136, v76, v108
	v_fma_f32 v137, v137, v77, v109
	v_fma_f32 v138, v138, v78, v110
	v_fma_f32 v139, v139, v79, v111
	v_cvt_pk_bf16_f32 v134, v136, v137
	v_cvt_pk_bf16_f32 v135, v138, v139
	global_store_dwordx2 v130, v[134:135], s[14:15] offset:1536
	v_mul_f32_e32 v136, v143, v16
	v_mul_f32_e32 v137, v143, v17
	v_mul_f32_e32 v138, v143, v18
	v_mul_f32_e32 v139, v143, v19
	v_fma_f32 v136, v136, v80, v112
	v_fma_f32 v137, v137, v81, v113
	v_fma_f32 v138, v138, v82, v114
	v_fma_f32 v139, v139, v83, v115
	v_cvt_pk_bf16_f32 v132, v136, v137
	v_cvt_pk_bf16_f32 v133, v138, v139
	global_store_dwordx2 v130, v[132:133], s[14:15] offset:2048
	v_mul_f32_e32 v136, v143, v20
	v_mul_f32_e32 v137, v143, v21
	v_mul_f32_e32 v138, v143, v22
	v_mul_f32_e32 v139, v143, v23
	v_fma_f32 v136, v136, v84, v116
	v_fma_f32 v137, v137, v85, v117
	v_fma_f32 v138, v138, v86, v118
	v_fma_f32 v139, v139, v87, v119
	v_cvt_pk_bf16_f32 v134, v136, v137
	v_cvt_pk_bf16_f32 v135, v138, v139
	global_store_dwordx2 v130, v[134:135], s[14:15] offset:2560
	v_mul_f32_e32 v136, v143, v24
	v_mul_f32_e32 v137, v143, v25
	v_mul_f32_e32 v138, v143, v26
	v_mul_f32_e32 v139, v143, v27
	v_fma_f32 v136, v136, v88, v120
	v_fma_f32 v137, v137, v89, v121
	v_fma_f32 v138, v138, v90, v122
	v_fma_f32 v139, v139, v91, v123
	v_cvt_pk_bf16_f32 v132, v136, v137
	v_cvt_pk_bf16_f32 v133, v138, v139
	global_store_dwordx2 v130, v[132:133], s[14:15] offset:3072
	v_mul_f32_e32 v136, v143, v28
	v_mul_f32_e32 v137, v143, v29
	v_mul_f32_e32 v138, v143, v30
	v_mul_f32_e32 v139, v143, v31
	v_fma_f32 v136, v136, v92, v124
	v_fma_f32 v137, v137, v93, v125
	v_fma_f32 v138, v138, v94, v126
	v_fma_f32 v139, v139, v95, v127
	v_cvt_pk_bf16_f32 v134, v136, v137
	v_cvt_pk_bf16_f32 v135, v138, v139
	global_store_dwordx2 v130, v[134:135], s[14:15] offset:3584
	s_branch .LBB0_194
; #define FRESH() int gtid; do { int t_ = threadIdx.x; asm volatile("" : "+v"(t_)); F.tid = t_; F.lane = t_ & 63; gtid = blockIdx.x * (NWAVES * 64) + t_; (void)gtid; } while (0)
; __device__ __forceinline__ float wave_sum(float v) {
; #pragma unroll
;     for (int o = 1; o < 64; o <<= 1) v += __shfl_xor(v, o);
;     return v;
; }
; __global__ void __launch_bounds__(NWAVES * 64, 2) mk_fwd(Args args) {
;     ...
;     if (IN(1)) { FRESH();
;         for (int row0 = F.gw * 3; row0 < MT; row0 += F.NGW * 3) {
;             f32x4 v[3][8];
; #pragma unroll
;             for (int q = 0; q < 3; ++q) { const int row = row0 + q; const float* src = row < ML ? x + (size_t)row * DM : ctx + (size_t)(row - ML) * DM; load_row_f32(src, F.lane, v[q]); }
; #pragma unroll
;             for (int q = 0; q < 3; ++q) { const int row = row0 + q; const int r = row < ML ? row / SEQ : 8;
;                 const float rstd = __builtin_amdgcn_rsqf(sumsq8(v[q]) * (1.f / DM) + EPS);
;                 modulate_store(v[q], rstd, pre_norm, mod + (size_t)r * 6144, H + (size_t)row * DM, F.lane); }
;         }
.Lp1_generic:
	v_mov_b32_e32 v0, v198
	s_cmpk_gt_i32 s33, 0x17ff
	s_cbranch_scc1 .LBB0_194
	v_lshlrev_b32_e32 v1, 2, v0
	v_and_b32_e32 v2, 0xfc, v1
	v_mbcnt_lo_u32_b32 v1, -1, 0
	v_mbcnt_hi_u32_b32 v1, -1, v1
	v_and_b32_e32 v3, 64, v1
	v_add_u32_e32 v3, 64, v3
	v_xor_b32_e32 v4, 1, v1
	v_cmp_lt_i32_e32 vcc, v4, v3
	v_mov_b32_e32 v97, 0
	v_lshlrev_b32_e32 v96, 2, v2
	v_cndmask_b32_e32 v4, v1, v4, vcc
	v_lshlrev_b32_e32 v112, 2, v4
	v_xor_b32_e32 v4, 2, v1
	v_cmp_lt_i32_e32 vcc, v4, v3
	v_or_b32_e32 v10, 0x400, v2
	v_lshl_add_u64 v[98:99], s[80:81], 0, v[96:97]
	v_cndmask_b32_e32 v4, v1, v4, vcc
	v_lshlrev_b32_e32 v113, 2, v4
	v_xor_b32_e32 v4, 4, v1
	v_cmp_lt_i32_e32 vcc, v4, v3
	v_lshlrev_b32_e32 v96, 2, v10
	v_or_b32_e32 v12, 0x500, v2
	v_cndmask_b32_e32 v4, v1, v4, vcc
	v_lshlrev_b32_e32 v114, 2, v4
	v_xor_b32_e32 v4, 8, v1
	v_cmp_lt_i32_e32 vcc, v4, v3
	s_mul_i32 s4, s33, 3
	v_lshl_add_u64 v[100:101], s[80:81], 0, v[96:97]
	v_cndmask_b32_e32 v4, v1, v4, vcc
	v_lshlrev_b32_e32 v115, 2, v4
	v_xor_b32_e32 v4, 16, v1
	v_cmp_lt_i32_e32 vcc, v4, v3
	v_lshlrev_b32_e32 v96, 2, v12
	v_or_b32_e32 v14, 0x600, v2
	v_cndmask_b32_e32 v4, v1, v4, vcc
	v_lshl_add_u64 v[102:103], s[80:81], 0, v[96:97]
	v_lshlrev_b32_e32 v96, 2, v14
	v_or_b32_e32 v16, 0x700, v2
	s_ashr_i32 s5, s4, 31
	v_lshlrev_b32_e32 v116, 2, v4
	v_xor_b32_e32 v4, 32, v1
	v_lshl_add_u64 v[104:105], s[80:81], 0, v[96:97]
	v_lshlrev_b32_e32 v96, 2, v16
	s_lshl_b64 s[8:9], s[4:5], 12
	v_cmp_lt_i32_e32 vcc, v4, v3
	v_lshl_add_u64 v[106:107], s[80:81], 0, v[96:97]
	v_lshlrev_b32_e32 v96, 1, v2
	v_and_b32_e32 v0, 63, v0
	s_add_u32 s8, s84, s8
	v_cndmask_b32_e32 v1, v1, v4, vcc
	s_mul_i32 s6, s63, 24
	v_lshl_add_u64 v[108:109], s[12:13], 0, v[96:97]
	v_lshlrev_b32_e32 v96, 3, v0
	s_addc_u32 s9, s85, s9
	v_lshlrev_b32_e32 v117, 2, v1
	v_or_b32_e32 v4, 0x100, v2
	v_or_b32_e32 v6, 0x200, v2
	v_or_b32_e32 v8, 0x300, v2
	v_lshl_add_u64 v[0:1], s[8:9], 0, v[96:97]
	s_mov_b64 s[8:9], 0x4000000
	s_ashr_i32 s7, s6, 31
	v_lshl_add_u64 v[110:111], v[0:1], 0, s[8:9]
	s_lshl_b64 s[8:9], s[6:7], 12
	v_lshlrev_b32_e32 v96, 2, v2
	s_movk_i32 s26, 0x1000
	v_mov_b32_e32 v118, 0x358637bd
	v_lshlrev_b32_e32 v119, 2, v4
	v_lshlrev_b32_e32 v120, 2, v6
	v_lshlrev_b32_e32 v121, 2, v8
	v_lshlrev_b32_e32 v122, 2, v10
	v_lshlrev_b32_e32 v123, 2, v12
	v_lshlrev_b32_e32 v124, 2, v14
	v_lshlrev_b32_e32 v125, 2, v16
	s_branch .LBB0_188

; __device__ __forceinline__ float bf_lo(unsigned w) { return __uint_as_float(w << 16); }
; __device__ __forceinline__ float bf_hi(unsigned w) { return __uint_as_float(w & 0xffff0000u); }
; #define FRESH() int gtid; do { int t_ = threadIdx.x; asm volatile("" : "+v"(t_)); F.tid = t_; F.lane = t_ & 63; gtid = blockIdx.x * (NWAVES * 64) + t_; (void)gtid; } while (0)
; __global__ void __launch_bounds__(NWAVES * 64, 2) mk_fwd(Args args) {
;     ...
;     if (IN(6)) { FRESH();
;         for (int row0 = F.gw * 3; row0 < MT; row0 += F.NGW * 3) {
;             f32x4 v[3][8]; u32x2 yw[3][8];
; #pragma unroll
;             for (int q = 0; q < 3; ++q) { const int row = row0 + q; const float* src = row < ML ? x + (size_t)row * DM : ctx + (size_t)(row - ML) * DM; load_row_f32(src, F.lane, v[q]);
;                 const bf16_t* yr = Y + (size_t)row * DM;
; #pragma unroll
;                 for (int j = 0; j < 8; ++j) yw[q][j] = *(const u32x2*)(yr + 4 * F.lane + 256 * j); }
; #pragma unroll
;             for (int q = 0; q < 3; ++q) { const int row = row0 + q; const bool lat = row < ML; const int r = lat ? row / SEQ : 8;
;                 float sy = 0.f;
; #pragma unroll
;                 for (int j = 0; j < 8; ++j) { const float a = bf_lo(yw[q][j].x), b = bf_hi(yw[q][j].x), c2 = bf_lo(yw[q][j].y), d = bf_hi(yw[q][j].y); sy += (a * a + b * b) + (c2 * c2 + d * d); }
;                 const float rsy = __builtin_amdgcn_rsqf(wave_sum(sy) * (1.f / DM) + EPS);
;                 const float* m0 = mod + (size_t)r * 6144;
; #pragma unroll
;                 for (int j = 0; j < 8; ++j) { const int col = 4 * F.lane + 256 * j; const f32x4 gt = *(const f32x4*)(m0 + 2 * DM + col), pn = *(const f32x4*)(post_norm + col);
.LBB0_716:
	s_cmp_lt_i32 s86, 7
	s_cselect_b64 s[4:5], -1, 0
	s_and_b64 s[0:1], s[4:5], s[0:1]
	s_andn2_b64 vcc, exec, s[0:1]
	s_cbranch_vccnz .LBB0_778
	s_cmpk_lg_i32 s63, 0x100
	s_cbranch_scc1 .Lp6_generic
	v_and_b32_e32 v194, 63, v198
	v_lshlrev_b32_e32 v192, 4, v194
	v_add_u32_e32 v193, 0x1000, v192
	v_lshlrev_b32_e32 v194, 3, v194
	v_mov_b32_e32 v195, 0x358637bd
	s_mul_i32 s6, s33, 9
	s_mov_b32 s7, -1
	s_add_i32 s0, s6, 0
	s_cmp_lt_u32 s0, 0x4000
	s_cselect_b32 s10, s68, s72
	s_cselect_b32 s11, s69, s73
	s_cselect_b32 s1, 0, 0x4000
	s_sub_i32 s1, s0, s1
	s_lshl_b32 s1, s1, 13
	s_add_u32 s10, s10, s1
	s_addc_u32 s11, s11, 0
	s_add_i32 s0, s6, 0
	s_lshl_b32 s1, s0, 12
	s_add_u32 s22, s84, s1
	s_addc_u32 s23, s85, 0
	s_add_u32 s22, s22, 0x11800000
	s_addc_u32 s23, s23, 0
	global_load_dwordx4 v[0:3], v192, s[10:11] offset:0
	global_load_dwordx4 v[4:7], v192, s[10:11] offset:1024
	global_load_dwordx4 v[8:11], v192, s[10:11] offset:2048
	global_load_dwordx4 v[12:15], v192, s[10:11] offset:3072
	global_load_dwordx4 v[16:19], v193, s[10:11] offset:0
	global_load_dwordx4 v[20:23], v193, s[10:11] offset:1024
	global_load_dwordx4 v[24:27], v193, s[10:11] offset:2048
	global_load_dwordx4 v[28:31], v193, s[10:11] offset:3072
	global_load_dwordx2 v[32:33], v194, s[22:23] offset:0
	global_load_dwordx2 v[34:35], v194, s[22:23] offset:512
	global_load_dwordx2 v[36:37], v194, s[22:23] offset:1024
	global_load_dwordx2 v[38:39], v194, s[22:23] offset:1536
	global_load_dwordx2 v[40:41], v194, s[22:23] offset:2048
	global_load_dwordx2 v[42:43], v194, s[22:23] offset:2560
	global_load_dwordx2 v[44:45], v194, s[22:23] offset:3072
	global_load_dwordx2 v[46:47], v194, s[22:23] offset:3584
	s_add_i32 s0, s6, 1
	s_cmp_lt_u32 s0, 0x4000
	s_cselect_b32 s10, s68, s72
	s_cselect_b32 s11, s69, s73
	s_cselect_b32 s1, 0, 0x4000
	s_sub_i32 s1, s0, s1
	s_lshl_b32 s1, s1, 13
	s_add_u32 s10, s10, s1
	s_addc_u32 s11, s11, 0
	s_add_i32 s0, s6, 1
	s_lshl_b32 s1, s0, 12
	s_add_u32 s22, s84, s1
	s_addc_u32 s23, s85, 0
	s_add_u32 s22, s22, 0x11800000
	s_addc_u32 s23, s23, 0
	global_load_dwordx4 v[48:51], v192, s[10:11] offset:0
	global_load_dwordx4 v[52:55], v192, s[10:11] offset:1024
	global_load_dwordx4 v[56:59], v192, s[10:11] offset:2048
	global_load_dwordx4 v[60:63], v192, s[10:11] offset:3072
	global_load_dwordx4 v[64:67], v193, s[10:11] offset:0
	global_load_dwordx4 v[68:71], v193, s[10:11] offset:1024
	global_load_dwordx4 v[72:75], v193, s[10:11] offset:2048
	global_load_dwordx4 v[76:79], v193, s[10:11] offset:3072
	global_load_dwordx2 v[80:81], v194, s[22:23] offset:0
	global_load_dwordx2 v[82:83], v194, s[22:23] offset:512
	global_load_dwordx2 v[84:85], v194, s[22:23] offset:1024
	global_load_dwordx2 v[86:87], v194, s[22:23] offset:1536
	global_load_dwordx2 v[88:89], v194, s[22:23] offset:2048
	global_load_dwordx2 v[90:91], v194, s[22:23] offset:2560
	global_load_dwordx2 v[92:93], v194, s[22:23] offset:3072
	global_load_dwordx2 v[94:95], v194, s[22:23] offset:3584
	s_add_i32 s0, s6, 0
	s_add_i32 s0, s6, 0
	s_lshr_b32 s8, s0, 11
	s_cmp_lt_u32 s0, 0x4000
	s_cselect_b32 s8, s8, 8
	s_cmp_eq_u32 s8, s7
	s_cbranch_scc1 .Lp6_np0
	s_mov_b32 s7, s8
	s_add_i32 s1, s8, 9
	s_mul_i32 s1, s1, 0x6000
	s_add_u32 s44, s84, s1
	s_addc_u32 s45, s85, 0
	s_add_u32 s44, s44, 0x2000
	s_addc_u32 s45, s45, 0
	s_add_i32 s1, s8, 9
	s_mul_i32 s1, s1, 0x6000
	s_add_u32 s36, s84, s1
	s_addc_u32 s37, s85, 0
	s_add_u32 s38, s80, 0x2000
	s_addc_u32 s39, s81, 0
	s_mul_i32 s1, s8, 0x6000
	s_add_u32 s34, s84, s1
	s_addc_u32 s35, s85, 0
	s_add_u32 s34, s34, 0x4000
	s_addc_u32 s35, s35, 0
	global_load_dwordx4 v[96:99], v192, s[34:35] offset:0
	global_load_dwordx4 v[200:203], v192, s[82:83] offset:0
	global_load_dwordx4 v[100:103], v192, s[34:35] offset:1024
	global_load_dwordx4 v[204:207], v192, s[82:83] offset:1024
	global_load_dwordx4 v[104:107], v192, s[34:35] offset:2048
	global_load_dwordx4 v[208:211], v192, s[82:83] offset:2048
	global_load_dwordx4 v[108:111], v192, s[34:35] offset:3072
	global_load_dwordx4 v[212:215], v192, s[82:83] offset:3072
	s_waitcnt vmcnt(0)
	v_mul_f32_e32 v96, v96, v200
	v_mul_f32_e32 v97, v97, v201
	v_mul_f32_e32 v98, v98, v202
	v_mul_f32_e32 v99, v99, v203
	v_mul_f32_e32 v100, v100, v204
	v_mul_f32_e32 v101, v101, v205
	v_mul_f32_e32 v102, v102, v206
	v_mul_f32_e32 v103, v103, v207
	v_mul_f32_e32 v104, v104, v208
	v_mul_f32_e32 v105, v105, v209
	v_mul_f32_e32 v106, v106, v210
	v_mul_f32_e32 v107, v107, v211
	v_mul_f32_e32 v108, v108, v212
	v_mul_f32_e32 v109, v109, v213
	v_mul_f32_e32 v110, v110, v214
	v_mul_f32_e32 v111, v111, v215
	global_load_dwordx4 v[128:131], v192, s[38:39] offset:0
	global_load_dwordx4 v[200:203], v192, s[44:45] offset:0
	global_load_dwordx4 v[160:163], v192, s[36:37] offset:0
	global_load_dwordx4 v[132:135], v192, s[38:39] offset:1024
	global_load_dwordx4 v[204:207], v192, s[44:45] offset:1024
	global_load_dwordx4 v[164:167], v192, s[36:37] offset:1024
	global_load_dwordx4 v[136:139], v192, s[38:39] offset:2048
	global_load_dwordx4 v[208:211], v192, s[44:45] offset:2048
	global_load_dwordx4 v[168:171], v192, s[36:37] offset:2048
	global_load_dwordx4 v[140:143], v192, s[38:39] offset:3072
	global_load_dwordx4 v[212:215], v192, s[44:45] offset:3072
	global_load_dwordx4 v[172:175], v192, s[36:37] offset:3072
	s_waitcnt vmcnt(0)
; __device__ __forceinline__ float bf_lo(unsigned w) { return __uint_as_float(w << 16); }
; __device__ __forceinline__ float bf_hi(unsigned w) { return __uint_as_float(w & 0xffff0000u); }
; __device__ __forceinline__ void modulate_store(const f32x4 (&v)[8], float rstd, const float* pn, const float* modr, bf16_t* orow, int lane) {
;     ...
;         const f32x4 g = *(const f32x4*)(pn + col), sh = *(const f32x4*)(modr + col), sc = *(const f32x4*)(modr + DM + col);
;         const f32x4 hh = v[j] * rstd * g * (sc + 1.f) + sh;
; __global__ void __launch_bounds__(NWAVES * 64, 2) mk_fwd(Args args) {
;     ...
;                 for (int j = 0; j < 8; ++j) { const float a = bf_lo(yw[q][j].x), b = bf_hi(yw[q][j].x), c2 = bf_lo(yw[q][j].y), d = bf_hi(yw[q][j].y); sy += (a * a + b * b) + (c2 * c2 + d * d); }
;                 const float rsy = __builtin_amdgcn_rsqf(wave_sum(sy) * (1.f / DM) + EPS);
;                 const float* m0 = mod + (size_t)r * 6144;
; #pragma unroll
;                 for (int j = 0; j < 8; ++j) { const int col = 4 * F.lane + 256 * j; const f32x4 gt = *(const f32x4*)(m0 + 2 * DM + col), pn = *(const f32x4*)(post_norm + col);
;                     const f32x4 y4 = (f32x4){bf_lo(yw[q][j].x), bf_hi(yw[q][j].x), bf_lo(yw[q][j].y), bf_hi(yw[q][j].y)};
;                     v[q][j] = v[q][j] + gt * (y4 * rsy * pn);
	v_add_f32_e32 v200, 1.0, v200
	v_add_f32_e32 v201, 1.0, v201
	v_add_f32_e32 v202, 1.0, v202
	v_add_f32_e32 v203, 1.0, v203
	v_mul_f32_e32 v128, v128, v200
	v_mul_f32_e32 v129, v129, v201
	v_mul_f32_e32 v130, v130, v202
	v_mul_f32_e32 v131, v131, v203
	v_add_f32_e32 v204, 1.0, v204
	v_add_f32_e32 v205, 1.0, v205
	v_add_f32_e32 v206, 1.0, v206
	v_add_f32_e32 v207, 1.0, v207
	v_mul_f32_e32 v132, v132, v204
	v_mul_f32_e32 v133, v133, v205
	v_mul_f32_e32 v134, v134, v206
	v_mul_f32_e32 v135, v135, v207
	v_add_f32_e32 v208, 1.0, v208
	v_add_f32_e32 v209, 1.0, v209
	v_add_f32_e32 v210, 1.0, v210
	v_add_f32_e32 v211, 1.0, v211
	v_mul_f32_e32 v136, v136, v208
	v_mul_f32_e32 v137, v137, v209
	v_mul_f32_e32 v138, v138, v210
	v_mul_f32_e32 v139, v139, v211
	v_add_f32_e32 v212, 1.0, v212
	v_add_f32_e32 v213, 1.0, v213
	v_add_f32_e32 v214, 1.0, v214
	v_add_f32_e32 v215, 1.0, v215
	v_mul_f32_e32 v140, v140, v212
	v_mul_f32_e32 v141, v141, v213
	v_mul_f32_e32 v142, v142, v214
	v_mul_f32_e32 v143, v143, v215
	global_load_dwordx4 v[112:115], v193, s[34:35] offset:0
	global_load_dwordx4 v[200:203], v193, s[82:83] offset:0
	global_load_dwordx4 v[116:119], v193, s[34:35] offset:1024
	global_load_dwordx4 v[204:207], v193, s[82:83] offset:1024
	global_load_dwordx4 v[120:123], v193, s[34:35] offset:2048
	global_load_dwordx4 v[208:211], v193, s[82:83] offset:2048
	global_load_dwordx4 v[124:127], v193, s[34:35] offset:3072
	global_load_dwordx4 v[212:215], v193, s[82:83] offset:3072
	s_waitcnt vmcnt(0)
	v_mul_f32_e32 v112, v112, v200
	v_mul_f32_e32 v113, v113, v201
	v_mul_f32_e32 v114, v114, v202
	v_mul_f32_e32 v115, v115, v203
	v_mul_f32_e32 v116, v116, v204
	v_mul_f32_e32 v117, v117, v205
	v_mul_f32_e32 v118, v118, v206
	v_mul_f32_e32 v119, v119, v207
	v_mul_f32_e32 v120, v120, v208
	v_mul_f32_e32 v121, v121, v209
	v_mul_f32_e32 v122, v122, v210
	v_mul_f32_e32 v123, v123, v211
	v_mul_f32_e32 v124, v124, v212
	v_mul_f32_e32 v125, v125, v213
	v_mul_f32_e32 v126, v126, v214
	v_mul_f32_e32 v127, v127, v215
	global_load_dwordx4 v[144:147], v193, s[38:39] offset:0
	global_load_dwordx4 v[200:203], v193, s[44:45] offset:0
	global_load_dwordx4 v[176:179], v193, s[36:37] offset:0
	global_load_dwordx4 v[148:151], v193, s[38:39] offset:1024
	global_load_dwordx4 v[204:207], v193, s[44:45] offset:1024
	global_load_dwordx4 v[180:183], v193, s[36:37] offset:1024
	global_load_dwordx4 v[152:155], v193, s[38:39] offset:2048
	global_load_dwordx4 v[208:211], v193, s[44:45] offset:2048
	global_load_dwordx4 v[184:187], v193, s[36:37] offset:2048
	global_load_dwordx4 v[156:159], v193, s[38:39] offset:3072
	global_load_dwordx4 v[212:215], v193, s[44:45] offset:3072
	global_load_dwordx4 v[188:191], v193, s[36:37] offset:3072
	s_waitcnt vmcnt(0)
	v_add_f32_e32 v200, 1.0, v200
	v_add_f32_e32 v201, 1.0, v201
	v_add_f32_e32 v202, 1.0, v202
	v_add_f32_e32 v203, 1.0, v203
	v_mul_f32_e32 v144, v144, v200
	v_mul_f32_e32 v145, v145, v201
	v_mul_f32_e32 v146, v146, v202
	v_mul_f32_e32 v147, v147, v203
	v_add_f32_e32 v204, 1.0, v204
	v_add_f32_e32 v205, 1.0, v205
	v_add_f32_e32 v206, 1.0, v206
	v_add_f32_e32 v207, 1.0, v207
	v_mul_f32_e32 v148, v148, v204
	v_mul_f32_e32 v149, v149, v205
	v_mul_f32_e32 v150, v150, v206
	v_mul_f32_e32 v151, v151, v207
	v_add_f32_e32 v208, 1.0, v208
	v_add_f32_e32 v209, 1.0, v209
	v_add_f32_e32 v210, 1.0, v210
	v_add_f32_e32 v211, 1.0, v211
	v_mul_f32_e32 v152, v152, v208
	v_mul_f32_e32 v153, v153, v209
	v_mul_f32_e32 v154, v154, v210
	v_mul_f32_e32 v155, v155, v211
	v_add_f32_e32 v212, 1.0, v212
	v_add_f32_e32 v213, 1.0, v213
	v_add_f32_e32 v214, 1.0, v214
	v_add_f32_e32 v215, 1.0, v215
	v_mul_f32_e32 v156, v156, v212
	v_mul_f32_e32 v157, v157, v213
	v_mul_f32_e32 v158, v158, v214
	v_mul_f32_e32 v159, v159, v215
.Lp6_np0:
	s_waitcnt vmcnt(16)
	v_lshlrev_b32_e32 v216, 16, v32
	v_and_b32_e32 v217, 0xffff0000, v32
	v_lshlrev_b32_e32 v218, 16, v33
	v_and_b32_e32 v219, 0xffff0000, v33
	v_mul_f32_e32 v222, v216, v216
	v_mul_f32_e32 v223, v217, v217
	v_fmac_f32_e32 v222, v218, v218
	v_fmac_f32_e32 v223, v219, v219
	v_lshlrev_b32_e32 v216, 16, v34
	v_and_b32_e32 v217, 0xffff0000, v34
	v_lshlrev_b32_e32 v218, 16, v35
	v_and_b32_e32 v219, 0xffff0000, v35
	v_fmac_f32_e32 v222, v216, v216
	v_fmac_f32_e32 v223, v217, v217
	v_fmac_f32_e32 v222, v218, v218
	v_fmac_f32_e32 v223, v219, v219
	v_lshlrev_b32_e32 v216, 16, v36
	v_and_b32_e32 v217, 0xffff0000, v36
	v_lshlrev_b32_e32 v218, 16, v37
	v_and_b32_e32 v219, 0xffff0000, v37
	v_fmac_f32_e32 v222, v216, v216
	v_fmac_f32_e32 v223, v217, v217
	v_fmac_f32_e32 v222, v218, v218
	v_fmac_f32_e32 v223, v219, v219
	v_lshlrev_b32_e32 v216, 16, v38
	v_and_b32_e32 v217, 0xffff0000, v38
	v_lshlrev_b32_e32 v218, 16, v39
	v_and_b32_e32 v219, 0xffff0000, v39
	v_fmac_f32_e32 v222, v216, v216
	v_fmac_f32_e32 v223, v217, v217
	v_fmac_f32_e32 v222, v218, v218
	v_fmac_f32_e32 v223, v219, v219
	v_lshlrev_b32_e32 v216, 16, v40
	v_and_b32_e32 v217, 0xffff0000, v40
	v_lshlrev_b32_e32 v218, 16, v41
	v_and_b32_e32 v219, 0xffff0000, v41
	v_fmac_f32_e32 v222, v216, v216
	v_fmac_f32_e32 v223, v217, v217
	v_fmac_f32_e32 v222, v218, v218
	v_fmac_f32_e32 v223, v219, v219
	v_lshlrev_b32_e32 v216, 16, v42
	v_and_b32_e32 v217, 0xffff0000, v42
	v_lshlrev_b32_e32 v218, 16, v43
	v_and_b32_e32 v219, 0xffff0000, v43
	v_fmac_f32_e32 v222, v216, v216
	v_fmac_f32_e32 v223, v217, v217
	v_fmac_f32_e32 v222, v218, v218
	v_fmac_f32_e32 v223, v219, v219
	v_lshlrev_b32_e32 v216, 16, v44
	v_and_b32_e32 v217, 0xffff0000, v44
	v_lshlrev_b32_e32 v218, 16, v45
	v_and_b32_e32 v219, 0xffff0000, v45
	v_fmac_f32_e32 v222, v216, v216
	v_fmac_f32_e32 v223, v217, v217
	v_fmac_f32_e32 v222, v218, v218
; __device__ __forceinline__ float bf_lo(unsigned w) { return __uint_as_float(w << 16); }
; __device__ __forceinline__ float bf_hi(unsigned w) { return __uint_as_float(w & 0xffff0000u); }
; __global__ void __launch_bounds__(NWAVES * 64, 2) mk_fwd(Args args) {
;     ...
;                 for (int j = 0; j < 8; ++j) { const float a = bf_lo(yw[q][j].x), b = bf_hi(yw[q][j].x), c2 = bf_lo(yw[q][j].y), d = bf_hi(yw[q][j].y); sy += (a * a + b * b) + (c2 * c2 + d * d); }
;                 const float rsy = __builtin_amdgcn_rsqf(wave_sum(sy) * (1.f / DM) + EPS);
;                 const float* m0 = mod + (size_t)r * 6144;
; #pragma unroll
;                 for (int j = 0; j < 8; ++j) { const int col = 4 * F.lane + 256 * j; const f32x4 gt = *(const f32x4*)(m0 + 2 * DM + col), pn = *(const f32x4*)(post_norm + col);
;                     const f32x4 y4 = (f32x4){bf_lo(yw[q][j].x), bf_hi(yw[q][j].x), bf_lo(yw[q][j].y), bf_hi(yw[q][j].y)};
;                     v[q][j] = v[q][j] + gt * (y4 * rsy * pn);
;                     if (lat) *(f32x4*)(args.out + (size_t)row * DM + col) = v[q][j]; }
;                 const float rstd = __builtin_amdgcn_rsqf(sumsq8(v[q]) * (1.f / DM) + EPS);
	v_fmac_f32_e32 v223, v219, v219
	v_lshlrev_b32_e32 v216, 16, v46
	v_and_b32_e32 v217, 0xffff0000, v46
	v_lshlrev_b32_e32 v218, 16, v47
	v_and_b32_e32 v219, 0xffff0000, v47
	v_fmac_f32_e32 v222, v216, v216
	v_fmac_f32_e32 v223, v217, v217
	v_fmac_f32_e32 v222, v218, v218
	v_fmac_f32_e32 v223, v219, v219
	v_add_f32_e32 v222, v222, v223
	s_nop 1
	v_add_f32_dpp v224, v222, v222 quad_perm:[1,0,3,2] row_mask:0xf bank_mask:0xf
	s_nop 1
	v_add_f32_dpp v224, v224, v224 quad_perm:[2,3,0,1] row_mask:0xf bank_mask:0xf
	s_nop 1
	v_add_f32_dpp v224, v224, v224 row_half_mirror row_mask:0xf bank_mask:0xf
	s_nop 1
	v_add_f32_dpp v224, v224, v224 row_mirror row_mask:0xf bank_mask:0xf
	s_nop 1
	v_readlane_b32 s40, v224, 0
	v_readlane_b32 s41, v224, 16
	v_readlane_b32 s42, v224, 32
	v_readlane_b32 s43, v224, 48
	s_nop 1
	v_mov_b32_e32 v225, s40
	v_add_f32_e32 v225, s41, v225
	v_add_f32_e32 v225, s42, v225
	v_add_f32_e32 v225, s43, v225
	v_fmamk_f32 v225, v225, 0x3a000000, v195
	v_rsq_f32_e32 v225, v225
	s_nop 0
	s_add_i32 s0, s6, 0
	s_cmp_lt_u32 s0, 0x4000
	s_cselect_b32 s24, s94, s84
	s_cselect_b32 s25, s95, s85
	s_cselect_b32 s44, 0, 0x16000000
	s_cselect_b32 s1, 0, 0x4000
	s_sub_i32 s1, s0, s1
	s_lshl_b32 s1, s1, 13
	s_add_u32 s24, s24, s1
	s_addc_u32 s25, s25, 0
	s_add_u32 s24, s24, s44
	s_addc_u32 s25, s25, 0
	v_lshlrev_b32_e32 v216, 16, v32
	v_and_b32_e32 v217, 0xffff0000, v32
	v_lshlrev_b32_e32 v218, 16, v33
	v_and_b32_e32 v219, 0xffff0000, v33
	v_mul_f32_e32 v216, v225, v216
	v_mul_f32_e32 v217, v225, v217
	v_mul_f32_e32 v218, v225, v218
	v_mul_f32_e32 v219, v225, v219
	v_fmac_f32_e32 v0, v96, v216
	v_fmac_f32_e32 v1, v97, v217
	v_fmac_f32_e32 v2, v98, v218
	v_fmac_f32_e32 v3, v99, v219
	global_store_dwordx4 v192, v[0:3], s[24:25] offset:0
	v_lshlrev_b32_e32 v216, 16, v34
	v_and_b32_e32 v217, 0xffff0000, v34
	v_lshlrev_b32_e32 v218, 16, v35
	v_and_b32_e32 v219, 0xffff0000, v35
	v_mul_f32_e32 v216, v225, v216
	v_mul_f32_e32 v217, v225, v217
	v_mul_f32_e32 v218, v225, v218
	v_mul_f32_e32 v219, v225, v219
	v_fmac_f32_e32 v4, v100, v216
	v_fmac_f32_e32 v5, v101, v217
	v_fmac_f32_e32 v6, v102, v218
	v_fmac_f32_e32 v7, v103, v219
	global_store_dwordx4 v192, v[4:7], s[24:25] offset:1024
	v_lshlrev_b32_e32 v216, 16, v36
	v_and_b32_e32 v217, 0xffff0000, v36
	v_lshlrev_b32_e32 v218, 16, v37
	v_and_b32_e32 v219, 0xffff0000, v37
	v_mul_f32_e32 v216, v225, v216
	v_mul_f32_e32 v217, v225, v217
	v_mul_f32_e32 v218, v225, v218
	v_mul_f32_e32 v219, v225, v219
	v_fmac_f32_e32 v8, v104, v216
	v_fmac_f32_e32 v9, v105, v217
	v_fmac_f32_e32 v10, v106, v218
	v_fmac_f32_e32 v11, v107, v219
	global_store_dwordx4 v192, v[8:11], s[24:25] offset:2048
	v_lshlrev_b32_e32 v216, 16, v38
	v_and_b32_e32 v217, 0xffff0000, v38
	v_lshlrev_b32_e32 v218, 16, v39
	v_and_b32_e32 v219, 0xffff0000, v39
	v_mul_f32_e32 v216, v225, v216
	v_mul_f32_e32 v217, v225, v217
	v_mul_f32_e32 v218, v225, v218
	v_mul_f32_e32 v219, v225, v219
	v_fmac_f32_e32 v12, v108, v216
	v_fmac_f32_e32 v13, v109, v217
	v_fmac_f32_e32 v14, v110, v218
	v_fmac_f32_e32 v15, v111, v219
	global_store_dwordx4 v192, v[12:15], s[24:25] offset:3072
	v_lshlrev_b32_e32 v216, 16, v40
	v_and_b32_e32 v217, 0xffff0000, v40
	v_lshlrev_b32_e32 v218, 16, v41
	v_and_b32_e32 v219, 0xffff0000, v41
	v_mul_f32_e32 v216, v225, v216
	v_mul_f32_e32 v217, v225, v217
	v_mul_f32_e32 v218, v225, v218
	v_mul_f32_e32 v219, v225, v219
	v_fmac_f32_e32 v16, v112, v216
	v_fmac_f32_e32 v17, v113, v217
	v_fmac_f32_e32 v18, v114, v218
	v_fmac_f32_e32 v19, v115, v219
	global_store_dwordx4 v193, v[16:19], s[24:25] offset:0
	v_lshlrev_b32_e32 v216, 16, v42
	v_and_b32_e32 v217, 0xffff0000, v42
	v_lshlrev_b32_e32 v218, 16, v43
	v_and_b32_e32 v219, 0xffff0000, v43
	v_mul_f32_e32 v216, v225, v216
	v_mul_f32_e32 v217, v225, v217
	v_mul_f32_e32 v218, v225, v218
	v_mul_f32_e32 v219, v225, v219
	v_fmac_f32_e32 v20, v116, v216
	v_fmac_f32_e32 v21, v117, v217
	v_fmac_f32_e32 v22, v118, v218
	v_fmac_f32_e32 v23, v119, v219
	global_store_dwordx4 v193, v[20:23], s[24:25] offset:1024
	v_lshlrev_b32_e32 v216, 16, v44
	v_and_b32_e32 v217, 0xffff0000, v44
	v_lshlrev_b32_e32 v218, 16, v45
	v_and_b32_e32 v219, 0xffff0000, v45
	v_mul_f32_e32 v216, v225, v216
	v_mul_f32_e32 v217, v225, v217
	v_mul_f32_e32 v218, v225, v218
	v_mul_f32_e32 v219, v225, v219
	v_fmac_f32_e32 v24, v120, v216
	v_fmac_f32_e32 v25, v121, v217
	v_fmac_f32_e32 v26, v122, v218
	v_fmac_f32_e32 v27, v123, v219
	global_store_dwordx4 v193, v[24:27], s[24:25] offset:2048
	v_lshlrev_b32_e32 v216, 16, v46
	v_and_b32_e32 v217, 0xffff0000, v46
	v_lshlrev_b32_e32 v218, 16, v47
	v_and_b32_e32 v219, 0xffff0000, v47
	v_mul_f32_e32 v216, v225, v216
	v_mul_f32_e32 v217, v225, v217
	v_mul_f32_e32 v218, v225, v218
	v_mul_f32_e32 v219, v225, v219
	v_fmac_f32_e32 v28, v124, v216
	v_fmac_f32_e32 v29, v125, v217
	v_fmac_f32_e32 v30, v126, v218
	v_fmac_f32_e32 v31, v127, v219
	global_store_dwordx4 v193, v[28:31], s[24:25] offset:3072
	v_mul_f32_e32 v222, v0, v0
	v_mul_f32_e32 v223, v1, v1
	v_fmac_f32_e32 v222, v2, v2
	v_fmac_f32_e32 v223, v3, v3
	v_fmac_f32_e32 v222, v4, v4
	v_fmac_f32_e32 v223, v5, v5
	v_fmac_f32_e32 v222, v6, v6
	v_fmac_f32_e32 v223, v7, v7
	v_fmac_f32_e32 v222, v8, v8
	v_fmac_f32_e32 v223, v9, v9
	v_fmac_f32_e32 v222, v10, v10
	v_fmac_f32_e32 v223, v11, v11
	v_fmac_f32_e32 v222, v12, v12
	v_fmac_f32_e32 v223, v13, v13
	v_fmac_f32_e32 v222, v14, v14
	v_fmac_f32_e32 v223, v15, v15
	v_fmac_f32_e32 v222, v16, v16
	v_fmac_f32_e32 v223, v17, v17
	v_fmac_f32_e32 v222, v18, v18
	v_fmac_f32_e32 v223, v19, v19
	v_fmac_f32_e32 v222, v20, v20
	v_fmac_f32_e32 v223, v21, v21
	v_fmac_f32_e32 v222, v22, v22
	v_fmac_f32_e32 v223, v23, v23
; __device__ __forceinline__ float bf_lo(unsigned w) { return __uint_as_float(w << 16); }
; __device__ __forceinline__ float bf_hi(unsigned w) { return __uint_as_float(w & 0xffff0000u); }
; __global__ void __launch_bounds__(NWAVES * 64, 2) mk_fwd(Args args) {
;     ...
;             f32x4 v[3][8]; u32x2 yw[3][8];
; #pragma unroll
;             for (int q = 0; q < 3; ++q) { const int row = row0 + q; const float* src = row < ML ? x + (size_t)row * DM : ctx + (size_t)(row - ML) * DM; load_row_f32(src, F.lane, v[q]);
;                 const bf16_t* yr = Y + (size_t)row * DM;
; #pragma unroll
;                 for (int j = 0; j < 8; ++j) yw[q][j] = *(const u32x2*)(yr + 4 * F.lane + 256 * j); }
; #pragma unroll
;             for (int q = 0; q < 3; ++q) { const int row = row0 + q; const bool lat = row < ML; const int r = lat ? row / SEQ : 8;
;                 float sy = 0.f;
; #pragma unroll
;                 for (int j = 0; j < 8; ++j) { const float a = bf_lo(yw[q][j].x), b = bf_hi(yw[q][j].x), c2 = bf_lo(yw[q][j].y), d = bf_hi(yw[q][j].y); sy += (a * a + b * b) + (c2 * c2 + d * d); }
;                 const float rsy = __builtin_amdgcn_rsqf(wave_sum(sy) * (1.f / DM) + EPS);
;                 const float* m0 = mod + (size_t)r * 6144;
; #pragma unroll
;                 for (int j = 0; j < 8; ++j) { const int col = 4 * F.lane + 256 * j; const f32x4 gt = *(const f32x4*)(m0 + 2 * DM + col), pn = *(const f32x4*)(post_norm + col);
;                     const f32x4 y4 = (f32x4){bf_lo(yw[q][j].x), bf_hi(yw[q][j].x), bf_lo(yw[q][j].y), bf_hi(yw[q][j].y)};
;                     v[q][j] = v[q][j] + gt * (y4 * rsy * pn);
;                     if (lat) *(f32x4*)(args.out + (size_t)row * DM + col) = v[q][j]; }
;                 const float rstd = __builtin_amdgcn_rsqf(sumsq8(v[q]) * (1.f / DM) + EPS);
;                 modulate_store(v[q], rstd, pre_norm + DM, mod + (size_t)(9 + r) * 6144, H + (size_t)row * DM, F.lane); }
	v_fmac_f32_e32 v222, v24, v24
	v_fmac_f32_e32 v223, v25, v25
	v_fmac_f32_e32 v222, v26, v26
	v_fmac_f32_e32 v223, v27, v27
	v_fmac_f32_e32 v222, v28, v28
	v_fmac_f32_e32 v223, v29, v29
	v_fmac_f32_e32 v222, v30, v30
	v_fmac_f32_e32 v223, v31, v31
	v_add_f32_e32 v222, v222, v223
	s_nop 1
	v_add_f32_dpp v224, v222, v222 quad_perm:[1,0,3,2] row_mask:0xf bank_mask:0xf
	s_nop 1
	v_add_f32_dpp v224, v224, v224 quad_perm:[2,3,0,1] row_mask:0xf bank_mask:0xf
	s_nop 1
	v_add_f32_dpp v224, v224, v224 row_half_mirror row_mask:0xf bank_mask:0xf
	s_nop 1
	v_add_f32_dpp v224, v224, v224 row_mirror row_mask:0xf bank_mask:0xf
	s_nop 1
	v_readlane_b32 s40, v224, 0
	v_readlane_b32 s41, v224, 16
	v_readlane_b32 s42, v224, 32
	v_readlane_b32 s43, v224, 48
	s_nop 1
	v_mov_b32_e32 v225, s40
	v_add_f32_e32 v225, s41, v225
	v_add_f32_e32 v225, s42, v225
	v_add_f32_e32 v225, s43, v225
	v_fmamk_f32 v225, v225, 0x3a000000, v195
	v_rsq_f32_e32 v225, v225
	s_nop 0
	s_add_i32 s0, s6, 0
	s_lshl_b32 s1, s0, 12
	s_add_u32 s26, s84, s1
	s_addc_u32 s27, s85, 0
	s_add_u32 s26, s26, 0x4000000
	s_addc_u32 s27, s27, 0
	v_mul_f32_e32 v216, v225, v0
	v_mul_f32_e32 v217, v225, v1
	v_mul_f32_e32 v218, v225, v2
	v_mul_f32_e32 v219, v225, v3
	v_fma_f32 v216, v216, v128, v160
	v_fma_f32 v217, v217, v129, v161
	v_fma_f32 v218, v218, v130, v162
	v_fma_f32 v219, v219, v131, v163
	v_cvt_pk_bf16_f32 v196, v216, v217
	v_cvt_pk_bf16_f32 v197, v218, v219
	global_store_dwordx2 v194, v[196:197], s[26:27] offset:0
	v_mul_f32_e32 v216, v225, v4
	v_mul_f32_e32 v217, v225, v5
	v_mul_f32_e32 v218, v225, v6
	v_mul_f32_e32 v219, v225, v7
	v_fma_f32 v216, v216, v132, v164
	v_fma_f32 v217, v217, v133, v165
	v_fma_f32 v218, v218, v134, v166
	v_fma_f32 v219, v219, v135, v167
	v_cvt_pk_bf16_f32 v220, v216, v217
	v_cvt_pk_bf16_f32 v221, v218, v219
	global_store_dwordx2 v194, v[220:221], s[26:27] offset:512
	v_mul_f32_e32 v216, v225, v8
	v_mul_f32_e32 v217, v225, v9
	v_mul_f32_e32 v218, v225, v10
	v_mul_f32_e32 v219, v225, v11
	v_fma_f32 v216, v216, v136, v168
	v_fma_f32 v217, v217, v137, v169
	v_fma_f32 v218, v218, v138, v170
	v_fma_f32 v219, v219, v139, v171
	v_cvt_pk_bf16_f32 v196, v216, v217
	v_cvt_pk_bf16_f32 v197, v218, v219
	global_store_dwordx2 v194, v[196:197], s[26:27] offset:1024
	v_mul_f32_e32 v216, v225, v12
	v_mul_f32_e32 v217, v225, v13
	v_mul_f32_e32 v218, v225, v14
	v_mul_f32_e32 v219, v225, v15
	v_fma_f32 v216, v216, v140, v172
	v_fma_f32 v217, v217, v141, v173
	v_fma_f32 v218, v218, v142, v174
	v_fma_f32 v219, v219, v143, v175
	v_cvt_pk_bf16_f32 v220, v216, v217
	v_cvt_pk_bf16_f32 v221, v218, v219
	global_store_dwordx2 v194, v[220:221], s[26:27] offset:1536
	v_mul_f32_e32 v216, v225, v16
	v_mul_f32_e32 v217, v225, v17
	v_mul_f32_e32 v218, v225, v18
	v_mul_f32_e32 v219, v225, v19
	v_fma_f32 v216, v216, v144, v176
	v_fma_f32 v217, v217, v145, v177
	v_fma_f32 v218, v218, v146, v178
	v_fma_f32 v219, v219, v147, v179
	v_cvt_pk_bf16_f32 v196, v216, v217
	v_cvt_pk_bf16_f32 v197, v218, v219
	global_store_dwordx2 v194, v[196:197], s[26:27] offset:2048
	v_mul_f32_e32 v216, v225, v20
	v_mul_f32_e32 v217, v225, v21
	v_mul_f32_e32 v218, v225, v22
	v_mul_f32_e32 v219, v225, v23
	v_fma_f32 v216, v216, v148, v180
	v_fma_f32 v217, v217, v149, v181
	v_fma_f32 v218, v218, v150, v182
	v_fma_f32 v219, v219, v151, v183
	v_cvt_pk_bf16_f32 v220, v216, v217
	v_cvt_pk_bf16_f32 v221, v218, v219
	global_store_dwordx2 v194, v[220:221], s[26:27] offset:2560
	v_mul_f32_e32 v216, v225, v24
	v_mul_f32_e32 v217, v225, v25
	v_mul_f32_e32 v218, v225, v26
	v_mul_f32_e32 v219, v225, v27
	v_fma_f32 v216, v216, v152, v184
	v_fma_f32 v217, v217, v153, v185
	v_fma_f32 v218, v218, v154, v186
	v_fma_f32 v219, v219, v155, v187
	v_cvt_pk_bf16_f32 v196, v216, v217
	v_cvt_pk_bf16_f32 v197, v218, v219
	global_store_dwordx2 v194, v[196:197], s[26:27] offset:3072
	v_mul_f32_e32 v216, v225, v28
	v_mul_f32_e32 v217, v225, v29
	v_mul_f32_e32 v218, v225, v30
	v_mul_f32_e32 v219, v225, v31
	v_fma_f32 v216, v216, v156, v188
	v_fma_f32 v217, v217, v157, v189
	v_fma_f32 v218, v218, v158, v190
	v_fma_f32 v219, v219, v159, v191
	v_cvt_pk_bf16_f32 v220, v216, v217
	v_cvt_pk_bf16_f32 v221, v218, v219
	global_store_dwordx2 v194, v[220:221], s[26:27] offset:3584
	s_add_i32 s0, s6, 2
	s_cmp_lt_u32 s0, 0x4000
	s_cselect_b32 s10, s68, s72
	s_cselect_b32 s11, s69, s73
	s_cselect_b32 s1, 0, 0x4000
	s_sub_i32 s1, s0, s1
	s_lshl_b32 s1, s1, 13
	s_add_u32 s10, s10, s1
	s_addc_u32 s11, s11, 0
	s_add_i32 s0, s6, 2
	s_lshl_b32 s1, s0, 12
	s_add_u32 s22, s84, s1
	s_addc_u32 s23, s85, 0
	s_add_u32 s22, s22, 0x11800000
	s_addc_u32 s23, s23, 0
	global_load_dwordx4 v[0:3], v192, s[10:11] offset:0
	global_load_dwordx4 v[4:7], v192, s[10:11] offset:1024
	global_load_dwordx4 v[8:11], v192, s[10:11] offset:2048
	global_load_dwordx4 v[12:15], v192, s[10:11] offset:3072
	global_load_dwordx4 v[16:19], v193, s[10:11] offset:0
	global_load_dwordx4 v[20:23], v193, s[10:11] offset:1024
	global_load_dwordx4 v[24:27], v193, s[10:11] offset:2048
	global_load_dwordx4 v[28:31], v193, s[10:11] offset:3072
	global_load_dwordx2 v[32:33], v194, s[22:23] offset:0
	global_load_dwordx2 v[34:35], v194, s[22:23] offset:512
	global_load_dwordx2 v[36:37], v194, s[22:23] offset:1024
	global_load_dwordx2 v[38:39], v194, s[22:23] offset:1536
	global_load_dwordx2 v[40:41], v194, s[22:23] offset:2048
	global_load_dwordx2 v[42:43], v194, s[22:23] offset:2560
	global_load_dwordx2 v[44:45], v194, s[22:23] offset:3072
	global_load_dwordx2 v[46:47], v194, s[22:23] offset:3584
	s_add_i32 s0, s6, 1
	s_add_i32 s0, s6, 1
	s_lshr_b32 s8, s0, 11
	s_cmp_lt_u32 s0, 0x4000
	s_cselect_b32 s8, s8, 8
	s_cmp_eq_u32 s8, s7
	s_cbranch_scc1 .Lp6_np1
; __device__ __forceinline__ float bf_lo(unsigned w) { return __uint_as_float(w << 16); }
; __device__ __forceinline__ float bf_hi(unsigned w) { return __uint_as_float(w & 0xffff0000u); }
; __device__ __forceinline__ void modulate_store(const f32x4 (&v)[8], float rstd, const float* pn, const float* modr, bf16_t* orow, int lane) {
;     ...
;         const f32x4 g = *(const f32x4*)(pn + col), sh = *(const f32x4*)(modr + col), sc = *(const f32x4*)(modr + DM + col);
;         const f32x4 hh = v[j] * rstd * g * (sc + 1.f) + sh;
; __global__ void __launch_bounds__(NWAVES * 64, 2) mk_fwd(Args args) {
;     ...
;                 const float* m0 = mod + (size_t)r * 6144;
; #pragma unroll
;                 for (int j = 0; j < 8; ++j) { const int col = 4 * F.lane + 256 * j; const f32x4 gt = *(const f32x4*)(m0 + 2 * DM + col), pn = *(const f32x4*)(post_norm + col);
;                     const f32x4 y4 = (f32x4){bf_lo(yw[q][j].x), bf_hi(yw[q][j].x), bf_lo(yw[q][j].y), bf_hi(yw[q][j].y)};
;                     v[q][j] = v[q][j] + gt * (y4 * rsy * pn);
	s_mov_b32 s7, s8
	s_add_i32 s1, s8, 9
	s_mul_i32 s1, s1, 0x6000
	s_add_u32 s44, s84, s1
	s_addc_u32 s45, s85, 0
	s_add_u32 s44, s44, 0x2000
	s_addc_u32 s45, s45, 0
	s_add_i32 s1, s8, 9
	s_mul_i32 s1, s1, 0x6000
	s_add_u32 s36, s84, s1
	s_addc_u32 s37, s85, 0
	s_add_u32 s38, s80, 0x2000
	s_addc_u32 s39, s81, 0
	s_mul_i32 s1, s8, 0x6000
	s_add_u32 s34, s84, s1
	s_addc_u32 s35, s85, 0
	s_add_u32 s34, s34, 0x4000
	s_addc_u32 s35, s35, 0
	global_load_dwordx4 v[96:99], v192, s[34:35] offset:0
	global_load_dwordx4 v[200:203], v192, s[82:83] offset:0
	global_load_dwordx4 v[100:103], v192, s[34:35] offset:1024
	global_load_dwordx4 v[204:207], v192, s[82:83] offset:1024
	global_load_dwordx4 v[104:107], v192, s[34:35] offset:2048
	global_load_dwordx4 v[208:211], v192, s[82:83] offset:2048
	global_load_dwordx4 v[108:111], v192, s[34:35] offset:3072
	global_load_dwordx4 v[212:215], v192, s[82:83] offset:3072
	s_waitcnt vmcnt(0)
	v_mul_f32_e32 v96, v96, v200
	v_mul_f32_e32 v97, v97, v201
	v_mul_f32_e32 v98, v98, v202
	v_mul_f32_e32 v99, v99, v203
	v_mul_f32_e32 v100, v100, v204
	v_mul_f32_e32 v101, v101, v205
	v_mul_f32_e32 v102, v102, v206
	v_mul_f32_e32 v103, v103, v207
	v_mul_f32_e32 v104, v104, v208
	v_mul_f32_e32 v105, v105, v209
	v_mul_f32_e32 v106, v106, v210
	v_mul_f32_e32 v107, v107, v211
	v_mul_f32_e32 v108, v108, v212
	v_mul_f32_e32 v109, v109, v213
	v_mul_f32_e32 v110, v110, v214
	v_mul_f32_e32 v111, v111, v215
	global_load_dwordx4 v[128:131], v192, s[38:39] offset:0
	global_load_dwordx4 v[200:203], v192, s[44:45] offset:0
	global_load_dwordx4 v[160:163], v192, s[36:37] offset:0
	global_load_dwordx4 v[132:135], v192, s[38:39] offset:1024
	global_load_dwordx4 v[204:207], v192, s[44:45] offset:1024
	global_load_dwordx4 v[164:167], v192, s[36:37] offset:1024
	global_load_dwordx4 v[136:139], v192, s[38:39] offset:2048
	global_load_dwordx4 v[208:211], v192, s[44:45] offset:2048
	global_load_dwordx4 v[168:171], v192, s[36:37] offset:2048
	global_load_dwordx4 v[140:143], v192, s[38:39] offset:3072
	global_load_dwordx4 v[212:215], v192, s[44:45] offset:3072
	global_load_dwordx4 v[172:175], v192, s[36:37] offset:3072
	s_waitcnt vmcnt(0)
	v_add_f32_e32 v200, 1.0, v200
	v_add_f32_e32 v201, 1.0, v201
	v_add_f32_e32 v202, 1.0, v202
	v_add_f32_e32 v203, 1.0, v203
	v_mul_f32_e32 v128, v128, v200
	v_mul_f32_e32 v129, v129, v201
	v_mul_f32_e32 v130, v130, v202
	v_mul_f32_e32 v131, v131, v203
	v_add_f32_e32 v204, 1.0, v204
	v_add_f32_e32 v205, 1.0, v205
	v_add_f32_e32 v206, 1.0, v206
	v_add_f32_e32 v207, 1.0, v207
	v_mul_f32_e32 v132, v132, v204
	v_mul_f32_e32 v133, v133, v205
	v_mul_f32_e32 v134, v134, v206
	v_mul_f32_e32 v135, v135, v207
	v_add_f32_e32 v208, 1.0, v208
	v_add_f32_e32 v209, 1.0, v209
	v_add_f32_e32 v210, 1.0, v210
	v_add_f32_e32 v211, 1.0, v211
	v_mul_f32_e32 v136, v136, v208
	v_mul_f32_e32 v137, v137, v209
	v_mul_f32_e32 v138, v138, v210
	v_mul_f32_e32 v139, v139, v211
	v_add_f32_e32 v212, 1.0, v212
	v_add_f32_e32 v213, 1.0, v213
	v_add_f32_e32 v214, 1.0, v214
	v_add_f32_e32 v215, 1.0, v215
	v_mul_f32_e32 v140, v140, v212
	v_mul_f32_e32 v141, v141, v213
	v_mul_f32_e32 v142, v142, v214
	v_mul_f32_e32 v143, v143, v215
	global_load_dwordx4 v[112:115], v193, s[34:35] offset:0
	global_load_dwordx4 v[200:203], v193, s[82:83] offset:0
	global_load_dwordx4 v[116:119], v193, s[34:35] offset:1024
	global_load_dwordx4 v[204:207], v193, s[82:83] offset:1024
	global_load_dwordx4 v[120:123], v193, s[34:35] offset:2048
	global_load_dwordx4 v[208:211], v193, s[82:83] offset:2048
	global_load_dwordx4 v[124:127], v193, s[34:35] offset:3072
	global_load_dwordx4 v[212:215], v193, s[82:83] offset:3072
	s_waitcnt vmcnt(0)
	v_mul_f32_e32 v112, v112, v200
	v_mul_f32_e32 v113, v113, v201
	v_mul_f32_e32 v114, v114, v202
	v_mul_f32_e32 v115, v115, v203
	v_mul_f32_e32 v116, v116, v204
	v_mul_f32_e32 v117, v117, v205
	v_mul_f32_e32 v118, v118, v206
	v_mul_f32_e32 v119, v119, v207
	v_mul_f32_e32 v120, v120, v208
	v_mul_f32_e32 v121, v121, v209
	v_mul_f32_e32 v122, v122, v210
	v_mul_f32_e32 v123, v123, v211
	v_mul_f32_e32 v124, v124, v212
	v_mul_f32_e32 v125, v125, v213
	v_mul_f32_e32 v126, v126, v214
	v_mul_f32_e32 v127, v127, v215
	global_load_dwordx4 v[144:147], v193, s[38:39] offset:0
	global_load_dwordx4 v[200:203], v193, s[44:45] offset:0
	global_load_dwordx4 v[176:179], v193, s[36:37] offset:0
	global_load_dwordx4 v[148:151], v193, s[38:39] offset:1024
	global_load_dwordx4 v[204:207], v193, s[44:45] offset:1024
	global_load_dwordx4 v[180:183], v193, s[36:37] offset:1024
	global_load_dwordx4 v[152:155], v193, s[38:39] offset:2048
	global_load_dwordx4 v[208:211], v193, s[44:45] offset:2048
	global_load_dwordx4 v[184:187], v193, s[36:37] offset:2048
	global_load_dwordx4 v[156:159], v193, s[38:39] offset:3072
	global_load_dwordx4 v[212:215], v193, s[44:45] offset:3072
	global_load_dwordx4 v[188:191], v193, s[36:37] offset:3072
	s_waitcnt vmcnt(0)
	v_add_f32_e32 v200, 1.0, v200
	v_add_f32_e32 v201, 1.0, v201
	v_add_f32_e32 v202, 1.0, v202
	v_add_f32_e32 v203, 1.0, v203
	v_mul_f32_e32 v144, v144, v200
	v_mul_f32_e32 v145, v145, v201
	v_mul_f32_e32 v146, v146, v202
	v_mul_f32_e32 v147, v147, v203
	v_add_f32_e32 v204, 1.0, v204
	v_add_f32_e32 v205, 1.0, v205
	v_add_f32_e32 v206, 1.0, v206
	v_add_f32_e32 v207, 1.0, v207
	v_mul_f32_e32 v148, v148, v204
	v_mul_f32_e32 v149, v149, v205
	v_mul_f32_e32 v150, v150, v206
	v_mul_f32_e32 v151, v151, v207
	v_add_f32_e32 v208, 1.0, v208
	v_add_f32_e32 v209, 1.0, v209
	v_add_f32_e32 v210, 1.0, v210
	v_add_f32_e32 v211, 1.0, v211
	v_mul_f32_e32 v152, v152, v208
	v_mul_f32_e32 v153, v153, v209
	v_mul_f32_e32 v154, v154, v210
	v_mul_f32_e32 v155, v155, v211
	v_add_f32_e32 v212, 1.0, v212
	v_add_f32_e32 v213, 1.0, v213
	v_add_f32_e32 v214, 1.0, v214
	v_add_f32_e32 v215, 1.0, v215
	v_mul_f32_e32 v156, v156, v212
	v_mul_f32_e32 v157, v157, v213
	v_mul_f32_e32 v158, v158, v214
	v_mul_f32_e32 v159, v159, v215
; __device__ __forceinline__ float bf_lo(unsigned w) { return __uint_as_float(w << 16); }
; __device__ __forceinline__ float bf_hi(unsigned w) { return __uint_as_float(w & 0xffff0000u); }
; __global__ void __launch_bounds__(NWAVES * 64, 2) mk_fwd(Args args) {
;     ...
;                 for (int j = 0; j < 8; ++j) { const float a = bf_lo(yw[q][j].x), b = bf_hi(yw[q][j].x), c2 = bf_lo(yw[q][j].y), d = bf_hi(yw[q][j].y); sy += (a * a + b * b) + (c2 * c2 + d * d); }
;                 const float rsy = __builtin_amdgcn_rsqf(wave_sum(sy) * (1.f / DM) + EPS);
;                 const float* m0 = mod + (size_t)r * 6144;
; #pragma unroll
;                 for (int j = 0; j < 8; ++j) { const int col = 4 * F.lane + 256 * j; const f32x4 gt = *(const f32x4*)(m0 + 2 * DM + col), pn = *(const f32x4*)(post_norm + col);
;                     const f32x4 y4 = (f32x4){bf_lo(yw[q][j].x), bf_hi(yw[q][j].x), bf_lo(yw[q][j].y), bf_hi(yw[q][j].y)};
;                     v[q][j] = v[q][j] + gt * (y4 * rsy * pn);
;                     if (lat) *(f32x4*)(args.out + (size_t)row * DM + col) = v[q][j]; }
.Lp6_np1:
	s_waitcnt vmcnt(32)
	v_lshlrev_b32_e32 v216, 16, v80
	v_and_b32_e32 v217, 0xffff0000, v80
	v_lshlrev_b32_e32 v218, 16, v81
	v_and_b32_e32 v219, 0xffff0000, v81
	v_mul_f32_e32 v222, v216, v216
	v_mul_f32_e32 v223, v217, v217
	v_fmac_f32_e32 v222, v218, v218
	v_fmac_f32_e32 v223, v219, v219
	v_lshlrev_b32_e32 v216, 16, v82
	v_and_b32_e32 v217, 0xffff0000, v82
	v_lshlrev_b32_e32 v218, 16, v83
	v_and_b32_e32 v219, 0xffff0000, v83
	v_fmac_f32_e32 v222, v216, v216
	v_fmac_f32_e32 v223, v217, v217
	v_fmac_f32_e32 v222, v218, v218
	v_fmac_f32_e32 v223, v219, v219
	v_lshlrev_b32_e32 v216, 16, v84
	v_and_b32_e32 v217, 0xffff0000, v84
	v_lshlrev_b32_e32 v218, 16, v85
	v_and_b32_e32 v219, 0xffff0000, v85
	v_fmac_f32_e32 v222, v216, v216
	v_fmac_f32_e32 v223, v217, v217
	v_fmac_f32_e32 v222, v218, v218
	v_fmac_f32_e32 v223, v219, v219
	v_lshlrev_b32_e32 v216, 16, v86
	v_and_b32_e32 v217, 0xffff0000, v86
	v_lshlrev_b32_e32 v218, 16, v87
	v_and_b32_e32 v219, 0xffff0000, v87
	v_fmac_f32_e32 v222, v216, v216
	v_fmac_f32_e32 v223, v217, v217
	v_fmac_f32_e32 v222, v218, v218
	v_fmac_f32_e32 v223, v219, v219
	v_lshlrev_b32_e32 v216, 16, v88
	v_and_b32_e32 v217, 0xffff0000, v88
	v_lshlrev_b32_e32 v218, 16, v89
	v_and_b32_e32 v219, 0xffff0000, v89
	v_fmac_f32_e32 v222, v216, v216
	v_fmac_f32_e32 v223, v217, v217
	v_fmac_f32_e32 v222, v218, v218
	v_fmac_f32_e32 v223, v219, v219
	v_lshlrev_b32_e32 v216, 16, v90
	v_and_b32_e32 v217, 0xffff0000, v90
	v_lshlrev_b32_e32 v218, 16, v91
	v_and_b32_e32 v219, 0xffff0000, v91
	v_fmac_f32_e32 v222, v216, v216
	v_fmac_f32_e32 v223, v217, v217
	v_fmac_f32_e32 v222, v218, v218
	v_fmac_f32_e32 v223, v219, v219
	v_lshlrev_b32_e32 v216, 16, v92
	v_and_b32_e32 v217, 0xffff0000, v92
	v_lshlrev_b32_e32 v218, 16, v93
	v_and_b32_e32 v219, 0xffff0000, v93
	v_fmac_f32_e32 v222, v216, v216
	v_fmac_f32_e32 v223, v217, v217
	v_fmac_f32_e32 v222, v218, v218
	v_fmac_f32_e32 v223, v219, v219
	v_lshlrev_b32_e32 v216, 16, v94
	v_and_b32_e32 v217, 0xffff0000, v94
	v_lshlrev_b32_e32 v218, 16, v95
	v_and_b32_e32 v219, 0xffff0000, v95
	v_fmac_f32_e32 v222, v216, v216
	v_fmac_f32_e32 v223, v217, v217
	v_fmac_f32_e32 v222, v218, v218
	v_fmac_f32_e32 v223, v219, v219
	v_add_f32_e32 v222, v222, v223
	s_nop 1
	v_add_f32_dpp v224, v222, v222 quad_perm:[1,0,3,2] row_mask:0xf bank_mask:0xf
	s_nop 1
	v_add_f32_dpp v224, v224, v224 quad_perm:[2,3,0,1] row_mask:0xf bank_mask:0xf
	s_nop 1
	v_add_f32_dpp v224, v224, v224 row_half_mirror row_mask:0xf bank_mask:0xf
	s_nop 1
	v_add_f32_dpp v224, v224, v224 row_mirror row_mask:0xf bank_mask:0xf
	s_nop 1
	v_readlane_b32 s40, v224, 0
	v_readlane_b32 s41, v224, 16
	v_readlane_b32 s42, v224, 32
	v_readlane_b32 s43, v224, 48
	s_nop 1
	v_mov_b32_e32 v225, s40
	v_add_f32_e32 v225, s41, v225
	v_add_f32_e32 v225, s42, v225
	v_add_f32_e32 v225, s43, v225
	v_fmamk_f32 v225, v225, 0x3a000000, v195
	v_rsq_f32_e32 v225, v225
	s_nop 0
	s_add_i32 s0, s6, 1
	s_cmp_lt_u32 s0, 0x4000
	s_cselect_b32 s24, s94, s84
	s_cselect_b32 s25, s95, s85
	s_cselect_b32 s44, 0, 0x16000000
	s_cselect_b32 s1, 0, 0x4000
	s_sub_i32 s1, s0, s1
	s_lshl_b32 s1, s1, 13
	s_add_u32 s24, s24, s1
	s_addc_u32 s25, s25, 0
	s_add_u32 s24, s24, s44
	s_addc_u32 s25, s25, 0
	v_lshlrev_b32_e32 v216, 16, v80
	v_and_b32_e32 v217, 0xffff0000, v80
	v_lshlrev_b32_e32 v218, 16, v81
	v_and_b32_e32 v219, 0xffff0000, v81
	v_mul_f32_e32 v216, v225, v216
	v_mul_f32_e32 v217, v225, v217
	v_mul_f32_e32 v218, v225, v218
	v_mul_f32_e32 v219, v225, v219
	v_fmac_f32_e32 v48, v96, v216
	v_fmac_f32_e32 v49, v97, v217
	v_fmac_f32_e32 v50, v98, v218
	v_fmac_f32_e32 v51, v99, v219
	global_store_dwordx4 v192, v[48:51], s[24:25] offset:0
	v_lshlrev_b32_e32 v216, 16, v82
	v_and_b32_e32 v217, 0xffff0000, v82
	v_lshlrev_b32_e32 v218, 16, v83
	v_and_b32_e32 v219, 0xffff0000, v83
	v_mul_f32_e32 v216, v225, v216
	v_mul_f32_e32 v217, v225, v217
	v_mul_f32_e32 v218, v225, v218
	v_mul_f32_e32 v219, v225, v219
	v_fmac_f32_e32 v52, v100, v216
	v_fmac_f32_e32 v53, v101, v217
	v_fmac_f32_e32 v54, v102, v218
	v_fmac_f32_e32 v55, v103, v219
	global_store_dwordx4 v192, v[52:55], s[24:25] offset:1024
	v_lshlrev_b32_e32 v216, 16, v84
	v_and_b32_e32 v217, 0xffff0000, v84
	v_lshlrev_b32_e32 v218, 16, v85
	v_and_b32_e32 v219, 0xffff0000, v85
	v_mul_f32_e32 v216, v225, v216
	v_mul_f32_e32 v217, v225, v217
	v_mul_f32_e32 v218, v225, v218
	v_mul_f32_e32 v219, v225, v219
	v_fmac_f32_e32 v56, v104, v216
	v_fmac_f32_e32 v57, v105, v217
	v_fmac_f32_e32 v58, v106, v218
	v_fmac_f32_e32 v59, v107, v219
	global_store_dwordx4 v192, v[56:59], s[24:25] offset:2048
	v_lshlrev_b32_e32 v216, 16, v86
	v_and_b32_e32 v217, 0xffff0000, v86
	v_lshlrev_b32_e32 v218, 16, v87
	v_and_b32_e32 v219, 0xffff0000, v87
	v_mul_f32_e32 v216, v225, v216
	v_mul_f32_e32 v217, v225, v217
	v_mul_f32_e32 v218, v225, v218
	v_mul_f32_e32 v219, v225, v219
	v_fmac_f32_e32 v60, v108, v216
	v_fmac_f32_e32 v61, v109, v217
	v_fmac_f32_e32 v62, v110, v218
	v_fmac_f32_e32 v63, v111, v219
	global_store_dwordx4 v192, v[60:63], s[24:25] offset:3072
	v_lshlrev_b32_e32 v216, 16, v88
	v_and_b32_e32 v217, 0xffff0000, v88
	v_lshlrev_b32_e32 v218, 16, v89
	v_and_b32_e32 v219, 0xffff0000, v89
	v_mul_f32_e32 v216, v225, v216
	v_mul_f32_e32 v217, v225, v217
	v_mul_f32_e32 v218, v225, v218
	v_mul_f32_e32 v219, v225, v219
	v_fmac_f32_e32 v64, v112, v216
	v_fmac_f32_e32 v65, v113, v217
	v_fmac_f32_e32 v66, v114, v218
	v_fmac_f32_e32 v67, v115, v219
	global_store_dwordx4 v193, v[64:67], s[24:25] offset:0
	v_lshlrev_b32_e32 v216, 16, v90
	v_and_b32_e32 v217, 0xffff0000, v90
	v_lshlrev_b32_e32 v218, 16, v91
	v_and_b32_e32 v219, 0xffff0000, v91
	v_mul_f32_e32 v216, v225, v216
; __device__ __forceinline__ unsigned cvt_pk_bf16(float lo, float hi) { unsigned r; asm volatile("v_cvt_pk_bf16_f32 %0, %1, %2" : "=v"(r) : "v"(lo), "v"(hi)); return r; }
; __device__ __forceinline__ float bf_lo(unsigned w) { return __uint_as_float(w << 16); }
; __device__ __forceinline__ float bf_hi(unsigned w) { return __uint_as_float(w & 0xffff0000u); }
; __device__ __forceinline__ float sumsq8(const f32x4 (&v)[8]) {
;     float s = 0.f;
; #pragma unroll
;     for (int j = 0; j < 8; ++j) s += (v[j][0] * v[j][0] + v[j][1] * v[j][1]) + (v[j][2] * v[j][2] + v[j][3] * v[j][3]);
;     return wave_sum(s);
; }
; __device__ __forceinline__ void modulate_store(const f32x4 (&v)[8], float rstd, const float* pn, const float* modr, bf16_t* orow, int lane) {
; #pragma unroll
;     for (int j = 0; j < 8; ++j) { const int col = 4 * lane + 256 * j;
;         const f32x4 g = *(const f32x4*)(pn + col), sh = *(const f32x4*)(modr + col), sc = *(const f32x4*)(modr + DM + col);
;         const f32x4 hh = v[j] * rstd * g * (sc + 1.f) + sh;
;         u32x2 w; w.x = cvt_pk_bf16(hh[0], hh[1]); w.y = cvt_pk_bf16(hh[2], hh[3]);
;         *(u32x2*)(orow + col) = w; }
; }
; __global__ void __launch_bounds__(NWAVES * 64, 2) mk_fwd(Args args) {
;     ...
;                 for (int j = 0; j < 8; ++j) { const int col = 4 * F.lane + 256 * j; const f32x4 gt = *(const f32x4*)(m0 + 2 * DM + col), pn = *(const f32x4*)(post_norm + col);
;                     const f32x4 y4 = (f32x4){bf_lo(yw[q][j].x), bf_hi(yw[q][j].x), bf_lo(yw[q][j].y), bf_hi(yw[q][j].y)};
;                     v[q][j] = v[q][j] + gt * (y4 * rsy * pn);
;                     if (lat) *(f32x4*)(args.out + (size_t)row * DM + col) = v[q][j]; }
;                 const float rstd = __builtin_amdgcn_rsqf(sumsq8(v[q]) * (1.f / DM) + EPS);
;                 modulate_store(v[q], rstd, pre_norm + DM, mod + (size_t)(9 + r) * 6144, H + (size_t)row * DM, F.lane); }
	v_mul_f32_e32 v217, v225, v217
	v_mul_f32_e32 v218, v225, v218
	v_mul_f32_e32 v219, v225, v219
	v_fmac_f32_e32 v68, v116, v216
	v_fmac_f32_e32 v69, v117, v217
	v_fmac_f32_e32 v70, v118, v218
	v_fmac_f32_e32 v71, v119, v219
	global_store_dwordx4 v193, v[68:71], s[24:25] offset:1024
	v_lshlrev_b32_e32 v216, 16, v92
	v_and_b32_e32 v217, 0xffff0000, v92
	v_lshlrev_b32_e32 v218, 16, v93
	v_and_b32_e32 v219, 0xffff0000, v93
	v_mul_f32_e32 v216, v225, v216
	v_mul_f32_e32 v217, v225, v217
	v_mul_f32_e32 v218, v225, v218
	v_mul_f32_e32 v219, v225, v219
	v_fmac_f32_e32 v72, v120, v216
	v_fmac_f32_e32 v73, v121, v217
	v_fmac_f32_e32 v74, v122, v218
	v_fmac_f32_e32 v75, v123, v219
	global_store_dwordx4 v193, v[72:75], s[24:25] offset:2048
	v_lshlrev_b32_e32 v216, 16, v94
	v_and_b32_e32 v217, 0xffff0000, v94
	v_lshlrev_b32_e32 v218, 16, v95
	v_and_b32_e32 v219, 0xffff0000, v95
	v_mul_f32_e32 v216, v225, v216
	v_mul_f32_e32 v217, v225, v217
	v_mul_f32_e32 v218, v225, v218
	v_mul_f32_e32 v219, v225, v219
	v_fmac_f32_e32 v76, v124, v216
	v_fmac_f32_e32 v77, v125, v217
	v_fmac_f32_e32 v78, v126, v218
	v_fmac_f32_e32 v79, v127, v219
	global_store_dwordx4 v193, v[76:79], s[24:25] offset:3072
	v_mul_f32_e32 v222, v48, v48
	v_mul_f32_e32 v223, v49, v49
	v_fmac_f32_e32 v222, v50, v50
	v_fmac_f32_e32 v223, v51, v51
	v_fmac_f32_e32 v222, v52, v52
	v_fmac_f32_e32 v223, v53, v53
	v_fmac_f32_e32 v222, v54, v54
	v_fmac_f32_e32 v223, v55, v55
	v_fmac_f32_e32 v222, v56, v56
	v_fmac_f32_e32 v223, v57, v57
	v_fmac_f32_e32 v222, v58, v58
	v_fmac_f32_e32 v223, v59, v59
	v_fmac_f32_e32 v222, v60, v60
	v_fmac_f32_e32 v223, v61, v61
	v_fmac_f32_e32 v222, v62, v62
	v_fmac_f32_e32 v223, v63, v63
	v_fmac_f32_e32 v222, v64, v64
	v_fmac_f32_e32 v223, v65, v65
	v_fmac_f32_e32 v222, v66, v66
	v_fmac_f32_e32 v223, v67, v67
	v_fmac_f32_e32 v222, v68, v68
	v_fmac_f32_e32 v223, v69, v69
	v_fmac_f32_e32 v222, v70, v70
	v_fmac_f32_e32 v223, v71, v71
	v_fmac_f32_e32 v222, v72, v72
	v_fmac_f32_e32 v223, v73, v73
	v_fmac_f32_e32 v222, v74, v74
	v_fmac_f32_e32 v223, v75, v75
	v_fmac_f32_e32 v222, v76, v76
	v_fmac_f32_e32 v223, v77, v77
	v_fmac_f32_e32 v222, v78, v78
	v_fmac_f32_e32 v223, v79, v79
	v_add_f32_e32 v222, v222, v223
	s_nop 1
	v_add_f32_dpp v224, v222, v222 quad_perm:[1,0,3,2] row_mask:0xf bank_mask:0xf
	s_nop 1
	v_add_f32_dpp v224, v224, v224 quad_perm:[2,3,0,1] row_mask:0xf bank_mask:0xf
	s_nop 1
	v_add_f32_dpp v224, v224, v224 row_half_mirror row_mask:0xf bank_mask:0xf
	s_nop 1
	v_add_f32_dpp v224, v224, v224 row_mirror row_mask:0xf bank_mask:0xf
	s_nop 1
	v_readlane_b32 s40, v224, 0
	v_readlane_b32 s41, v224, 16
	v_readlane_b32 s42, v224, 32
	v_readlane_b32 s43, v224, 48
	s_nop 1
	v_mov_b32_e32 v225, s40
	v_add_f32_e32 v225, s41, v225
	v_add_f32_e32 v225, s42, v225
	v_add_f32_e32 v225, s43, v225
	v_fmamk_f32 v225, v225, 0x3a000000, v195
	v_rsq_f32_e32 v225, v225
	s_nop 0
	s_add_i32 s0, s6, 1
	s_lshl_b32 s1, s0, 12
	s_add_u32 s26, s84, s1
	s_addc_u32 s27, s85, 0
	s_add_u32 s26, s26, 0x4000000
	s_addc_u32 s27, s27, 0
	v_mul_f32_e32 v216, v225, v48
	v_mul_f32_e32 v217, v225, v49
	v_mul_f32_e32 v218, v225, v50
	v_mul_f32_e32 v219, v225, v51
	v_fma_f32 v216, v216, v128, v160
	v_fma_f32 v217, v217, v129, v161
	v_fma_f32 v218, v218, v130, v162
	v_fma_f32 v219, v219, v131, v163
	v_cvt_pk_bf16_f32 v196, v216, v217
	v_cvt_pk_bf16_f32 v197, v218, v219
	global_store_dwordx2 v194, v[196:197], s[26:27] offset:0
	v_mul_f32_e32 v216, v225, v52
	v_mul_f32_e32 v217, v225, v53
	v_mul_f32_e32 v218, v225, v54
	v_mul_f32_e32 v219, v225, v55
	v_fma_f32 v216, v216, v132, v164
	v_fma_f32 v217, v217, v133, v165
	v_fma_f32 v218, v218, v134, v166
	v_fma_f32 v219, v219, v135, v167
	v_cvt_pk_bf16_f32 v220, v216, v217
	v_cvt_pk_bf16_f32 v221, v218, v219
	global_store_dwordx2 v194, v[220:221], s[26:27] offset:512
	v_mul_f32_e32 v216, v225, v56
	v_mul_f32_e32 v217, v225, v57
	v_mul_f32_e32 v218, v225, v58
	v_mul_f32_e32 v219, v225, v59
	v_fma_f32 v216, v216, v136, v168
	v_fma_f32 v217, v217, v137, v169
	v_fma_f32 v218, v218, v138, v170
	v_fma_f32 v219, v219, v139, v171
	v_cvt_pk_bf16_f32 v196, v216, v217
	v_cvt_pk_bf16_f32 v197, v218, v219
	global_store_dwordx2 v194, v[196:197], s[26:27] offset:1024
	v_mul_f32_e32 v216, v225, v60
	v_mul_f32_e32 v217, v225, v61
	v_mul_f32_e32 v218, v225, v62
	v_mul_f32_e32 v219, v225, v63
	v_fma_f32 v216, v216, v140, v172
	v_fma_f32 v217, v217, v141, v173
	v_fma_f32 v218, v218, v142, v174
	v_fma_f32 v219, v219, v143, v175
	v_cvt_pk_bf16_f32 v220, v216, v217
	v_cvt_pk_bf16_f32 v221, v218, v219
	global_store_dwordx2 v194, v[220:221], s[26:27] offset:1536
	v_mul_f32_e32 v216, v225, v64
	v_mul_f32_e32 v217, v225, v65
	v_mul_f32_e32 v218, v225, v66
	v_mul_f32_e32 v219, v225, v67
	v_fma_f32 v216, v216, v144, v176
	v_fma_f32 v217, v217, v145, v177
	v_fma_f32 v218, v218, v146, v178
	v_fma_f32 v219, v219, v147, v179
	v_cvt_pk_bf16_f32 v196, v216, v217
	v_cvt_pk_bf16_f32 v197, v218, v219
	global_store_dwordx2 v194, v[196:197], s[26:27] offset:2048
	v_mul_f32_e32 v216, v225, v68
	v_mul_f32_e32 v217, v225, v69
	v_mul_f32_e32 v218, v225, v70
	v_mul_f32_e32 v219, v225, v71
	v_fma_f32 v216, v216, v148, v180
	v_fma_f32 v217, v217, v149, v181
	v_fma_f32 v218, v218, v150, v182
	v_fma_f32 v219, v219, v151, v183
	v_cvt_pk_bf16_f32 v220, v216, v217
	v_cvt_pk_bf16_f32 v221, v218, v219
	global_store_dwordx2 v194, v[220:221], s[26:27] offset:2560
	v_mul_f32_e32 v216, v225, v72
	v_mul_f32_e32 v217, v225, v73
	v_mul_f32_e32 v218, v225, v74
	v_mul_f32_e32 v219, v225, v75
	v_fma_f32 v216, v216, v152, v184
	v_fma_f32 v217, v217, v153, v185
	v_fma_f32 v218, v218, v154, v186
	v_fma_f32 v219, v219, v155, v187
; __device__ __forceinline__ unsigned cvt_pk_bf16(float lo, float hi) { unsigned r; asm volatile("v_cvt_pk_bf16_f32 %0, %1, %2" : "=v"(r) : "v"(lo), "v"(hi)); return r; }
; __device__ __forceinline__ float bf_lo(unsigned w) { return __uint_as_float(w << 16); }
; __device__ __forceinline__ float bf_hi(unsigned w) { return __uint_as_float(w & 0xffff0000u); }
; __device__ __forceinline__ void modulate_store(const f32x4 (&v)[8], float rstd, const float* pn, const float* modr, bf16_t* orow, int lane) {
; #pragma unroll
;     for (int j = 0; j < 8; ++j) { const int col = 4 * lane + 256 * j;
;         const f32x4 g = *(const f32x4*)(pn + col), sh = *(const f32x4*)(modr + col), sc = *(const f32x4*)(modr + DM + col);
;         const f32x4 hh = v[j] * rstd * g * (sc + 1.f) + sh;
;         u32x2 w; w.x = cvt_pk_bf16(hh[0], hh[1]); w.y = cvt_pk_bf16(hh[2], hh[3]);
;         *(u32x2*)(orow + col) = w; }
; }
; __global__ void __launch_bounds__(NWAVES * 64, 2) mk_fwd(Args args) {
;     ...
;         for (int row0 = F.gw * 3; row0 < MT; row0 += F.NGW * 3) {
;             f32x4 v[3][8]; u32x2 yw[3][8];
; #pragma unroll
;             for (int q = 0; q < 3; ++q) { const int row = row0 + q; const float* src = row < ML ? x + (size_t)row * DM : ctx + (size_t)(row - ML) * DM; load_row_f32(src, F.lane, v[q]);
;                 const bf16_t* yr = Y + (size_t)row * DM;
; #pragma unroll
;                 for (int j = 0; j < 8; ++j) yw[q][j] = *(const u32x2*)(yr + 4 * F.lane + 256 * j); }
; #pragma unroll
;             for (int q = 0; q < 3; ++q) { const int row = row0 + q; const bool lat = row < ML; const int r = lat ? row / SEQ : 8;
;                 float sy = 0.f;
; #pragma unroll
;                 for (int j = 0; j < 8; ++j) { const float a = bf_lo(yw[q][j].x), b = bf_hi(yw[q][j].x), c2 = bf_lo(yw[q][j].y), d = bf_hi(yw[q][j].y); sy += (a * a + b * b) + (c2 * c2 + d * d); }
;                 const float rsy = __builtin_amdgcn_rsqf(wave_sum(sy) * (1.f / DM) + EPS);
;                 const float* m0 = mod + (size_t)r * 6144;
; #pragma unroll
;                 for (int j = 0; j < 8; ++j) { const int col = 4 * F.lane + 256 * j; const f32x4 gt = *(const f32x4*)(m0 + 2 * DM + col), pn = *(const f32x4*)(post_norm + col);
	v_cvt_pk_bf16_f32 v196, v216, v217
	v_cvt_pk_bf16_f32 v197, v218, v219
	global_store_dwordx2 v194, v[196:197], s[26:27] offset:3072
	v_mul_f32_e32 v216, v225, v76
	v_mul_f32_e32 v217, v225, v77
	v_mul_f32_e32 v218, v225, v78
	v_mul_f32_e32 v219, v225, v79
	v_fma_f32 v216, v216, v156, v188
	v_fma_f32 v217, v217, v157, v189
	v_fma_f32 v218, v218, v158, v190
	v_fma_f32 v219, v219, v159, v191
	v_cvt_pk_bf16_f32 v220, v216, v217
	v_cvt_pk_bf16_f32 v221, v218, v219
	global_store_dwordx2 v194, v[220:221], s[26:27] offset:3584
	s_add_i32 s0, s6, 3
	s_cmp_lt_u32 s0, 0x4000
	s_cselect_b32 s10, s68, s72
	s_cselect_b32 s11, s69, s73
	s_cselect_b32 s1, 0, 0x4000
	s_sub_i32 s1, s0, s1
	s_lshl_b32 s1, s1, 13
	s_add_u32 s10, s10, s1
	s_addc_u32 s11, s11, 0
	s_add_i32 s0, s6, 3
	s_lshl_b32 s1, s0, 12
	s_add_u32 s22, s84, s1
	s_addc_u32 s23, s85, 0
	s_add_u32 s22, s22, 0x11800000
	s_addc_u32 s23, s23, 0
	global_load_dwordx4 v[48:51], v192, s[10:11] offset:0
	global_load_dwordx4 v[52:55], v192, s[10:11] offset:1024
	global_load_dwordx4 v[56:59], v192, s[10:11] offset:2048
	global_load_dwordx4 v[60:63], v192, s[10:11] offset:3072
	global_load_dwordx4 v[64:67], v193, s[10:11] offset:0
	global_load_dwordx4 v[68:71], v193, s[10:11] offset:1024
	global_load_dwordx4 v[72:75], v193, s[10:11] offset:2048
	global_load_dwordx4 v[76:79], v193, s[10:11] offset:3072
	global_load_dwordx2 v[80:81], v194, s[22:23] offset:0
	global_load_dwordx2 v[82:83], v194, s[22:23] offset:512
	global_load_dwordx2 v[84:85], v194, s[22:23] offset:1024
	global_load_dwordx2 v[86:87], v194, s[22:23] offset:1536
	global_load_dwordx2 v[88:89], v194, s[22:23] offset:2048
	global_load_dwordx2 v[90:91], v194, s[22:23] offset:2560
	global_load_dwordx2 v[92:93], v194, s[22:23] offset:3072
	global_load_dwordx2 v[94:95], v194, s[22:23] offset:3584
	s_add_i32 s0, s6, 2
	s_add_i32 s0, s6, 2
	s_lshr_b32 s8, s0, 11
	s_cmp_lt_u32 s0, 0x4000
	s_cselect_b32 s8, s8, 8
	s_cmp_eq_u32 s8, s7
	s_cbranch_scc1 .Lp6_np2
	s_mov_b32 s7, s8
	s_add_i32 s1, s8, 9
	s_mul_i32 s1, s1, 0x6000
	s_add_u32 s44, s84, s1
	s_addc_u32 s45, s85, 0
	s_add_u32 s44, s44, 0x2000
	s_addc_u32 s45, s45, 0
	s_add_i32 s1, s8, 9
	s_mul_i32 s1, s1, 0x6000
	s_add_u32 s36, s84, s1
	s_addc_u32 s37, s85, 0
	s_add_u32 s38, s80, 0x2000
	s_addc_u32 s39, s81, 0
	s_mul_i32 s1, s8, 0x6000
	s_add_u32 s34, s84, s1
	s_addc_u32 s35, s85, 0
	s_add_u32 s34, s34, 0x4000
	s_addc_u32 s35, s35, 0
	global_load_dwordx4 v[96:99], v192, s[34:35] offset:0
	global_load_dwordx4 v[200:203], v192, s[82:83] offset:0
	global_load_dwordx4 v[100:103], v192, s[34:35] offset:1024
	global_load_dwordx4 v[204:207], v192, s[82:83] offset:1024
	global_load_dwordx4 v[104:107], v192, s[34:35] offset:2048
	global_load_dwordx4 v[208:211], v192, s[82:83] offset:2048
	global_load_dwordx4 v[108:111], v192, s[34:35] offset:3072
	global_load_dwordx4 v[212:215], v192, s[82:83] offset:3072
	s_waitcnt vmcnt(0)
	v_mul_f32_e32 v96, v96, v200
	v_mul_f32_e32 v97, v97, v201
	v_mul_f32_e32 v98, v98, v202
	v_mul_f32_e32 v99, v99, v203
	v_mul_f32_e32 v100, v100, v204
	v_mul_f32_e32 v101, v101, v205
	v_mul_f32_e32 v102, v102, v206
	v_mul_f32_e32 v103, v103, v207
	v_mul_f32_e32 v104, v104, v208
	v_mul_f32_e32 v105, v105, v209
	v_mul_f32_e32 v106, v106, v210
	v_mul_f32_e32 v107, v107, v211
	v_mul_f32_e32 v108, v108, v212
	v_mul_f32_e32 v109, v109, v213
	v_mul_f32_e32 v110, v110, v214
	v_mul_f32_e32 v111, v111, v215
	global_load_dwordx4 v[128:131], v192, s[38:39] offset:0
	global_load_dwordx4 v[200:203], v192, s[44:45] offset:0
	global_load_dwordx4 v[160:163], v192, s[36:37] offset:0
	global_load_dwordx4 v[132:135], v192, s[38:39] offset:1024
	global_load_dwordx4 v[204:207], v192, s[44:45] offset:1024
	global_load_dwordx4 v[164:167], v192, s[36:37] offset:1024
	global_load_dwordx4 v[136:139], v192, s[38:39] offset:2048
	global_load_dwordx4 v[208:211], v192, s[44:45] offset:2048
	global_load_dwordx4 v[168:171], v192, s[36:37] offset:2048
	global_load_dwordx4 v[140:143], v192, s[38:39] offset:3072
	global_load_dwordx4 v[212:215], v192, s[44:45] offset:3072
	global_load_dwordx4 v[172:175], v192, s[36:37] offset:3072
	s_waitcnt vmcnt(0)
	v_add_f32_e32 v200, 1.0, v200
	v_add_f32_e32 v201, 1.0, v201
	v_add_f32_e32 v202, 1.0, v202
	v_add_f32_e32 v203, 1.0, v203
	v_mul_f32_e32 v128, v128, v200
	v_mul_f32_e32 v129, v129, v201
	v_mul_f32_e32 v130, v130, v202
	v_mul_f32_e32 v131, v131, v203
	v_add_f32_e32 v204, 1.0, v204
	v_add_f32_e32 v205, 1.0, v205
	v_add_f32_e32 v206, 1.0, v206
	v_add_f32_e32 v207, 1.0, v207
	v_mul_f32_e32 v132, v132, v204
	v_mul_f32_e32 v133, v133, v205
	v_mul_f32_e32 v134, v134, v206
	v_mul_f32_e32 v135, v135, v207
	v_add_f32_e32 v208, 1.0, v208
	v_add_f32_e32 v209, 1.0, v209
	v_add_f32_e32 v210, 1.0, v210
	v_add_f32_e32 v211, 1.0, v211
	v_mul_f32_e32 v136, v136, v208
	v_mul_f32_e32 v137, v137, v209
	v_mul_f32_e32 v138, v138, v210
	v_mul_f32_e32 v139, v139, v211
	v_add_f32_e32 v212, 1.0, v212
	v_add_f32_e32 v213, 1.0, v213
	v_add_f32_e32 v214, 1.0, v214
	v_add_f32_e32 v215, 1.0, v215
	v_mul_f32_e32 v140, v140, v212
	v_mul_f32_e32 v141, v141, v213
	v_mul_f32_e32 v142, v142, v214
	v_mul_f32_e32 v143, v143, v215
	global_load_dwordx4 v[112:115], v193, s[34:35] offset:0
	global_load_dwordx4 v[200:203], v193, s[82:83] offset:0
	global_load_dwordx4 v[116:119], v193, s[34:35] offset:1024
	global_load_dwordx4 v[204:207], v193, s[82:83] offset:1024
	global_load_dwordx4 v[120:123], v193, s[34:35] offset:2048
	global_load_dwordx4 v[208:211], v193, s[82:83] offset:2048
	global_load_dwordx4 v[124:127], v193, s[34:35] offset:3072
	global_load_dwordx4 v[212:215], v193, s[82:83] offset:3072
	s_waitcnt vmcnt(0)
; __device__ __forceinline__ float bf_lo(unsigned w) { return __uint_as_float(w << 16); }
; __device__ __forceinline__ float bf_hi(unsigned w) { return __uint_as_float(w & 0xffff0000u); }
; __device__ __forceinline__ void modulate_store(const f32x4 (&v)[8], float rstd, const float* pn, const float* modr, bf16_t* orow, int lane) {
;     ...
;         const f32x4 g = *(const f32x4*)(pn + col), sh = *(const f32x4*)(modr + col), sc = *(const f32x4*)(modr + DM + col);
;         const f32x4 hh = v[j] * rstd * g * (sc + 1.f) + sh;
; __global__ void __launch_bounds__(NWAVES * 64, 2) mk_fwd(Args args) {
;     ...
;             for (int q = 0; q < 3; ++q) { const int row = row0 + q; const bool lat = row < ML; const int r = lat ? row / SEQ : 8;
;                 float sy = 0.f;
; #pragma unroll
;                 for (int j = 0; j < 8; ++j) { const float a = bf_lo(yw[q][j].x), b = bf_hi(yw[q][j].x), c2 = bf_lo(yw[q][j].y), d = bf_hi(yw[q][j].y); sy += (a * a + b * b) + (c2 * c2 + d * d); }
;                 const float rsy = __builtin_amdgcn_rsqf(wave_sum(sy) * (1.f / DM) + EPS);
;                 const float* m0 = mod + (size_t)r * 6144;
; #pragma unroll
;                 for (int j = 0; j < 8; ++j) { const int col = 4 * F.lane + 256 * j; const f32x4 gt = *(const f32x4*)(m0 + 2 * DM + col), pn = *(const f32x4*)(post_norm + col);
;                     const f32x4 y4 = (f32x4){bf_lo(yw[q][j].x), bf_hi(yw[q][j].x), bf_lo(yw[q][j].y), bf_hi(yw[q][j].y)};
;                     v[q][j] = v[q][j] + gt * (y4 * rsy * pn);
;                     if (lat) *(f32x4*)(args.out + (size_t)row * DM + col) = v[q][j]; }
	v_mul_f32_e32 v112, v112, v200
	v_mul_f32_e32 v113, v113, v201
	v_mul_f32_e32 v114, v114, v202
	v_mul_f32_e32 v115, v115, v203
	v_mul_f32_e32 v116, v116, v204
	v_mul_f32_e32 v117, v117, v205
	v_mul_f32_e32 v118, v118, v206
	v_mul_f32_e32 v119, v119, v207
	v_mul_f32_e32 v120, v120, v208
	v_mul_f32_e32 v121, v121, v209
	v_mul_f32_e32 v122, v122, v210
	v_mul_f32_e32 v123, v123, v211
	v_mul_f32_e32 v124, v124, v212
	v_mul_f32_e32 v125, v125, v213
	v_mul_f32_e32 v126, v126, v214
	v_mul_f32_e32 v127, v127, v215
	global_load_dwordx4 v[144:147], v193, s[38:39] offset:0
	global_load_dwordx4 v[200:203], v193, s[44:45] offset:0
	global_load_dwordx4 v[176:179], v193, s[36:37] offset:0
	global_load_dwordx4 v[148:151], v193, s[38:39] offset:1024
	global_load_dwordx4 v[204:207], v193, s[44:45] offset:1024
	global_load_dwordx4 v[180:183], v193, s[36:37] offset:1024
	global_load_dwordx4 v[152:155], v193, s[38:39] offset:2048
	global_load_dwordx4 v[208:211], v193, s[44:45] offset:2048
	global_load_dwordx4 v[184:187], v193, s[36:37] offset:2048
	global_load_dwordx4 v[156:159], v193, s[38:39] offset:3072
	global_load_dwordx4 v[212:215], v193, s[44:45] offset:3072
	global_load_dwordx4 v[188:191], v193, s[36:37] offset:3072
	s_waitcnt vmcnt(0)
	v_add_f32_e32 v200, 1.0, v200
	v_add_f32_e32 v201, 1.0, v201
	v_add_f32_e32 v202, 1.0, v202
	v_add_f32_e32 v203, 1.0, v203
	v_mul_f32_e32 v144, v144, v200
	v_mul_f32_e32 v145, v145, v201
	v_mul_f32_e32 v146, v146, v202
	v_mul_f32_e32 v147, v147, v203
	v_add_f32_e32 v204, 1.0, v204
	v_add_f32_e32 v205, 1.0, v205
	v_add_f32_e32 v206, 1.0, v206
	v_add_f32_e32 v207, 1.0, v207
	v_mul_f32_e32 v148, v148, v204
	v_mul_f32_e32 v149, v149, v205
	v_mul_f32_e32 v150, v150, v206
	v_mul_f32_e32 v151, v151, v207
	v_add_f32_e32 v208, 1.0, v208
	v_add_f32_e32 v209, 1.0, v209
	v_add_f32_e32 v210, 1.0, v210
	v_add_f32_e32 v211, 1.0, v211
	v_mul_f32_e32 v152, v152, v208
	v_mul_f32_e32 v153, v153, v209
	v_mul_f32_e32 v154, v154, v210
	v_mul_f32_e32 v155, v155, v211
	v_add_f32_e32 v212, 1.0, v212
	v_add_f32_e32 v213, 1.0, v213
	v_add_f32_e32 v214, 1.0, v214
	v_add_f32_e32 v215, 1.0, v215
	v_mul_f32_e32 v156, v156, v212
	v_mul_f32_e32 v157, v157, v213
	v_mul_f32_e32 v158, v158, v214
	v_mul_f32_e32 v159, v159, v215
.Lp6_np2:
	s_waitcnt vmcnt(32)
	v_lshlrev_b32_e32 v216, 16, v32
	v_and_b32_e32 v217, 0xffff0000, v32
	v_lshlrev_b32_e32 v218, 16, v33
	v_and_b32_e32 v219, 0xffff0000, v33
	v_mul_f32_e32 v222, v216, v216
	v_mul_f32_e32 v223, v217, v217
	v_fmac_f32_e32 v222, v218, v218
	v_fmac_f32_e32 v223, v219, v219
	v_lshlrev_b32_e32 v216, 16, v34
	v_and_b32_e32 v217, 0xffff0000, v34
	v_lshlrev_b32_e32 v218, 16, v35
	v_and_b32_e32 v219, 0xffff0000, v35
	v_fmac_f32_e32 v222, v216, v216
	v_fmac_f32_e32 v223, v217, v217
	v_fmac_f32_e32 v222, v218, v218
	v_fmac_f32_e32 v223, v219, v219
	v_lshlrev_b32_e32 v216, 16, v36
	v_and_b32_e32 v217, 0xffff0000, v36
	v_lshlrev_b32_e32 v218, 16, v37
	v_and_b32_e32 v219, 0xffff0000, v37
	v_fmac_f32_e32 v222, v216, v216
	v_fmac_f32_e32 v223, v217, v217
	v_fmac_f32_e32 v222, v218, v218
	v_fmac_f32_e32 v223, v219, v219
	v_lshlrev_b32_e32 v216, 16, v38
	v_and_b32_e32 v217, 0xffff0000, v38
	v_lshlrev_b32_e32 v218, 16, v39
	v_and_b32_e32 v219, 0xffff0000, v39
	v_fmac_f32_e32 v222, v216, v216
	v_fmac_f32_e32 v223, v217, v217
	v_fmac_f32_e32 v222, v218, v218
	v_fmac_f32_e32 v223, v219, v219
	v_lshlrev_b32_e32 v216, 16, v40
	v_and_b32_e32 v217, 0xffff0000, v40
	v_lshlrev_b32_e32 v218, 16, v41
	v_and_b32_e32 v219, 0xffff0000, v41
	v_fmac_f32_e32 v222, v216, v216
	v_fmac_f32_e32 v223, v217, v217
	v_fmac_f32_e32 v222, v218, v218
	v_fmac_f32_e32 v223, v219, v219
	v_lshlrev_b32_e32 v216, 16, v42
	v_and_b32_e32 v217, 0xffff0000, v42
	v_lshlrev_b32_e32 v218, 16, v43
	v_and_b32_e32 v219, 0xffff0000, v43
	v_fmac_f32_e32 v222, v216, v216
	v_fmac_f32_e32 v223, v217, v217
	v_fmac_f32_e32 v222, v218, v218
	v_fmac_f32_e32 v223, v219, v219
	v_lshlrev_b32_e32 v216, 16, v44
	v_and_b32_e32 v217, 0xffff0000, v44
	v_lshlrev_b32_e32 v218, 16, v45
	v_and_b32_e32 v219, 0xffff0000, v45
	v_fmac_f32_e32 v222, v216, v216
	v_fmac_f32_e32 v223, v217, v217
	v_fmac_f32_e32 v222, v218, v218
	v_fmac_f32_e32 v223, v219, v219
	v_lshlrev_b32_e32 v216, 16, v46
	v_and_b32_e32 v217, 0xffff0000, v46
	v_lshlrev_b32_e32 v218, 16, v47
	v_and_b32_e32 v219, 0xffff0000, v47
	v_fmac_f32_e32 v222, v216, v216
	v_fmac_f32_e32 v223, v217, v217
	v_fmac_f32_e32 v222, v218, v218
	v_fmac_f32_e32 v223, v219, v219
	v_add_f32_e32 v222, v222, v223
	s_nop 1
	v_add_f32_dpp v224, v222, v222 quad_perm:[1,0,3,2] row_mask:0xf bank_mask:0xf
	s_nop 1
	v_add_f32_dpp v224, v224, v224 quad_perm:[2,3,0,1] row_mask:0xf bank_mask:0xf
	s_nop 1
	v_add_f32_dpp v224, v224, v224 row_half_mirror row_mask:0xf bank_mask:0xf
	s_nop 1
	v_add_f32_dpp v224, v224, v224 row_mirror row_mask:0xf bank_mask:0xf
	s_nop 1
	v_readlane_b32 s40, v224, 0
	v_readlane_b32 s41, v224, 16
	v_readlane_b32 s42, v224, 32
	v_readlane_b32 s43, v224, 48
	s_nop 1
	v_mov_b32_e32 v225, s40
	v_add_f32_e32 v225, s41, v225
	v_add_f32_e32 v225, s42, v225
	v_add_f32_e32 v225, s43, v225
	v_fmamk_f32 v225, v225, 0x3a000000, v195
	v_rsq_f32_e32 v225, v225
	s_nop 0
	s_add_i32 s0, s6, 2
	s_cmp_lt_u32 s0, 0x4000
	s_cselect_b32 s24, s94, s84
	s_cselect_b32 s25, s95, s85
	s_cselect_b32 s44, 0, 0x16000000
	s_cselect_b32 s1, 0, 0x4000
	s_sub_i32 s1, s0, s1
	s_lshl_b32 s1, s1, 13
	s_add_u32 s24, s24, s1
	s_addc_u32 s25, s25, 0
	s_add_u32 s24, s24, s44
	s_addc_u32 s25, s25, 0
	v_lshlrev_b32_e32 v216, 16, v32
	v_and_b32_e32 v217, 0xffff0000, v32
	v_lshlrev_b32_e32 v218, 16, v33
	v_and_b32_e32 v219, 0xffff0000, v33
	v_mul_f32_e32 v216, v225, v216
; __device__ __forceinline__ unsigned cvt_pk_bf16(float lo, float hi) { unsigned r; asm volatile("v_cvt_pk_bf16_f32 %0, %1, %2" : "=v"(r) : "v"(lo), "v"(hi)); return r; }
; __device__ __forceinline__ float bf_lo(unsigned w) { return __uint_as_float(w << 16); }
; __device__ __forceinline__ float bf_hi(unsigned w) { return __uint_as_float(w & 0xffff0000u); }
; __device__ __forceinline__ float sumsq8(const f32x4 (&v)[8]) {
;     float s = 0.f;
; #pragma unroll
;     for (int j = 0; j < 8; ++j) s += (v[j][0] * v[j][0] + v[j][1] * v[j][1]) + (v[j][2] * v[j][2] + v[j][3] * v[j][3]);
;     return wave_sum(s);
; }
; __device__ __forceinline__ void modulate_store(const f32x4 (&v)[8], float rstd, const float* pn, const float* modr, bf16_t* orow, int lane) {
; #pragma unroll
;     for (int j = 0; j < 8; ++j) { const int col = 4 * lane + 256 * j;
;         const f32x4 g = *(const f32x4*)(pn + col), sh = *(const f32x4*)(modr + col), sc = *(const f32x4*)(modr + DM + col);
;         const f32x4 hh = v[j] * rstd * g * (sc + 1.f) + sh;
;         u32x2 w; w.x = cvt_pk_bf16(hh[0], hh[1]); w.y = cvt_pk_bf16(hh[2], hh[3]);
;         *(u32x2*)(orow + col) = w; }
; }
; __global__ void __launch_bounds__(NWAVES * 64, 2) mk_fwd(Args args) {
;     ...
;                 for (int j = 0; j < 8; ++j) { const int col = 4 * F.lane + 256 * j; const f32x4 gt = *(const f32x4*)(m0 + 2 * DM + col), pn = *(const f32x4*)(post_norm + col);
;                     const f32x4 y4 = (f32x4){bf_lo(yw[q][j].x), bf_hi(yw[q][j].x), bf_lo(yw[q][j].y), bf_hi(yw[q][j].y)};
;                     v[q][j] = v[q][j] + gt * (y4 * rsy * pn);
;                     if (lat) *(f32x4*)(args.out + (size_t)row * DM + col) = v[q][j]; }
;                 const float rstd = __builtin_amdgcn_rsqf(sumsq8(v[q]) * (1.f / DM) + EPS);
;                 modulate_store(v[q], rstd, pre_norm + DM, mod + (size_t)(9 + r) * 6144, H + (size_t)row * DM, F.lane); }
	v_mul_f32_e32 v217, v225, v217
	v_mul_f32_e32 v218, v225, v218
	v_mul_f32_e32 v219, v225, v219
	v_fmac_f32_e32 v0, v96, v216
	v_fmac_f32_e32 v1, v97, v217
	v_fmac_f32_e32 v2, v98, v218
	v_fmac_f32_e32 v3, v99, v219
	global_store_dwordx4 v192, v[0:3], s[24:25] offset:0
	v_lshlrev_b32_e32 v216, 16, v34
	v_and_b32_e32 v217, 0xffff0000, v34
	v_lshlrev_b32_e32 v218, 16, v35
	v_and_b32_e32 v219, 0xffff0000, v35
	v_mul_f32_e32 v216, v225, v216
	v_mul_f32_e32 v217, v225, v217
	v_mul_f32_e32 v218, v225, v218
	v_mul_f32_e32 v219, v225, v219
	v_fmac_f32_e32 v4, v100, v216
	v_fmac_f32_e32 v5, v101, v217
	v_fmac_f32_e32 v6, v102, v218
	v_fmac_f32_e32 v7, v103, v219
	global_store_dwordx4 v192, v[4:7], s[24:25] offset:1024
	v_lshlrev_b32_e32 v216, 16, v36
	v_and_b32_e32 v217, 0xffff0000, v36
	v_lshlrev_b32_e32 v218, 16, v37
	v_and_b32_e32 v219, 0xffff0000, v37
	v_mul_f32_e32 v216, v225, v216
	v_mul_f32_e32 v217, v225, v217
	v_mul_f32_e32 v218, v225, v218
	v_mul_f32_e32 v219, v225, v219
	v_fmac_f32_e32 v8, v104, v216
	v_fmac_f32_e32 v9, v105, v217
	v_fmac_f32_e32 v10, v106, v218
	v_fmac_f32_e32 v11, v107, v219
	global_store_dwordx4 v192, v[8:11], s[24:25] offset:2048
	v_lshlrev_b32_e32 v216, 16, v38
	v_and_b32_e32 v217, 0xffff0000, v38
	v_lshlrev_b32_e32 v218, 16, v39
	v_and_b32_e32 v219, 0xffff0000, v39
	v_mul_f32_e32 v216, v225, v216
	v_mul_f32_e32 v217, v225, v217
	v_mul_f32_e32 v218, v225, v218
	v_mul_f32_e32 v219, v225, v219
	v_fmac_f32_e32 v12, v108, v216
	v_fmac_f32_e32 v13, v109, v217
	v_fmac_f32_e32 v14, v110, v218
	v_fmac_f32_e32 v15, v111, v219
	global_store_dwordx4 v192, v[12:15], s[24:25] offset:3072
	v_lshlrev_b32_e32 v216, 16, v40
	v_and_b32_e32 v217, 0xffff0000, v40
	v_lshlrev_b32_e32 v218, 16, v41
	v_and_b32_e32 v219, 0xffff0000, v41
	v_mul_f32_e32 v216, v225, v216
	v_mul_f32_e32 v217, v225, v217
	v_mul_f32_e32 v218, v225, v218
	v_mul_f32_e32 v219, v225, v219
	v_fmac_f32_e32 v16, v112, v216
	v_fmac_f32_e32 v17, v113, v217
	v_fmac_f32_e32 v18, v114, v218
	v_fmac_f32_e32 v19, v115, v219
	global_store_dwordx4 v193, v[16:19], s[24:25] offset:0
	v_lshlrev_b32_e32 v216, 16, v42
	v_and_b32_e32 v217, 0xffff0000, v42
	v_lshlrev_b32_e32 v218, 16, v43
	v_and_b32_e32 v219, 0xffff0000, v43
	v_mul_f32_e32 v216, v225, v216
	v_mul_f32_e32 v217, v225, v217
	v_mul_f32_e32 v218, v225, v218
	v_mul_f32_e32 v219, v225, v219
	v_fmac_f32_e32 v20, v116, v216
	v_fmac_f32_e32 v21, v117, v217
	v_fmac_f32_e32 v22, v118, v218
	v_fmac_f32_e32 v23, v119, v219
	global_store_dwordx4 v193, v[20:23], s[24:25] offset:1024
	v_lshlrev_b32_e32 v216, 16, v44
	v_and_b32_e32 v217, 0xffff0000, v44
	v_lshlrev_b32_e32 v218, 16, v45
	v_and_b32_e32 v219, 0xffff0000, v45
	v_mul_f32_e32 v216, v225, v216
	v_mul_f32_e32 v217, v225, v217
	v_mul_f32_e32 v218, v225, v218
	v_mul_f32_e32 v219, v225, v219
	v_fmac_f32_e32 v24, v120, v216
	v_fmac_f32_e32 v25, v121, v217
	v_fmac_f32_e32 v26, v122, v218
	v_fmac_f32_e32 v27, v123, v219
	global_store_dwordx4 v193, v[24:27], s[24:25] offset:2048
	v_lshlrev_b32_e32 v216, 16, v46
	v_and_b32_e32 v217, 0xffff0000, v46
	v_lshlrev_b32_e32 v218, 16, v47
	v_and_b32_e32 v219, 0xffff0000, v47
	v_mul_f32_e32 v216, v225, v216
	v_mul_f32_e32 v217, v225, v217
	v_mul_f32_e32 v218, v225, v218
	v_mul_f32_e32 v219, v225, v219
	v_fmac_f32_e32 v28, v124, v216
	v_fmac_f32_e32 v29, v125, v217
	v_fmac_f32_e32 v30, v126, v218
	v_fmac_f32_e32 v31, v127, v219
	global_store_dwordx4 v193, v[28:31], s[24:25] offset:3072
	v_mul_f32_e32 v222, v0, v0
	v_mul_f32_e32 v223, v1, v1
	v_fmac_f32_e32 v222, v2, v2
	v_fmac_f32_e32 v223, v3, v3
	v_fmac_f32_e32 v222, v4, v4
	v_fmac_f32_e32 v223, v5, v5
	v_fmac_f32_e32 v222, v6, v6
	v_fmac_f32_e32 v223, v7, v7
	v_fmac_f32_e32 v222, v8, v8
	v_fmac_f32_e32 v223, v9, v9
	v_fmac_f32_e32 v222, v10, v10
	v_fmac_f32_e32 v223, v11, v11
	v_fmac_f32_e32 v222, v12, v12
	v_fmac_f32_e32 v223, v13, v13
	v_fmac_f32_e32 v222, v14, v14
	v_fmac_f32_e32 v223, v15, v15
	v_fmac_f32_e32 v222, v16, v16
	v_fmac_f32_e32 v223, v17, v17
	v_fmac_f32_e32 v222, v18, v18
	v_fmac_f32_e32 v223, v19, v19
	v_fmac_f32_e32 v222, v20, v20
	v_fmac_f32_e32 v223, v21, v21
	v_fmac_f32_e32 v222, v22, v22
	v_fmac_f32_e32 v223, v23, v23
	v_fmac_f32_e32 v222, v24, v24
	v_fmac_f32_e32 v223, v25, v25
	v_fmac_f32_e32 v222, v26, v26
	v_fmac_f32_e32 v223, v27, v27
	v_fmac_f32_e32 v222, v28, v28
	v_fmac_f32_e32 v223, v29, v29
	v_fmac_f32_e32 v222, v30, v30
	v_fmac_f32_e32 v223, v31, v31
	v_add_f32_e32 v222, v222, v223
	s_nop 1
	v_add_f32_dpp v224, v222, v222 quad_perm:[1,0,3,2] row_mask:0xf bank_mask:0xf
	s_nop 1
	v_add_f32_dpp v224, v224, v224 quad_perm:[2,3,0,1] row_mask:0xf bank_mask:0xf
	s_nop 1
	v_add_f32_dpp v224, v224, v224 row_half_mirror row_mask:0xf bank_mask:0xf
	s_nop 1
	v_add_f32_dpp v224, v224, v224 row_mirror row_mask:0xf bank_mask:0xf
	s_nop 1
	v_readlane_b32 s40, v224, 0
	v_readlane_b32 s41, v224, 16
	v_readlane_b32 s42, v224, 32
	v_readlane_b32 s43, v224, 48
	s_nop 1
	v_mov_b32_e32 v225, s40
	v_add_f32_e32 v225, s41, v225
	v_add_f32_e32 v225, s42, v225
	v_add_f32_e32 v225, s43, v225
	v_fmamk_f32 v225, v225, 0x3a000000, v195
	v_rsq_f32_e32 v225, v225
	s_nop 0
	s_add_i32 s0, s6, 2
	s_lshl_b32 s1, s0, 12
	s_add_u32 s26, s84, s1
	s_addc_u32 s27, s85, 0
	s_add_u32 s26, s26, 0x4000000
	s_addc_u32 s27, s27, 0
	v_mul_f32_e32 v216, v225, v0
	v_mul_f32_e32 v217, v225, v1
	v_mul_f32_e32 v218, v225, v2
	v_mul_f32_e32 v219, v225, v3
	v_fma_f32 v216, v216, v128, v160
	v_fma_f32 v217, v217, v129, v161
	v_fma_f32 v218, v218, v130, v162
	v_fma_f32 v219, v219, v131, v163
	v_cvt_pk_bf16_f32 v196, v216, v217
	v_cvt_pk_bf16_f32 v197, v218, v219
	global_store_dwordx2 v194, v[196:197], s[26:27] offset:0
; __device__ __forceinline__ unsigned cvt_pk_bf16(float lo, float hi) { unsigned r; asm volatile("v_cvt_pk_bf16_f32 %0, %1, %2" : "=v"(r) : "v"(lo), "v"(hi)); return r; }
; __device__ __forceinline__ float bf_lo(unsigned w) { return __uint_as_float(w << 16); }
; __device__ __forceinline__ float bf_hi(unsigned w) { return __uint_as_float(w & 0xffff0000u); }
; __device__ __forceinline__ void modulate_store(const f32x4 (&v)[8], float rstd, const float* pn, const float* modr, bf16_t* orow, int lane) {
; #pragma unroll
;     for (int j = 0; j < 8; ++j) { const int col = 4 * lane + 256 * j;
;         const f32x4 g = *(const f32x4*)(pn + col), sh = *(const f32x4*)(modr + col), sc = *(const f32x4*)(modr + DM + col);
;         const f32x4 hh = v[j] * rstd * g * (sc + 1.f) + sh;
;         u32x2 w; w.x = cvt_pk_bf16(hh[0], hh[1]); w.y = cvt_pk_bf16(hh[2], hh[3]);
;         *(u32x2*)(orow + col) = w; }
; }
; __global__ void __launch_bounds__(NWAVES * 64, 2) mk_fwd(Args args) {
;     ...
;         for (int row0 = F.gw * 3; row0 < MT; row0 += F.NGW * 3) {
;             f32x4 v[3][8]; u32x2 yw[3][8];
; #pragma unroll
;             for (int q = 0; q < 3; ++q) { const int row = row0 + q; const float* src = row < ML ? x + (size_t)row * DM : ctx + (size_t)(row - ML) * DM; load_row_f32(src, F.lane, v[q]);
;                 const bf16_t* yr = Y + (size_t)row * DM;
; #pragma unroll
;                 for (int j = 0; j < 8; ++j) yw[q][j] = *(const u32x2*)(yr + 4 * F.lane + 256 * j); }
; #pragma unroll
;             for (int q = 0; q < 3; ++q) { const int row = row0 + q; const bool lat = row < ML; const int r = lat ? row / SEQ : 8;
;                 float sy = 0.f;
; #pragma unroll
;                 for (int j = 0; j < 8; ++j) { const float a = bf_lo(yw[q][j].x), b = bf_hi(yw[q][j].x), c2 = bf_lo(yw[q][j].y), d = bf_hi(yw[q][j].y); sy += (a * a + b * b) + (c2 * c2 + d * d); }
;                 const float rsy = __builtin_amdgcn_rsqf(wave_sum(sy) * (1.f / DM) + EPS);
;                 const float* m0 = mod + (size_t)r * 6144;
; #pragma unroll
;                 for (int j = 0; j < 8; ++j) { const int col = 4 * F.lane + 256 * j; const f32x4 gt = *(const f32x4*)(m0 + 2 * DM + col), pn = *(const f32x4*)(post_norm + col);
	v_mul_f32_e32 v216, v225, v4
	v_mul_f32_e32 v217, v225, v5
	v_mul_f32_e32 v218, v225, v6
	v_mul_f32_e32 v219, v225, v7
	v_fma_f32 v216, v216, v132, v164
	v_fma_f32 v217, v217, v133, v165
	v_fma_f32 v218, v218, v134, v166
	v_fma_f32 v219, v219, v135, v167
	v_cvt_pk_bf16_f32 v220, v216, v217
	v_cvt_pk_bf16_f32 v221, v218, v219
	global_store_dwordx2 v194, v[220:221], s[26:27] offset:512
	v_mul_f32_e32 v216, v225, v8
	v_mul_f32_e32 v217, v225, v9
	v_mul_f32_e32 v218, v225, v10
	v_mul_f32_e32 v219, v225, v11
	v_fma_f32 v216, v216, v136, v168
	v_fma_f32 v217, v217, v137, v169
	v_fma_f32 v218, v218, v138, v170
	v_fma_f32 v219, v219, v139, v171
	v_cvt_pk_bf16_f32 v196, v216, v217
	v_cvt_pk_bf16_f32 v197, v218, v219
	global_store_dwordx2 v194, v[196:197], s[26:27] offset:1024
	v_mul_f32_e32 v216, v225, v12
	v_mul_f32_e32 v217, v225, v13
	v_mul_f32_e32 v218, v225, v14
	v_mul_f32_e32 v219, v225, v15
	v_fma_f32 v216, v216, v140, v172
	v_fma_f32 v217, v217, v141, v173
	v_fma_f32 v218, v218, v142, v174
	v_fma_f32 v219, v219, v143, v175
	v_cvt_pk_bf16_f32 v220, v216, v217
	v_cvt_pk_bf16_f32 v221, v218, v219
	global_store_dwordx2 v194, v[220:221], s[26:27] offset:1536
	v_mul_f32_e32 v216, v225, v16
	v_mul_f32_e32 v217, v225, v17
	v_mul_f32_e32 v218, v225, v18
	v_mul_f32_e32 v219, v225, v19
	v_fma_f32 v216, v216, v144, v176
	v_fma_f32 v217, v217, v145, v177
	v_fma_f32 v218, v218, v146, v178
	v_fma_f32 v219, v219, v147, v179
	v_cvt_pk_bf16_f32 v196, v216, v217
	v_cvt_pk_bf16_f32 v197, v218, v219
	global_store_dwordx2 v194, v[196:197], s[26:27] offset:2048
	v_mul_f32_e32 v216, v225, v20
	v_mul_f32_e32 v217, v225, v21
	v_mul_f32_e32 v218, v225, v22
	v_mul_f32_e32 v219, v225, v23
	v_fma_f32 v216, v216, v148, v180
	v_fma_f32 v217, v217, v149, v181
	v_fma_f32 v218, v218, v150, v182
	v_fma_f32 v219, v219, v151, v183
	v_cvt_pk_bf16_f32 v220, v216, v217
	v_cvt_pk_bf16_f32 v221, v218, v219
	global_store_dwordx2 v194, v[220:221], s[26:27] offset:2560
	v_mul_f32_e32 v216, v225, v24
	v_mul_f32_e32 v217, v225, v25
	v_mul_f32_e32 v218, v225, v26
	v_mul_f32_e32 v219, v225, v27
	v_fma_f32 v216, v216, v152, v184
	v_fma_f32 v217, v217, v153, v185
	v_fma_f32 v218, v218, v154, v186
	v_fma_f32 v219, v219, v155, v187
	v_cvt_pk_bf16_f32 v196, v216, v217
	v_cvt_pk_bf16_f32 v197, v218, v219
	global_store_dwordx2 v194, v[196:197], s[26:27] offset:3072
	v_mul_f32_e32 v216, v225, v28
	v_mul_f32_e32 v217, v225, v29
	v_mul_f32_e32 v218, v225, v30
	v_mul_f32_e32 v219, v225, v31
	v_fma_f32 v216, v216, v156, v188
	v_fma_f32 v217, v217, v157, v189
	v_fma_f32 v218, v218, v158, v190
	v_fma_f32 v219, v219, v159, v191
	v_cvt_pk_bf16_f32 v220, v216, v217
	v_cvt_pk_bf16_f32 v221, v218, v219
	global_store_dwordx2 v194, v[220:221], s[26:27] offset:3584
	s_add_i32 s0, s6, 4
	s_cmp_lt_u32 s0, 0x4000
	s_cselect_b32 s10, s68, s72
	s_cselect_b32 s11, s69, s73
	s_cselect_b32 s1, 0, 0x4000
	s_sub_i32 s1, s0, s1
	s_lshl_b32 s1, s1, 13
	s_add_u32 s10, s10, s1
	s_addc_u32 s11, s11, 0
	s_add_i32 s0, s6, 4
	s_lshl_b32 s1, s0, 12
	s_add_u32 s22, s84, s1
	s_addc_u32 s23, s85, 0
	s_add_u32 s22, s22, 0x11800000
	s_addc_u32 s23, s23, 0
	global_load_dwordx4 v[0:3], v192, s[10:11] offset:0
	global_load_dwordx4 v[4:7], v192, s[10:11] offset:1024
	global_load_dwordx4 v[8:11], v192, s[10:11] offset:2048
	global_load_dwordx4 v[12:15], v192, s[10:11] offset:3072
	global_load_dwordx4 v[16:19], v193, s[10:11] offset:0
	global_load_dwordx4 v[20:23], v193, s[10:11] offset:1024
	global_load_dwordx4 v[24:27], v193, s[10:11] offset:2048
	global_load_dwordx4 v[28:31], v193, s[10:11] offset:3072
	global_load_dwordx2 v[32:33], v194, s[22:23] offset:0
	global_load_dwordx2 v[34:35], v194, s[22:23] offset:512
	global_load_dwordx2 v[36:37], v194, s[22:23] offset:1024
	global_load_dwordx2 v[38:39], v194, s[22:23] offset:1536
	global_load_dwordx2 v[40:41], v194, s[22:23] offset:2048
	global_load_dwordx2 v[42:43], v194, s[22:23] offset:2560
	global_load_dwordx2 v[44:45], v194, s[22:23] offset:3072
	global_load_dwordx2 v[46:47], v194, s[22:23] offset:3584
	s_add_i32 s0, s6, 3
	s_add_i32 s0, s6, 3
	s_lshr_b32 s8, s0, 11
	s_cmp_lt_u32 s0, 0x4000
	s_cselect_b32 s8, s8, 8
	s_cmp_eq_u32 s8, s7
	s_cbranch_scc1 .Lp6_np3
	s_mov_b32 s7, s8
	s_add_i32 s1, s8, 9
	s_mul_i32 s1, s1, 0x6000
	s_add_u32 s44, s84, s1
	s_addc_u32 s45, s85, 0
	s_add_u32 s44, s44, 0x2000
	s_addc_u32 s45, s45, 0
	s_add_i32 s1, s8, 9
	s_mul_i32 s1, s1, 0x6000
	s_add_u32 s36, s84, s1
	s_addc_u32 s37, s85, 0
	s_add_u32 s38, s80, 0x2000
	s_addc_u32 s39, s81, 0
	s_mul_i32 s1, s8, 0x6000
	s_add_u32 s34, s84, s1
	s_addc_u32 s35, s85, 0
	s_add_u32 s34, s34, 0x4000
	s_addc_u32 s35, s35, 0
	global_load_dwordx4 v[96:99], v192, s[34:35] offset:0
	global_load_dwordx4 v[200:203], v192, s[82:83] offset:0
	global_load_dwordx4 v[100:103], v192, s[34:35] offset:1024
	global_load_dwordx4 v[204:207], v192, s[82:83] offset:1024
	global_load_dwordx4 v[104:107], v192, s[34:35] offset:2048
	global_load_dwordx4 v[208:211], v192, s[82:83] offset:2048
	global_load_dwordx4 v[108:111], v192, s[34:35] offset:3072
	global_load_dwordx4 v[212:215], v192, s[82:83] offset:3072
	s_waitcnt vmcnt(0)
; __device__ __forceinline__ void modulate_store(const f32x4 (&v)[8], float rstd, const float* pn, const float* modr, bf16_t* orow, int lane) {
;     ...
;         const f32x4 g = *(const f32x4*)(pn + col), sh = *(const f32x4*)(modr + col), sc = *(const f32x4*)(modr + DM + col);
;         const f32x4 hh = v[j] * rstd * g * (sc + 1.f) + sh;
; __global__ void __launch_bounds__(NWAVES * 64, 2) mk_fwd(Args args) {
;     ...
;                 const float* m0 = mod + (size_t)r * 6144;
; #pragma unroll
;                 for (int j = 0; j < 8; ++j) { const int col = 4 * F.lane + 256 * j; const f32x4 gt = *(const f32x4*)(m0 + 2 * DM + col), pn = *(const f32x4*)(post_norm + col);
	v_mul_f32_e32 v96, v96, v200
	v_mul_f32_e32 v97, v97, v201
	v_mul_f32_e32 v98, v98, v202
	v_mul_f32_e32 v99, v99, v203
	v_mul_f32_e32 v100, v100, v204
	v_mul_f32_e32 v101, v101, v205
	v_mul_f32_e32 v102, v102, v206
	v_mul_f32_e32 v103, v103, v207
	v_mul_f32_e32 v104, v104, v208
	v_mul_f32_e32 v105, v105, v209
	v_mul_f32_e32 v106, v106, v210
	v_mul_f32_e32 v107, v107, v211
	v_mul_f32_e32 v108, v108, v212
	v_mul_f32_e32 v109, v109, v213
	v_mul_f32_e32 v110, v110, v214
	v_mul_f32_e32 v111, v111, v215
	global_load_dwordx4 v[128:131], v192, s[38:39] offset:0
	global_load_dwordx4 v[200:203], v192, s[44:45] offset:0
	global_load_dwordx4 v[160:163], v192, s[36:37] offset:0
	global_load_dwordx4 v[132:135], v192, s[38:39] offset:1024
	global_load_dwordx4 v[204:207], v192, s[44:45] offset:1024
	global_load_dwordx4 v[164:167], v192, s[36:37] offset:1024
	global_load_dwordx4 v[136:139], v192, s[38:39] offset:2048
	global_load_dwordx4 v[208:211], v192, s[44:45] offset:2048
	global_load_dwordx4 v[168:171], v192, s[36:37] offset:2048
	global_load_dwordx4 v[140:143], v192, s[38:39] offset:3072
	global_load_dwordx4 v[212:215], v192, s[44:45] offset:3072
	global_load_dwordx4 v[172:175], v192, s[36:37] offset:3072
	s_waitcnt vmcnt(0)
	v_add_f32_e32 v200, 1.0, v200
	v_add_f32_e32 v201, 1.0, v201
	v_add_f32_e32 v202, 1.0, v202
	v_add_f32_e32 v203, 1.0, v203
	v_mul_f32_e32 v128, v128, v200
	v_mul_f32_e32 v129, v129, v201
	v_mul_f32_e32 v130, v130, v202
	v_mul_f32_e32 v131, v131, v203
	v_add_f32_e32 v204, 1.0, v204
	v_add_f32_e32 v205, 1.0, v205
	v_add_f32_e32 v206, 1.0, v206
	v_add_f32_e32 v207, 1.0, v207
	v_mul_f32_e32 v132, v132, v204
	v_mul_f32_e32 v133, v133, v205
	v_mul_f32_e32 v134, v134, v206
	v_mul_f32_e32 v135, v135, v207
	v_add_f32_e32 v208, 1.0, v208
	v_add_f32_e32 v209, 1.0, v209
	v_add_f32_e32 v210, 1.0, v210
	v_add_f32_e32 v211, 1.0, v211
	v_mul_f32_e32 v136, v136, v208
	v_mul_f32_e32 v137, v137, v209
	v_mul_f32_e32 v138, v138, v210
	v_mul_f32_e32 v139, v139, v211
	v_add_f32_e32 v212, 1.0, v212
	v_add_f32_e32 v213, 1.0, v213
	v_add_f32_e32 v214, 1.0, v214
	v_add_f32_e32 v215, 1.0, v215
	v_mul_f32_e32 v140, v140, v212
	v_mul_f32_e32 v141, v141, v213
	v_mul_f32_e32 v142, v142, v214
	v_mul_f32_e32 v143, v143, v215
	global_load_dwordx4 v[112:115], v193, s[34:35] offset:0
	global_load_dwordx4 v[200:203], v193, s[82:83] offset:0
	global_load_dwordx4 v[116:119], v193, s[34:35] offset:1024
	global_load_dwordx4 v[204:207], v193, s[82:83] offset:1024
	global_load_dwordx4 v[120:123], v193, s[34:35] offset:2048
	global_load_dwordx4 v[208:211], v193, s[82:83] offset:2048
	global_load_dwordx4 v[124:127], v193, s[34:35] offset:3072
	global_load_dwordx4 v[212:215], v193, s[82:83] offset:3072
	s_waitcnt vmcnt(0)
	v_mul_f32_e32 v112, v112, v200
	v_mul_f32_e32 v113, v113, v201
	v_mul_f32_e32 v114, v114, v202
	v_mul_f32_e32 v115, v115, v203
	v_mul_f32_e32 v116, v116, v204
	v_mul_f32_e32 v117, v117, v205
	v_mul_f32_e32 v118, v118, v206
	v_mul_f32_e32 v119, v119, v207
	v_mul_f32_e32 v120, v120, v208
	v_mul_f32_e32 v121, v121, v209
	v_mul_f32_e32 v122, v122, v210
	v_mul_f32_e32 v123, v123, v211
	v_mul_f32_e32 v124, v124, v212
	v_mul_f32_e32 v125, v125, v213
	v_mul_f32_e32 v126, v126, v214
	v_mul_f32_e32 v127, v127, v215
	global_load_dwordx4 v[144:147], v193, s[38:39] offset:0
	global_load_dwordx4 v[200:203], v193, s[44:45] offset:0
	global_load_dwordx4 v[176:179], v193, s[36:37] offset:0
	global_load_dwordx4 v[148:151], v193, s[38:39] offset:1024
	global_load_dwordx4 v[204:207], v193, s[44:45] offset:1024
	global_load_dwordx4 v[180:183], v193, s[36:37] offset:1024
	global_load_dwordx4 v[152:155], v193, s[38:39] offset:2048
	global_load_dwordx4 v[208:211], v193, s[44:45] offset:2048
	global_load_dwordx4 v[184:187], v193, s[36:37] offset:2048
	global_load_dwordx4 v[156:159], v193, s[38:39] offset:3072
	global_load_dwordx4 v[212:215], v193, s[44:45] offset:3072
	global_load_dwordx4 v[188:191], v193, s[36:37] offset:3072
	s_waitcnt vmcnt(0)
	v_add_f32_e32 v200, 1.0, v200
	v_add_f32_e32 v201, 1.0, v201
	v_add_f32_e32 v202, 1.0, v202
	v_add_f32_e32 v203, 1.0, v203
	v_mul_f32_e32 v144, v144, v200
	v_mul_f32_e32 v145, v145, v201
	v_mul_f32_e32 v146, v146, v202
	v_mul_f32_e32 v147, v147, v203
	v_add_f32_e32 v204, 1.0, v204
	v_add_f32_e32 v205, 1.0, v205
	v_add_f32_e32 v206, 1.0, v206
	v_add_f32_e32 v207, 1.0, v207
	v_mul_f32_e32 v148, v148, v204
	v_mul_f32_e32 v149, v149, v205
	v_mul_f32_e32 v150, v150, v206
	v_mul_f32_e32 v151, v151, v207
	v_add_f32_e32 v208, 1.0, v208
	v_add_f32_e32 v209, 1.0, v209
	v_add_f32_e32 v210, 1.0, v210
	v_add_f32_e32 v211, 1.0, v211
	v_mul_f32_e32 v152, v152, v208
	v_mul_f32_e32 v153, v153, v209
	v_mul_f32_e32 v154, v154, v210
	v_mul_f32_e32 v155, v155, v211
	v_add_f32_e32 v212, 1.0, v212
	v_add_f32_e32 v213, 1.0, v213
	v_add_f32_e32 v214, 1.0, v214
	v_add_f32_e32 v215, 1.0, v215
	v_mul_f32_e32 v156, v156, v212
	v_mul_f32_e32 v157, v157, v213
	v_mul_f32_e32 v158, v158, v214
	v_mul_f32_e32 v159, v159, v215
; __device__ __forceinline__ float bf_lo(unsigned w) { return __uint_as_float(w << 16); }
; __device__ __forceinline__ float bf_hi(unsigned w) { return __uint_as_float(w & 0xffff0000u); }
; __global__ void __launch_bounds__(NWAVES * 64, 2) mk_fwd(Args args) {
;     ...
;             for (int q = 0; q < 3; ++q) { const int row = row0 + q; const bool lat = row < ML; const int r = lat ? row / SEQ : 8;
;                 float sy = 0.f;
; #pragma unroll
;                 for (int j = 0; j < 8; ++j) { const float a = bf_lo(yw[q][j].x), b = bf_hi(yw[q][j].x), c2 = bf_lo(yw[q][j].y), d = bf_hi(yw[q][j].y); sy += (a * a + b * b) + (c2 * c2 + d * d); }
;                 const float rsy = __builtin_amdgcn_rsqf(wave_sum(sy) * (1.f / DM) + EPS);
;                 const float* m0 = mod + (size_t)r * 6144;
; #pragma unroll
;                 for (int j = 0; j < 8; ++j) { const int col = 4 * F.lane + 256 * j; const f32x4 gt = *(const f32x4*)(m0 + 2 * DM + col), pn = *(const f32x4*)(post_norm + col);
;                     const f32x4 y4 = (f32x4){bf_lo(yw[q][j].x), bf_hi(yw[q][j].x), bf_lo(yw[q][j].y), bf_hi(yw[q][j].y)};
;                     v[q][j] = v[q][j] + gt * (y4 * rsy * pn);
;                     if (lat) *(f32x4*)(args.out + (size_t)row * DM + col) = v[q][j]; }
.Lp6_np3:
	s_waitcnt vmcnt(32)
	v_lshlrev_b32_e32 v216, 16, v80
	v_and_b32_e32 v217, 0xffff0000, v80
	v_lshlrev_b32_e32 v218, 16, v81
	v_and_b32_e32 v219, 0xffff0000, v81
	v_mul_f32_e32 v222, v216, v216
	v_mul_f32_e32 v223, v217, v217
	v_fmac_f32_e32 v222, v218, v218
	v_fmac_f32_e32 v223, v219, v219
	v_lshlrev_b32_e32 v216, 16, v82
	v_and_b32_e32 v217, 0xffff0000, v82
	v_lshlrev_b32_e32 v218, 16, v83
	v_and_b32_e32 v219, 0xffff0000, v83
	v_fmac_f32_e32 v222, v216, v216
	v_fmac_f32_e32 v223, v217, v217
	v_fmac_f32_e32 v222, v218, v218
	v_fmac_f32_e32 v223, v219, v219
	v_lshlrev_b32_e32 v216, 16, v84
	v_and_b32_e32 v217, 0xffff0000, v84
	v_lshlrev_b32_e32 v218, 16, v85
	v_and_b32_e32 v219, 0xffff0000, v85
	v_fmac_f32_e32 v222, v216, v216
	v_fmac_f32_e32 v223, v217, v217
	v_fmac_f32_e32 v222, v218, v218
	v_fmac_f32_e32 v223, v219, v219
	v_lshlrev_b32_e32 v216, 16, v86
	v_and_b32_e32 v217, 0xffff0000, v86
	v_lshlrev_b32_e32 v218, 16, v87
	v_and_b32_e32 v219, 0xffff0000, v87
	v_fmac_f32_e32 v222, v216, v216
	v_fmac_f32_e32 v223, v217, v217
	v_fmac_f32_e32 v222, v218, v218
	v_fmac_f32_e32 v223, v219, v219
	v_lshlrev_b32_e32 v216, 16, v88
	v_and_b32_e32 v217, 0xffff0000, v88
	v_lshlrev_b32_e32 v218, 16, v89
	v_and_b32_e32 v219, 0xffff0000, v89
	v_fmac_f32_e32 v222, v216, v216
	v_fmac_f32_e32 v223, v217, v217
	v_fmac_f32_e32 v222, v218, v218
	v_fmac_f32_e32 v223, v219, v219
	v_lshlrev_b32_e32 v216, 16, v90
	v_and_b32_e32 v217, 0xffff0000, v90
	v_lshlrev_b32_e32 v218, 16, v91
	v_and_b32_e32 v219, 0xffff0000, v91
	v_fmac_f32_e32 v222, v216, v216
	v_fmac_f32_e32 v223, v217, v217
	v_fmac_f32_e32 v222, v218, v218
	v_fmac_f32_e32 v223, v219, v219
	v_lshlrev_b32_e32 v216, 16, v92
	v_and_b32_e32 v217, 0xffff0000, v92
	v_lshlrev_b32_e32 v218, 16, v93
	v_and_b32_e32 v219, 0xffff0000, v93
	v_fmac_f32_e32 v222, v216, v216
	v_fmac_f32_e32 v223, v217, v217
	v_fmac_f32_e32 v222, v218, v218
	v_fmac_f32_e32 v223, v219, v219
	v_lshlrev_b32_e32 v216, 16, v94
	v_and_b32_e32 v217, 0xffff0000, v94
	v_lshlrev_b32_e32 v218, 16, v95
	v_and_b32_e32 v219, 0xffff0000, v95
	v_fmac_f32_e32 v222, v216, v216
	v_fmac_f32_e32 v223, v217, v217
	v_fmac_f32_e32 v222, v218, v218
	v_fmac_f32_e32 v223, v219, v219
	v_add_f32_e32 v222, v222, v223
	s_nop 1
	v_add_f32_dpp v224, v222, v222 quad_perm:[1,0,3,2] row_mask:0xf bank_mask:0xf
	s_nop 1
	v_add_f32_dpp v224, v224, v224 quad_perm:[2,3,0,1] row_mask:0xf bank_mask:0xf
	s_nop 1
	v_add_f32_dpp v224, v224, v224 row_half_mirror row_mask:0xf bank_mask:0xf
	s_nop 1
	v_add_f32_dpp v224, v224, v224 row_mirror row_mask:0xf bank_mask:0xf
	s_nop 1
	v_readlane_b32 s40, v224, 0
	v_readlane_b32 s41, v224, 16
	v_readlane_b32 s42, v224, 32
	v_readlane_b32 s43, v224, 48
	s_nop 1
	v_mov_b32_e32 v225, s40
	v_add_f32_e32 v225, s41, v225
	v_add_f32_e32 v225, s42, v225
	v_add_f32_e32 v225, s43, v225
	v_fmamk_f32 v225, v225, 0x3a000000, v195
	v_rsq_f32_e32 v225, v225
	s_nop 0
	s_add_i32 s0, s6, 3
	s_cmp_lt_u32 s0, 0x4000
	s_cselect_b32 s24, s94, s84
	s_cselect_b32 s25, s95, s85
	s_cselect_b32 s44, 0, 0x16000000
	s_cselect_b32 s1, 0, 0x4000
	s_sub_i32 s1, s0, s1
	s_lshl_b32 s1, s1, 13
	s_add_u32 s24, s24, s1
	s_addc_u32 s25, s25, 0
	s_add_u32 s24, s24, s44
	s_addc_u32 s25, s25, 0
	v_lshlrev_b32_e32 v216, 16, v80
	v_and_b32_e32 v217, 0xffff0000, v80
	v_lshlrev_b32_e32 v218, 16, v81
	v_and_b32_e32 v219, 0xffff0000, v81
	v_mul_f32_e32 v216, v225, v216
	v_mul_f32_e32 v217, v225, v217
	v_mul_f32_e32 v218, v225, v218
	v_mul_f32_e32 v219, v225, v219
	v_fmac_f32_e32 v48, v96, v216
	v_fmac_f32_e32 v49, v97, v217
	v_fmac_f32_e32 v50, v98, v218
	v_fmac_f32_e32 v51, v99, v219
	global_store_dwordx4 v192, v[48:51], s[24:25] offset:0
	v_lshlrev_b32_e32 v216, 16, v82
	v_and_b32_e32 v217, 0xffff0000, v82
	v_lshlrev_b32_e32 v218, 16, v83
	v_and_b32_e32 v219, 0xffff0000, v83
	v_mul_f32_e32 v216, v225, v216
	v_mul_f32_e32 v217, v225, v217
	v_mul_f32_e32 v218, v225, v218
	v_mul_f32_e32 v219, v225, v219
	v_fmac_f32_e32 v52, v100, v216
	v_fmac_f32_e32 v53, v101, v217
	v_fmac_f32_e32 v54, v102, v218
	v_fmac_f32_e32 v55, v103, v219
	global_store_dwordx4 v192, v[52:55], s[24:25] offset:1024
	v_lshlrev_b32_e32 v216, 16, v84
	v_and_b32_e32 v217, 0xffff0000, v84
	v_lshlrev_b32_e32 v218, 16, v85
	v_and_b32_e32 v219, 0xffff0000, v85
	v_mul_f32_e32 v216, v225, v216
	v_mul_f32_e32 v217, v225, v217
	v_mul_f32_e32 v218, v225, v218
	v_mul_f32_e32 v219, v225, v219
	v_fmac_f32_e32 v56, v104, v216
	v_fmac_f32_e32 v57, v105, v217
	v_fmac_f32_e32 v58, v106, v218
	v_fmac_f32_e32 v59, v107, v219
	global_store_dwordx4 v192, v[56:59], s[24:25] offset:2048
	v_lshlrev_b32_e32 v216, 16, v86
	v_and_b32_e32 v217, 0xffff0000, v86
	v_lshlrev_b32_e32 v218, 16, v87
	v_and_b32_e32 v219, 0xffff0000, v87
	v_mul_f32_e32 v216, v225, v216
	v_mul_f32_e32 v217, v225, v217
	v_mul_f32_e32 v218, v225, v218
	v_mul_f32_e32 v219, v225, v219
	v_fmac_f32_e32 v60, v108, v216
	v_fmac_f32_e32 v61, v109, v217
	v_fmac_f32_e32 v62, v110, v218
	v_fmac_f32_e32 v63, v111, v219
	global_store_dwordx4 v192, v[60:63], s[24:25] offset:3072
	v_lshlrev_b32_e32 v216, 16, v88
	v_and_b32_e32 v217, 0xffff0000, v88
	v_lshlrev_b32_e32 v218, 16, v89
	v_and_b32_e32 v219, 0xffff0000, v89
	v_mul_f32_e32 v216, v225, v216
	v_mul_f32_e32 v217, v225, v217
	v_mul_f32_e32 v218, v225, v218
	v_mul_f32_e32 v219, v225, v219
	v_fmac_f32_e32 v64, v112, v216
	v_fmac_f32_e32 v65, v113, v217
	v_fmac_f32_e32 v66, v114, v218
	v_fmac_f32_e32 v67, v115, v219
	global_store_dwordx4 v193, v[64:67], s[24:25] offset:0
	v_lshlrev_b32_e32 v216, 16, v90
	v_and_b32_e32 v217, 0xffff0000, v90
	v_lshlrev_b32_e32 v218, 16, v91
	v_and_b32_e32 v219, 0xffff0000, v91
	v_mul_f32_e32 v216, v225, v216
; __device__ __forceinline__ unsigned cvt_pk_bf16(float lo, float hi) { unsigned r; asm volatile("v_cvt_pk_bf16_f32 %0, %1, %2" : "=v"(r) : "v"(lo), "v"(hi)); return r; }
; __device__ __forceinline__ float bf_lo(unsigned w) { return __uint_as_float(w << 16); }
; __device__ __forceinline__ float bf_hi(unsigned w) { return __uint_as_float(w & 0xffff0000u); }
; __device__ __forceinline__ float sumsq8(const f32x4 (&v)[8]) {
;     float s = 0.f;
; #pragma unroll
;     for (int j = 0; j < 8; ++j) s += (v[j][0] * v[j][0] + v[j][1] * v[j][1]) + (v[j][2] * v[j][2] + v[j][3] * v[j][3]);
;     return wave_sum(s);
; }
; __device__ __forceinline__ void modulate_store(const f32x4 (&v)[8], float rstd, const float* pn, const float* modr, bf16_t* orow, int lane) {
; #pragma unroll
;     for (int j = 0; j < 8; ++j) { const int col = 4 * lane + 256 * j;
;         const f32x4 g = *(const f32x4*)(pn + col), sh = *(const f32x4*)(modr + col), sc = *(const f32x4*)(modr + DM + col);
;         const f32x4 hh = v[j] * rstd * g * (sc + 1.f) + sh;
;         u32x2 w; w.x = cvt_pk_bf16(hh[0], hh[1]); w.y = cvt_pk_bf16(hh[2], hh[3]);
;         *(u32x2*)(orow + col) = w; }
; }
; __global__ void __launch_bounds__(NWAVES * 64, 2) mk_fwd(Args args) {
;     ...
;                 for (int j = 0; j < 8; ++j) { const int col = 4 * F.lane + 256 * j; const f32x4 gt = *(const f32x4*)(m0 + 2 * DM + col), pn = *(const f32x4*)(post_norm + col);
;                     const f32x4 y4 = (f32x4){bf_lo(yw[q][j].x), bf_hi(yw[q][j].x), bf_lo(yw[q][j].y), bf_hi(yw[q][j].y)};
;                     v[q][j] = v[q][j] + gt * (y4 * rsy * pn);
;                     if (lat) *(f32x4*)(args.out + (size_t)row * DM + col) = v[q][j]; }
;                 const float rstd = __builtin_amdgcn_rsqf(sumsq8(v[q]) * (1.f / DM) + EPS);
;                 modulate_store(v[q], rstd, pre_norm + DM, mod + (size_t)(9 + r) * 6144, H + (size_t)row * DM, F.lane); }
	v_mul_f32_e32 v217, v225, v217
	v_mul_f32_e32 v218, v225, v218
	v_mul_f32_e32 v219, v225, v219
	v_fmac_f32_e32 v68, v116, v216
	v_fmac_f32_e32 v69, v117, v217
	v_fmac_f32_e32 v70, v118, v218
	v_fmac_f32_e32 v71, v119, v219
	global_store_dwordx4 v193, v[68:71], s[24:25] offset:1024
	v_lshlrev_b32_e32 v216, 16, v92
	v_and_b32_e32 v217, 0xffff0000, v92
	v_lshlrev_b32_e32 v218, 16, v93
	v_and_b32_e32 v219, 0xffff0000, v93
	v_mul_f32_e32 v216, v225, v216
	v_mul_f32_e32 v217, v225, v217
	v_mul_f32_e32 v218, v225, v218
	v_mul_f32_e32 v219, v225, v219
	v_fmac_f32_e32 v72, v120, v216
	v_fmac_f32_e32 v73, v121, v217
	v_fmac_f32_e32 v74, v122, v218
	v_fmac_f32_e32 v75, v123, v219
	global_store_dwordx4 v193, v[72:75], s[24:25] offset:2048
	v_lshlrev_b32_e32 v216, 16, v94
	v_and_b32_e32 v217, 0xffff0000, v94
	v_lshlrev_b32_e32 v218, 16, v95
	v_and_b32_e32 v219, 0xffff0000, v95
	v_mul_f32_e32 v216, v225, v216
	v_mul_f32_e32 v217, v225, v217
	v_mul_f32_e32 v218, v225, v218
	v_mul_f32_e32 v219, v225, v219
	v_fmac_f32_e32 v76, v124, v216
	v_fmac_f32_e32 v77, v125, v217
	v_fmac_f32_e32 v78, v126, v218
	v_fmac_f32_e32 v79, v127, v219
	global_store_dwordx4 v193, v[76:79], s[24:25] offset:3072
	v_mul_f32_e32 v222, v48, v48
	v_mul_f32_e32 v223, v49, v49
	v_fmac_f32_e32 v222, v50, v50
	v_fmac_f32_e32 v223, v51, v51
	v_fmac_f32_e32 v222, v52, v52
	v_fmac_f32_e32 v223, v53, v53
	v_fmac_f32_e32 v222, v54, v54
	v_fmac_f32_e32 v223, v55, v55
	v_fmac_f32_e32 v222, v56, v56
	v_fmac_f32_e32 v223, v57, v57
	v_fmac_f32_e32 v222, v58, v58
	v_fmac_f32_e32 v223, v59, v59
	v_fmac_f32_e32 v222, v60, v60
	v_fmac_f32_e32 v223, v61, v61
	v_fmac_f32_e32 v222, v62, v62
	v_fmac_f32_e32 v223, v63, v63
	v_fmac_f32_e32 v222, v64, v64
	v_fmac_f32_e32 v223, v65, v65
	v_fmac_f32_e32 v222, v66, v66
	v_fmac_f32_e32 v223, v67, v67
	v_fmac_f32_e32 v222, v68, v68
	v_fmac_f32_e32 v223, v69, v69
	v_fmac_f32_e32 v222, v70, v70
	v_fmac_f32_e32 v223, v71, v71
	v_fmac_f32_e32 v222, v72, v72
	v_fmac_f32_e32 v223, v73, v73
	v_fmac_f32_e32 v222, v74, v74
	v_fmac_f32_e32 v223, v75, v75
	v_fmac_f32_e32 v222, v76, v76
	v_fmac_f32_e32 v223, v77, v77
	v_fmac_f32_e32 v222, v78, v78
	v_fmac_f32_e32 v223, v79, v79
	v_add_f32_e32 v222, v222, v223
	s_nop 1
	v_add_f32_dpp v224, v222, v222 quad_perm:[1,0,3,2] row_mask:0xf bank_mask:0xf
	s_nop 1
	v_add_f32_dpp v224, v224, v224 quad_perm:[2,3,0,1] row_mask:0xf bank_mask:0xf
	s_nop 1
	v_add_f32_dpp v224, v224, v224 row_half_mirror row_mask:0xf bank_mask:0xf
	s_nop 1
	v_add_f32_dpp v224, v224, v224 row_mirror row_mask:0xf bank_mask:0xf
	s_nop 1
	v_readlane_b32 s40, v224, 0
	v_readlane_b32 s41, v224, 16
	v_readlane_b32 s42, v224, 32
	v_readlane_b32 s43, v224, 48
	s_nop 1
	v_mov_b32_e32 v225, s40
	v_add_f32_e32 v225, s41, v225
	v_add_f32_e32 v225, s42, v225
	v_add_f32_e32 v225, s43, v225
	v_fmamk_f32 v225, v225, 0x3a000000, v195
	v_rsq_f32_e32 v225, v225
	s_nop 0
	s_add_i32 s0, s6, 3
	s_lshl_b32 s1, s0, 12
	s_add_u32 s26, s84, s1
	s_addc_u32 s27, s85, 0
	s_add_u32 s26, s26, 0x4000000
	s_addc_u32 s27, s27, 0
	v_mul_f32_e32 v216, v225, v48
	v_mul_f32_e32 v217, v225, v49
	v_mul_f32_e32 v218, v225, v50
	v_mul_f32_e32 v219, v225, v51
	v_fma_f32 v216, v216, v128, v160
	v_fma_f32 v217, v217, v129, v161
	v_fma_f32 v218, v218, v130, v162
	v_fma_f32 v219, v219, v131, v163
	v_cvt_pk_bf16_f32 v196, v216, v217
	v_cvt_pk_bf16_f32 v197, v218, v219
	global_store_dwordx2 v194, v[196:197], s[26:27] offset:0
	v_mul_f32_e32 v216, v225, v52
	v_mul_f32_e32 v217, v225, v53
	v_mul_f32_e32 v218, v225, v54
	v_mul_f32_e32 v219, v225, v55
	v_fma_f32 v216, v216, v132, v164
	v_fma_f32 v217, v217, v133, v165
	v_fma_f32 v218, v218, v134, v166
	v_fma_f32 v219, v219, v135, v167
	v_cvt_pk_bf16_f32 v220, v216, v217
	v_cvt_pk_bf16_f32 v221, v218, v219
	global_store_dwordx2 v194, v[220:221], s[26:27] offset:512
	v_mul_f32_e32 v216, v225, v56
	v_mul_f32_e32 v217, v225, v57
	v_mul_f32_e32 v218, v225, v58
	v_mul_f32_e32 v219, v225, v59
	v_fma_f32 v216, v216, v136, v168
	v_fma_f32 v217, v217, v137, v169
	v_fma_f32 v218, v218, v138, v170
	v_fma_f32 v219, v219, v139, v171
	v_cvt_pk_bf16_f32 v196, v216, v217
	v_cvt_pk_bf16_f32 v197, v218, v219
	global_store_dwordx2 v194, v[196:197], s[26:27] offset:1024
	v_mul_f32_e32 v216, v225, v60
	v_mul_f32_e32 v217, v225, v61
	v_mul_f32_e32 v218, v225, v62
	v_mul_f32_e32 v219, v225, v63
	v_fma_f32 v216, v216, v140, v172
	v_fma_f32 v217, v217, v141, v173
	v_fma_f32 v218, v218, v142, v174
	v_fma_f32 v219, v219, v143, v175
	v_cvt_pk_bf16_f32 v220, v216, v217
	v_cvt_pk_bf16_f32 v221, v218, v219
	global_store_dwordx2 v194, v[220:221], s[26:27] offset:1536
	v_mul_f32_e32 v216, v225, v64
	v_mul_f32_e32 v217, v225, v65
	v_mul_f32_e32 v218, v225, v66
	v_mul_f32_e32 v219, v225, v67
	v_fma_f32 v216, v216, v144, v176
	v_fma_f32 v217, v217, v145, v177
	v_fma_f32 v218, v218, v146, v178
	v_fma_f32 v219, v219, v147, v179
	v_cvt_pk_bf16_f32 v196, v216, v217
	v_cvt_pk_bf16_f32 v197, v218, v219
	global_store_dwordx2 v194, v[196:197], s[26:27] offset:2048
	v_mul_f32_e32 v216, v225, v68
	v_mul_f32_e32 v217, v225, v69
	v_mul_f32_e32 v218, v225, v70
	v_mul_f32_e32 v219, v225, v71
	v_fma_f32 v216, v216, v148, v180
	v_fma_f32 v217, v217, v149, v181
	v_fma_f32 v218, v218, v150, v182
	v_fma_f32 v219, v219, v151, v183
	v_cvt_pk_bf16_f32 v220, v216, v217
	v_cvt_pk_bf16_f32 v221, v218, v219
	global_store_dwordx2 v194, v[220:221], s[26:27] offset:2560
	v_mul_f32_e32 v216, v225, v72
	v_mul_f32_e32 v217, v225, v73
	v_mul_f32_e32 v218, v225, v74
	v_mul_f32_e32 v219, v225, v75
	v_fma_f32 v216, v216, v152, v184
	v_fma_f32 v217, v217, v153, v185
	v_fma_f32 v218, v218, v154, v186
	v_fma_f32 v219, v219, v155, v187
; __device__ __forceinline__ unsigned cvt_pk_bf16(float lo, float hi) { unsigned r; asm volatile("v_cvt_pk_bf16_f32 %0, %1, %2" : "=v"(r) : "v"(lo), "v"(hi)); return r; }
; __device__ __forceinline__ float bf_lo(unsigned w) { return __uint_as_float(w << 16); }
; __device__ __forceinline__ float bf_hi(unsigned w) { return __uint_as_float(w & 0xffff0000u); }
; __device__ __forceinline__ void modulate_store(const f32x4 (&v)[8], float rstd, const float* pn, const float* modr, bf16_t* orow, int lane) {
; #pragma unroll
;     for (int j = 0; j < 8; ++j) { const int col = 4 * lane + 256 * j;
;         const f32x4 g = *(const f32x4*)(pn + col), sh = *(const f32x4*)(modr + col), sc = *(const f32x4*)(modr + DM + col);
;         const f32x4 hh = v[j] * rstd * g * (sc + 1.f) + sh;
;         u32x2 w; w.x = cvt_pk_bf16(hh[0], hh[1]); w.y = cvt_pk_bf16(hh[2], hh[3]);
;         *(u32x2*)(orow + col) = w; }
; }
; __global__ void __launch_bounds__(NWAVES * 64, 2) mk_fwd(Args args) {
;     ...
;         for (int row0 = F.gw * 3; row0 < MT; row0 += F.NGW * 3) {
;             f32x4 v[3][8]; u32x2 yw[3][8];
; #pragma unroll
;             for (int q = 0; q < 3; ++q) { const int row = row0 + q; const float* src = row < ML ? x + (size_t)row * DM : ctx + (size_t)(row - ML) * DM; load_row_f32(src, F.lane, v[q]);
;                 const bf16_t* yr = Y + (size_t)row * DM;
; #pragma unroll
;                 for (int j = 0; j < 8; ++j) yw[q][j] = *(const u32x2*)(yr + 4 * F.lane + 256 * j); }
; #pragma unroll
;             for (int q = 0; q < 3; ++q) { const int row = row0 + q; const bool lat = row < ML; const int r = lat ? row / SEQ : 8;
;                 float sy = 0.f;
; #pragma unroll
;                 for (int j = 0; j < 8; ++j) { const float a = bf_lo(yw[q][j].x), b = bf_hi(yw[q][j].x), c2 = bf_lo(yw[q][j].y), d = bf_hi(yw[q][j].y); sy += (a * a + b * b) + (c2 * c2 + d * d); }
;                 const float rsy = __builtin_amdgcn_rsqf(wave_sum(sy) * (1.f / DM) + EPS);
;                 const float* m0 = mod + (size_t)r * 6144;
; #pragma unroll
;                 for (int j = 0; j < 8; ++j) { const int col = 4 * F.lane + 256 * j; const f32x4 gt = *(const f32x4*)(m0 + 2 * DM + col), pn = *(const f32x4*)(post_norm + col);
	v_cvt_pk_bf16_f32 v196, v216, v217
	v_cvt_pk_bf16_f32 v197, v218, v219
	global_store_dwordx2 v194, v[196:197], s[26:27] offset:3072
	v_mul_f32_e32 v216, v225, v76
	v_mul_f32_e32 v217, v225, v77
	v_mul_f32_e32 v218, v225, v78
	v_mul_f32_e32 v219, v225, v79
	v_fma_f32 v216, v216, v156, v188
	v_fma_f32 v217, v217, v157, v189
	v_fma_f32 v218, v218, v158, v190
	v_fma_f32 v219, v219, v159, v191
	v_cvt_pk_bf16_f32 v220, v216, v217
	v_cvt_pk_bf16_f32 v221, v218, v219
	global_store_dwordx2 v194, v[220:221], s[26:27] offset:3584
	s_add_i32 s0, s6, 5
	s_cmp_lt_u32 s0, 0x4000
	s_cselect_b32 s10, s68, s72
	s_cselect_b32 s11, s69, s73
	s_cselect_b32 s1, 0, 0x4000
	s_sub_i32 s1, s0, s1
	s_lshl_b32 s1, s1, 13
	s_add_u32 s10, s10, s1
	s_addc_u32 s11, s11, 0
	s_add_i32 s0, s6, 5
	s_lshl_b32 s1, s0, 12
	s_add_u32 s22, s84, s1
	s_addc_u32 s23, s85, 0
	s_add_u32 s22, s22, 0x11800000
	s_addc_u32 s23, s23, 0
	global_load_dwordx4 v[48:51], v192, s[10:11] offset:0
	global_load_dwordx4 v[52:55], v192, s[10:11] offset:1024
	global_load_dwordx4 v[56:59], v192, s[10:11] offset:2048
	global_load_dwordx4 v[60:63], v192, s[10:11] offset:3072
	global_load_dwordx4 v[64:67], v193, s[10:11] offset:0
	global_load_dwordx4 v[68:71], v193, s[10:11] offset:1024
	global_load_dwordx4 v[72:75], v193, s[10:11] offset:2048
	global_load_dwordx4 v[76:79], v193, s[10:11] offset:3072
	global_load_dwordx2 v[80:81], v194, s[22:23] offset:0
	global_load_dwordx2 v[82:83], v194, s[22:23] offset:512
	global_load_dwordx2 v[84:85], v194, s[22:23] offset:1024
	global_load_dwordx2 v[86:87], v194, s[22:23] offset:1536
	global_load_dwordx2 v[88:89], v194, s[22:23] offset:2048
	global_load_dwordx2 v[90:91], v194, s[22:23] offset:2560
	global_load_dwordx2 v[92:93], v194, s[22:23] offset:3072
	global_load_dwordx2 v[94:95], v194, s[22:23] offset:3584
	s_add_i32 s0, s6, 4
	s_add_i32 s0, s6, 4
	s_lshr_b32 s8, s0, 11
	s_cmp_lt_u32 s0, 0x4000
	s_cselect_b32 s8, s8, 8
	s_cmp_eq_u32 s8, s7
	s_cbranch_scc1 .Lp6_np4
	s_mov_b32 s7, s8
	s_add_i32 s1, s8, 9
	s_mul_i32 s1, s1, 0x6000
	s_add_u32 s44, s84, s1
	s_addc_u32 s45, s85, 0
	s_add_u32 s44, s44, 0x2000
	s_addc_u32 s45, s45, 0
	s_add_i32 s1, s8, 9
	s_mul_i32 s1, s1, 0x6000
	s_add_u32 s36, s84, s1
	s_addc_u32 s37, s85, 0
	s_add_u32 s38, s80, 0x2000
	s_addc_u32 s39, s81, 0
	s_mul_i32 s1, s8, 0x6000
	s_add_u32 s34, s84, s1
	s_addc_u32 s35, s85, 0
	s_add_u32 s34, s34, 0x4000
	s_addc_u32 s35, s35, 0
	global_load_dwordx4 v[96:99], v192, s[34:35] offset:0
	global_load_dwordx4 v[200:203], v192, s[82:83] offset:0
	global_load_dwordx4 v[100:103], v192, s[34:35] offset:1024
	global_load_dwordx4 v[204:207], v192, s[82:83] offset:1024
	global_load_dwordx4 v[104:107], v192, s[34:35] offset:2048
	global_load_dwordx4 v[208:211], v192, s[82:83] offset:2048
	global_load_dwordx4 v[108:111], v192, s[34:35] offset:3072
	global_load_dwordx4 v[212:215], v192, s[82:83] offset:3072
	s_waitcnt vmcnt(0)
	v_mul_f32_e32 v96, v96, v200
	v_mul_f32_e32 v97, v97, v201
	v_mul_f32_e32 v98, v98, v202
	v_mul_f32_e32 v99, v99, v203
	v_mul_f32_e32 v100, v100, v204
	v_mul_f32_e32 v101, v101, v205
	v_mul_f32_e32 v102, v102, v206
	v_mul_f32_e32 v103, v103, v207
	v_mul_f32_e32 v104, v104, v208
	v_mul_f32_e32 v105, v105, v209
	v_mul_f32_e32 v106, v106, v210
	v_mul_f32_e32 v107, v107, v211
	v_mul_f32_e32 v108, v108, v212
	v_mul_f32_e32 v109, v109, v213
	v_mul_f32_e32 v110, v110, v214
	v_mul_f32_e32 v111, v111, v215
	global_load_dwordx4 v[128:131], v192, s[38:39] offset:0
	global_load_dwordx4 v[200:203], v192, s[44:45] offset:0
	global_load_dwordx4 v[160:163], v192, s[36:37] offset:0
	global_load_dwordx4 v[132:135], v192, s[38:39] offset:1024
	global_load_dwordx4 v[204:207], v192, s[44:45] offset:1024
	global_load_dwordx4 v[164:167], v192, s[36:37] offset:1024
	global_load_dwordx4 v[136:139], v192, s[38:39] offset:2048
	global_load_dwordx4 v[208:211], v192, s[44:45] offset:2048
	global_load_dwordx4 v[168:171], v192, s[36:37] offset:2048
	global_load_dwordx4 v[140:143], v192, s[38:39] offset:3072
	global_load_dwordx4 v[212:215], v192, s[44:45] offset:3072
	global_load_dwordx4 v[172:175], v192, s[36:37] offset:3072
	s_waitcnt vmcnt(0)
	v_add_f32_e32 v200, 1.0, v200
	v_add_f32_e32 v201, 1.0, v201
	v_add_f32_e32 v202, 1.0, v202
	v_add_f32_e32 v203, 1.0, v203
	v_mul_f32_e32 v128, v128, v200
	v_mul_f32_e32 v129, v129, v201
	v_mul_f32_e32 v130, v130, v202
	v_mul_f32_e32 v131, v131, v203
	v_add_f32_e32 v204, 1.0, v204
	v_add_f32_e32 v205, 1.0, v205
	v_add_f32_e32 v206, 1.0, v206
	v_add_f32_e32 v207, 1.0, v207
	v_mul_f32_e32 v132, v132, v204
	v_mul_f32_e32 v133, v133, v205
	v_mul_f32_e32 v134, v134, v206
	v_mul_f32_e32 v135, v135, v207
	v_add_f32_e32 v208, 1.0, v208
	v_add_f32_e32 v209, 1.0, v209
	v_add_f32_e32 v210, 1.0, v210
	v_add_f32_e32 v211, 1.0, v211
	v_mul_f32_e32 v136, v136, v208
	v_mul_f32_e32 v137, v137, v209
	v_mul_f32_e32 v138, v138, v210
	v_mul_f32_e32 v139, v139, v211
	v_add_f32_e32 v212, 1.0, v212
	v_add_f32_e32 v213, 1.0, v213
	v_add_f32_e32 v214, 1.0, v214
	v_add_f32_e32 v215, 1.0, v215
	v_mul_f32_e32 v140, v140, v212
	v_mul_f32_e32 v141, v141, v213
	v_mul_f32_e32 v142, v142, v214
	v_mul_f32_e32 v143, v143, v215
	global_load_dwordx4 v[112:115], v193, s[34:35] offset:0
	global_load_dwordx4 v[200:203], v193, s[82:83] offset:0
	global_load_dwordx4 v[116:119], v193, s[34:35] offset:1024
	global_load_dwordx4 v[204:207], v193, s[82:83] offset:1024
	global_load_dwordx4 v[120:123], v193, s[34:35] offset:2048
	global_load_dwordx4 v[208:211], v193, s[82:83] offset:2048
	global_load_dwordx4 v[124:127], v193, s[34:35] offset:3072
	global_load_dwordx4 v[212:215], v193, s[82:83] offset:3072
	s_waitcnt vmcnt(0)
; __device__ __forceinline__ float bf_lo(unsigned w) { return __uint_as_float(w << 16); }
; __device__ __forceinline__ float bf_hi(unsigned w) { return __uint_as_float(w & 0xffff0000u); }
; __device__ __forceinline__ void modulate_store(const f32x4 (&v)[8], float rstd, const float* pn, const float* modr, bf16_t* orow, int lane) {
;     ...
;         const f32x4 g = *(const f32x4*)(pn + col), sh = *(const f32x4*)(modr + col), sc = *(const f32x4*)(modr + DM + col);
;         const f32x4 hh = v[j] * rstd * g * (sc + 1.f) + sh;
; __global__ void __launch_bounds__(NWAVES * 64, 2) mk_fwd(Args args) {
;     ...
;             for (int q = 0; q < 3; ++q) { const int row = row0 + q; const bool lat = row < ML; const int r = lat ? row / SEQ : 8;
;                 float sy = 0.f;
; #pragma unroll
;                 for (int j = 0; j < 8; ++j) { const float a = bf_lo(yw[q][j].x), b = bf_hi(yw[q][j].x), c2 = bf_lo(yw[q][j].y), d = bf_hi(yw[q][j].y); sy += (a * a + b * b) + (c2 * c2 + d * d); }
;                 const float rsy = __builtin_amdgcn_rsqf(wave_sum(sy) * (1.f / DM) + EPS);
;                 const float* m0 = mod + (size_t)r * 6144;
; #pragma unroll
;                 for (int j = 0; j < 8; ++j) { const int col = 4 * F.lane + 256 * j; const f32x4 gt = *(const f32x4*)(m0 + 2 * DM + col), pn = *(const f32x4*)(post_norm + col);
;                     const f32x4 y4 = (f32x4){bf_lo(yw[q][j].x), bf_hi(yw[q][j].x), bf_lo(yw[q][j].y), bf_hi(yw[q][j].y)};
;                     v[q][j] = v[q][j] + gt * (y4 * rsy * pn);
;                     if (lat) *(f32x4*)(args.out + (size_t)row * DM + col) = v[q][j]; }
	v_mul_f32_e32 v112, v112, v200
	v_mul_f32_e32 v113, v113, v201
	v_mul_f32_e32 v114, v114, v202
	v_mul_f32_e32 v115, v115, v203
	v_mul_f32_e32 v116, v116, v204
	v_mul_f32_e32 v117, v117, v205
	v_mul_f32_e32 v118, v118, v206
	v_mul_f32_e32 v119, v119, v207
	v_mul_f32_e32 v120, v120, v208
	v_mul_f32_e32 v121, v121, v209
	v_mul_f32_e32 v122, v122, v210
	v_mul_f32_e32 v123, v123, v211
	v_mul_f32_e32 v124, v124, v212
	v_mul_f32_e32 v125, v125, v213
	v_mul_f32_e32 v126, v126, v214
	v_mul_f32_e32 v127, v127, v215
	global_load_dwordx4 v[144:147], v193, s[38:39] offset:0
	global_load_dwordx4 v[200:203], v193, s[44:45] offset:0
	global_load_dwordx4 v[176:179], v193, s[36:37] offset:0
	global_load_dwordx4 v[148:151], v193, s[38:39] offset:1024
	global_load_dwordx4 v[204:207], v193, s[44:45] offset:1024
	global_load_dwordx4 v[180:183], v193, s[36:37] offset:1024
	global_load_dwordx4 v[152:155], v193, s[38:39] offset:2048
	global_load_dwordx4 v[208:211], v193, s[44:45] offset:2048
	global_load_dwordx4 v[184:187], v193, s[36:37] offset:2048
	global_load_dwordx4 v[156:159], v193, s[38:39] offset:3072
	global_load_dwordx4 v[212:215], v193, s[44:45] offset:3072
	global_load_dwordx4 v[188:191], v193, s[36:37] offset:3072
	s_waitcnt vmcnt(0)
	v_add_f32_e32 v200, 1.0, v200
	v_add_f32_e32 v201, 1.0, v201
	v_add_f32_e32 v202, 1.0, v202
	v_add_f32_e32 v203, 1.0, v203
	v_mul_f32_e32 v144, v144, v200
	v_mul_f32_e32 v145, v145, v201
	v_mul_f32_e32 v146, v146, v202
	v_mul_f32_e32 v147, v147, v203
	v_add_f32_e32 v204, 1.0, v204
	v_add_f32_e32 v205, 1.0, v205
	v_add_f32_e32 v206, 1.0, v206
	v_add_f32_e32 v207, 1.0, v207
	v_mul_f32_e32 v148, v148, v204
	v_mul_f32_e32 v149, v149, v205
	v_mul_f32_e32 v150, v150, v206
	v_mul_f32_e32 v151, v151, v207
	v_add_f32_e32 v208, 1.0, v208
	v_add_f32_e32 v209, 1.0, v209
	v_add_f32_e32 v210, 1.0, v210
	v_add_f32_e32 v211, 1.0, v211
	v_mul_f32_e32 v152, v152, v208
	v_mul_f32_e32 v153, v153, v209
	v_mul_f32_e32 v154, v154, v210
	v_mul_f32_e32 v155, v155, v211
	v_add_f32_e32 v212, 1.0, v212
	v_add_f32_e32 v213, 1.0, v213
	v_add_f32_e32 v214, 1.0, v214
	v_add_f32_e32 v215, 1.0, v215
	v_mul_f32_e32 v156, v156, v212
	v_mul_f32_e32 v157, v157, v213
	v_mul_f32_e32 v158, v158, v214
	v_mul_f32_e32 v159, v159, v215
.Lp6_np4:
	s_waitcnt vmcnt(32)
	v_lshlrev_b32_e32 v216, 16, v32
	v_and_b32_e32 v217, 0xffff0000, v32
	v_lshlrev_b32_e32 v218, 16, v33
	v_and_b32_e32 v219, 0xffff0000, v33
	v_mul_f32_e32 v222, v216, v216
	v_mul_f32_e32 v223, v217, v217
	v_fmac_f32_e32 v222, v218, v218
	v_fmac_f32_e32 v223, v219, v219
	v_lshlrev_b32_e32 v216, 16, v34
	v_and_b32_e32 v217, 0xffff0000, v34
	v_lshlrev_b32_e32 v218, 16, v35
	v_and_b32_e32 v219, 0xffff0000, v35
	v_fmac_f32_e32 v222, v216, v216
	v_fmac_f32_e32 v223, v217, v217
	v_fmac_f32_e32 v222, v218, v218
	v_fmac_f32_e32 v223, v219, v219
	v_lshlrev_b32_e32 v216, 16, v36
	v_and_b32_e32 v217, 0xffff0000, v36
	v_lshlrev_b32_e32 v218, 16, v37
	v_and_b32_e32 v219, 0xffff0000, v37
	v_fmac_f32_e32 v222, v216, v216
	v_fmac_f32_e32 v223, v217, v217
	v_fmac_f32_e32 v222, v218, v218
	v_fmac_f32_e32 v223, v219, v219
	v_lshlrev_b32_e32 v216, 16, v38
	v_and_b32_e32 v217, 0xffff0000, v38
	v_lshlrev_b32_e32 v218, 16, v39
	v_and_b32_e32 v219, 0xffff0000, v39
	v_fmac_f32_e32 v222, v216, v216
	v_fmac_f32_e32 v223, v217, v217
	v_fmac_f32_e32 v222, v218, v218
	v_fmac_f32_e32 v223, v219, v219
	v_lshlrev_b32_e32 v216, 16, v40
	v_and_b32_e32 v217, 0xffff0000, v40
	v_lshlrev_b32_e32 v218, 16, v41
	v_and_b32_e32 v219, 0xffff0000, v41
	v_fmac_f32_e32 v222, v216, v216
	v_fmac_f32_e32 v223, v217, v217
	v_fmac_f32_e32 v222, v218, v218
	v_fmac_f32_e32 v223, v219, v219
	v_lshlrev_b32_e32 v216, 16, v42
	v_and_b32_e32 v217, 0xffff0000, v42
	v_lshlrev_b32_e32 v218, 16, v43
	v_and_b32_e32 v219, 0xffff0000, v43
	v_fmac_f32_e32 v222, v216, v216
	v_fmac_f32_e32 v223, v217, v217
	v_fmac_f32_e32 v222, v218, v218
	v_fmac_f32_e32 v223, v219, v219
	v_lshlrev_b32_e32 v216, 16, v44
	v_and_b32_e32 v217, 0xffff0000, v44
	v_lshlrev_b32_e32 v218, 16, v45
	v_and_b32_e32 v219, 0xffff0000, v45
	v_fmac_f32_e32 v222, v216, v216
	v_fmac_f32_e32 v223, v217, v217
	v_fmac_f32_e32 v222, v218, v218
	v_fmac_f32_e32 v223, v219, v219
	v_lshlrev_b32_e32 v216, 16, v46
	v_and_b32_e32 v217, 0xffff0000, v46
	v_lshlrev_b32_e32 v218, 16, v47
	v_and_b32_e32 v219, 0xffff0000, v47
	v_fmac_f32_e32 v222, v216, v216
	v_fmac_f32_e32 v223, v217, v217
	v_fmac_f32_e32 v222, v218, v218
	v_fmac_f32_e32 v223, v219, v219
	v_add_f32_e32 v222, v222, v223
	s_nop 1
	v_add_f32_dpp v224, v222, v222 quad_perm:[1,0,3,2] row_mask:0xf bank_mask:0xf
	s_nop 1
	v_add_f32_dpp v224, v224, v224 quad_perm:[2,3,0,1] row_mask:0xf bank_mask:0xf
	s_nop 1
	v_add_f32_dpp v224, v224, v224 row_half_mirror row_mask:0xf bank_mask:0xf
	s_nop 1
	v_add_f32_dpp v224, v224, v224 row_mirror row_mask:0xf bank_mask:0xf
	s_nop 1
	v_readlane_b32 s40, v224, 0
	v_readlane_b32 s41, v224, 16
	v_readlane_b32 s42, v224, 32
	v_readlane_b32 s43, v224, 48
	s_nop 1
	v_mov_b32_e32 v225, s40
	v_add_f32_e32 v225, s41, v225
	v_add_f32_e32 v225, s42, v225
	v_add_f32_e32 v225, s43, v225
	v_fmamk_f32 v225, v225, 0x3a000000, v195
	v_rsq_f32_e32 v225, v225
	s_nop 0
	s_add_i32 s0, s6, 4
	s_cmp_lt_u32 s0, 0x4000
	s_cselect_b32 s24, s94, s84
	s_cselect_b32 s25, s95, s85
	s_cselect_b32 s44, 0, 0x16000000
	s_cselect_b32 s1, 0, 0x4000
	s_sub_i32 s1, s0, s1
	s_lshl_b32 s1, s1, 13
	s_add_u32 s24, s24, s1
	s_addc_u32 s25, s25, 0
	s_add_u32 s24, s24, s44
	s_addc_u32 s25, s25, 0
	v_lshlrev_b32_e32 v216, 16, v32
	v_and_b32_e32 v217, 0xffff0000, v32
	v_lshlrev_b32_e32 v218, 16, v33
	v_and_b32_e32 v219, 0xffff0000, v33
	v_mul_f32_e32 v216, v225, v216
; __device__ __forceinline__ unsigned cvt_pk_bf16(float lo, float hi) { unsigned r; asm volatile("v_cvt_pk_bf16_f32 %0, %1, %2" : "=v"(r) : "v"(lo), "v"(hi)); return r; }
; __device__ __forceinline__ float bf_lo(unsigned w) { return __uint_as_float(w << 16); }
; __device__ __forceinline__ float bf_hi(unsigned w) { return __uint_as_float(w & 0xffff0000u); }
; __device__ __forceinline__ float sumsq8(const f32x4 (&v)[8]) {
;     float s = 0.f;
; #pragma unroll
;     for (int j = 0; j < 8; ++j) s += (v[j][0] * v[j][0] + v[j][1] * v[j][1]) + (v[j][2] * v[j][2] + v[j][3] * v[j][3]);
;     return wave_sum(s);
; }
; __device__ __forceinline__ void modulate_store(const f32x4 (&v)[8], float rstd, const float* pn, const float* modr, bf16_t* orow, int lane) {
; #pragma unroll
;     for (int j = 0; j < 8; ++j) { const int col = 4 * lane + 256 * j;
;         const f32x4 g = *(const f32x4*)(pn + col), sh = *(const f32x4*)(modr + col), sc = *(const f32x4*)(modr + DM + col);
;         const f32x4 hh = v[j] * rstd * g * (sc + 1.f) + sh;
;         u32x2 w; w.x = cvt_pk_bf16(hh[0], hh[1]); w.y = cvt_pk_bf16(hh[2], hh[3]);
;         *(u32x2*)(orow + col) = w; }
; }
; __global__ void __launch_bounds__(NWAVES * 64, 2) mk_fwd(Args args) {
;     ...
;                 for (int j = 0; j < 8; ++j) { const int col = 4 * F.lane + 256 * j; const f32x4 gt = *(const f32x4*)(m0 + 2 * DM + col), pn = *(const f32x4*)(post_norm + col);
;                     const f32x4 y4 = (f32x4){bf_lo(yw[q][j].x), bf_hi(yw[q][j].x), bf_lo(yw[q][j].y), bf_hi(yw[q][j].y)};
;                     v[q][j] = v[q][j] + gt * (y4 * rsy * pn);
;                     if (lat) *(f32x4*)(args.out + (size_t)row * DM + col) = v[q][j]; }
;                 const float rstd = __builtin_amdgcn_rsqf(sumsq8(v[q]) * (1.f / DM) + EPS);
;                 modulate_store(v[q], rstd, pre_norm + DM, mod + (size_t)(9 + r) * 6144, H + (size_t)row * DM, F.lane); }
	v_mul_f32_e32 v217, v225, v217
	v_mul_f32_e32 v218, v225, v218
	v_mul_f32_e32 v219, v225, v219
	v_fmac_f32_e32 v0, v96, v216
	v_fmac_f32_e32 v1, v97, v217
	v_fmac_f32_e32 v2, v98, v218
	v_fmac_f32_e32 v3, v99, v219
	global_store_dwordx4 v192, v[0:3], s[24:25] offset:0
	v_lshlrev_b32_e32 v216, 16, v34
	v_and_b32_e32 v217, 0xffff0000, v34
	v_lshlrev_b32_e32 v218, 16, v35
	v_and_b32_e32 v219, 0xffff0000, v35
	v_mul_f32_e32 v216, v225, v216
	v_mul_f32_e32 v217, v225, v217
	v_mul_f32_e32 v218, v225, v218
	v_mul_f32_e32 v219, v225, v219
	v_fmac_f32_e32 v4, v100, v216
	v_fmac_f32_e32 v5, v101, v217
	v_fmac_f32_e32 v6, v102, v218
	v_fmac_f32_e32 v7, v103, v219
	global_store_dwordx4 v192, v[4:7], s[24:25] offset:1024
	v_lshlrev_b32_e32 v216, 16, v36
	v_and_b32_e32 v217, 0xffff0000, v36
	v_lshlrev_b32_e32 v218, 16, v37
	v_and_b32_e32 v219, 0xffff0000, v37
	v_mul_f32_e32 v216, v225, v216
	v_mul_f32_e32 v217, v225, v217
	v_mul_f32_e32 v218, v225, v218
	v_mul_f32_e32 v219, v225, v219
	v_fmac_f32_e32 v8, v104, v216
	v_fmac_f32_e32 v9, v105, v217
	v_fmac_f32_e32 v10, v106, v218
	v_fmac_f32_e32 v11, v107, v219
	global_store_dwordx4 v192, v[8:11], s[24:25] offset:2048
	v_lshlrev_b32_e32 v216, 16, v38
	v_and_b32_e32 v217, 0xffff0000, v38
	v_lshlrev_b32_e32 v218, 16, v39
	v_and_b32_e32 v219, 0xffff0000, v39
	v_mul_f32_e32 v216, v225, v216
	v_mul_f32_e32 v217, v225, v217
	v_mul_f32_e32 v218, v225, v218
	v_mul_f32_e32 v219, v225, v219
	v_fmac_f32_e32 v12, v108, v216
	v_fmac_f32_e32 v13, v109, v217
	v_fmac_f32_e32 v14, v110, v218
	v_fmac_f32_e32 v15, v111, v219
	global_store_dwordx4 v192, v[12:15], s[24:25] offset:3072
	v_lshlrev_b32_e32 v216, 16, v40
	v_and_b32_e32 v217, 0xffff0000, v40
	v_lshlrev_b32_e32 v218, 16, v41
	v_and_b32_e32 v219, 0xffff0000, v41
	v_mul_f32_e32 v216, v225, v216
	v_mul_f32_e32 v217, v225, v217
	v_mul_f32_e32 v218, v225, v218
	v_mul_f32_e32 v219, v225, v219
	v_fmac_f32_e32 v16, v112, v216
	v_fmac_f32_e32 v17, v113, v217
	v_fmac_f32_e32 v18, v114, v218
	v_fmac_f32_e32 v19, v115, v219
	global_store_dwordx4 v193, v[16:19], s[24:25] offset:0
	v_lshlrev_b32_e32 v216, 16, v42
	v_and_b32_e32 v217, 0xffff0000, v42
	v_lshlrev_b32_e32 v218, 16, v43
	v_and_b32_e32 v219, 0xffff0000, v43
	v_mul_f32_e32 v216, v225, v216
	v_mul_f32_e32 v217, v225, v217
	v_mul_f32_e32 v218, v225, v218
	v_mul_f32_e32 v219, v225, v219
	v_fmac_f32_e32 v20, v116, v216
	v_fmac_f32_e32 v21, v117, v217
	v_fmac_f32_e32 v22, v118, v218
	v_fmac_f32_e32 v23, v119, v219
	global_store_dwordx4 v193, v[20:23], s[24:25] offset:1024
	v_lshlrev_b32_e32 v216, 16, v44
	v_and_b32_e32 v217, 0xffff0000, v44
	v_lshlrev_b32_e32 v218, 16, v45
	v_and_b32_e32 v219, 0xffff0000, v45
	v_mul_f32_e32 v216, v225, v216
	v_mul_f32_e32 v217, v225, v217
	v_mul_f32_e32 v218, v225, v218
	v_mul_f32_e32 v219, v225, v219
	v_fmac_f32_e32 v24, v120, v216
	v_fmac_f32_e32 v25, v121, v217
	v_fmac_f32_e32 v26, v122, v218
	v_fmac_f32_e32 v27, v123, v219
	global_store_dwordx4 v193, v[24:27], s[24:25] offset:2048
	v_lshlrev_b32_e32 v216, 16, v46
	v_and_b32_e32 v217, 0xffff0000, v46
	v_lshlrev_b32_e32 v218, 16, v47
	v_and_b32_e32 v219, 0xffff0000, v47
	v_mul_f32_e32 v216, v225, v216
	v_mul_f32_e32 v217, v225, v217
	v_mul_f32_e32 v218, v225, v218
	v_mul_f32_e32 v219, v225, v219
	v_fmac_f32_e32 v28, v124, v216
	v_fmac_f32_e32 v29, v125, v217
	v_fmac_f32_e32 v30, v126, v218
	v_fmac_f32_e32 v31, v127, v219
	global_store_dwordx4 v193, v[28:31], s[24:25] offset:3072
	v_mul_f32_e32 v222, v0, v0
	v_mul_f32_e32 v223, v1, v1
	v_fmac_f32_e32 v222, v2, v2
	v_fmac_f32_e32 v223, v3, v3
	v_fmac_f32_e32 v222, v4, v4
	v_fmac_f32_e32 v223, v5, v5
	v_fmac_f32_e32 v222, v6, v6
	v_fmac_f32_e32 v223, v7, v7
	v_fmac_f32_e32 v222, v8, v8
	v_fmac_f32_e32 v223, v9, v9
	v_fmac_f32_e32 v222, v10, v10
	v_fmac_f32_e32 v223, v11, v11
	v_fmac_f32_e32 v222, v12, v12
	v_fmac_f32_e32 v223, v13, v13
	v_fmac_f32_e32 v222, v14, v14
	v_fmac_f32_e32 v223, v15, v15
	v_fmac_f32_e32 v222, v16, v16
	v_fmac_f32_e32 v223, v17, v17
	v_fmac_f32_e32 v222, v18, v18
	v_fmac_f32_e32 v223, v19, v19
	v_fmac_f32_e32 v222, v20, v20
	v_fmac_f32_e32 v223, v21, v21
	v_fmac_f32_e32 v222, v22, v22
	v_fmac_f32_e32 v223, v23, v23
	v_fmac_f32_e32 v222, v24, v24
	v_fmac_f32_e32 v223, v25, v25
	v_fmac_f32_e32 v222, v26, v26
	v_fmac_f32_e32 v223, v27, v27
	v_fmac_f32_e32 v222, v28, v28
	v_fmac_f32_e32 v223, v29, v29
	v_fmac_f32_e32 v222, v30, v30
	v_fmac_f32_e32 v223, v31, v31
	v_add_f32_e32 v222, v222, v223
	s_nop 1
	v_add_f32_dpp v224, v222, v222 quad_perm:[1,0,3,2] row_mask:0xf bank_mask:0xf
	s_nop 1
	v_add_f32_dpp v224, v224, v224 quad_perm:[2,3,0,1] row_mask:0xf bank_mask:0xf
	s_nop 1
	v_add_f32_dpp v224, v224, v224 row_half_mirror row_mask:0xf bank_mask:0xf
	s_nop 1
	v_add_f32_dpp v224, v224, v224 row_mirror row_mask:0xf bank_mask:0xf
	s_nop 1
	v_readlane_b32 s40, v224, 0
	v_readlane_b32 s41, v224, 16
	v_readlane_b32 s42, v224, 32
	v_readlane_b32 s43, v224, 48
	s_nop 1
	v_mov_b32_e32 v225, s40
	v_add_f32_e32 v225, s41, v225
	v_add_f32_e32 v225, s42, v225
	v_add_f32_e32 v225, s43, v225
	v_fmamk_f32 v225, v225, 0x3a000000, v195
	v_rsq_f32_e32 v225, v225
	s_nop 0
	s_add_i32 s0, s6, 4
	s_lshl_b32 s1, s0, 12
	s_add_u32 s26, s84, s1
	s_addc_u32 s27, s85, 0
	s_add_u32 s26, s26, 0x4000000
	s_addc_u32 s27, s27, 0
	v_mul_f32_e32 v216, v225, v0
	v_mul_f32_e32 v217, v225, v1
	v_mul_f32_e32 v218, v225, v2
	v_mul_f32_e32 v219, v225, v3
	v_fma_f32 v216, v216, v128, v160
	v_fma_f32 v217, v217, v129, v161
	v_fma_f32 v218, v218, v130, v162
	v_fma_f32 v219, v219, v131, v163
	v_cvt_pk_bf16_f32 v196, v216, v217
	v_cvt_pk_bf16_f32 v197, v218, v219
	global_store_dwordx2 v194, v[196:197], s[26:27] offset:0
; __device__ __forceinline__ unsigned cvt_pk_bf16(float lo, float hi) { unsigned r; asm volatile("v_cvt_pk_bf16_f32 %0, %1, %2" : "=v"(r) : "v"(lo), "v"(hi)); return r; }
; __device__ __forceinline__ float bf_lo(unsigned w) { return __uint_as_float(w << 16); }
; __device__ __forceinline__ float bf_hi(unsigned w) { return __uint_as_float(w & 0xffff0000u); }
; __device__ __forceinline__ void modulate_store(const f32x4 (&v)[8], float rstd, const float* pn, const float* modr, bf16_t* orow, int lane) {
; #pragma unroll
;     for (int j = 0; j < 8; ++j) { const int col = 4 * lane + 256 * j;
;         const f32x4 g = *(const f32x4*)(pn + col), sh = *(const f32x4*)(modr + col), sc = *(const f32x4*)(modr + DM + col);
;         const f32x4 hh = v[j] * rstd * g * (sc + 1.f) + sh;
;         u32x2 w; w.x = cvt_pk_bf16(hh[0], hh[1]); w.y = cvt_pk_bf16(hh[2], hh[3]);
;         *(u32x2*)(orow + col) = w; }
; }
; __global__ void __launch_bounds__(NWAVES * 64, 2) mk_fwd(Args args) {
;     ...
;         for (int row0 = F.gw * 3; row0 < MT; row0 += F.NGW * 3) {
;             f32x4 v[3][8]; u32x2 yw[3][8];
; #pragma unroll
;             for (int q = 0; q < 3; ++q) { const int row = row0 + q; const float* src = row < ML ? x + (size_t)row * DM : ctx + (size_t)(row - ML) * DM; load_row_f32(src, F.lane, v[q]);
;                 const bf16_t* yr = Y + (size_t)row * DM;
; #pragma unroll
;                 for (int j = 0; j < 8; ++j) yw[q][j] = *(const u32x2*)(yr + 4 * F.lane + 256 * j); }
; #pragma unroll
;             for (int q = 0; q < 3; ++q) { const int row = row0 + q; const bool lat = row < ML; const int r = lat ? row / SEQ : 8;
;                 float sy = 0.f;
; #pragma unroll
;                 for (int j = 0; j < 8; ++j) { const float a = bf_lo(yw[q][j].x), b = bf_hi(yw[q][j].x), c2 = bf_lo(yw[q][j].y), d = bf_hi(yw[q][j].y); sy += (a * a + b * b) + (c2 * c2 + d * d); }
;                 const float rsy = __builtin_amdgcn_rsqf(wave_sum(sy) * (1.f / DM) + EPS);
;                 const float* m0 = mod + (size_t)r * 6144;
; #pragma unroll
;                 for (int j = 0; j < 8; ++j) { const int col = 4 * F.lane + 256 * j; const f32x4 gt = *(const f32x4*)(m0 + 2 * DM + col), pn = *(const f32x4*)(post_norm + col);
	v_mul_f32_e32 v216, v225, v4
	v_mul_f32_e32 v217, v225, v5
	v_mul_f32_e32 v218, v225, v6
	v_mul_f32_e32 v219, v225, v7
	v_fma_f32 v216, v216, v132, v164
	v_fma_f32 v217, v217, v133, v165
	v_fma_f32 v218, v218, v134, v166
	v_fma_f32 v219, v219, v135, v167
	v_cvt_pk_bf16_f32 v220, v216, v217
	v_cvt_pk_bf16_f32 v221, v218, v219
	global_store_dwordx2 v194, v[220:221], s[26:27] offset:512
	v_mul_f32_e32 v216, v225, v8
	v_mul_f32_e32 v217, v225, v9
	v_mul_f32_e32 v218, v225, v10
	v_mul_f32_e32 v219, v225, v11
	v_fma_f32 v216, v216, v136, v168
	v_fma_f32 v217, v217, v137, v169
	v_fma_f32 v218, v218, v138, v170
	v_fma_f32 v219, v219, v139, v171
	v_cvt_pk_bf16_f32 v196, v216, v217
	v_cvt_pk_bf16_f32 v197, v218, v219
	global_store_dwordx2 v194, v[196:197], s[26:27] offset:1024
	v_mul_f32_e32 v216, v225, v12
	v_mul_f32_e32 v217, v225, v13
	v_mul_f32_e32 v218, v225, v14
	v_mul_f32_e32 v219, v225, v15
	v_fma_f32 v216, v216, v140, v172
	v_fma_f32 v217, v217, v141, v173
	v_fma_f32 v218, v218, v142, v174
	v_fma_f32 v219, v219, v143, v175
	v_cvt_pk_bf16_f32 v220, v216, v217
	v_cvt_pk_bf16_f32 v221, v218, v219
	global_store_dwordx2 v194, v[220:221], s[26:27] offset:1536
	v_mul_f32_e32 v216, v225, v16
	v_mul_f32_e32 v217, v225, v17
	v_mul_f32_e32 v218, v225, v18
	v_mul_f32_e32 v219, v225, v19
	v_fma_f32 v216, v216, v144, v176
	v_fma_f32 v217, v217, v145, v177
	v_fma_f32 v218, v218, v146, v178
	v_fma_f32 v219, v219, v147, v179
	v_cvt_pk_bf16_f32 v196, v216, v217
	v_cvt_pk_bf16_f32 v197, v218, v219
	global_store_dwordx2 v194, v[196:197], s[26:27] offset:2048
	v_mul_f32_e32 v216, v225, v20
	v_mul_f32_e32 v217, v225, v21
	v_mul_f32_e32 v218, v225, v22
	v_mul_f32_e32 v219, v225, v23
	v_fma_f32 v216, v216, v148, v180
	v_fma_f32 v217, v217, v149, v181
	v_fma_f32 v218, v218, v150, v182
	v_fma_f32 v219, v219, v151, v183
	v_cvt_pk_bf16_f32 v220, v216, v217
	v_cvt_pk_bf16_f32 v221, v218, v219
	global_store_dwordx2 v194, v[220:221], s[26:27] offset:2560
	v_mul_f32_e32 v216, v225, v24
	v_mul_f32_e32 v217, v225, v25
	v_mul_f32_e32 v218, v225, v26
	v_mul_f32_e32 v219, v225, v27
	v_fma_f32 v216, v216, v152, v184
	v_fma_f32 v217, v217, v153, v185
	v_fma_f32 v218, v218, v154, v186
	v_fma_f32 v219, v219, v155, v187
	v_cvt_pk_bf16_f32 v196, v216, v217
	v_cvt_pk_bf16_f32 v197, v218, v219
	global_store_dwordx2 v194, v[196:197], s[26:27] offset:3072
	v_mul_f32_e32 v216, v225, v28
	v_mul_f32_e32 v217, v225, v29
	v_mul_f32_e32 v218, v225, v30
	v_mul_f32_e32 v219, v225, v31
	v_fma_f32 v216, v216, v156, v188
	v_fma_f32 v217, v217, v157, v189
	v_fma_f32 v218, v218, v158, v190
	v_fma_f32 v219, v219, v159, v191
	v_cvt_pk_bf16_f32 v220, v216, v217
	v_cvt_pk_bf16_f32 v221, v218, v219
	global_store_dwordx2 v194, v[220:221], s[26:27] offset:3584
	s_add_i32 s0, s6, 6
	s_cmp_lt_u32 s0, 0x4000
	s_cselect_b32 s10, s68, s72
	s_cselect_b32 s11, s69, s73
	s_cselect_b32 s1, 0, 0x4000
	s_sub_i32 s1, s0, s1
	s_lshl_b32 s1, s1, 13
	s_add_u32 s10, s10, s1
	s_addc_u32 s11, s11, 0
	s_add_i32 s0, s6, 6
	s_lshl_b32 s1, s0, 12
	s_add_u32 s22, s84, s1
	s_addc_u32 s23, s85, 0
	s_add_u32 s22, s22, 0x11800000
	s_addc_u32 s23, s23, 0
	global_load_dwordx4 v[0:3], v192, s[10:11] offset:0
	global_load_dwordx4 v[4:7], v192, s[10:11] offset:1024
	global_load_dwordx4 v[8:11], v192, s[10:11] offset:2048
	global_load_dwordx4 v[12:15], v192, s[10:11] offset:3072
	global_load_dwordx4 v[16:19], v193, s[10:11] offset:0
	global_load_dwordx4 v[20:23], v193, s[10:11] offset:1024
	global_load_dwordx4 v[24:27], v193, s[10:11] offset:2048
	global_load_dwordx4 v[28:31], v193, s[10:11] offset:3072
	global_load_dwordx2 v[32:33], v194, s[22:23] offset:0
	global_load_dwordx2 v[34:35], v194, s[22:23] offset:512
	global_load_dwordx2 v[36:37], v194, s[22:23] offset:1024
	global_load_dwordx2 v[38:39], v194, s[22:23] offset:1536
	global_load_dwordx2 v[40:41], v194, s[22:23] offset:2048
	global_load_dwordx2 v[42:43], v194, s[22:23] offset:2560
	global_load_dwordx2 v[44:45], v194, s[22:23] offset:3072
	global_load_dwordx2 v[46:47], v194, s[22:23] offset:3584
	s_add_i32 s0, s6, 5
	s_add_i32 s0, s6, 5
	s_lshr_b32 s8, s0, 11
	s_cmp_lt_u32 s0, 0x4000
	s_cselect_b32 s8, s8, 8
	s_cmp_eq_u32 s8, s7
	s_cbranch_scc1 .Lp6_np5
	s_mov_b32 s7, s8
	s_add_i32 s1, s8, 9
	s_mul_i32 s1, s1, 0x6000
	s_add_u32 s44, s84, s1
	s_addc_u32 s45, s85, 0
	s_add_u32 s44, s44, 0x2000
	s_addc_u32 s45, s45, 0
	s_add_i32 s1, s8, 9
	s_mul_i32 s1, s1, 0x6000
	s_add_u32 s36, s84, s1
	s_addc_u32 s37, s85, 0
	s_add_u32 s38, s80, 0x2000
	s_addc_u32 s39, s81, 0
	s_mul_i32 s1, s8, 0x6000
	s_add_u32 s34, s84, s1
	s_addc_u32 s35, s85, 0
	s_add_u32 s34, s34, 0x4000
	s_addc_u32 s35, s35, 0
	global_load_dwordx4 v[96:99], v192, s[34:35] offset:0
	global_load_dwordx4 v[200:203], v192, s[82:83] offset:0
	global_load_dwordx4 v[100:103], v192, s[34:35] offset:1024
	global_load_dwordx4 v[204:207], v192, s[82:83] offset:1024
	global_load_dwordx4 v[104:107], v192, s[34:35] offset:2048
	global_load_dwordx4 v[208:211], v192, s[82:83] offset:2048
	global_load_dwordx4 v[108:111], v192, s[34:35] offset:3072
	global_load_dwordx4 v[212:215], v192, s[82:83] offset:3072
	s_waitcnt vmcnt(0)
; __device__ __forceinline__ void modulate_store(const f32x4 (&v)[8], float rstd, const float* pn, const float* modr, bf16_t* orow, int lane) {
;     ...
;         const f32x4 g = *(const f32x4*)(pn + col), sh = *(const f32x4*)(modr + col), sc = *(const f32x4*)(modr + DM + col);
;         const f32x4 hh = v[j] * rstd * g * (sc + 1.f) + sh;
; __global__ void __launch_bounds__(NWAVES * 64, 2) mk_fwd(Args args) {
;     ...
;                 const float* m0 = mod + (size_t)r * 6144;
; #pragma unroll
;                 for (int j = 0; j < 8; ++j) { const int col = 4 * F.lane + 256 * j; const f32x4 gt = *(const f32x4*)(m0 + 2 * DM + col), pn = *(const f32x4*)(post_norm + col);
	v_mul_f32_e32 v96, v96, v200
	v_mul_f32_e32 v97, v97, v201
	v_mul_f32_e32 v98, v98, v202
	v_mul_f32_e32 v99, v99, v203
	v_mul_f32_e32 v100, v100, v204
	v_mul_f32_e32 v101, v101, v205
	v_mul_f32_e32 v102, v102, v206
	v_mul_f32_e32 v103, v103, v207
	v_mul_f32_e32 v104, v104, v208
	v_mul_f32_e32 v105, v105, v209
	v_mul_f32_e32 v106, v106, v210
	v_mul_f32_e32 v107, v107, v211
	v_mul_f32_e32 v108, v108, v212
	v_mul_f32_e32 v109, v109, v213
	v_mul_f32_e32 v110, v110, v214
	v_mul_f32_e32 v111, v111, v215
	global_load_dwordx4 v[128:131], v192, s[38:39] offset:0
	global_load_dwordx4 v[200:203], v192, s[44:45] offset:0
	global_load_dwordx4 v[160:163], v192, s[36:37] offset:0
	global_load_dwordx4 v[132:135], v192, s[38:39] offset:1024
	global_load_dwordx4 v[204:207], v192, s[44:45] offset:1024
	global_load_dwordx4 v[164:167], v192, s[36:37] offset:1024
	global_load_dwordx4 v[136:139], v192, s[38:39] offset:2048
	global_load_dwordx4 v[208:211], v192, s[44:45] offset:2048
	global_load_dwordx4 v[168:171], v192, s[36:37] offset:2048
	global_load_dwordx4 v[140:143], v192, s[38:39] offset:3072
	global_load_dwordx4 v[212:215], v192, s[44:45] offset:3072
	global_load_dwordx4 v[172:175], v192, s[36:37] offset:3072
	s_waitcnt vmcnt(0)
	v_add_f32_e32 v200, 1.0, v200
	v_add_f32_e32 v201, 1.0, v201
	v_add_f32_e32 v202, 1.0, v202
	v_add_f32_e32 v203, 1.0, v203
	v_mul_f32_e32 v128, v128, v200
	v_mul_f32_e32 v129, v129, v201
	v_mul_f32_e32 v130, v130, v202
	v_mul_f32_e32 v131, v131, v203
	v_add_f32_e32 v204, 1.0, v204
	v_add_f32_e32 v205, 1.0, v205
	v_add_f32_e32 v206, 1.0, v206
	v_add_f32_e32 v207, 1.0, v207
	v_mul_f32_e32 v132, v132, v204
	v_mul_f32_e32 v133, v133, v205
	v_mul_f32_e32 v134, v134, v206
	v_mul_f32_e32 v135, v135, v207
	v_add_f32_e32 v208, 1.0, v208
	v_add_f32_e32 v209, 1.0, v209
	v_add_f32_e32 v210, 1.0, v210
	v_add_f32_e32 v211, 1.0, v211
	v_mul_f32_e32 v136, v136, v208
	v_mul_f32_e32 v137, v137, v209
	v_mul_f32_e32 v138, v138, v210
	v_mul_f32_e32 v139, v139, v211
	v_add_f32_e32 v212, 1.0, v212
	v_add_f32_e32 v213, 1.0, v213
	v_add_f32_e32 v214, 1.0, v214
	v_add_f32_e32 v215, 1.0, v215
	v_mul_f32_e32 v140, v140, v212
	v_mul_f32_e32 v141, v141, v213
	v_mul_f32_e32 v142, v142, v214
	v_mul_f32_e32 v143, v143, v215
	global_load_dwordx4 v[112:115], v193, s[34:35] offset:0
	global_load_dwordx4 v[200:203], v193, s[82:83] offset:0
	global_load_dwordx4 v[116:119], v193, s[34:35] offset:1024
	global_load_dwordx4 v[204:207], v193, s[82:83] offset:1024
	global_load_dwordx4 v[120:123], v193, s[34:35] offset:2048
	global_load_dwordx4 v[208:211], v193, s[82:83] offset:2048
	global_load_dwordx4 v[124:127], v193, s[34:35] offset:3072
	global_load_dwordx4 v[212:215], v193, s[82:83] offset:3072
	s_waitcnt vmcnt(0)
	v_mul_f32_e32 v112, v112, v200
	v_mul_f32_e32 v113, v113, v201
	v_mul_f32_e32 v114, v114, v202
	v_mul_f32_e32 v115, v115, v203
	v_mul_f32_e32 v116, v116, v204
	v_mul_f32_e32 v117, v117, v205
	v_mul_f32_e32 v118, v118, v206
	v_mul_f32_e32 v119, v119, v207
	v_mul_f32_e32 v120, v120, v208
	v_mul_f32_e32 v121, v121, v209
	v_mul_f32_e32 v122, v122, v210
	v_mul_f32_e32 v123, v123, v211
	v_mul_f32_e32 v124, v124, v212
	v_mul_f32_e32 v125, v125, v213
	v_mul_f32_e32 v126, v126, v214
	v_mul_f32_e32 v127, v127, v215
	global_load_dwordx4 v[144:147], v193, s[38:39] offset:0
	global_load_dwordx4 v[200:203], v193, s[44:45] offset:0
	global_load_dwordx4 v[176:179], v193, s[36:37] offset:0
	global_load_dwordx4 v[148:151], v193, s[38:39] offset:1024
	global_load_dwordx4 v[204:207], v193, s[44:45] offset:1024
	global_load_dwordx4 v[180:183], v193, s[36:37] offset:1024
	global_load_dwordx4 v[152:155], v193, s[38:39] offset:2048
	global_load_dwordx4 v[208:211], v193, s[44:45] offset:2048
	global_load_dwordx4 v[184:187], v193, s[36:37] offset:2048
	global_load_dwordx4 v[156:159], v193, s[38:39] offset:3072
	global_load_dwordx4 v[212:215], v193, s[44:45] offset:3072
	global_load_dwordx4 v[188:191], v193, s[36:37] offset:3072
	s_waitcnt vmcnt(0)
	v_add_f32_e32 v200, 1.0, v200
	v_add_f32_e32 v201, 1.0, v201
	v_add_f32_e32 v202, 1.0, v202
	v_add_f32_e32 v203, 1.0, v203
	v_mul_f32_e32 v144, v144, v200
	v_mul_f32_e32 v145, v145, v201
	v_mul_f32_e32 v146, v146, v202
	v_mul_f32_e32 v147, v147, v203
	v_add_f32_e32 v204, 1.0, v204
	v_add_f32_e32 v205, 1.0, v205
	v_add_f32_e32 v206, 1.0, v206
	v_add_f32_e32 v207, 1.0, v207
	v_mul_f32_e32 v148, v148, v204
	v_mul_f32_e32 v149, v149, v205
	v_mul_f32_e32 v150, v150, v206
	v_mul_f32_e32 v151, v151, v207
	v_add_f32_e32 v208, 1.0, v208
	v_add_f32_e32 v209, 1.0, v209
	v_add_f32_e32 v210, 1.0, v210
	v_add_f32_e32 v211, 1.0, v211
	v_mul_f32_e32 v152, v152, v208
	v_mul_f32_e32 v153, v153, v209
	v_mul_f32_e32 v154, v154, v210
	v_mul_f32_e32 v155, v155, v211
	v_add_f32_e32 v212, 1.0, v212
	v_add_f32_e32 v213, 1.0, v213
	v_add_f32_e32 v214, 1.0, v214
	v_add_f32_e32 v215, 1.0, v215
	v_mul_f32_e32 v156, v156, v212
	v_mul_f32_e32 v157, v157, v213
	v_mul_f32_e32 v158, v158, v214
	v_mul_f32_e32 v159, v159, v215
; __device__ __forceinline__ float bf_lo(unsigned w) { return __uint_as_float(w << 16); }
; __device__ __forceinline__ float bf_hi(unsigned w) { return __uint_as_float(w & 0xffff0000u); }
; __global__ void __launch_bounds__(NWAVES * 64, 2) mk_fwd(Args args) {
;     ...
;             for (int q = 0; q < 3; ++q) { const int row = row0 + q; const bool lat = row < ML; const int r = lat ? row / SEQ : 8;
;                 float sy = 0.f;
; #pragma unroll
;                 for (int j = 0; j < 8; ++j) { const float a = bf_lo(yw[q][j].x), b = bf_hi(yw[q][j].x), c2 = bf_lo(yw[q][j].y), d = bf_hi(yw[q][j].y); sy += (a * a + b * b) + (c2 * c2 + d * d); }
;                 const float rsy = __builtin_amdgcn_rsqf(wave_sum(sy) * (1.f / DM) + EPS);
;                 const float* m0 = mod + (size_t)r * 6144;
; #pragma unroll
;                 for (int j = 0; j < 8; ++j) { const int col = 4 * F.lane + 256 * j; const f32x4 gt = *(const f32x4*)(m0 + 2 * DM + col), pn = *(const f32x4*)(post_norm + col);
;                     const f32x4 y4 = (f32x4){bf_lo(yw[q][j].x), bf_hi(yw[q][j].x), bf_lo(yw[q][j].y), bf_hi(yw[q][j].y)};
;                     v[q][j] = v[q][j] + gt * (y4 * rsy * pn);
;                     if (lat) *(f32x4*)(args.out + (size_t)row * DM + col) = v[q][j]; }
.Lp6_np5:
	s_waitcnt vmcnt(32)
	v_lshlrev_b32_e32 v216, 16, v80
	v_and_b32_e32 v217, 0xffff0000, v80
	v_lshlrev_b32_e32 v218, 16, v81
	v_and_b32_e32 v219, 0xffff0000, v81
	v_mul_f32_e32 v222, v216, v216
	v_mul_f32_e32 v223, v217, v217
	v_fmac_f32_e32 v222, v218, v218
	v_fmac_f32_e32 v223, v219, v219
	v_lshlrev_b32_e32 v216, 16, v82
	v_and_b32_e32 v217, 0xffff0000, v82
	v_lshlrev_b32_e32 v218, 16, v83
	v_and_b32_e32 v219, 0xffff0000, v83
	v_fmac_f32_e32 v222, v216, v216
	v_fmac_f32_e32 v223, v217, v217
	v_fmac_f32_e32 v222, v218, v218
	v_fmac_f32_e32 v223, v219, v219
	v_lshlrev_b32_e32 v216, 16, v84
	v_and_b32_e32 v217, 0xffff0000, v84
	v_lshlrev_b32_e32 v218, 16, v85
	v_and_b32_e32 v219, 0xffff0000, v85
	v_fmac_f32_e32 v222, v216, v216
	v_fmac_f32_e32 v223, v217, v217
	v_fmac_f32_e32 v222, v218, v218
	v_fmac_f32_e32 v223, v219, v219
	v_lshlrev_b32_e32 v216, 16, v86
	v_and_b32_e32 v217, 0xffff0000, v86
	v_lshlrev_b32_e32 v218, 16, v87
	v_and_b32_e32 v219, 0xffff0000, v87
	v_fmac_f32_e32 v222, v216, v216
	v_fmac_f32_e32 v223, v217, v217
	v_fmac_f32_e32 v222, v218, v218
	v_fmac_f32_e32 v223, v219, v219
	v_lshlrev_b32_e32 v216, 16, v88
	v_and_b32_e32 v217, 0xffff0000, v88
	v_lshlrev_b32_e32 v218, 16, v89
	v_and_b32_e32 v219, 0xffff0000, v89
	v_fmac_f32_e32 v222, v216, v216
	v_fmac_f32_e32 v223, v217, v217
	v_fmac_f32_e32 v222, v218, v218
	v_fmac_f32_e32 v223, v219, v219
	v_lshlrev_b32_e32 v216, 16, v90
	v_and_b32_e32 v217, 0xffff0000, v90
	v_lshlrev_b32_e32 v218, 16, v91
	v_and_b32_e32 v219, 0xffff0000, v91
	v_fmac_f32_e32 v222, v216, v216
	v_fmac_f32_e32 v223, v217, v217
	v_fmac_f32_e32 v222, v218, v218
	v_fmac_f32_e32 v223, v219, v219
	v_lshlrev_b32_e32 v216, 16, v92
	v_and_b32_e32 v217, 0xffff0000, v92
	v_lshlrev_b32_e32 v218, 16, v93
	v_and_b32_e32 v219, 0xffff0000, v93
	v_fmac_f32_e32 v222, v216, v216
	v_fmac_f32_e32 v223, v217, v217
	v_fmac_f32_e32 v222, v218, v218
	v_fmac_f32_e32 v223, v219, v219
	v_lshlrev_b32_e32 v216, 16, v94
	v_and_b32_e32 v217, 0xffff0000, v94
	v_lshlrev_b32_e32 v218, 16, v95
	v_and_b32_e32 v219, 0xffff0000, v95
	v_fmac_f32_e32 v222, v216, v216
	v_fmac_f32_e32 v223, v217, v217
	v_fmac_f32_e32 v222, v218, v218
	v_fmac_f32_e32 v223, v219, v219
	v_add_f32_e32 v222, v222, v223
	s_nop 1
	v_add_f32_dpp v224, v222, v222 quad_perm:[1,0,3,2] row_mask:0xf bank_mask:0xf
	s_nop 1
	v_add_f32_dpp v224, v224, v224 quad_perm:[2,3,0,1] row_mask:0xf bank_mask:0xf
	s_nop 1
	v_add_f32_dpp v224, v224, v224 row_half_mirror row_mask:0xf bank_mask:0xf
	s_nop 1
	v_add_f32_dpp v224, v224, v224 row_mirror row_mask:0xf bank_mask:0xf
	s_nop 1
	v_readlane_b32 s40, v224, 0
	v_readlane_b32 s41, v224, 16
	v_readlane_b32 s42, v224, 32
	v_readlane_b32 s43, v224, 48
	s_nop 1
	v_mov_b32_e32 v225, s40
	v_add_f32_e32 v225, s41, v225
	v_add_f32_e32 v225, s42, v225
	v_add_f32_e32 v225, s43, v225
	v_fmamk_f32 v225, v225, 0x3a000000, v195
	v_rsq_f32_e32 v225, v225
	s_nop 0
	s_add_i32 s0, s6, 5
	s_cmp_lt_u32 s0, 0x4000
	s_cselect_b32 s24, s94, s84
	s_cselect_b32 s25, s95, s85
	s_cselect_b32 s44, 0, 0x16000000
	s_cselect_b32 s1, 0, 0x4000
	s_sub_i32 s1, s0, s1
	s_lshl_b32 s1, s1, 13
	s_add_u32 s24, s24, s1
	s_addc_u32 s25, s25, 0
	s_add_u32 s24, s24, s44
	s_addc_u32 s25, s25, 0
	v_lshlrev_b32_e32 v216, 16, v80
	v_and_b32_e32 v217, 0xffff0000, v80
	v_lshlrev_b32_e32 v218, 16, v81
	v_and_b32_e32 v219, 0xffff0000, v81
	v_mul_f32_e32 v216, v225, v216
	v_mul_f32_e32 v217, v225, v217
	v_mul_f32_e32 v218, v225, v218
	v_mul_f32_e32 v219, v225, v219
	v_fmac_f32_e32 v48, v96, v216
	v_fmac_f32_e32 v49, v97, v217
	v_fmac_f32_e32 v50, v98, v218
	v_fmac_f32_e32 v51, v99, v219
	global_store_dwordx4 v192, v[48:51], s[24:25] offset:0
	v_lshlrev_b32_e32 v216, 16, v82
	v_and_b32_e32 v217, 0xffff0000, v82
	v_lshlrev_b32_e32 v218, 16, v83
	v_and_b32_e32 v219, 0xffff0000, v83
	v_mul_f32_e32 v216, v225, v216
	v_mul_f32_e32 v217, v225, v217
	v_mul_f32_e32 v218, v225, v218
	v_mul_f32_e32 v219, v225, v219
	v_fmac_f32_e32 v52, v100, v216
	v_fmac_f32_e32 v53, v101, v217
	v_fmac_f32_e32 v54, v102, v218
	v_fmac_f32_e32 v55, v103, v219
	global_store_dwordx4 v192, v[52:55], s[24:25] offset:1024
	v_lshlrev_b32_e32 v216, 16, v84
	v_and_b32_e32 v217, 0xffff0000, v84
	v_lshlrev_b32_e32 v218, 16, v85
	v_and_b32_e32 v219, 0xffff0000, v85
	v_mul_f32_e32 v216, v225, v216
	v_mul_f32_e32 v217, v225, v217
	v_mul_f32_e32 v218, v225, v218
	v_mul_f32_e32 v219, v225, v219
	v_fmac_f32_e32 v56, v104, v216
	v_fmac_f32_e32 v57, v105, v217
	v_fmac_f32_e32 v58, v106, v218
	v_fmac_f32_e32 v59, v107, v219
	global_store_dwordx4 v192, v[56:59], s[24:25] offset:2048
	v_lshlrev_b32_e32 v216, 16, v86
	v_and_b32_e32 v217, 0xffff0000, v86
	v_lshlrev_b32_e32 v218, 16, v87
	v_and_b32_e32 v219, 0xffff0000, v87
	v_mul_f32_e32 v216, v225, v216
	v_mul_f32_e32 v217, v225, v217
	v_mul_f32_e32 v218, v225, v218
	v_mul_f32_e32 v219, v225, v219
	v_fmac_f32_e32 v60, v108, v216
	v_fmac_f32_e32 v61, v109, v217
	v_fmac_f32_e32 v62, v110, v218
	v_fmac_f32_e32 v63, v111, v219
	global_store_dwordx4 v192, v[60:63], s[24:25] offset:3072
	v_lshlrev_b32_e32 v216, 16, v88
	v_and_b32_e32 v217, 0xffff0000, v88
	v_lshlrev_b32_e32 v218, 16, v89
	v_and_b32_e32 v219, 0xffff0000, v89
	v_mul_f32_e32 v216, v225, v216
	v_mul_f32_e32 v217, v225, v217
	v_mul_f32_e32 v218, v225, v218
	v_mul_f32_e32 v219, v225, v219
	v_fmac_f32_e32 v64, v112, v216
	v_fmac_f32_e32 v65, v113, v217
	v_fmac_f32_e32 v66, v114, v218
	v_fmac_f32_e32 v67, v115, v219
	global_store_dwordx4 v193, v[64:67], s[24:25] offset:0
	v_lshlrev_b32_e32 v216, 16, v90
	v_and_b32_e32 v217, 0xffff0000, v90
	v_lshlrev_b32_e32 v218, 16, v91
	v_and_b32_e32 v219, 0xffff0000, v91
	v_mul_f32_e32 v216, v225, v216
; __device__ __forceinline__ unsigned cvt_pk_bf16(float lo, float hi) { unsigned r; asm volatile("v_cvt_pk_bf16_f32 %0, %1, %2" : "=v"(r) : "v"(lo), "v"(hi)); return r; }
; __device__ __forceinline__ float bf_lo(unsigned w) { return __uint_as_float(w << 16); }
; __device__ __forceinline__ float bf_hi(unsigned w) { return __uint_as_float(w & 0xffff0000u); }
; __device__ __forceinline__ float sumsq8(const f32x4 (&v)[8]) {
;     float s = 0.f;
; #pragma unroll
;     for (int j = 0; j < 8; ++j) s += (v[j][0] * v[j][0] + v[j][1] * v[j][1]) + (v[j][2] * v[j][2] + v[j][3] * v[j][3]);
;     return wave_sum(s);
; }
; __device__ __forceinline__ void modulate_store(const f32x4 (&v)[8], float rstd, const float* pn, const float* modr, bf16_t* orow, int lane) {
; #pragma unroll
;     for (int j = 0; j < 8; ++j) { const int col = 4 * lane + 256 * j;
;         const f32x4 g = *(const f32x4*)(pn + col), sh = *(const f32x4*)(modr + col), sc = *(const f32x4*)(modr + DM + col);
;         const f32x4 hh = v[j] * rstd * g * (sc + 1.f) + sh;
;         u32x2 w; w.x = cvt_pk_bf16(hh[0], hh[1]); w.y = cvt_pk_bf16(hh[2], hh[3]);
;         *(u32x2*)(orow + col) = w; }
; }
; __global__ void __launch_bounds__(NWAVES * 64, 2) mk_fwd(Args args) {
;     ...
;                 for (int j = 0; j < 8; ++j) { const int col = 4 * F.lane + 256 * j; const f32x4 gt = *(const f32x4*)(m0 + 2 * DM + col), pn = *(const f32x4*)(post_norm + col);
;                     const f32x4 y4 = (f32x4){bf_lo(yw[q][j].x), bf_hi(yw[q][j].x), bf_lo(yw[q][j].y), bf_hi(yw[q][j].y)};
;                     v[q][j] = v[q][j] + gt * (y4 * rsy * pn);
;                     if (lat) *(f32x4*)(args.out + (size_t)row * DM + col) = v[q][j]; }
;                 const float rstd = __builtin_amdgcn_rsqf(sumsq8(v[q]) * (1.f / DM) + EPS);
;                 modulate_store(v[q], rstd, pre_norm + DM, mod + (size_t)(9 + r) * 6144, H + (size_t)row * DM, F.lane); }
	v_mul_f32_e32 v217, v225, v217
	v_mul_f32_e32 v218, v225, v218
	v_mul_f32_e32 v219, v225, v219
	v_fmac_f32_e32 v68, v116, v216
	v_fmac_f32_e32 v69, v117, v217
	v_fmac_f32_e32 v70, v118, v218
	v_fmac_f32_e32 v71, v119, v219
	global_store_dwordx4 v193, v[68:71], s[24:25] offset:1024
	v_lshlrev_b32_e32 v216, 16, v92
	v_and_b32_e32 v217, 0xffff0000, v92
	v_lshlrev_b32_e32 v218, 16, v93
	v_and_b32_e32 v219, 0xffff0000, v93
	v_mul_f32_e32 v216, v225, v216
	v_mul_f32_e32 v217, v225, v217
	v_mul_f32_e32 v218, v225, v218
	v_mul_f32_e32 v219, v225, v219
	v_fmac_f32_e32 v72, v120, v216
	v_fmac_f32_e32 v73, v121, v217
	v_fmac_f32_e32 v74, v122, v218
	v_fmac_f32_e32 v75, v123, v219
	global_store_dwordx4 v193, v[72:75], s[24:25] offset:2048
	v_lshlrev_b32_e32 v216, 16, v94
	v_and_b32_e32 v217, 0xffff0000, v94
	v_lshlrev_b32_e32 v218, 16, v95
	v_and_b32_e32 v219, 0xffff0000, v95
	v_mul_f32_e32 v216, v225, v216
	v_mul_f32_e32 v217, v225, v217
	v_mul_f32_e32 v218, v225, v218
	v_mul_f32_e32 v219, v225, v219
	v_fmac_f32_e32 v76, v124, v216
	v_fmac_f32_e32 v77, v125, v217
	v_fmac_f32_e32 v78, v126, v218
	v_fmac_f32_e32 v79, v127, v219
	global_store_dwordx4 v193, v[76:79], s[24:25] offset:3072
	v_mul_f32_e32 v222, v48, v48
	v_mul_f32_e32 v223, v49, v49
	v_fmac_f32_e32 v222, v50, v50
	v_fmac_f32_e32 v223, v51, v51
	v_fmac_f32_e32 v222, v52, v52
	v_fmac_f32_e32 v223, v53, v53
	v_fmac_f32_e32 v222, v54, v54
	v_fmac_f32_e32 v223, v55, v55
	v_fmac_f32_e32 v222, v56, v56
	v_fmac_f32_e32 v223, v57, v57
	v_fmac_f32_e32 v222, v58, v58
	v_fmac_f32_e32 v223, v59, v59
	v_fmac_f32_e32 v222, v60, v60
	v_fmac_f32_e32 v223, v61, v61
	v_fmac_f32_e32 v222, v62, v62
	v_fmac_f32_e32 v223, v63, v63
	v_fmac_f32_e32 v222, v64, v64
	v_fmac_f32_e32 v223, v65, v65
	v_fmac_f32_e32 v222, v66, v66
	v_fmac_f32_e32 v223, v67, v67
	v_fmac_f32_e32 v222, v68, v68
	v_fmac_f32_e32 v223, v69, v69
	v_fmac_f32_e32 v222, v70, v70
	v_fmac_f32_e32 v223, v71, v71
	v_fmac_f32_e32 v222, v72, v72
	v_fmac_f32_e32 v223, v73, v73
	v_fmac_f32_e32 v222, v74, v74
	v_fmac_f32_e32 v223, v75, v75
	v_fmac_f32_e32 v222, v76, v76
	v_fmac_f32_e32 v223, v77, v77
	v_fmac_f32_e32 v222, v78, v78
	v_fmac_f32_e32 v223, v79, v79
	v_add_f32_e32 v222, v222, v223
	s_nop 1
	v_add_f32_dpp v224, v222, v222 quad_perm:[1,0,3,2] row_mask:0xf bank_mask:0xf
	s_nop 1
	v_add_f32_dpp v224, v224, v224 quad_perm:[2,3,0,1] row_mask:0xf bank_mask:0xf
	s_nop 1
	v_add_f32_dpp v224, v224, v224 row_half_mirror row_mask:0xf bank_mask:0xf
	s_nop 1
	v_add_f32_dpp v224, v224, v224 row_mirror row_mask:0xf bank_mask:0xf
	s_nop 1
	v_readlane_b32 s40, v224, 0
	v_readlane_b32 s41, v224, 16
	v_readlane_b32 s42, v224, 32
	v_readlane_b32 s43, v224, 48
	s_nop 1
	v_mov_b32_e32 v225, s40
	v_add_f32_e32 v225, s41, v225
	v_add_f32_e32 v225, s42, v225
	v_add_f32_e32 v225, s43, v225
	v_fmamk_f32 v225, v225, 0x3a000000, v195
	v_rsq_f32_e32 v225, v225
	s_nop 0
	s_add_i32 s0, s6, 5
	s_lshl_b32 s1, s0, 12
	s_add_u32 s26, s84, s1
	s_addc_u32 s27, s85, 0
	s_add_u32 s26, s26, 0x4000000
	s_addc_u32 s27, s27, 0
	v_mul_f32_e32 v216, v225, v48
	v_mul_f32_e32 v217, v225, v49
	v_mul_f32_e32 v218, v225, v50
	v_mul_f32_e32 v219, v225, v51
	v_fma_f32 v216, v216, v128, v160
	v_fma_f32 v217, v217, v129, v161
	v_fma_f32 v218, v218, v130, v162
	v_fma_f32 v219, v219, v131, v163
	v_cvt_pk_bf16_f32 v196, v216, v217
	v_cvt_pk_bf16_f32 v197, v218, v219
	global_store_dwordx2 v194, v[196:197], s[26:27] offset:0
	v_mul_f32_e32 v216, v225, v52
	v_mul_f32_e32 v217, v225, v53
	v_mul_f32_e32 v218, v225, v54
	v_mul_f32_e32 v219, v225, v55
	v_fma_f32 v216, v216, v132, v164
	v_fma_f32 v217, v217, v133, v165
	v_fma_f32 v218, v218, v134, v166
	v_fma_f32 v219, v219, v135, v167
	v_cvt_pk_bf16_f32 v220, v216, v217
	v_cvt_pk_bf16_f32 v221, v218, v219
	global_store_dwordx2 v194, v[220:221], s[26:27] offset:512
	v_mul_f32_e32 v216, v225, v56
	v_mul_f32_e32 v217, v225, v57
	v_mul_f32_e32 v218, v225, v58
	v_mul_f32_e32 v219, v225, v59
	v_fma_f32 v216, v216, v136, v168
	v_fma_f32 v217, v217, v137, v169
	v_fma_f32 v218, v218, v138, v170
	v_fma_f32 v219, v219, v139, v171
	v_cvt_pk_bf16_f32 v196, v216, v217
	v_cvt_pk_bf16_f32 v197, v218, v219
	global_store_dwordx2 v194, v[196:197], s[26:27] offset:1024
	v_mul_f32_e32 v216, v225, v60
	v_mul_f32_e32 v217, v225, v61
	v_mul_f32_e32 v218, v225, v62
	v_mul_f32_e32 v219, v225, v63
	v_fma_f32 v216, v216, v140, v172
	v_fma_f32 v217, v217, v141, v173
	v_fma_f32 v218, v218, v142, v174
	v_fma_f32 v219, v219, v143, v175
	v_cvt_pk_bf16_f32 v220, v216, v217
	v_cvt_pk_bf16_f32 v221, v218, v219
	global_store_dwordx2 v194, v[220:221], s[26:27] offset:1536
	v_mul_f32_e32 v216, v225, v64
	v_mul_f32_e32 v217, v225, v65
	v_mul_f32_e32 v218, v225, v66
	v_mul_f32_e32 v219, v225, v67
	v_fma_f32 v216, v216, v144, v176
	v_fma_f32 v217, v217, v145, v177
	v_fma_f32 v218, v218, v146, v178
	v_fma_f32 v219, v219, v147, v179
	v_cvt_pk_bf16_f32 v196, v216, v217
	v_cvt_pk_bf16_f32 v197, v218, v219
	global_store_dwordx2 v194, v[196:197], s[26:27] offset:2048
	v_mul_f32_e32 v216, v225, v68
	v_mul_f32_e32 v217, v225, v69
	v_mul_f32_e32 v218, v225, v70
	v_mul_f32_e32 v219, v225, v71
	v_fma_f32 v216, v216, v148, v180
	v_fma_f32 v217, v217, v149, v181
	v_fma_f32 v218, v218, v150, v182
	v_fma_f32 v219, v219, v151, v183
	v_cvt_pk_bf16_f32 v220, v216, v217
	v_cvt_pk_bf16_f32 v221, v218, v219
	global_store_dwordx2 v194, v[220:221], s[26:27] offset:2560
	v_mul_f32_e32 v216, v225, v72
	v_mul_f32_e32 v217, v225, v73
	v_mul_f32_e32 v218, v225, v74
	v_mul_f32_e32 v219, v225, v75
	v_fma_f32 v216, v216, v152, v184
	v_fma_f32 v217, v217, v153, v185
	v_fma_f32 v218, v218, v154, v186
	v_fma_f32 v219, v219, v155, v187
; __device__ __forceinline__ unsigned cvt_pk_bf16(float lo, float hi) { unsigned r; asm volatile("v_cvt_pk_bf16_f32 %0, %1, %2" : "=v"(r) : "v"(lo), "v"(hi)); return r; }
; __device__ __forceinline__ float bf_lo(unsigned w) { return __uint_as_float(w << 16); }
; __device__ __forceinline__ float bf_hi(unsigned w) { return __uint_as_float(w & 0xffff0000u); }
; __device__ __forceinline__ void modulate_store(const f32x4 (&v)[8], float rstd, const float* pn, const float* modr, bf16_t* orow, int lane) {
; #pragma unroll
;     for (int j = 0; j < 8; ++j) { const int col = 4 * lane + 256 * j;
;         const f32x4 g = *(const f32x4*)(pn + col), sh = *(const f32x4*)(modr + col), sc = *(const f32x4*)(modr + DM + col);
;         const f32x4 hh = v[j] * rstd * g * (sc + 1.f) + sh;
;         u32x2 w; w.x = cvt_pk_bf16(hh[0], hh[1]); w.y = cvt_pk_bf16(hh[2], hh[3]);
;         *(u32x2*)(orow + col) = w; }
; }
; __global__ void __launch_bounds__(NWAVES * 64, 2) mk_fwd(Args args) {
;     ...
;         for (int row0 = F.gw * 3; row0 < MT; row0 += F.NGW * 3) {
;             f32x4 v[3][8]; u32x2 yw[3][8];
; #pragma unroll
;             for (int q = 0; q < 3; ++q) { const int row = row0 + q; const float* src = row < ML ? x + (size_t)row * DM : ctx + (size_t)(row - ML) * DM; load_row_f32(src, F.lane, v[q]);
;                 const bf16_t* yr = Y + (size_t)row * DM;
; #pragma unroll
;                 for (int j = 0; j < 8; ++j) yw[q][j] = *(const u32x2*)(yr + 4 * F.lane + 256 * j); }
; #pragma unroll
;             for (int q = 0; q < 3; ++q) { const int row = row0 + q; const bool lat = row < ML; const int r = lat ? row / SEQ : 8;
;                 float sy = 0.f;
; #pragma unroll
;                 for (int j = 0; j < 8; ++j) { const float a = bf_lo(yw[q][j].x), b = bf_hi(yw[q][j].x), c2 = bf_lo(yw[q][j].y), d = bf_hi(yw[q][j].y); sy += (a * a + b * b) + (c2 * c2 + d * d); }
;                 const float rsy = __builtin_amdgcn_rsqf(wave_sum(sy) * (1.f / DM) + EPS);
;                 const float* m0 = mod + (size_t)r * 6144;
; #pragma unroll
;                 for (int j = 0; j < 8; ++j) { const int col = 4 * F.lane + 256 * j; const f32x4 gt = *(const f32x4*)(m0 + 2 * DM + col), pn = *(const f32x4*)(post_norm + col);
	v_cvt_pk_bf16_f32 v196, v216, v217
	v_cvt_pk_bf16_f32 v197, v218, v219
	global_store_dwordx2 v194, v[196:197], s[26:27] offset:3072
	v_mul_f32_e32 v216, v225, v76
	v_mul_f32_e32 v217, v225, v77
	v_mul_f32_e32 v218, v225, v78
	v_mul_f32_e32 v219, v225, v79
	v_fma_f32 v216, v216, v156, v188
	v_fma_f32 v217, v217, v157, v189
	v_fma_f32 v218, v218, v158, v190
	v_fma_f32 v219, v219, v159, v191
	v_cvt_pk_bf16_f32 v220, v216, v217
	v_cvt_pk_bf16_f32 v221, v218, v219
	global_store_dwordx2 v194, v[220:221], s[26:27] offset:3584
	s_add_i32 s0, s6, 7
	s_cmp_lt_u32 s0, 0x4000
	s_cselect_b32 s10, s68, s72
	s_cselect_b32 s11, s69, s73
	s_cselect_b32 s1, 0, 0x4000
	s_sub_i32 s1, s0, s1
	s_lshl_b32 s1, s1, 13
	s_add_u32 s10, s10, s1
	s_addc_u32 s11, s11, 0
	s_add_i32 s0, s6, 7
	s_lshl_b32 s1, s0, 12
	s_add_u32 s22, s84, s1
	s_addc_u32 s23, s85, 0
	s_add_u32 s22, s22, 0x11800000
	s_addc_u32 s23, s23, 0
	global_load_dwordx4 v[48:51], v192, s[10:11] offset:0
	global_load_dwordx4 v[52:55], v192, s[10:11] offset:1024
	global_load_dwordx4 v[56:59], v192, s[10:11] offset:2048
	global_load_dwordx4 v[60:63], v192, s[10:11] offset:3072
	global_load_dwordx4 v[64:67], v193, s[10:11] offset:0
	global_load_dwordx4 v[68:71], v193, s[10:11] offset:1024
	global_load_dwordx4 v[72:75], v193, s[10:11] offset:2048
	global_load_dwordx4 v[76:79], v193, s[10:11] offset:3072
	global_load_dwordx2 v[80:81], v194, s[22:23] offset:0
	global_load_dwordx2 v[82:83], v194, s[22:23] offset:512
	global_load_dwordx2 v[84:85], v194, s[22:23] offset:1024
	global_load_dwordx2 v[86:87], v194, s[22:23] offset:1536
	global_load_dwordx2 v[88:89], v194, s[22:23] offset:2048
	global_load_dwordx2 v[90:91], v194, s[22:23] offset:2560
	global_load_dwordx2 v[92:93], v194, s[22:23] offset:3072
	global_load_dwordx2 v[94:95], v194, s[22:23] offset:3584
	s_add_i32 s0, s6, 6
	s_add_i32 s0, s6, 6
	s_lshr_b32 s8, s0, 11
	s_cmp_lt_u32 s0, 0x4000
	s_cselect_b32 s8, s8, 8
	s_cmp_eq_u32 s8, s7
	s_cbranch_scc1 .Lp6_np6
	s_mov_b32 s7, s8
	s_add_i32 s1, s8, 9
	s_mul_i32 s1, s1, 0x6000
	s_add_u32 s44, s84, s1
	s_addc_u32 s45, s85, 0
	s_add_u32 s44, s44, 0x2000
	s_addc_u32 s45, s45, 0
	s_add_i32 s1, s8, 9
	s_mul_i32 s1, s1, 0x6000
	s_add_u32 s36, s84, s1
	s_addc_u32 s37, s85, 0
	s_add_u32 s38, s80, 0x2000
	s_addc_u32 s39, s81, 0
	s_mul_i32 s1, s8, 0x6000
	s_add_u32 s34, s84, s1
	s_addc_u32 s35, s85, 0
	s_add_u32 s34, s34, 0x4000
	s_addc_u32 s35, s35, 0
	global_load_dwordx4 v[96:99], v192, s[34:35] offset:0
	global_load_dwordx4 v[200:203], v192, s[82:83] offset:0
	global_load_dwordx4 v[100:103], v192, s[34:35] offset:1024
	global_load_dwordx4 v[204:207], v192, s[82:83] offset:1024
	global_load_dwordx4 v[104:107], v192, s[34:35] offset:2048
	global_load_dwordx4 v[208:211], v192, s[82:83] offset:2048
	global_load_dwordx4 v[108:111], v192, s[34:35] offset:3072
	global_load_dwordx4 v[212:215], v192, s[82:83] offset:3072
	s_waitcnt vmcnt(0)
	v_mul_f32_e32 v96, v96, v200
	v_mul_f32_e32 v97, v97, v201
	v_mul_f32_e32 v98, v98, v202
	v_mul_f32_e32 v99, v99, v203
	v_mul_f32_e32 v100, v100, v204
	v_mul_f32_e32 v101, v101, v205
	v_mul_f32_e32 v102, v102, v206
	v_mul_f32_e32 v103, v103, v207
	v_mul_f32_e32 v104, v104, v208
	v_mul_f32_e32 v105, v105, v209
	v_mul_f32_e32 v106, v106, v210
	v_mul_f32_e32 v107, v107, v211
	v_mul_f32_e32 v108, v108, v212
	v_mul_f32_e32 v109, v109, v213
	v_mul_f32_e32 v110, v110, v214
	v_mul_f32_e32 v111, v111, v215
	global_load_dwordx4 v[128:131], v192, s[38:39] offset:0
	global_load_dwordx4 v[200:203], v192, s[44:45] offset:0
	global_load_dwordx4 v[160:163], v192, s[36:37] offset:0
	global_load_dwordx4 v[132:135], v192, s[38:39] offset:1024
	global_load_dwordx4 v[204:207], v192, s[44:45] offset:1024
	global_load_dwordx4 v[164:167], v192, s[36:37] offset:1024
	global_load_dwordx4 v[136:139], v192, s[38:39] offset:2048
	global_load_dwordx4 v[208:211], v192, s[44:45] offset:2048
	global_load_dwordx4 v[168:171], v192, s[36:37] offset:2048
	global_load_dwordx4 v[140:143], v192, s[38:39] offset:3072
	global_load_dwordx4 v[212:215], v192, s[44:45] offset:3072
	global_load_dwordx4 v[172:175], v192, s[36:37] offset:3072
	s_waitcnt vmcnt(0)
	v_add_f32_e32 v200, 1.0, v200
	v_add_f32_e32 v201, 1.0, v201
	v_add_f32_e32 v202, 1.0, v202
	v_add_f32_e32 v203, 1.0, v203
	v_mul_f32_e32 v128, v128, v200
	v_mul_f32_e32 v129, v129, v201
	v_mul_f32_e32 v130, v130, v202
	v_mul_f32_e32 v131, v131, v203
	v_add_f32_e32 v204, 1.0, v204
	v_add_f32_e32 v205, 1.0, v205
	v_add_f32_e32 v206, 1.0, v206
	v_add_f32_e32 v207, 1.0, v207
	v_mul_f32_e32 v132, v132, v204
	v_mul_f32_e32 v133, v133, v205
	v_mul_f32_e32 v134, v134, v206
	v_mul_f32_e32 v135, v135, v207
	v_add_f32_e32 v208, 1.0, v208
	v_add_f32_e32 v209, 1.0, v209
	v_add_f32_e32 v210, 1.0, v210
	v_add_f32_e32 v211, 1.0, v211
	v_mul_f32_e32 v136, v136, v208
	v_mul_f32_e32 v137, v137, v209
	v_mul_f32_e32 v138, v138, v210
	v_mul_f32_e32 v139, v139, v211
	v_add_f32_e32 v212, 1.0, v212
	v_add_f32_e32 v213, 1.0, v213
	v_add_f32_e32 v214, 1.0, v214
	v_add_f32_e32 v215, 1.0, v215
	v_mul_f32_e32 v140, v140, v212
	v_mul_f32_e32 v141, v141, v213
	v_mul_f32_e32 v142, v142, v214
	v_mul_f32_e32 v143, v143, v215
	global_load_dwordx4 v[112:115], v193, s[34:35] offset:0
	global_load_dwordx4 v[200:203], v193, s[82:83] offset:0
	global_load_dwordx4 v[116:119], v193, s[34:35] offset:1024
	global_load_dwordx4 v[204:207], v193, s[82:83] offset:1024
	global_load_dwordx4 v[120:123], v193, s[34:35] offset:2048
	global_load_dwordx4 v[208:211], v193, s[82:83] offset:2048
	global_load_dwordx4 v[124:127], v193, s[34:35] offset:3072
	global_load_dwordx4 v[212:215], v193, s[82:83] offset:3072
	s_waitcnt vmcnt(0)
; __device__ __forceinline__ float bf_lo(unsigned w) { return __uint_as_float(w << 16); }
; __device__ __forceinline__ float bf_hi(unsigned w) { return __uint_as_float(w & 0xffff0000u); }
; __device__ __forceinline__ void modulate_store(const f32x4 (&v)[8], float rstd, const float* pn, const float* modr, bf16_t* orow, int lane) {
;     ...
;         const f32x4 g = *(const f32x4*)(pn + col), sh = *(const f32x4*)(modr + col), sc = *(const f32x4*)(modr + DM + col);
;         const f32x4 hh = v[j] * rstd * g * (sc + 1.f) + sh;
; __global__ void __launch_bounds__(NWAVES * 64, 2) mk_fwd(Args args) {
;     ...
;             for (int q = 0; q < 3; ++q) { const int row = row0 + q; const bool lat = row < ML; const int r = lat ? row / SEQ : 8;
;                 float sy = 0.f;
; #pragma unroll
;                 for (int j = 0; j < 8; ++j) { const float a = bf_lo(yw[q][j].x), b = bf_hi(yw[q][j].x), c2 = bf_lo(yw[q][j].y), d = bf_hi(yw[q][j].y); sy += (a * a + b * b) + (c2 * c2 + d * d); }
;                 const float rsy = __builtin_amdgcn_rsqf(wave_sum(sy) * (1.f / DM) + EPS);
;                 const float* m0 = mod + (size_t)r * 6144;
; #pragma unroll
;                 for (int j = 0; j < 8; ++j) { const int col = 4 * F.lane + 256 * j; const f32x4 gt = *(const f32x4*)(m0 + 2 * DM + col), pn = *(const f32x4*)(post_norm + col);
;                     const f32x4 y4 = (f32x4){bf_lo(yw[q][j].x), bf_hi(yw[q][j].x), bf_lo(yw[q][j].y), bf_hi(yw[q][j].y)};
;                     v[q][j] = v[q][j] + gt * (y4 * rsy * pn);
;                     if (lat) *(f32x4*)(args.out + (size_t)row * DM + col) = v[q][j]; }
	v_mul_f32_e32 v112, v112, v200
	v_mul_f32_e32 v113, v113, v201
	v_mul_f32_e32 v114, v114, v202
	v_mul_f32_e32 v115, v115, v203
	v_mul_f32_e32 v116, v116, v204
	v_mul_f32_e32 v117, v117, v205
	v_mul_f32_e32 v118, v118, v206
	v_mul_f32_e32 v119, v119, v207
	v_mul_f32_e32 v120, v120, v208
	v_mul_f32_e32 v121, v121, v209
	v_mul_f32_e32 v122, v122, v210
	v_mul_f32_e32 v123, v123, v211
	v_mul_f32_e32 v124, v124, v212
	v_mul_f32_e32 v125, v125, v213
	v_mul_f32_e32 v126, v126, v214
	v_mul_f32_e32 v127, v127, v215
	global_load_dwordx4 v[144:147], v193, s[38:39] offset:0
	global_load_dwordx4 v[200:203], v193, s[44:45] offset:0
	global_load_dwordx4 v[176:179], v193, s[36:37] offset:0
	global_load_dwordx4 v[148:151], v193, s[38:39] offset:1024
	global_load_dwordx4 v[204:207], v193, s[44:45] offset:1024
	global_load_dwordx4 v[180:183], v193, s[36:37] offset:1024
	global_load_dwordx4 v[152:155], v193, s[38:39] offset:2048
	global_load_dwordx4 v[208:211], v193, s[44:45] offset:2048
	global_load_dwordx4 v[184:187], v193, s[36:37] offset:2048
	global_load_dwordx4 v[156:159], v193, s[38:39] offset:3072
	global_load_dwordx4 v[212:215], v193, s[44:45] offset:3072
	global_load_dwordx4 v[188:191], v193, s[36:37] offset:3072
	s_waitcnt vmcnt(0)
	v_add_f32_e32 v200, 1.0, v200
	v_add_f32_e32 v201, 1.0, v201
	v_add_f32_e32 v202, 1.0, v202
	v_add_f32_e32 v203, 1.0, v203
	v_mul_f32_e32 v144, v144, v200
	v_mul_f32_e32 v145, v145, v201
	v_mul_f32_e32 v146, v146, v202
	v_mul_f32_e32 v147, v147, v203
	v_add_f32_e32 v204, 1.0, v204
	v_add_f32_e32 v205, 1.0, v205
	v_add_f32_e32 v206, 1.0, v206
	v_add_f32_e32 v207, 1.0, v207
	v_mul_f32_e32 v148, v148, v204
	v_mul_f32_e32 v149, v149, v205
	v_mul_f32_e32 v150, v150, v206
	v_mul_f32_e32 v151, v151, v207
	v_add_f32_e32 v208, 1.0, v208
	v_add_f32_e32 v209, 1.0, v209
	v_add_f32_e32 v210, 1.0, v210
	v_add_f32_e32 v211, 1.0, v211
	v_mul_f32_e32 v152, v152, v208
	v_mul_f32_e32 v153, v153, v209
	v_mul_f32_e32 v154, v154, v210
	v_mul_f32_e32 v155, v155, v211
	v_add_f32_e32 v212, 1.0, v212
	v_add_f32_e32 v213, 1.0, v213
	v_add_f32_e32 v214, 1.0, v214
	v_add_f32_e32 v215, 1.0, v215
	v_mul_f32_e32 v156, v156, v212
	v_mul_f32_e32 v157, v157, v213
	v_mul_f32_e32 v158, v158, v214
	v_mul_f32_e32 v159, v159, v215
.Lp6_np6:
	s_waitcnt vmcnt(32)
	v_lshlrev_b32_e32 v216, 16, v32
	v_and_b32_e32 v217, 0xffff0000, v32
	v_lshlrev_b32_e32 v218, 16, v33
	v_and_b32_e32 v219, 0xffff0000, v33
	v_mul_f32_e32 v222, v216, v216
	v_mul_f32_e32 v223, v217, v217
	v_fmac_f32_e32 v222, v218, v218
	v_fmac_f32_e32 v223, v219, v219
	v_lshlrev_b32_e32 v216, 16, v34
	v_and_b32_e32 v217, 0xffff0000, v34
	v_lshlrev_b32_e32 v218, 16, v35
	v_and_b32_e32 v219, 0xffff0000, v35
	v_fmac_f32_e32 v222, v216, v216
	v_fmac_f32_e32 v223, v217, v217
	v_fmac_f32_e32 v222, v218, v218
	v_fmac_f32_e32 v223, v219, v219
	v_lshlrev_b32_e32 v216, 16, v36
	v_and_b32_e32 v217, 0xffff0000, v36
	v_lshlrev_b32_e32 v218, 16, v37
	v_and_b32_e32 v219, 0xffff0000, v37
	v_fmac_f32_e32 v222, v216, v216
	v_fmac_f32_e32 v223, v217, v217
	v_fmac_f32_e32 v222, v218, v218
	v_fmac_f32_e32 v223, v219, v219
	v_lshlrev_b32_e32 v216, 16, v38
	v_and_b32_e32 v217, 0xffff0000, v38
	v_lshlrev_b32_e32 v218, 16, v39
	v_and_b32_e32 v219, 0xffff0000, v39
	v_fmac_f32_e32 v222, v216, v216
	v_fmac_f32_e32 v223, v217, v217
	v_fmac_f32_e32 v222, v218, v218
	v_fmac_f32_e32 v223, v219, v219
	v_lshlrev_b32_e32 v216, 16, v40
	v_and_b32_e32 v217, 0xffff0000, v40
	v_lshlrev_b32_e32 v218, 16, v41
	v_and_b32_e32 v219, 0xffff0000, v41
	v_fmac_f32_e32 v222, v216, v216
	v_fmac_f32_e32 v223, v217, v217
	v_fmac_f32_e32 v222, v218, v218
	v_fmac_f32_e32 v223, v219, v219
	v_lshlrev_b32_e32 v216, 16, v42
	v_and_b32_e32 v217, 0xffff0000, v42
	v_lshlrev_b32_e32 v218, 16, v43
	v_and_b32_e32 v219, 0xffff0000, v43
	v_fmac_f32_e32 v222, v216, v216
	v_fmac_f32_e32 v223, v217, v217
	v_fmac_f32_e32 v222, v218, v218
	v_fmac_f32_e32 v223, v219, v219
	v_lshlrev_b32_e32 v216, 16, v44
	v_and_b32_e32 v217, 0xffff0000, v44
	v_lshlrev_b32_e32 v218, 16, v45
	v_and_b32_e32 v219, 0xffff0000, v45
	v_fmac_f32_e32 v222, v216, v216
	v_fmac_f32_e32 v223, v217, v217
	v_fmac_f32_e32 v222, v218, v218
	v_fmac_f32_e32 v223, v219, v219
	v_lshlrev_b32_e32 v216, 16, v46
	v_and_b32_e32 v217, 0xffff0000, v46
	v_lshlrev_b32_e32 v218, 16, v47
	v_and_b32_e32 v219, 0xffff0000, v47
	v_fmac_f32_e32 v222, v216, v216
	v_fmac_f32_e32 v223, v217, v217
	v_fmac_f32_e32 v222, v218, v218
	v_fmac_f32_e32 v223, v219, v219
	v_add_f32_e32 v222, v222, v223
	s_nop 1
	v_add_f32_dpp v224, v222, v222 quad_perm:[1,0,3,2] row_mask:0xf bank_mask:0xf
	s_nop 1
	v_add_f32_dpp v224, v224, v224 quad_perm:[2,3,0,1] row_mask:0xf bank_mask:0xf
	s_nop 1
	v_add_f32_dpp v224, v224, v224 row_half_mirror row_mask:0xf bank_mask:0xf
	s_nop 1
	v_add_f32_dpp v224, v224, v224 row_mirror row_mask:0xf bank_mask:0xf
	s_nop 1
	v_readlane_b32 s40, v224, 0
	v_readlane_b32 s41, v224, 16
	v_readlane_b32 s42, v224, 32
	v_readlane_b32 s43, v224, 48
	s_nop 1
	v_mov_b32_e32 v225, s40
	v_add_f32_e32 v225, s41, v225
	v_add_f32_e32 v225, s42, v225
	v_add_f32_e32 v225, s43, v225
	v_fmamk_f32 v225, v225, 0x3a000000, v195
	v_rsq_f32_e32 v225, v225
	s_nop 0
	s_add_i32 s0, s6, 6
	s_cmp_lt_u32 s0, 0x4000
	s_cselect_b32 s24, s94, s84
	s_cselect_b32 s25, s95, s85
	s_cselect_b32 s44, 0, 0x16000000
	s_cselect_b32 s1, 0, 0x4000
	s_sub_i32 s1, s0, s1
	s_lshl_b32 s1, s1, 13
	s_add_u32 s24, s24, s1
	s_addc_u32 s25, s25, 0
	s_add_u32 s24, s24, s44
	s_addc_u32 s25, s25, 0
	v_lshlrev_b32_e32 v216, 16, v32
	v_and_b32_e32 v217, 0xffff0000, v32
	v_lshlrev_b32_e32 v218, 16, v33
	v_and_b32_e32 v219, 0xffff0000, v33
	v_mul_f32_e32 v216, v225, v216
; __device__ __forceinline__ unsigned cvt_pk_bf16(float lo, float hi) { unsigned r; asm volatile("v_cvt_pk_bf16_f32 %0, %1, %2" : "=v"(r) : "v"(lo), "v"(hi)); return r; }
; __device__ __forceinline__ float bf_lo(unsigned w) { return __uint_as_float(w << 16); }
; __device__ __forceinline__ float bf_hi(unsigned w) { return __uint_as_float(w & 0xffff0000u); }
; __device__ __forceinline__ float sumsq8(const f32x4 (&v)[8]) {
;     float s = 0.f;
; #pragma unroll
;     for (int j = 0; j < 8; ++j) s += (v[j][0] * v[j][0] + v[j][1] * v[j][1]) + (v[j][2] * v[j][2] + v[j][3] * v[j][3]);
;     return wave_sum(s);
; }
; __device__ __forceinline__ void modulate_store(const f32x4 (&v)[8], float rstd, const float* pn, const float* modr, bf16_t* orow, int lane) {
; #pragma unroll
;     for (int j = 0; j < 8; ++j) { const int col = 4 * lane + 256 * j;
;         const f32x4 g = *(const f32x4*)(pn + col), sh = *(const f32x4*)(modr + col), sc = *(const f32x4*)(modr + DM + col);
;         const f32x4 hh = v[j] * rstd * g * (sc + 1.f) + sh;
;         u32x2 w; w.x = cvt_pk_bf16(hh[0], hh[1]); w.y = cvt_pk_bf16(hh[2], hh[3]);
;         *(u32x2*)(orow + col) = w; }
; }
; __global__ void __launch_bounds__(NWAVES * 64, 2) mk_fwd(Args args) {
;     ...
;                 for (int j = 0; j < 8; ++j) { const int col = 4 * F.lane + 256 * j; const f32x4 gt = *(const f32x4*)(m0 + 2 * DM + col), pn = *(const f32x4*)(post_norm + col);
;                     const f32x4 y4 = (f32x4){bf_lo(yw[q][j].x), bf_hi(yw[q][j].x), bf_lo(yw[q][j].y), bf_hi(yw[q][j].y)};
;                     v[q][j] = v[q][j] + gt * (y4 * rsy * pn);
;                     if (lat) *(f32x4*)(args.out + (size_t)row * DM + col) = v[q][j]; }
;                 const float rstd = __builtin_amdgcn_rsqf(sumsq8(v[q]) * (1.f / DM) + EPS);
;                 modulate_store(v[q], rstd, pre_norm + DM, mod + (size_t)(9 + r) * 6144, H + (size_t)row * DM, F.lane); }
	v_mul_f32_e32 v217, v225, v217
	v_mul_f32_e32 v218, v225, v218
	v_mul_f32_e32 v219, v225, v219
	v_fmac_f32_e32 v0, v96, v216
	v_fmac_f32_e32 v1, v97, v217
	v_fmac_f32_e32 v2, v98, v218
	v_fmac_f32_e32 v3, v99, v219
	global_store_dwordx4 v192, v[0:3], s[24:25] offset:0
	v_lshlrev_b32_e32 v216, 16, v34
	v_and_b32_e32 v217, 0xffff0000, v34
	v_lshlrev_b32_e32 v218, 16, v35
	v_and_b32_e32 v219, 0xffff0000, v35
	v_mul_f32_e32 v216, v225, v216
	v_mul_f32_e32 v217, v225, v217
	v_mul_f32_e32 v218, v225, v218
	v_mul_f32_e32 v219, v225, v219
	v_fmac_f32_e32 v4, v100, v216
	v_fmac_f32_e32 v5, v101, v217
	v_fmac_f32_e32 v6, v102, v218
	v_fmac_f32_e32 v7, v103, v219
	global_store_dwordx4 v192, v[4:7], s[24:25] offset:1024
	v_lshlrev_b32_e32 v216, 16, v36
	v_and_b32_e32 v217, 0xffff0000, v36
	v_lshlrev_b32_e32 v218, 16, v37
	v_and_b32_e32 v219, 0xffff0000, v37
	v_mul_f32_e32 v216, v225, v216
	v_mul_f32_e32 v217, v225, v217
	v_mul_f32_e32 v218, v225, v218
	v_mul_f32_e32 v219, v225, v219
	v_fmac_f32_e32 v8, v104, v216
	v_fmac_f32_e32 v9, v105, v217
	v_fmac_f32_e32 v10, v106, v218
	v_fmac_f32_e32 v11, v107, v219
	global_store_dwordx4 v192, v[8:11], s[24:25] offset:2048
	v_lshlrev_b32_e32 v216, 16, v38
	v_and_b32_e32 v217, 0xffff0000, v38
	v_lshlrev_b32_e32 v218, 16, v39
	v_and_b32_e32 v219, 0xffff0000, v39
	v_mul_f32_e32 v216, v225, v216
	v_mul_f32_e32 v217, v225, v217
	v_mul_f32_e32 v218, v225, v218
	v_mul_f32_e32 v219, v225, v219
	v_fmac_f32_e32 v12, v108, v216
	v_fmac_f32_e32 v13, v109, v217
	v_fmac_f32_e32 v14, v110, v218
	v_fmac_f32_e32 v15, v111, v219
	global_store_dwordx4 v192, v[12:15], s[24:25] offset:3072
	v_lshlrev_b32_e32 v216, 16, v40
	v_and_b32_e32 v217, 0xffff0000, v40
	v_lshlrev_b32_e32 v218, 16, v41
	v_and_b32_e32 v219, 0xffff0000, v41
	v_mul_f32_e32 v216, v225, v216
	v_mul_f32_e32 v217, v225, v217
	v_mul_f32_e32 v218, v225, v218
	v_mul_f32_e32 v219, v225, v219
	v_fmac_f32_e32 v16, v112, v216
	v_fmac_f32_e32 v17, v113, v217
	v_fmac_f32_e32 v18, v114, v218
	v_fmac_f32_e32 v19, v115, v219
	global_store_dwordx4 v193, v[16:19], s[24:25] offset:0
	v_lshlrev_b32_e32 v216, 16, v42
	v_and_b32_e32 v217, 0xffff0000, v42
	v_lshlrev_b32_e32 v218, 16, v43
	v_and_b32_e32 v219, 0xffff0000, v43
	v_mul_f32_e32 v216, v225, v216
	v_mul_f32_e32 v217, v225, v217
	v_mul_f32_e32 v218, v225, v218
	v_mul_f32_e32 v219, v225, v219
	v_fmac_f32_e32 v20, v116, v216
	v_fmac_f32_e32 v21, v117, v217
	v_fmac_f32_e32 v22, v118, v218
	v_fmac_f32_e32 v23, v119, v219
	global_store_dwordx4 v193, v[20:23], s[24:25] offset:1024
	v_lshlrev_b32_e32 v216, 16, v44
	v_and_b32_e32 v217, 0xffff0000, v44
	v_lshlrev_b32_e32 v218, 16, v45
	v_and_b32_e32 v219, 0xffff0000, v45
	v_mul_f32_e32 v216, v225, v216
	v_mul_f32_e32 v217, v225, v217
	v_mul_f32_e32 v218, v225, v218
	v_mul_f32_e32 v219, v225, v219
	v_fmac_f32_e32 v24, v120, v216
	v_fmac_f32_e32 v25, v121, v217
	v_fmac_f32_e32 v26, v122, v218
	v_fmac_f32_e32 v27, v123, v219
	global_store_dwordx4 v193, v[24:27], s[24:25] offset:2048
	v_lshlrev_b32_e32 v216, 16, v46
	v_and_b32_e32 v217, 0xffff0000, v46
	v_lshlrev_b32_e32 v218, 16, v47
	v_and_b32_e32 v219, 0xffff0000, v47
	v_mul_f32_e32 v216, v225, v216
	v_mul_f32_e32 v217, v225, v217
	v_mul_f32_e32 v218, v225, v218
	v_mul_f32_e32 v219, v225, v219
	v_fmac_f32_e32 v28, v124, v216
	v_fmac_f32_e32 v29, v125, v217
	v_fmac_f32_e32 v30, v126, v218
	v_fmac_f32_e32 v31, v127, v219
	global_store_dwordx4 v193, v[28:31], s[24:25] offset:3072
	v_mul_f32_e32 v222, v0, v0
	v_mul_f32_e32 v223, v1, v1
	v_fmac_f32_e32 v222, v2, v2
	v_fmac_f32_e32 v223, v3, v3
	v_fmac_f32_e32 v222, v4, v4
	v_fmac_f32_e32 v223, v5, v5
	v_fmac_f32_e32 v222, v6, v6
	v_fmac_f32_e32 v223, v7, v7
	v_fmac_f32_e32 v222, v8, v8
	v_fmac_f32_e32 v223, v9, v9
	v_fmac_f32_e32 v222, v10, v10
	v_fmac_f32_e32 v223, v11, v11
	v_fmac_f32_e32 v222, v12, v12
	v_fmac_f32_e32 v223, v13, v13
	v_fmac_f32_e32 v222, v14, v14
	v_fmac_f32_e32 v223, v15, v15
	v_fmac_f32_e32 v222, v16, v16
	v_fmac_f32_e32 v223, v17, v17
	v_fmac_f32_e32 v222, v18, v18
	v_fmac_f32_e32 v223, v19, v19
	v_fmac_f32_e32 v222, v20, v20
	v_fmac_f32_e32 v223, v21, v21
	v_fmac_f32_e32 v222, v22, v22
	v_fmac_f32_e32 v223, v23, v23
	v_fmac_f32_e32 v222, v24, v24
	v_fmac_f32_e32 v223, v25, v25
	v_fmac_f32_e32 v222, v26, v26
	v_fmac_f32_e32 v223, v27, v27
	v_fmac_f32_e32 v222, v28, v28
	v_fmac_f32_e32 v223, v29, v29
	v_fmac_f32_e32 v222, v30, v30
	v_fmac_f32_e32 v223, v31, v31
	v_add_f32_e32 v222, v222, v223
	s_nop 1
	v_add_f32_dpp v224, v222, v222 quad_perm:[1,0,3,2] row_mask:0xf bank_mask:0xf
	s_nop 1
	v_add_f32_dpp v224, v224, v224 quad_perm:[2,3,0,1] row_mask:0xf bank_mask:0xf
	s_nop 1
	v_add_f32_dpp v224, v224, v224 row_half_mirror row_mask:0xf bank_mask:0xf
	s_nop 1
	v_add_f32_dpp v224, v224, v224 row_mirror row_mask:0xf bank_mask:0xf
	s_nop 1
	v_readlane_b32 s40, v224, 0
	v_readlane_b32 s41, v224, 16
	v_readlane_b32 s42, v224, 32
	v_readlane_b32 s43, v224, 48
	s_nop 1
	v_mov_b32_e32 v225, s40
	v_add_f32_e32 v225, s41, v225
	v_add_f32_e32 v225, s42, v225
	v_add_f32_e32 v225, s43, v225
	v_fmamk_f32 v225, v225, 0x3a000000, v195
	v_rsq_f32_e32 v225, v225
	s_nop 0
	s_add_i32 s0, s6, 6
	s_lshl_b32 s1, s0, 12
	s_add_u32 s26, s84, s1
	s_addc_u32 s27, s85, 0
	s_add_u32 s26, s26, 0x4000000
	s_addc_u32 s27, s27, 0
	v_mul_f32_e32 v216, v225, v0
	v_mul_f32_e32 v217, v225, v1
	v_mul_f32_e32 v218, v225, v2
	v_mul_f32_e32 v219, v225, v3
	v_fma_f32 v216, v216, v128, v160
	v_fma_f32 v217, v217, v129, v161
	v_fma_f32 v218, v218, v130, v162
	v_fma_f32 v219, v219, v131, v163
	v_cvt_pk_bf16_f32 v196, v216, v217
	v_cvt_pk_bf16_f32 v197, v218, v219
	global_store_dwordx2 v194, v[196:197], s[26:27] offset:0
; __device__ __forceinline__ unsigned cvt_pk_bf16(float lo, float hi) { unsigned r; asm volatile("v_cvt_pk_bf16_f32 %0, %1, %2" : "=v"(r) : "v"(lo), "v"(hi)); return r; }
; __device__ __forceinline__ float bf_lo(unsigned w) { return __uint_as_float(w << 16); }
; __device__ __forceinline__ float bf_hi(unsigned w) { return __uint_as_float(w & 0xffff0000u); }
; __device__ __forceinline__ void modulate_store(const f32x4 (&v)[8], float rstd, const float* pn, const float* modr, bf16_t* orow, int lane) {
; #pragma unroll
;     for (int j = 0; j < 8; ++j) { const int col = 4 * lane + 256 * j;
;         const f32x4 g = *(const f32x4*)(pn + col), sh = *(const f32x4*)(modr + col), sc = *(const f32x4*)(modr + DM + col);
;         const f32x4 hh = v[j] * rstd * g * (sc + 1.f) + sh;
;         u32x2 w; w.x = cvt_pk_bf16(hh[0], hh[1]); w.y = cvt_pk_bf16(hh[2], hh[3]);
;         *(u32x2*)(orow + col) = w; }
; }
; __global__ void __launch_bounds__(NWAVES * 64, 2) mk_fwd(Args args) {
;     ...
;         for (int row0 = F.gw * 3; row0 < MT; row0 += F.NGW * 3) {
;             f32x4 v[3][8]; u32x2 yw[3][8];
; #pragma unroll
;             for (int q = 0; q < 3; ++q) { const int row = row0 + q; const float* src = row < ML ? x + (size_t)row * DM : ctx + (size_t)(row - ML) * DM; load_row_f32(src, F.lane, v[q]);
;                 const bf16_t* yr = Y + (size_t)row * DM;
; #pragma unroll
;                 for (int j = 0; j < 8; ++j) yw[q][j] = *(const u32x2*)(yr + 4 * F.lane + 256 * j); }
; #pragma unroll
;             for (int q = 0; q < 3; ++q) { const int row = row0 + q; const bool lat = row < ML; const int r = lat ? row / SEQ : 8;
;                 float sy = 0.f;
; #pragma unroll
;                 for (int j = 0; j < 8; ++j) { const float a = bf_lo(yw[q][j].x), b = bf_hi(yw[q][j].x), c2 = bf_lo(yw[q][j].y), d = bf_hi(yw[q][j].y); sy += (a * a + b * b) + (c2 * c2 + d * d); }
;                 const float rsy = __builtin_amdgcn_rsqf(wave_sum(sy) * (1.f / DM) + EPS);
;                 const float* m0 = mod + (size_t)r * 6144;
; #pragma unroll
;                 for (int j = 0; j < 8; ++j) { const int col = 4 * F.lane + 256 * j; const f32x4 gt = *(const f32x4*)(m0 + 2 * DM + col), pn = *(const f32x4*)(post_norm + col);
	v_mul_f32_e32 v216, v225, v4
	v_mul_f32_e32 v217, v225, v5
	v_mul_f32_e32 v218, v225, v6
	v_mul_f32_e32 v219, v225, v7
	v_fma_f32 v216, v216, v132, v164
	v_fma_f32 v217, v217, v133, v165
	v_fma_f32 v218, v218, v134, v166
	v_fma_f32 v219, v219, v135, v167
	v_cvt_pk_bf16_f32 v220, v216, v217
	v_cvt_pk_bf16_f32 v221, v218, v219
	global_store_dwordx2 v194, v[220:221], s[26:27] offset:512
	v_mul_f32_e32 v216, v225, v8
	v_mul_f32_e32 v217, v225, v9
	v_mul_f32_e32 v218, v225, v10
	v_mul_f32_e32 v219, v225, v11
	v_fma_f32 v216, v216, v136, v168
	v_fma_f32 v217, v217, v137, v169
	v_fma_f32 v218, v218, v138, v170
	v_fma_f32 v219, v219, v139, v171
	v_cvt_pk_bf16_f32 v196, v216, v217
	v_cvt_pk_bf16_f32 v197, v218, v219
	global_store_dwordx2 v194, v[196:197], s[26:27] offset:1024
	v_mul_f32_e32 v216, v225, v12
	v_mul_f32_e32 v217, v225, v13
	v_mul_f32_e32 v218, v225, v14
	v_mul_f32_e32 v219, v225, v15
	v_fma_f32 v216, v216, v140, v172
	v_fma_f32 v217, v217, v141, v173
	v_fma_f32 v218, v218, v142, v174
	v_fma_f32 v219, v219, v143, v175
	v_cvt_pk_bf16_f32 v220, v216, v217
	v_cvt_pk_bf16_f32 v221, v218, v219
	global_store_dwordx2 v194, v[220:221], s[26:27] offset:1536
	v_mul_f32_e32 v216, v225, v16
	v_mul_f32_e32 v217, v225, v17
	v_mul_f32_e32 v218, v225, v18
	v_mul_f32_e32 v219, v225, v19
	v_fma_f32 v216, v216, v144, v176
	v_fma_f32 v217, v217, v145, v177
	v_fma_f32 v218, v218, v146, v178
	v_fma_f32 v219, v219, v147, v179
	v_cvt_pk_bf16_f32 v196, v216, v217
	v_cvt_pk_bf16_f32 v197, v218, v219
	global_store_dwordx2 v194, v[196:197], s[26:27] offset:2048
	v_mul_f32_e32 v216, v225, v20
	v_mul_f32_e32 v217, v225, v21
	v_mul_f32_e32 v218, v225, v22
	v_mul_f32_e32 v219, v225, v23
	v_fma_f32 v216, v216, v148, v180
	v_fma_f32 v217, v217, v149, v181
	v_fma_f32 v218, v218, v150, v182
	v_fma_f32 v219, v219, v151, v183
	v_cvt_pk_bf16_f32 v220, v216, v217
	v_cvt_pk_bf16_f32 v221, v218, v219
	global_store_dwordx2 v194, v[220:221], s[26:27] offset:2560
	v_mul_f32_e32 v216, v225, v24
	v_mul_f32_e32 v217, v225, v25
	v_mul_f32_e32 v218, v225, v26
	v_mul_f32_e32 v219, v225, v27
	v_fma_f32 v216, v216, v152, v184
	v_fma_f32 v217, v217, v153, v185
	v_fma_f32 v218, v218, v154, v186
	v_fma_f32 v219, v219, v155, v187
	v_cvt_pk_bf16_f32 v196, v216, v217
	v_cvt_pk_bf16_f32 v197, v218, v219
	global_store_dwordx2 v194, v[196:197], s[26:27] offset:3072
	v_mul_f32_e32 v216, v225, v28
	v_mul_f32_e32 v217, v225, v29
	v_mul_f32_e32 v218, v225, v30
	v_mul_f32_e32 v219, v225, v31
	v_fma_f32 v216, v216, v156, v188
	v_fma_f32 v217, v217, v157, v189
	v_fma_f32 v218, v218, v158, v190
	v_fma_f32 v219, v219, v159, v191
	v_cvt_pk_bf16_f32 v220, v216, v217
	v_cvt_pk_bf16_f32 v221, v218, v219
	global_store_dwordx2 v194, v[220:221], s[26:27] offset:3584
	s_add_i32 s0, s6, 8
	s_cmp_lt_u32 s0, 0x4000
	s_cselect_b32 s10, s68, s72
	s_cselect_b32 s11, s69, s73
	s_cselect_b32 s1, 0, 0x4000
	s_sub_i32 s1, s0, s1
	s_lshl_b32 s1, s1, 13
	s_add_u32 s10, s10, s1
	s_addc_u32 s11, s11, 0
	s_add_i32 s0, s6, 8
	s_lshl_b32 s1, s0, 12
	s_add_u32 s22, s84, s1
	s_addc_u32 s23, s85, 0
	s_add_u32 s22, s22, 0x11800000
	s_addc_u32 s23, s23, 0
	global_load_dwordx4 v[0:3], v192, s[10:11] offset:0
	global_load_dwordx4 v[4:7], v192, s[10:11] offset:1024
	global_load_dwordx4 v[8:11], v192, s[10:11] offset:2048
	global_load_dwordx4 v[12:15], v192, s[10:11] offset:3072
	global_load_dwordx4 v[16:19], v193, s[10:11] offset:0
	global_load_dwordx4 v[20:23], v193, s[10:11] offset:1024
	global_load_dwordx4 v[24:27], v193, s[10:11] offset:2048
	global_load_dwordx4 v[28:31], v193, s[10:11] offset:3072
	global_load_dwordx2 v[32:33], v194, s[22:23] offset:0
	global_load_dwordx2 v[34:35], v194, s[22:23] offset:512
	global_load_dwordx2 v[36:37], v194, s[22:23] offset:1024
	global_load_dwordx2 v[38:39], v194, s[22:23] offset:1536
	global_load_dwordx2 v[40:41], v194, s[22:23] offset:2048
	global_load_dwordx2 v[42:43], v194, s[22:23] offset:2560
	global_load_dwordx2 v[44:45], v194, s[22:23] offset:3072
	global_load_dwordx2 v[46:47], v194, s[22:23] offset:3584
	s_add_i32 s0, s6, 7
	s_add_i32 s0, s6, 7
	s_lshr_b32 s8, s0, 11
	s_cmp_lt_u32 s0, 0x4000
	s_cselect_b32 s8, s8, 8
	s_cmp_eq_u32 s8, s7
	s_cbranch_scc1 .Lp6_np7
	s_mov_b32 s7, s8
	s_add_i32 s1, s8, 9
	s_mul_i32 s1, s1, 0x6000
	s_add_u32 s44, s84, s1
	s_addc_u32 s45, s85, 0
	s_add_u32 s44, s44, 0x2000
	s_addc_u32 s45, s45, 0
	s_add_i32 s1, s8, 9
	s_mul_i32 s1, s1, 0x6000
	s_add_u32 s36, s84, s1
	s_addc_u32 s37, s85, 0
	s_add_u32 s38, s80, 0x2000
	s_addc_u32 s39, s81, 0
	s_mul_i32 s1, s8, 0x6000
	s_add_u32 s34, s84, s1
	s_addc_u32 s35, s85, 0
	s_add_u32 s34, s34, 0x4000
	s_addc_u32 s35, s35, 0
	global_load_dwordx4 v[96:99], v192, s[34:35] offset:0
	global_load_dwordx4 v[200:203], v192, s[82:83] offset:0
	global_load_dwordx4 v[100:103], v192, s[34:35] offset:1024
	global_load_dwordx4 v[204:207], v192, s[82:83] offset:1024
	global_load_dwordx4 v[104:107], v192, s[34:35] offset:2048
	global_load_dwordx4 v[208:211], v192, s[82:83] offset:2048
	global_load_dwordx4 v[108:111], v192, s[34:35] offset:3072
	global_load_dwordx4 v[212:215], v192, s[82:83] offset:3072
	s_waitcnt vmcnt(0)
; __device__ __forceinline__ void modulate_store(const f32x4 (&v)[8], float rstd, const float* pn, const float* modr, bf16_t* orow, int lane) {
;     ...
;         const f32x4 g = *(const f32x4*)(pn + col), sh = *(const f32x4*)(modr + col), sc = *(const f32x4*)(modr + DM + col);
;         const f32x4 hh = v[j] * rstd * g * (sc + 1.f) + sh;
; __global__ void __launch_bounds__(NWAVES * 64, 2) mk_fwd(Args args) {
;     ...
;                 const float* m0 = mod + (size_t)r * 6144;
; #pragma unroll
;                 for (int j = 0; j < 8; ++j) { const int col = 4 * F.lane + 256 * j; const f32x4 gt = *(const f32x4*)(m0 + 2 * DM + col), pn = *(const f32x4*)(post_norm + col);
	v_mul_f32_e32 v96, v96, v200
	v_mul_f32_e32 v97, v97, v201
	v_mul_f32_e32 v98, v98, v202
	v_mul_f32_e32 v99, v99, v203
	v_mul_f32_e32 v100, v100, v204
	v_mul_f32_e32 v101, v101, v205
	v_mul_f32_e32 v102, v102, v206
	v_mul_f32_e32 v103, v103, v207
	v_mul_f32_e32 v104, v104, v208
	v_mul_f32_e32 v105, v105, v209
	v_mul_f32_e32 v106, v106, v210
	v_mul_f32_e32 v107, v107, v211
	v_mul_f32_e32 v108, v108, v212
	v_mul_f32_e32 v109, v109, v213
	v_mul_f32_e32 v110, v110, v214
	v_mul_f32_e32 v111, v111, v215
	global_load_dwordx4 v[128:131], v192, s[38:39] offset:0
	global_load_dwordx4 v[200:203], v192, s[44:45] offset:0
	global_load_dwordx4 v[160:163], v192, s[36:37] offset:0
	global_load_dwordx4 v[132:135], v192, s[38:39] offset:1024
	global_load_dwordx4 v[204:207], v192, s[44:45] offset:1024
	global_load_dwordx4 v[164:167], v192, s[36:37] offset:1024
	global_load_dwordx4 v[136:139], v192, s[38:39] offset:2048
	global_load_dwordx4 v[208:211], v192, s[44:45] offset:2048
	global_load_dwordx4 v[168:171], v192, s[36:37] offset:2048
	global_load_dwordx4 v[140:143], v192, s[38:39] offset:3072
	global_load_dwordx4 v[212:215], v192, s[44:45] offset:3072
	global_load_dwordx4 v[172:175], v192, s[36:37] offset:3072
	s_waitcnt vmcnt(0)
	v_add_f32_e32 v200, 1.0, v200
	v_add_f32_e32 v201, 1.0, v201
	v_add_f32_e32 v202, 1.0, v202
	v_add_f32_e32 v203, 1.0, v203
	v_mul_f32_e32 v128, v128, v200
	v_mul_f32_e32 v129, v129, v201
	v_mul_f32_e32 v130, v130, v202
	v_mul_f32_e32 v131, v131, v203
	v_add_f32_e32 v204, 1.0, v204
	v_add_f32_e32 v205, 1.0, v205
	v_add_f32_e32 v206, 1.0, v206
	v_add_f32_e32 v207, 1.0, v207
	v_mul_f32_e32 v132, v132, v204
	v_mul_f32_e32 v133, v133, v205
	v_mul_f32_e32 v134, v134, v206
	v_mul_f32_e32 v135, v135, v207
	v_add_f32_e32 v208, 1.0, v208
	v_add_f32_e32 v209, 1.0, v209
	v_add_f32_e32 v210, 1.0, v210
	v_add_f32_e32 v211, 1.0, v211
	v_mul_f32_e32 v136, v136, v208
	v_mul_f32_e32 v137, v137, v209
	v_mul_f32_e32 v138, v138, v210
	v_mul_f32_e32 v139, v139, v211
	v_add_f32_e32 v212, 1.0, v212
	v_add_f32_e32 v213, 1.0, v213
	v_add_f32_e32 v214, 1.0, v214
	v_add_f32_e32 v215, 1.0, v215
	v_mul_f32_e32 v140, v140, v212
	v_mul_f32_e32 v141, v141, v213
	v_mul_f32_e32 v142, v142, v214
	v_mul_f32_e32 v143, v143, v215
	global_load_dwordx4 v[112:115], v193, s[34:35] offset:0
	global_load_dwordx4 v[200:203], v193, s[82:83] offset:0
	global_load_dwordx4 v[116:119], v193, s[34:35] offset:1024
	global_load_dwordx4 v[204:207], v193, s[82:83] offset:1024
	global_load_dwordx4 v[120:123], v193, s[34:35] offset:2048
	global_load_dwordx4 v[208:211], v193, s[82:83] offset:2048
	global_load_dwordx4 v[124:127], v193, s[34:35] offset:3072
	global_load_dwordx4 v[212:215], v193, s[82:83] offset:3072
	s_waitcnt vmcnt(0)
	v_mul_f32_e32 v112, v112, v200
	v_mul_f32_e32 v113, v113, v201
	v_mul_f32_e32 v114, v114, v202
	v_mul_f32_e32 v115, v115, v203
	v_mul_f32_e32 v116, v116, v204
	v_mul_f32_e32 v117, v117, v205
	v_mul_f32_e32 v118, v118, v206
	v_mul_f32_e32 v119, v119, v207
	v_mul_f32_e32 v120, v120, v208
	v_mul_f32_e32 v121, v121, v209
	v_mul_f32_e32 v122, v122, v210
	v_mul_f32_e32 v123, v123, v211
	v_mul_f32_e32 v124, v124, v212
	v_mul_f32_e32 v125, v125, v213
	v_mul_f32_e32 v126, v126, v214
	v_mul_f32_e32 v127, v127, v215
	global_load_dwordx4 v[144:147], v193, s[38:39] offset:0
	global_load_dwordx4 v[200:203], v193, s[44:45] offset:0
	global_load_dwordx4 v[176:179], v193, s[36:37] offset:0
	global_load_dwordx4 v[148:151], v193, s[38:39] offset:1024
	global_load_dwordx4 v[204:207], v193, s[44:45] offset:1024
	global_load_dwordx4 v[180:183], v193, s[36:37] offset:1024
	global_load_dwordx4 v[152:155], v193, s[38:39] offset:2048
	global_load_dwordx4 v[208:211], v193, s[44:45] offset:2048
	global_load_dwordx4 v[184:187], v193, s[36:37] offset:2048
	global_load_dwordx4 v[156:159], v193, s[38:39] offset:3072
	global_load_dwordx4 v[212:215], v193, s[44:45] offset:3072
	global_load_dwordx4 v[188:191], v193, s[36:37] offset:3072
	s_waitcnt vmcnt(0)
	v_add_f32_e32 v200, 1.0, v200
	v_add_f32_e32 v201, 1.0, v201
	v_add_f32_e32 v202, 1.0, v202
	v_add_f32_e32 v203, 1.0, v203
	v_mul_f32_e32 v144, v144, v200
	v_mul_f32_e32 v145, v145, v201
	v_mul_f32_e32 v146, v146, v202
	v_mul_f32_e32 v147, v147, v203
	v_add_f32_e32 v204, 1.0, v204
	v_add_f32_e32 v205, 1.0, v205
	v_add_f32_e32 v206, 1.0, v206
	v_add_f32_e32 v207, 1.0, v207
	v_mul_f32_e32 v148, v148, v204
	v_mul_f32_e32 v149, v149, v205
	v_mul_f32_e32 v150, v150, v206
	v_mul_f32_e32 v151, v151, v207
	v_add_f32_e32 v208, 1.0, v208
	v_add_f32_e32 v209, 1.0, v209
	v_add_f32_e32 v210, 1.0, v210
	v_add_f32_e32 v211, 1.0, v211
	v_mul_f32_e32 v152, v152, v208
	v_mul_f32_e32 v153, v153, v209
	v_mul_f32_e32 v154, v154, v210
	v_mul_f32_e32 v155, v155, v211
	v_add_f32_e32 v212, 1.0, v212
	v_add_f32_e32 v213, 1.0, v213
	v_add_f32_e32 v214, 1.0, v214
	v_add_f32_e32 v215, 1.0, v215
	v_mul_f32_e32 v156, v156, v212
	v_mul_f32_e32 v157, v157, v213
	v_mul_f32_e32 v158, v158, v214
	v_mul_f32_e32 v159, v159, v215
; __device__ __forceinline__ float bf_lo(unsigned w) { return __uint_as_float(w << 16); }
; __device__ __forceinline__ float bf_hi(unsigned w) { return __uint_as_float(w & 0xffff0000u); }
; __global__ void __launch_bounds__(NWAVES * 64, 2) mk_fwd(Args args) {
;     ...
;             for (int q = 0; q < 3; ++q) { const int row = row0 + q; const bool lat = row < ML; const int r = lat ? row / SEQ : 8;
;                 float sy = 0.f;
; #pragma unroll
;                 for (int j = 0; j < 8; ++j) { const float a = bf_lo(yw[q][j].x), b = bf_hi(yw[q][j].x), c2 = bf_lo(yw[q][j].y), d = bf_hi(yw[q][j].y); sy += (a * a + b * b) + (c2 * c2 + d * d); }
;                 const float rsy = __builtin_amdgcn_rsqf(wave_sum(sy) * (1.f / DM) + EPS);
;                 const float* m0 = mod + (size_t)r * 6144;
; #pragma unroll
;                 for (int j = 0; j < 8; ++j) { const int col = 4 * F.lane + 256 * j; const f32x4 gt = *(const f32x4*)(m0 + 2 * DM + col), pn = *(const f32x4*)(post_norm + col);
;                     const f32x4 y4 = (f32x4){bf_lo(yw[q][j].x), bf_hi(yw[q][j].x), bf_lo(yw[q][j].y), bf_hi(yw[q][j].y)};
;                     v[q][j] = v[q][j] + gt * (y4 * rsy * pn);
;                     if (lat) *(f32x4*)(args.out + (size_t)row * DM + col) = v[q][j]; }
.Lp6_np7:
	s_waitcnt vmcnt(32)
	v_lshlrev_b32_e32 v216, 16, v80
	v_and_b32_e32 v217, 0xffff0000, v80
	v_lshlrev_b32_e32 v218, 16, v81
	v_and_b32_e32 v219, 0xffff0000, v81
	v_mul_f32_e32 v222, v216, v216
	v_mul_f32_e32 v223, v217, v217
	v_fmac_f32_e32 v222, v218, v218
	v_fmac_f32_e32 v223, v219, v219
	v_lshlrev_b32_e32 v216, 16, v82
	v_and_b32_e32 v217, 0xffff0000, v82
	v_lshlrev_b32_e32 v218, 16, v83
	v_and_b32_e32 v219, 0xffff0000, v83
	v_fmac_f32_e32 v222, v216, v216
	v_fmac_f32_e32 v223, v217, v217
	v_fmac_f32_e32 v222, v218, v218
	v_fmac_f32_e32 v223, v219, v219
	v_lshlrev_b32_e32 v216, 16, v84
	v_and_b32_e32 v217, 0xffff0000, v84
	v_lshlrev_b32_e32 v218, 16, v85
	v_and_b32_e32 v219, 0xffff0000, v85
	v_fmac_f32_e32 v222, v216, v216
	v_fmac_f32_e32 v223, v217, v217
	v_fmac_f32_e32 v222, v218, v218
	v_fmac_f32_e32 v223, v219, v219
	v_lshlrev_b32_e32 v216, 16, v86
	v_and_b32_e32 v217, 0xffff0000, v86
	v_lshlrev_b32_e32 v218, 16, v87
	v_and_b32_e32 v219, 0xffff0000, v87
	v_fmac_f32_e32 v222, v216, v216
	v_fmac_f32_e32 v223, v217, v217
	v_fmac_f32_e32 v222, v218, v218
	v_fmac_f32_e32 v223, v219, v219
	v_lshlrev_b32_e32 v216, 16, v88
	v_and_b32_e32 v217, 0xffff0000, v88
	v_lshlrev_b32_e32 v218, 16, v89
	v_and_b32_e32 v219, 0xffff0000, v89
	v_fmac_f32_e32 v222, v216, v216
	v_fmac_f32_e32 v223, v217, v217
	v_fmac_f32_e32 v222, v218, v218
	v_fmac_f32_e32 v223, v219, v219
	v_lshlrev_b32_e32 v216, 16, v90
	v_and_b32_e32 v217, 0xffff0000, v90
	v_lshlrev_b32_e32 v218, 16, v91
	v_and_b32_e32 v219, 0xffff0000, v91
	v_fmac_f32_e32 v222, v216, v216
	v_fmac_f32_e32 v223, v217, v217
	v_fmac_f32_e32 v222, v218, v218
	v_fmac_f32_e32 v223, v219, v219
	v_lshlrev_b32_e32 v216, 16, v92
	v_and_b32_e32 v217, 0xffff0000, v92
	v_lshlrev_b32_e32 v218, 16, v93
	v_and_b32_e32 v219, 0xffff0000, v93
	v_fmac_f32_e32 v222, v216, v216
	v_fmac_f32_e32 v223, v217, v217
	v_fmac_f32_e32 v222, v218, v218
	v_fmac_f32_e32 v223, v219, v219
	v_lshlrev_b32_e32 v216, 16, v94
	v_and_b32_e32 v217, 0xffff0000, v94
	v_lshlrev_b32_e32 v218, 16, v95
	v_and_b32_e32 v219, 0xffff0000, v95
	v_fmac_f32_e32 v222, v216, v216
	v_fmac_f32_e32 v223, v217, v217
	v_fmac_f32_e32 v222, v218, v218
	v_fmac_f32_e32 v223, v219, v219
	v_add_f32_e32 v222, v222, v223
	s_nop 1
	v_add_f32_dpp v224, v222, v222 quad_perm:[1,0,3,2] row_mask:0xf bank_mask:0xf
	s_nop 1
	v_add_f32_dpp v224, v224, v224 quad_perm:[2,3,0,1] row_mask:0xf bank_mask:0xf
	s_nop 1
	v_add_f32_dpp v224, v224, v224 row_half_mirror row_mask:0xf bank_mask:0xf
	s_nop 1
	v_add_f32_dpp v224, v224, v224 row_mirror row_mask:0xf bank_mask:0xf
	s_nop 1
	v_readlane_b32 s40, v224, 0
	v_readlane_b32 s41, v224, 16
	v_readlane_b32 s42, v224, 32
	v_readlane_b32 s43, v224, 48
	s_nop 1
	v_mov_b32_e32 v225, s40
	v_add_f32_e32 v225, s41, v225
	v_add_f32_e32 v225, s42, v225
	v_add_f32_e32 v225, s43, v225
	v_fmamk_f32 v225, v225, 0x3a000000, v195
	v_rsq_f32_e32 v225, v225
	s_nop 0
	s_add_i32 s0, s6, 7
	s_cmp_lt_u32 s0, 0x4000
	s_cselect_b32 s24, s94, s84
	s_cselect_b32 s25, s95, s85
	s_cselect_b32 s44, 0, 0x16000000
	s_cselect_b32 s1, 0, 0x4000
	s_sub_i32 s1, s0, s1
	s_lshl_b32 s1, s1, 13
	s_add_u32 s24, s24, s1
	s_addc_u32 s25, s25, 0
	s_add_u32 s24, s24, s44
	s_addc_u32 s25, s25, 0
	v_lshlrev_b32_e32 v216, 16, v80
	v_and_b32_e32 v217, 0xffff0000, v80
	v_lshlrev_b32_e32 v218, 16, v81
	v_and_b32_e32 v219, 0xffff0000, v81
	v_mul_f32_e32 v216, v225, v216
	v_mul_f32_e32 v217, v225, v217
	v_mul_f32_e32 v218, v225, v218
	v_mul_f32_e32 v219, v225, v219
	v_fmac_f32_e32 v48, v96, v216
	v_fmac_f32_e32 v49, v97, v217
	v_fmac_f32_e32 v50, v98, v218
	v_fmac_f32_e32 v51, v99, v219
	global_store_dwordx4 v192, v[48:51], s[24:25] offset:0
	v_lshlrev_b32_e32 v216, 16, v82
	v_and_b32_e32 v217, 0xffff0000, v82
	v_lshlrev_b32_e32 v218, 16, v83
	v_and_b32_e32 v219, 0xffff0000, v83
	v_mul_f32_e32 v216, v225, v216
	v_mul_f32_e32 v217, v225, v217
	v_mul_f32_e32 v218, v225, v218
	v_mul_f32_e32 v219, v225, v219
	v_fmac_f32_e32 v52, v100, v216
	v_fmac_f32_e32 v53, v101, v217
	v_fmac_f32_e32 v54, v102, v218
	v_fmac_f32_e32 v55, v103, v219
	global_store_dwordx4 v192, v[52:55], s[24:25] offset:1024
	v_lshlrev_b32_e32 v216, 16, v84
	v_and_b32_e32 v217, 0xffff0000, v84
	v_lshlrev_b32_e32 v218, 16, v85
	v_and_b32_e32 v219, 0xffff0000, v85
	v_mul_f32_e32 v216, v225, v216
	v_mul_f32_e32 v217, v225, v217
	v_mul_f32_e32 v218, v225, v218
	v_mul_f32_e32 v219, v225, v219
	v_fmac_f32_e32 v56, v104, v216
	v_fmac_f32_e32 v57, v105, v217
	v_fmac_f32_e32 v58, v106, v218
	v_fmac_f32_e32 v59, v107, v219
	global_store_dwordx4 v192, v[56:59], s[24:25] offset:2048
	v_lshlrev_b32_e32 v216, 16, v86
	v_and_b32_e32 v217, 0xffff0000, v86
	v_lshlrev_b32_e32 v218, 16, v87
	v_and_b32_e32 v219, 0xffff0000, v87
	v_mul_f32_e32 v216, v225, v216
	v_mul_f32_e32 v217, v225, v217
	v_mul_f32_e32 v218, v225, v218
	v_mul_f32_e32 v219, v225, v219
	v_fmac_f32_e32 v60, v108, v216
	v_fmac_f32_e32 v61, v109, v217
	v_fmac_f32_e32 v62, v110, v218
	v_fmac_f32_e32 v63, v111, v219
	global_store_dwordx4 v192, v[60:63], s[24:25] offset:3072
	v_lshlrev_b32_e32 v216, 16, v88
	v_and_b32_e32 v217, 0xffff0000, v88
	v_lshlrev_b32_e32 v218, 16, v89
	v_and_b32_e32 v219, 0xffff0000, v89
	v_mul_f32_e32 v216, v225, v216
	v_mul_f32_e32 v217, v225, v217
	v_mul_f32_e32 v218, v225, v218
	v_mul_f32_e32 v219, v225, v219
	v_fmac_f32_e32 v64, v112, v216
	v_fmac_f32_e32 v65, v113, v217
	v_fmac_f32_e32 v66, v114, v218
	v_fmac_f32_e32 v67, v115, v219
	global_store_dwordx4 v193, v[64:67], s[24:25] offset:0
	v_lshlrev_b32_e32 v216, 16, v90
	v_and_b32_e32 v217, 0xffff0000, v90
	v_lshlrev_b32_e32 v218, 16, v91
	v_and_b32_e32 v219, 0xffff0000, v91
	v_mul_f32_e32 v216, v225, v216
; __device__ __forceinline__ unsigned cvt_pk_bf16(float lo, float hi) { unsigned r; asm volatile("v_cvt_pk_bf16_f32 %0, %1, %2" : "=v"(r) : "v"(lo), "v"(hi)); return r; }
; __device__ __forceinline__ float bf_lo(unsigned w) { return __uint_as_float(w << 16); }
; __device__ __forceinline__ float bf_hi(unsigned w) { return __uint_as_float(w & 0xffff0000u); }
; __device__ __forceinline__ float sumsq8(const f32x4 (&v)[8]) {
;     float s = 0.f;
; #pragma unroll
;     for (int j = 0; j < 8; ++j) s += (v[j][0] * v[j][0] + v[j][1] * v[j][1]) + (v[j][2] * v[j][2] + v[j][3] * v[j][3]);
;     return wave_sum(s);
; }
; __device__ __forceinline__ void modulate_store(const f32x4 (&v)[8], float rstd, const float* pn, const float* modr, bf16_t* orow, int lane) {
; #pragma unroll
;     for (int j = 0; j < 8; ++j) { const int col = 4 * lane + 256 * j;
;         const f32x4 g = *(const f32x4*)(pn + col), sh = *(const f32x4*)(modr + col), sc = *(const f32x4*)(modr + DM + col);
;         const f32x4 hh = v[j] * rstd * g * (sc + 1.f) + sh;
;         u32x2 w; w.x = cvt_pk_bf16(hh[0], hh[1]); w.y = cvt_pk_bf16(hh[2], hh[3]);
;         *(u32x2*)(orow + col) = w; }
; }
; __global__ void __launch_bounds__(NWAVES * 64, 2) mk_fwd(Args args) {
;     ...
;                 for (int j = 0; j < 8; ++j) { const int col = 4 * F.lane + 256 * j; const f32x4 gt = *(const f32x4*)(m0 + 2 * DM + col), pn = *(const f32x4*)(post_norm + col);
;                     const f32x4 y4 = (f32x4){bf_lo(yw[q][j].x), bf_hi(yw[q][j].x), bf_lo(yw[q][j].y), bf_hi(yw[q][j].y)};
;                     v[q][j] = v[q][j] + gt * (y4 * rsy * pn);
;                     if (lat) *(f32x4*)(args.out + (size_t)row * DM + col) = v[q][j]; }
;                 const float rstd = __builtin_amdgcn_rsqf(sumsq8(v[q]) * (1.f / DM) + EPS);
;                 modulate_store(v[q], rstd, pre_norm + DM, mod + (size_t)(9 + r) * 6144, H + (size_t)row * DM, F.lane); }
	v_mul_f32_e32 v217, v225, v217
	v_mul_f32_e32 v218, v225, v218
	v_mul_f32_e32 v219, v225, v219
	v_fmac_f32_e32 v68, v116, v216
	v_fmac_f32_e32 v69, v117, v217
	v_fmac_f32_e32 v70, v118, v218
	v_fmac_f32_e32 v71, v119, v219
	global_store_dwordx4 v193, v[68:71], s[24:25] offset:1024
	v_lshlrev_b32_e32 v216, 16, v92
	v_and_b32_e32 v217, 0xffff0000, v92
	v_lshlrev_b32_e32 v218, 16, v93
	v_and_b32_e32 v219, 0xffff0000, v93
	v_mul_f32_e32 v216, v225, v216
	v_mul_f32_e32 v217, v225, v217
	v_mul_f32_e32 v218, v225, v218
	v_mul_f32_e32 v219, v225, v219
	v_fmac_f32_e32 v72, v120, v216
	v_fmac_f32_e32 v73, v121, v217
	v_fmac_f32_e32 v74, v122, v218
	v_fmac_f32_e32 v75, v123, v219
	global_store_dwordx4 v193, v[72:75], s[24:25] offset:2048
	v_lshlrev_b32_e32 v216, 16, v94
	v_and_b32_e32 v217, 0xffff0000, v94
	v_lshlrev_b32_e32 v218, 16, v95
	v_and_b32_e32 v219, 0xffff0000, v95
	v_mul_f32_e32 v216, v225, v216
	v_mul_f32_e32 v217, v225, v217
	v_mul_f32_e32 v218, v225, v218
	v_mul_f32_e32 v219, v225, v219
	v_fmac_f32_e32 v76, v124, v216
	v_fmac_f32_e32 v77, v125, v217
	v_fmac_f32_e32 v78, v126, v218
	v_fmac_f32_e32 v79, v127, v219
	global_store_dwordx4 v193, v[76:79], s[24:25] offset:3072
	v_mul_f32_e32 v222, v48, v48
	v_mul_f32_e32 v223, v49, v49
	v_fmac_f32_e32 v222, v50, v50
	v_fmac_f32_e32 v223, v51, v51
	v_fmac_f32_e32 v222, v52, v52
	v_fmac_f32_e32 v223, v53, v53
	v_fmac_f32_e32 v222, v54, v54
	v_fmac_f32_e32 v223, v55, v55
	v_fmac_f32_e32 v222, v56, v56
	v_fmac_f32_e32 v223, v57, v57
	v_fmac_f32_e32 v222, v58, v58
	v_fmac_f32_e32 v223, v59, v59
	v_fmac_f32_e32 v222, v60, v60
	v_fmac_f32_e32 v223, v61, v61
	v_fmac_f32_e32 v222, v62, v62
	v_fmac_f32_e32 v223, v63, v63
	v_fmac_f32_e32 v222, v64, v64
	v_fmac_f32_e32 v223, v65, v65
	v_fmac_f32_e32 v222, v66, v66
	v_fmac_f32_e32 v223, v67, v67
	v_fmac_f32_e32 v222, v68, v68
	v_fmac_f32_e32 v223, v69, v69
	v_fmac_f32_e32 v222, v70, v70
	v_fmac_f32_e32 v223, v71, v71
	v_fmac_f32_e32 v222, v72, v72
	v_fmac_f32_e32 v223, v73, v73
	v_fmac_f32_e32 v222, v74, v74
	v_fmac_f32_e32 v223, v75, v75
	v_fmac_f32_e32 v222, v76, v76
	v_fmac_f32_e32 v223, v77, v77
	v_fmac_f32_e32 v222, v78, v78
	v_fmac_f32_e32 v223, v79, v79
	v_add_f32_e32 v222, v222, v223
	s_nop 1
	v_add_f32_dpp v224, v222, v222 quad_perm:[1,0,3,2] row_mask:0xf bank_mask:0xf
	s_nop 1
	v_add_f32_dpp v224, v224, v224 quad_perm:[2,3,0,1] row_mask:0xf bank_mask:0xf
	s_nop 1
	v_add_f32_dpp v224, v224, v224 row_half_mirror row_mask:0xf bank_mask:0xf
	s_nop 1
	v_add_f32_dpp v224, v224, v224 row_mirror row_mask:0xf bank_mask:0xf
	s_nop 1
	v_readlane_b32 s40, v224, 0
	v_readlane_b32 s41, v224, 16
	v_readlane_b32 s42, v224, 32
	v_readlane_b32 s43, v224, 48
	s_nop 1
	v_mov_b32_e32 v225, s40
	v_add_f32_e32 v225, s41, v225
	v_add_f32_e32 v225, s42, v225
	v_add_f32_e32 v225, s43, v225
	v_fmamk_f32 v225, v225, 0x3a000000, v195
	v_rsq_f32_e32 v225, v225
	s_nop 0
	s_add_i32 s0, s6, 7
	s_lshl_b32 s1, s0, 12
	s_add_u32 s26, s84, s1
	s_addc_u32 s27, s85, 0
	s_add_u32 s26, s26, 0x4000000
	s_addc_u32 s27, s27, 0
	v_mul_f32_e32 v216, v225, v48
	v_mul_f32_e32 v217, v225, v49
	v_mul_f32_e32 v218, v225, v50
	v_mul_f32_e32 v219, v225, v51
	v_fma_f32 v216, v216, v128, v160
	v_fma_f32 v217, v217, v129, v161
	v_fma_f32 v218, v218, v130, v162
	v_fma_f32 v219, v219, v131, v163
	v_cvt_pk_bf16_f32 v196, v216, v217
	v_cvt_pk_bf16_f32 v197, v218, v219
	global_store_dwordx2 v194, v[196:197], s[26:27] offset:0
	v_mul_f32_e32 v216, v225, v52
	v_mul_f32_e32 v217, v225, v53
	v_mul_f32_e32 v218, v225, v54
	v_mul_f32_e32 v219, v225, v55
	v_fma_f32 v216, v216, v132, v164
	v_fma_f32 v217, v217, v133, v165
	v_fma_f32 v218, v218, v134, v166
	v_fma_f32 v219, v219, v135, v167
	v_cvt_pk_bf16_f32 v220, v216, v217
	v_cvt_pk_bf16_f32 v221, v218, v219
	global_store_dwordx2 v194, v[220:221], s[26:27] offset:512
	v_mul_f32_e32 v216, v225, v56
	v_mul_f32_e32 v217, v225, v57
	v_mul_f32_e32 v218, v225, v58
	v_mul_f32_e32 v219, v225, v59
	v_fma_f32 v216, v216, v136, v168
	v_fma_f32 v217, v217, v137, v169
	v_fma_f32 v218, v218, v138, v170
	v_fma_f32 v219, v219, v139, v171
	v_cvt_pk_bf16_f32 v196, v216, v217
	v_cvt_pk_bf16_f32 v197, v218, v219
	global_store_dwordx2 v194, v[196:197], s[26:27] offset:1024
	v_mul_f32_e32 v216, v225, v60
	v_mul_f32_e32 v217, v225, v61
	v_mul_f32_e32 v218, v225, v62
	v_mul_f32_e32 v219, v225, v63
	v_fma_f32 v216, v216, v140, v172
	v_fma_f32 v217, v217, v141, v173
	v_fma_f32 v218, v218, v142, v174
	v_fma_f32 v219, v219, v143, v175
	v_cvt_pk_bf16_f32 v220, v216, v217
	v_cvt_pk_bf16_f32 v221, v218, v219
	global_store_dwordx2 v194, v[220:221], s[26:27] offset:1536
	v_mul_f32_e32 v216, v225, v64
	v_mul_f32_e32 v217, v225, v65
	v_mul_f32_e32 v218, v225, v66
	v_mul_f32_e32 v219, v225, v67
	v_fma_f32 v216, v216, v144, v176
	v_fma_f32 v217, v217, v145, v177
	v_fma_f32 v218, v218, v146, v178
	v_fma_f32 v219, v219, v147, v179
	v_cvt_pk_bf16_f32 v196, v216, v217
	v_cvt_pk_bf16_f32 v197, v218, v219
	global_store_dwordx2 v194, v[196:197], s[26:27] offset:2048
	v_mul_f32_e32 v216, v225, v68
	v_mul_f32_e32 v217, v225, v69
	v_mul_f32_e32 v218, v225, v70
	v_mul_f32_e32 v219, v225, v71
	v_fma_f32 v216, v216, v148, v180
	v_fma_f32 v217, v217, v149, v181
	v_fma_f32 v218, v218, v150, v182
	v_fma_f32 v219, v219, v151, v183
	v_cvt_pk_bf16_f32 v220, v216, v217
	v_cvt_pk_bf16_f32 v221, v218, v219
	global_store_dwordx2 v194, v[220:221], s[26:27] offset:2560
	v_mul_f32_e32 v216, v225, v72
	v_mul_f32_e32 v217, v225, v73
	v_mul_f32_e32 v218, v225, v74
	v_mul_f32_e32 v219, v225, v75
	v_fma_f32 v216, v216, v152, v184
	v_fma_f32 v217, v217, v153, v185
	v_fma_f32 v218, v218, v154, v186
	v_fma_f32 v219, v219, v155, v187
	v_cvt_pk_bf16_f32 v196, v216, v217
	v_cvt_pk_bf16_f32 v197, v218, v219
	global_store_dwordx2 v194, v[196:197], s[26:27] offset:3072
	v_mul_f32_e32 v216, v225, v76
	v_mul_f32_e32 v217, v225, v77
	v_mul_f32_e32 v218, v225, v78
	v_mul_f32_e32 v219, v225, v79
	v_fma_f32 v216, v216, v156, v188
	v_fma_f32 v217, v217, v157, v189
	v_fma_f32 v218, v218, v158, v190
	v_fma_f32 v219, v219, v159, v191
	v_cvt_pk_bf16_f32 v220, v216, v217
	v_cvt_pk_bf16_f32 v221, v218, v219
	global_store_dwordx2 v194, v[220:221], s[26:27] offset:3584
	s_add_i32 s0, s6, 8
	s_add_i32 s0, s6, 8
	s_lshr_b32 s8, s0, 11
	s_cmp_lt_u32 s0, 0x4000
	s_cselect_b32 s8, s8, 8
	s_cmp_eq_u32 s8, s7
	s_cbranch_scc1 .Lp6_np8
; __device__ __forceinline__ void modulate_store(const f32x4 (&v)[8], float rstd, const float* pn, const float* modr, bf16_t* orow, int lane) {
; #pragma unroll
;     for (int j = 0; j < 8; ++j) { const int col = 4 * lane + 256 * j;
;         const f32x4 g = *(const f32x4*)(pn + col), sh = *(const f32x4*)(modr + col), sc = *(const f32x4*)(modr + DM + col);
;         const f32x4 hh = v[j] * rstd * g * (sc + 1.f) + sh;
; __global__ void __launch_bounds__(NWAVES * 64, 2) mk_fwd(Args args) {
;     ...
;                 const float* m0 = mod + (size_t)r * 6144;
; #pragma unroll
;                 for (int j = 0; j < 8; ++j) { const int col = 4 * F.lane + 256 * j; const f32x4 gt = *(const f32x4*)(m0 + 2 * DM + col), pn = *(const f32x4*)(post_norm + col);
	s_mov_b32 s7, s8
	s_add_i32 s1, s8, 9
	s_mul_i32 s1, s1, 0x6000
	s_add_u32 s44, s84, s1
	s_addc_u32 s45, s85, 0
	s_add_u32 s44, s44, 0x2000
	s_addc_u32 s45, s45, 0
	s_add_i32 s1, s8, 9
	s_mul_i32 s1, s1, 0x6000
	s_add_u32 s36, s84, s1
	s_addc_u32 s37, s85, 0
	s_add_u32 s38, s80, 0x2000
	s_addc_u32 s39, s81, 0
	s_mul_i32 s1, s8, 0x6000
	s_add_u32 s34, s84, s1
	s_addc_u32 s35, s85, 0
	s_add_u32 s34, s34, 0x4000
	s_addc_u32 s35, s35, 0
	global_load_dwordx4 v[96:99], v192, s[34:35] offset:0
	global_load_dwordx4 v[200:203], v192, s[82:83] offset:0
	global_load_dwordx4 v[100:103], v192, s[34:35] offset:1024
	global_load_dwordx4 v[204:207], v192, s[82:83] offset:1024
	global_load_dwordx4 v[104:107], v192, s[34:35] offset:2048
	global_load_dwordx4 v[208:211], v192, s[82:83] offset:2048
	global_load_dwordx4 v[108:111], v192, s[34:35] offset:3072
	global_load_dwordx4 v[212:215], v192, s[82:83] offset:3072
	s_waitcnt vmcnt(0)
	v_mul_f32_e32 v96, v96, v200
	v_mul_f32_e32 v97, v97, v201
	v_mul_f32_e32 v98, v98, v202
	v_mul_f32_e32 v99, v99, v203
	v_mul_f32_e32 v100, v100, v204
	v_mul_f32_e32 v101, v101, v205
	v_mul_f32_e32 v102, v102, v206
	v_mul_f32_e32 v103, v103, v207
	v_mul_f32_e32 v104, v104, v208
	v_mul_f32_e32 v105, v105, v209
	v_mul_f32_e32 v106, v106, v210
	v_mul_f32_e32 v107, v107, v211
	v_mul_f32_e32 v108, v108, v212
	v_mul_f32_e32 v109, v109, v213
	v_mul_f32_e32 v110, v110, v214
	v_mul_f32_e32 v111, v111, v215
	global_load_dwordx4 v[128:131], v192, s[38:39] offset:0
	global_load_dwordx4 v[200:203], v192, s[44:45] offset:0
	global_load_dwordx4 v[160:163], v192, s[36:37] offset:0
	global_load_dwordx4 v[132:135], v192, s[38:39] offset:1024
	global_load_dwordx4 v[204:207], v192, s[44:45] offset:1024
	global_load_dwordx4 v[164:167], v192, s[36:37] offset:1024
	global_load_dwordx4 v[136:139], v192, s[38:39] offset:2048
	global_load_dwordx4 v[208:211], v192, s[44:45] offset:2048
	global_load_dwordx4 v[168:171], v192, s[36:37] offset:2048
	global_load_dwordx4 v[140:143], v192, s[38:39] offset:3072
	global_load_dwordx4 v[212:215], v192, s[44:45] offset:3072
	global_load_dwordx4 v[172:175], v192, s[36:37] offset:3072
	s_waitcnt vmcnt(0)
	v_add_f32_e32 v200, 1.0, v200
	v_add_f32_e32 v201, 1.0, v201
	v_add_f32_e32 v202, 1.0, v202
	v_add_f32_e32 v203, 1.0, v203
	v_mul_f32_e32 v128, v128, v200
	v_mul_f32_e32 v129, v129, v201
	v_mul_f32_e32 v130, v130, v202
	v_mul_f32_e32 v131, v131, v203
	v_add_f32_e32 v204, 1.0, v204
	v_add_f32_e32 v205, 1.0, v205
	v_add_f32_e32 v206, 1.0, v206
	v_add_f32_e32 v207, 1.0, v207
	v_mul_f32_e32 v132, v132, v204
	v_mul_f32_e32 v133, v133, v205
	v_mul_f32_e32 v134, v134, v206
	v_mul_f32_e32 v135, v135, v207
	v_add_f32_e32 v208, 1.0, v208
	v_add_f32_e32 v209, 1.0, v209
	v_add_f32_e32 v210, 1.0, v210
	v_add_f32_e32 v211, 1.0, v211
	v_mul_f32_e32 v136, v136, v208
	v_mul_f32_e32 v137, v137, v209
	v_mul_f32_e32 v138, v138, v210
	v_mul_f32_e32 v139, v139, v211
	v_add_f32_e32 v212, 1.0, v212
	v_add_f32_e32 v213, 1.0, v213
	v_add_f32_e32 v214, 1.0, v214
	v_add_f32_e32 v215, 1.0, v215
	v_mul_f32_e32 v140, v140, v212
	v_mul_f32_e32 v141, v141, v213
	v_mul_f32_e32 v142, v142, v214
	v_mul_f32_e32 v143, v143, v215
	global_load_dwordx4 v[112:115], v193, s[34:35] offset:0
	global_load_dwordx4 v[200:203], v193, s[82:83] offset:0
	global_load_dwordx4 v[116:119], v193, s[34:35] offset:1024
	global_load_dwordx4 v[204:207], v193, s[82:83] offset:1024
	global_load_dwordx4 v[120:123], v193, s[34:35] offset:2048
	global_load_dwordx4 v[208:211], v193, s[82:83] offset:2048
	global_load_dwordx4 v[124:127], v193, s[34:35] offset:3072
	global_load_dwordx4 v[212:215], v193, s[82:83] offset:3072
	s_waitcnt vmcnt(0)
	v_mul_f32_e32 v112, v112, v200
	v_mul_f32_e32 v113, v113, v201
	v_mul_f32_e32 v114, v114, v202
	v_mul_f32_e32 v115, v115, v203
	v_mul_f32_e32 v116, v116, v204
	v_mul_f32_e32 v117, v117, v205
	v_mul_f32_e32 v118, v118, v206
	v_mul_f32_e32 v119, v119, v207
	v_mul_f32_e32 v120, v120, v208
	v_mul_f32_e32 v121, v121, v209
	v_mul_f32_e32 v122, v122, v210
	v_mul_f32_e32 v123, v123, v211
	v_mul_f32_e32 v124, v124, v212
	v_mul_f32_e32 v125, v125, v213
	v_mul_f32_e32 v126, v126, v214
	v_mul_f32_e32 v127, v127, v215
	global_load_dwordx4 v[144:147], v193, s[38:39] offset:0
	global_load_dwordx4 v[200:203], v193, s[44:45] offset:0
	global_load_dwordx4 v[176:179], v193, s[36:37] offset:0
	global_load_dwordx4 v[148:151], v193, s[38:39] offset:1024
	global_load_dwordx4 v[204:207], v193, s[44:45] offset:1024
	global_load_dwordx4 v[180:183], v193, s[36:37] offset:1024
	global_load_dwordx4 v[152:155], v193, s[38:39] offset:2048
	global_load_dwordx4 v[208:211], v193, s[44:45] offset:2048
	global_load_dwordx4 v[184:187], v193, s[36:37] offset:2048
	global_load_dwordx4 v[156:159], v193, s[38:39] offset:3072
	global_load_dwordx4 v[212:215], v193, s[44:45] offset:3072
	global_load_dwordx4 v[188:191], v193, s[36:37] offset:3072
	s_waitcnt vmcnt(0)
	v_add_f32_e32 v200, 1.0, v200
	v_add_f32_e32 v201, 1.0, v201
	v_add_f32_e32 v202, 1.0, v202
	v_add_f32_e32 v203, 1.0, v203
	v_mul_f32_e32 v144, v144, v200
	v_mul_f32_e32 v145, v145, v201
	v_mul_f32_e32 v146, v146, v202
	v_mul_f32_e32 v147, v147, v203
	v_add_f32_e32 v204, 1.0, v204
	v_add_f32_e32 v205, 1.0, v205
	v_add_f32_e32 v206, 1.0, v206
	v_add_f32_e32 v207, 1.0, v207
	v_mul_f32_e32 v148, v148, v204
	v_mul_f32_e32 v149, v149, v205
	v_mul_f32_e32 v150, v150, v206
	v_mul_f32_e32 v151, v151, v207
	v_add_f32_e32 v208, 1.0, v208
	v_add_f32_e32 v209, 1.0, v209
	v_add_f32_e32 v210, 1.0, v210
	v_add_f32_e32 v211, 1.0, v211
	v_mul_f32_e32 v152, v152, v208
	v_mul_f32_e32 v153, v153, v209
	v_mul_f32_e32 v154, v154, v210
	v_mul_f32_e32 v155, v155, v211
	v_add_f32_e32 v212, 1.0, v212
	v_add_f32_e32 v213, 1.0, v213
	v_add_f32_e32 v214, 1.0, v214
	v_add_f32_e32 v215, 1.0, v215
	v_mul_f32_e32 v156, v156, v212
	v_mul_f32_e32 v157, v157, v213
	v_mul_f32_e32 v158, v158, v214
	v_mul_f32_e32 v159, v159, v215
; __device__ __forceinline__ float bf_lo(unsigned w) { return __uint_as_float(w << 16); }
; __device__ __forceinline__ float bf_hi(unsigned w) { return __uint_as_float(w & 0xffff0000u); }
; __global__ void __launch_bounds__(NWAVES * 64, 2) mk_fwd(Args args) {
;     ...
;             for (int q = 0; q < 3; ++q) { const int row = row0 + q; const bool lat = row < ML; const int r = lat ? row / SEQ : 8;
;                 float sy = 0.f;
; #pragma unroll
;                 for (int j = 0; j < 8; ++j) { const float a = bf_lo(yw[q][j].x), b = bf_hi(yw[q][j].x), c2 = bf_lo(yw[q][j].y), d = bf_hi(yw[q][j].y); sy += (a * a + b * b) + (c2 * c2 + d * d); }
;                 const float rsy = __builtin_amdgcn_rsqf(wave_sum(sy) * (1.f / DM) + EPS);
;                 const float* m0 = mod + (size_t)r * 6144;
; #pragma unroll
;                 for (int j = 0; j < 8; ++j) { const int col = 4 * F.lane + 256 * j; const f32x4 gt = *(const f32x4*)(m0 + 2 * DM + col), pn = *(const f32x4*)(post_norm + col);
;                     const f32x4 y4 = (f32x4){bf_lo(yw[q][j].x), bf_hi(yw[q][j].x), bf_lo(yw[q][j].y), bf_hi(yw[q][j].y)};
;                     v[q][j] = v[q][j] + gt * (y4 * rsy * pn);
;                     if (lat) *(f32x4*)(args.out + (size_t)row * DM + col) = v[q][j]; }
.Lp6_np8:
	s_waitcnt vmcnt(16)
	v_lshlrev_b32_e32 v216, 16, v32
	v_and_b32_e32 v217, 0xffff0000, v32
	v_lshlrev_b32_e32 v218, 16, v33
	v_and_b32_e32 v219, 0xffff0000, v33
	v_mul_f32_e32 v222, v216, v216
	v_mul_f32_e32 v223, v217, v217
	v_fmac_f32_e32 v222, v218, v218
	v_fmac_f32_e32 v223, v219, v219
	v_lshlrev_b32_e32 v216, 16, v34
	v_and_b32_e32 v217, 0xffff0000, v34
	v_lshlrev_b32_e32 v218, 16, v35
	v_and_b32_e32 v219, 0xffff0000, v35
	v_fmac_f32_e32 v222, v216, v216
	v_fmac_f32_e32 v223, v217, v217
	v_fmac_f32_e32 v222, v218, v218
	v_fmac_f32_e32 v223, v219, v219
	v_lshlrev_b32_e32 v216, 16, v36
	v_and_b32_e32 v217, 0xffff0000, v36
	v_lshlrev_b32_e32 v218, 16, v37
	v_and_b32_e32 v219, 0xffff0000, v37
	v_fmac_f32_e32 v222, v216, v216
	v_fmac_f32_e32 v223, v217, v217
	v_fmac_f32_e32 v222, v218, v218
	v_fmac_f32_e32 v223, v219, v219
	v_lshlrev_b32_e32 v216, 16, v38
	v_and_b32_e32 v217, 0xffff0000, v38
	v_lshlrev_b32_e32 v218, 16, v39
	v_and_b32_e32 v219, 0xffff0000, v39
	v_fmac_f32_e32 v222, v216, v216
	v_fmac_f32_e32 v223, v217, v217
	v_fmac_f32_e32 v222, v218, v218
	v_fmac_f32_e32 v223, v219, v219
	v_lshlrev_b32_e32 v216, 16, v40
	v_and_b32_e32 v217, 0xffff0000, v40
	v_lshlrev_b32_e32 v218, 16, v41
	v_and_b32_e32 v219, 0xffff0000, v41
	v_fmac_f32_e32 v222, v216, v216
	v_fmac_f32_e32 v223, v217, v217
	v_fmac_f32_e32 v222, v218, v218
	v_fmac_f32_e32 v223, v219, v219
	v_lshlrev_b32_e32 v216, 16, v42
	v_and_b32_e32 v217, 0xffff0000, v42
	v_lshlrev_b32_e32 v218, 16, v43
	v_and_b32_e32 v219, 0xffff0000, v43
	v_fmac_f32_e32 v222, v216, v216
	v_fmac_f32_e32 v223, v217, v217
	v_fmac_f32_e32 v222, v218, v218
	v_fmac_f32_e32 v223, v219, v219
	v_lshlrev_b32_e32 v216, 16, v44
	v_and_b32_e32 v217, 0xffff0000, v44
	v_lshlrev_b32_e32 v218, 16, v45
	v_and_b32_e32 v219, 0xffff0000, v45
	v_fmac_f32_e32 v222, v216, v216
	v_fmac_f32_e32 v223, v217, v217
	v_fmac_f32_e32 v222, v218, v218
	v_fmac_f32_e32 v223, v219, v219
	v_lshlrev_b32_e32 v216, 16, v46
	v_and_b32_e32 v217, 0xffff0000, v46
	v_lshlrev_b32_e32 v218, 16, v47
	v_and_b32_e32 v219, 0xffff0000, v47
	v_fmac_f32_e32 v222, v216, v216
	v_fmac_f32_e32 v223, v217, v217
	v_fmac_f32_e32 v222, v218, v218
	v_fmac_f32_e32 v223, v219, v219
	v_add_f32_e32 v222, v222, v223
	s_nop 1
	v_add_f32_dpp v224, v222, v222 quad_perm:[1,0,3,2] row_mask:0xf bank_mask:0xf
	s_nop 1
	v_add_f32_dpp v224, v224, v224 quad_perm:[2,3,0,1] row_mask:0xf bank_mask:0xf
	s_nop 1
	v_add_f32_dpp v224, v224, v224 row_half_mirror row_mask:0xf bank_mask:0xf
	s_nop 1
	v_add_f32_dpp v224, v224, v224 row_mirror row_mask:0xf bank_mask:0xf
	s_nop 1
	v_readlane_b32 s40, v224, 0
	v_readlane_b32 s41, v224, 16
	v_readlane_b32 s42, v224, 32
	v_readlane_b32 s43, v224, 48
	s_nop 1
	v_mov_b32_e32 v225, s40
	v_add_f32_e32 v225, s41, v225
	v_add_f32_e32 v225, s42, v225
	v_add_f32_e32 v225, s43, v225
	v_fmamk_f32 v225, v225, 0x3a000000, v195
	v_rsq_f32_e32 v225, v225
	s_nop 0
	s_add_i32 s0, s6, 8
	s_cmp_lt_u32 s0, 0x4000
	s_cselect_b32 s24, s94, s84
	s_cselect_b32 s25, s95, s85
	s_cselect_b32 s44, 0, 0x16000000
	s_cselect_b32 s1, 0, 0x4000
	s_sub_i32 s1, s0, s1
	s_lshl_b32 s1, s1, 13
	s_add_u32 s24, s24, s1
	s_addc_u32 s25, s25, 0
	s_add_u32 s24, s24, s44
	s_addc_u32 s25, s25, 0
	v_lshlrev_b32_e32 v216, 16, v32
	v_and_b32_e32 v217, 0xffff0000, v32
	v_lshlrev_b32_e32 v218, 16, v33
	v_and_b32_e32 v219, 0xffff0000, v33
	v_mul_f32_e32 v216, v225, v216
	v_mul_f32_e32 v217, v225, v217
	v_mul_f32_e32 v218, v225, v218
	v_mul_f32_e32 v219, v225, v219
	v_fmac_f32_e32 v0, v96, v216
	v_fmac_f32_e32 v1, v97, v217
	v_fmac_f32_e32 v2, v98, v218
	v_fmac_f32_e32 v3, v99, v219
	global_store_dwordx4 v192, v[0:3], s[24:25] offset:0
	v_lshlrev_b32_e32 v216, 16, v34
	v_and_b32_e32 v217, 0xffff0000, v34
	v_lshlrev_b32_e32 v218, 16, v35
	v_and_b32_e32 v219, 0xffff0000, v35
	v_mul_f32_e32 v216, v225, v216
	v_mul_f32_e32 v217, v225, v217
	v_mul_f32_e32 v218, v225, v218
	v_mul_f32_e32 v219, v225, v219
	v_fmac_f32_e32 v4, v100, v216
	v_fmac_f32_e32 v5, v101, v217
	v_fmac_f32_e32 v6, v102, v218
	v_fmac_f32_e32 v7, v103, v219
	global_store_dwordx4 v192, v[4:7], s[24:25] offset:1024
	v_lshlrev_b32_e32 v216, 16, v36
	v_and_b32_e32 v217, 0xffff0000, v36
	v_lshlrev_b32_e32 v218, 16, v37
	v_and_b32_e32 v219, 0xffff0000, v37
	v_mul_f32_e32 v216, v225, v216
	v_mul_f32_e32 v217, v225, v217
	v_mul_f32_e32 v218, v225, v218
	v_mul_f32_e32 v219, v225, v219
	v_fmac_f32_e32 v8, v104, v216
	v_fmac_f32_e32 v9, v105, v217
	v_fmac_f32_e32 v10, v106, v218
	v_fmac_f32_e32 v11, v107, v219
	global_store_dwordx4 v192, v[8:11], s[24:25] offset:2048
	v_lshlrev_b32_e32 v216, 16, v38
	v_and_b32_e32 v217, 0xffff0000, v38
	v_lshlrev_b32_e32 v218, 16, v39
	v_and_b32_e32 v219, 0xffff0000, v39
	v_mul_f32_e32 v216, v225, v216
	v_mul_f32_e32 v217, v225, v217
	v_mul_f32_e32 v218, v225, v218
	v_mul_f32_e32 v219, v225, v219
	v_fmac_f32_e32 v12, v108, v216
	v_fmac_f32_e32 v13, v109, v217
	v_fmac_f32_e32 v14, v110, v218
	v_fmac_f32_e32 v15, v111, v219
	global_store_dwordx4 v192, v[12:15], s[24:25] offset:3072
	v_lshlrev_b32_e32 v216, 16, v40
	v_and_b32_e32 v217, 0xffff0000, v40
	v_lshlrev_b32_e32 v218, 16, v41
	v_and_b32_e32 v219, 0xffff0000, v41
	v_mul_f32_e32 v216, v225, v216
	v_mul_f32_e32 v217, v225, v217
	v_mul_f32_e32 v218, v225, v218
	v_mul_f32_e32 v219, v225, v219
	v_fmac_f32_e32 v16, v112, v216
	v_fmac_f32_e32 v17, v113, v217
	v_fmac_f32_e32 v18, v114, v218
	v_fmac_f32_e32 v19, v115, v219
	global_store_dwordx4 v193, v[16:19], s[24:25] offset:0
	v_lshlrev_b32_e32 v216, 16, v42
	v_and_b32_e32 v217, 0xffff0000, v42
	v_lshlrev_b32_e32 v218, 16, v43
	v_and_b32_e32 v219, 0xffff0000, v43
	v_mul_f32_e32 v216, v225, v216
; __device__ __forceinline__ unsigned cvt_pk_bf16(float lo, float hi) { unsigned r; asm volatile("v_cvt_pk_bf16_f32 %0, %1, %2" : "=v"(r) : "v"(lo), "v"(hi)); return r; }
; __device__ __forceinline__ float bf_lo(unsigned w) { return __uint_as_float(w << 16); }
; __device__ __forceinline__ float bf_hi(unsigned w) { return __uint_as_float(w & 0xffff0000u); }
; __device__ __forceinline__ float sumsq8(const f32x4 (&v)[8]) {
;     float s = 0.f;
; #pragma unroll
;     for (int j = 0; j < 8; ++j) s += (v[j][0] * v[j][0] + v[j][1] * v[j][1]) + (v[j][2] * v[j][2] + v[j][3] * v[j][3]);
;     return wave_sum(s);
; }
; __device__ __forceinline__ void modulate_store(const f32x4 (&v)[8], float rstd, const float* pn, const float* modr, bf16_t* orow, int lane) {
; #pragma unroll
;     for (int j = 0; j < 8; ++j) { const int col = 4 * lane + 256 * j;
;         const f32x4 g = *(const f32x4*)(pn + col), sh = *(const f32x4*)(modr + col), sc = *(const f32x4*)(modr + DM + col);
;         const f32x4 hh = v[j] * rstd * g * (sc + 1.f) + sh;
;         u32x2 w; w.x = cvt_pk_bf16(hh[0], hh[1]); w.y = cvt_pk_bf16(hh[2], hh[3]);
;         *(u32x2*)(orow + col) = w; }
; __global__ void __launch_bounds__(NWAVES * 64, 2) mk_fwd(Args args) {
;     ...
;                     const f32x4 y4 = (f32x4){bf_lo(yw[q][j].x), bf_hi(yw[q][j].x), bf_lo(yw[q][j].y), bf_hi(yw[q][j].y)};
;                     v[q][j] = v[q][j] + gt * (y4 * rsy * pn);
;                     if (lat) *(f32x4*)(args.out + (size_t)row * DM + col) = v[q][j]; }
;                 const float rstd = __builtin_amdgcn_rsqf(sumsq8(v[q]) * (1.f / DM) + EPS);
;                 modulate_store(v[q], rstd, pre_norm + DM, mod + (size_t)(9 + r) * 6144, H + (size_t)row * DM, F.lane); }
	v_mul_f32_e32 v217, v225, v217
	v_mul_f32_e32 v218, v225, v218
	v_mul_f32_e32 v219, v225, v219
	v_fmac_f32_e32 v20, v116, v216
	v_fmac_f32_e32 v21, v117, v217
	v_fmac_f32_e32 v22, v118, v218
	v_fmac_f32_e32 v23, v119, v219
	global_store_dwordx4 v193, v[20:23], s[24:25] offset:1024
	v_lshlrev_b32_e32 v216, 16, v44
	v_and_b32_e32 v217, 0xffff0000, v44
	v_lshlrev_b32_e32 v218, 16, v45
	v_and_b32_e32 v219, 0xffff0000, v45
	v_mul_f32_e32 v216, v225, v216
	v_mul_f32_e32 v217, v225, v217
	v_mul_f32_e32 v218, v225, v218
	v_mul_f32_e32 v219, v225, v219
	v_fmac_f32_e32 v24, v120, v216
	v_fmac_f32_e32 v25, v121, v217
	v_fmac_f32_e32 v26, v122, v218
	v_fmac_f32_e32 v27, v123, v219
	global_store_dwordx4 v193, v[24:27], s[24:25] offset:2048
	v_lshlrev_b32_e32 v216, 16, v46
	v_and_b32_e32 v217, 0xffff0000, v46
	v_lshlrev_b32_e32 v218, 16, v47
	v_and_b32_e32 v219, 0xffff0000, v47
	v_mul_f32_e32 v216, v225, v216
	v_mul_f32_e32 v217, v225, v217
	v_mul_f32_e32 v218, v225, v218
	v_mul_f32_e32 v219, v225, v219
	v_fmac_f32_e32 v28, v124, v216
	v_fmac_f32_e32 v29, v125, v217
	v_fmac_f32_e32 v30, v126, v218
	v_fmac_f32_e32 v31, v127, v219
	global_store_dwordx4 v193, v[28:31], s[24:25] offset:3072
	v_mul_f32_e32 v222, v0, v0
	v_mul_f32_e32 v223, v1, v1
	v_fmac_f32_e32 v222, v2, v2
	v_fmac_f32_e32 v223, v3, v3
	v_fmac_f32_e32 v222, v4, v4
	v_fmac_f32_e32 v223, v5, v5
	v_fmac_f32_e32 v222, v6, v6
	v_fmac_f32_e32 v223, v7, v7
	v_fmac_f32_e32 v222, v8, v8
	v_fmac_f32_e32 v223, v9, v9
	v_fmac_f32_e32 v222, v10, v10
	v_fmac_f32_e32 v223, v11, v11
	v_fmac_f32_e32 v222, v12, v12
	v_fmac_f32_e32 v223, v13, v13
	v_fmac_f32_e32 v222, v14, v14
	v_fmac_f32_e32 v223, v15, v15
	v_fmac_f32_e32 v222, v16, v16
	v_fmac_f32_e32 v223, v17, v17
	v_fmac_f32_e32 v222, v18, v18
	v_fmac_f32_e32 v223, v19, v19
	v_fmac_f32_e32 v222, v20, v20
	v_fmac_f32_e32 v223, v21, v21
	v_fmac_f32_e32 v222, v22, v22
	v_fmac_f32_e32 v223, v23, v23
	v_fmac_f32_e32 v222, v24, v24
	v_fmac_f32_e32 v223, v25, v25
	v_fmac_f32_e32 v222, v26, v26
	v_fmac_f32_e32 v223, v27, v27
	v_fmac_f32_e32 v222, v28, v28
	v_fmac_f32_e32 v223, v29, v29
	v_fmac_f32_e32 v222, v30, v30
	v_fmac_f32_e32 v223, v31, v31
	v_add_f32_e32 v222, v222, v223
	s_nop 1
	v_add_f32_dpp v224, v222, v222 quad_perm:[1,0,3,2] row_mask:0xf bank_mask:0xf
	s_nop 1
	v_add_f32_dpp v224, v224, v224 quad_perm:[2,3,0,1] row_mask:0xf bank_mask:0xf
	s_nop 1
	v_add_f32_dpp v224, v224, v224 row_half_mirror row_mask:0xf bank_mask:0xf
	s_nop 1
	v_add_f32_dpp v224, v224, v224 row_mirror row_mask:0xf bank_mask:0xf
	s_nop 1
	v_readlane_b32 s40, v224, 0
	v_readlane_b32 s41, v224, 16
	v_readlane_b32 s42, v224, 32
	v_readlane_b32 s43, v224, 48
	s_nop 1
	v_mov_b32_e32 v225, s40
	v_add_f32_e32 v225, s41, v225
	v_add_f32_e32 v225, s42, v225
	v_add_f32_e32 v225, s43, v225
	v_fmamk_f32 v225, v225, 0x3a000000, v195
	v_rsq_f32_e32 v225, v225
	s_nop 0
	s_add_i32 s0, s6, 8
	s_lshl_b32 s1, s0, 12
	s_add_u32 s26, s84, s1
	s_addc_u32 s27, s85, 0
	s_add_u32 s26, s26, 0x4000000
	s_addc_u32 s27, s27, 0
	v_mul_f32_e32 v216, v225, v0
	v_mul_f32_e32 v217, v225, v1
	v_mul_f32_e32 v218, v225, v2
	v_mul_f32_e32 v219, v225, v3
	v_fma_f32 v216, v216, v128, v160
	v_fma_f32 v217, v217, v129, v161
	v_fma_f32 v218, v218, v130, v162
	v_fma_f32 v219, v219, v131, v163
	v_cvt_pk_bf16_f32 v196, v216, v217
	v_cvt_pk_bf16_f32 v197, v218, v219
	global_store_dwordx2 v194, v[196:197], s[26:27] offset:0
	v_mul_f32_e32 v216, v225, v4
	v_mul_f32_e32 v217, v225, v5
	v_mul_f32_e32 v218, v225, v6
	v_mul_f32_e32 v219, v225, v7
	v_fma_f32 v216, v216, v132, v164
	v_fma_f32 v217, v217, v133, v165
	v_fma_f32 v218, v218, v134, v166
	v_fma_f32 v219, v219, v135, v167
	v_cvt_pk_bf16_f32 v220, v216, v217
	v_cvt_pk_bf16_f32 v221, v218, v219
	global_store_dwordx2 v194, v[220:221], s[26:27] offset:512
	v_mul_f32_e32 v216, v225, v8
	v_mul_f32_e32 v217, v225, v9
	v_mul_f32_e32 v218, v225, v10
	v_mul_f32_e32 v219, v225, v11
	v_fma_f32 v216, v216, v136, v168
	v_fma_f32 v217, v217, v137, v169
	v_fma_f32 v218, v218, v138, v170
	v_fma_f32 v219, v219, v139, v171
	v_cvt_pk_bf16_f32 v196, v216, v217
	v_cvt_pk_bf16_f32 v197, v218, v219
	global_store_dwordx2 v194, v[196:197], s[26:27] offset:1024
	v_mul_f32_e32 v216, v225, v12
	v_mul_f32_e32 v217, v225, v13
	v_mul_f32_e32 v218, v225, v14
	v_mul_f32_e32 v219, v225, v15
	v_fma_f32 v216, v216, v140, v172
	v_fma_f32 v217, v217, v141, v173
	v_fma_f32 v218, v218, v142, v174
	v_fma_f32 v219, v219, v143, v175
	v_cvt_pk_bf16_f32 v220, v216, v217
	v_cvt_pk_bf16_f32 v221, v218, v219
	global_store_dwordx2 v194, v[220:221], s[26:27] offset:1536
	v_mul_f32_e32 v216, v225, v16
	v_mul_f32_e32 v217, v225, v17
	v_mul_f32_e32 v218, v225, v18
	v_mul_f32_e32 v219, v225, v19
	v_fma_f32 v216, v216, v144, v176
	v_fma_f32 v217, v217, v145, v177
	v_fma_f32 v218, v218, v146, v178
	v_fma_f32 v219, v219, v147, v179
	v_cvt_pk_bf16_f32 v196, v216, v217
	v_cvt_pk_bf16_f32 v197, v218, v219
	global_store_dwordx2 v194, v[196:197], s[26:27] offset:2048
	v_mul_f32_e32 v216, v225, v20
	v_mul_f32_e32 v217, v225, v21
	v_mul_f32_e32 v218, v225, v22
	v_mul_f32_e32 v219, v225, v23
	v_fma_f32 v216, v216, v148, v180
	v_fma_f32 v217, v217, v149, v181
	v_fma_f32 v218, v218, v150, v182
	v_fma_f32 v219, v219, v151, v183
	v_cvt_pk_bf16_f32 v220, v216, v217
	v_cvt_pk_bf16_f32 v221, v218, v219
	global_store_dwordx2 v194, v[220:221], s[26:27] offset:2560
	v_mul_f32_e32 v216, v225, v24
	v_mul_f32_e32 v217, v225, v25
	v_mul_f32_e32 v218, v225, v26
	v_mul_f32_e32 v219, v225, v27
	v_fma_f32 v216, v216, v152, v184
	v_fma_f32 v217, v217, v153, v185
	v_fma_f32 v218, v218, v154, v186
	v_fma_f32 v219, v219, v155, v187
	v_cvt_pk_bf16_f32 v196, v216, v217
	v_cvt_pk_bf16_f32 v197, v218, v219
	global_store_dwordx2 v194, v[196:197], s[26:27] offset:3072
	v_mul_f32_e32 v216, v225, v28
	v_mul_f32_e32 v217, v225, v29
	v_mul_f32_e32 v218, v225, v30
	v_mul_f32_e32 v219, v225, v31
	v_fma_f32 v216, v216, v156, v188
	v_fma_f32 v217, v217, v157, v189
	v_fma_f32 v218, v218, v158, v190
	v_fma_f32 v219, v219, v159, v191
	v_cvt_pk_bf16_f32 v220, v216, v217
	v_cvt_pk_bf16_f32 v221, v218, v219
	global_store_dwordx2 v194, v[220:221], s[26:27] offset:3584
	s_branch .LBB0_778
; #define FRESH() int gtid; do { int t_ = threadIdx.x; asm volatile("" : "+v"(t_)); F.tid = t_; F.lane = t_ & 63; gtid = blockIdx.x * (NWAVES * 64) + t_; (void)gtid; } while (0)
; __global__ void __launch_bounds__(NWAVES * 64, 2) mk_fwd(Args args) {
;     ...
;     if (IN(6)) { FRESH();
;         for (int row0 = F.gw * 3; row0 < MT; row0 += F.NGW * 3) {
;             f32x4 v[3][8]; u32x2 yw[3][8];
; #pragma unroll
;             for (int q = 0; q < 3; ++q) { const int row = row0 + q; const float* src = row < ML ? x + (size_t)row * DM : ctx + (size_t)(row - ML) * DM; load_row_f32(src, F.lane, v[q]);
.Lp6_generic:
	v_mov_b32_e32 v0, v198
	s_cmpk_gt_i32 s33, 0x17ff
	s_cbranch_scc1 .LBB0_778
	v_lshlrev_b32_e32 v0, 2, v0
	v_and_b32_e32 v96, 0xfc, v0
	v_mbcnt_lo_u32_b32 v0, -1, 0
	v_mbcnt_hi_u32_b32 v0, -1, v0
	v_and_b32_e32 v1, 64, v0
	v_add_u32_e32 v1, 64, v1
	v_xor_b32_e32 v2, 1, v0
	v_cmp_lt_i32_e32 vcc, v2, v1
	v_mov_b32_e32 v99, 0
	s_add_u32 s0, s80, 0x2000
	v_cndmask_b32_e32 v2, v0, v2, vcc
	v_lshlrev_b32_e32 v97, 2, v2
	v_xor_b32_e32 v2, 2, v0
	v_cmp_lt_i32_e32 vcc, v2, v1
	s_addc_u32 s1, s81, 0
	v_mov_b32_e32 v5, v99
	v_cndmask_b32_e32 v2, v0, v2, vcc
	v_lshlrev_b32_e32 v199, 2, v2
	v_xor_b32_e32 v2, 4, v0
	v_cmp_lt_i32_e32 vcc, v2, v1
	v_mov_b32_e32 v7, v99
	v_mov_b32_e32 v9, v99
	v_cndmask_b32_e32 v2, v0, v2, vcc
	v_lshlrev_b32_e32 v200, 2, v2
	v_xor_b32_e32 v2, 8, v0
	v_cmp_lt_i32_e32 vcc, v2, v1
	s_mul_i32 s6, s33, 3
	v_or_b32_e32 v12, 0x500, v96
	v_cndmask_b32_e32 v2, v0, v2, vcc
	v_lshlrev_b32_e32 v201, 2, v2
	v_xor_b32_e32 v2, 16, v0
	v_cmp_lt_i32_e32 vcc, v2, v1
	v_or_b32_e32 v16, 0x600, v96
	v_or_b32_e32 v20, 0x700, v96
	v_cndmask_b32_e32 v2, v0, v2, vcc
	v_lshlrev_b32_e32 v202, 2, v2
	v_xor_b32_e32 v2, 32, v0
	v_cmp_lt_i32_e32 vcc, v2, v1
	v_mov_b32_e32 v1, v99
	v_mov_b32_e32 v11, v99
	v_cndmask_b32_e32 v0, v0, v2, vcc
	v_or_b32_e32 v2, 0x100, v96
	v_lshlrev_b32_e32 v4, 2, v2
	v_lshl_add_u64 v[104:105], s[0:1], 0, v[4:5]
	v_or_b32_e32 v4, 0x200, v96
	v_lshlrev_b32_e32 v6, 2, v4
	v_lshl_add_u64 v[106:107], s[0:1], 0, v[6:7]
	v_or_b32_e32 v6, 0x300, v96
	v_lshlrev_b32_e32 v8, 2, v6
	v_lshl_add_u64 v[108:109], s[0:1], 0, v[8:9]
	v_or_b32_e32 v8, 0x400, v96
	v_lshlrev_b32_e32 v203, 2, v0
	v_lshlrev_b32_e32 v0, 2, v96
	v_lshlrev_b32_e32 v10, 2, v8
	v_lshlrev_b32_e32 v14, 2, v12
	v_mov_b32_e32 v15, v99
	v_lshlrev_b32_e32 v18, 2, v16
	v_mov_b32_e32 v19, v99
	v_lshlrev_b32_e32 v22, 2, v20
	v_mov_b32_e32 v23, v99
	s_mul_i32 s10, s63, 24
	s_ashr_i32 s7, s6, 31
	v_lshl_add_u64 v[102:103], s[0:1], 0, v[0:1]
	v_lshl_add_u64 v[110:111], s[0:1], 0, v[10:11]
	v_lshl_add_u64 v[112:113], s[0:1], 0, v[14:15]
	v_lshl_add_u64 v[114:115], s[0:1], 0, v[18:19]
	v_lshl_add_u64 v[116:117], s[0:1], 0, v[22:23]
	s_ashr_i32 s11, s10, 31
	s_lshl_b64 s[0:1], s[6:7], 13
	v_lshlrev_b32_e32 v98, 1, v96
	s_add_u32 s22, s68, s0
	v_lshl_add_u64 v[100:101], s[20:21], 0, v[98:99]
	s_mov_b32 s9, 0
	v_lshl_add_u64 v[118:119], s[82:83], 0, v[0:1]
	v_lshl_add_u64 v[120:121], s[82:83], 0, v[10:11]
	v_lshl_add_u64 v[122:123], s[82:83], 0, v[14:15]
	v_lshl_add_u64 v[124:125], s[82:83], 0, v[18:19]
	v_lshl_add_u64 v[126:127], s[82:83], 0, v[22:23]
	v_lshl_add_u64 v[128:129], s[12:13], 0, v[98:99]
	s_addc_u32 s23, s69, s1
	s_lshl_b64 s[24:25], s[10:11], 13
	v_mov_b32_e32 v204, 0x358637bd
	v_lshlrev_b32_e32 v205, 2, v2
	v_lshlrev_b32_e32 v206, 2, v4
	v_lshlrev_b32_e32 v207, 2, v6
	v_lshlrev_b32_e32 v208, 2, v8
	v_lshlrev_b32_e32 v209, 2, v12
	v_lshlrev_b32_e32 v210, 2, v16
	v_lshlrev_b32_e32 v211, 2, v20
	s_branch .LBB0_720
